# speedup vs baseline: 1.0013x; 1.0013x over previous
; DEVI void rwkv_prep_item(const Params& p, const int l, const int item, char* smem) {
;     ...
;     for (int r = 0; r < 16; ++r) {
;       const int t = t0 + mt * 32 + (r & 3) + 8 * (r >> 2) + 4 * hi; const bool has_prev = (t & (SEQ_ - 1)) != 0;
;       float rv[2], kv[2], vv[2], av[2], kkv[2], kpv[2], omdv[2], gv[2];
;       float ssq = 0.f, bon = 0.f;
;       const u16* pr = PA + (size_t)t * 2560 + h * 64 + 2 * l31;
;       const unsigned cr2 = *(const unsigned*)pr, ck2 = *(const unsigned*)(pr + 768), cv2 = *(const unsigned*)(pr + 1536);
;       unsigned qr2 = 0u, qk2 = 0u, qv2 = 0u;
;       if (has_prev) { qr2 = *(const unsigned*)(pr - 2560); qk2 = *(const unsigned*)(pr + 768 - 2560); qv2 = *(const unsigned*)(pr + 1536 - 2560); }
; #pragma unroll
;       for (int n = 0; n < 2; ++n) {
;         const float cr = __uint_as_float(n ? (cr2 & 0xffff0000u) : (cr2 << 16)), ck = __uint_as_float(n ? (ck2 & 0xffff0000u) : (ck2 << 16)), cv = __uint_as_float(n ? (cv2 & 0xffff0000u) : (cv2 << 16));
;         const float qr = __uint_as_float(n ? (qr2 & 0xffff0000u) : (qr2 << 16)), qk = __uint_as_float(n ? (qk2 & 0xffff0000u) : (qk2 << 16)), qv = __uint_as_float(n ? (qv2 & 0xffff0000u) : (qv2 << 16));
;         rv[n] = cr + (qr - cr) * mur[n]; kv[n] = ck + (qk - ck) * muk[n]; vv[n] = cv + (qv - cv) * muv[n];
;         const float z = -(w0c[n] + aw[n][r]);
;         const float sp = fmaxf(z, 0.f) + __logf(1.f + __expf(-fabsf(z)));
;         const float ew = __expf(-sp - 0.5f);
;         omdv[n] = 1.f - __expf(-ew);
;         av[n] = sigmoidf_(a0c[n] + aa[n][r]);
;         gv[n] = ag[n][r];
;         kkv[n] = kv[n] * kkc[n];
;         kpv[n] = kv[n] * (1.f + (av[n] - 1.f) * kac[n]);
;         ssq += kkv[n] * kkv[n];
;         bon += rv[n] * kpv[n] * rkc[n];
;       }
;       ssq = reduce32(ssq); bon = reduce32(bon);
;       const float rn = rsqrtf(ssq + 1e-12f);
;       {
;         typedef _Float16 h2 __attribute__((ext_vector_type(2)));
;         const size_t o = (size_t)t * 768 + h * 64 + 2 * l31;
;         const float kn0 = kkv[0] * rn, kn1 = kkv[1] * rn;
;         *(h2*)(RW + o) = (h2){(f16)rv[0], (f16)rv[1]};
;         *(h2*)(RW + TS + o) = (h2){(f16)omdv[0], (f16)omdv[1]};
;         *(h2*)(RW + 2 * TS + o) = (h2){(f16)kpv[0], (f16)kpv[1]};
;         *(h2*)(RW + 3 * TS + o) = (h2){(f16)vv[0], (f16)vv[1]};
;         *(h2*)(RW + 4 * TS + o) = (h2){(f16)kn0, (f16)kn1};
.LBB0_452:
	s_or_b64 exec, exec, s[6:7]
	s_waitcnt vmcnt(10)
	s_nop 7
	v_add_f32_e32 v82, v82, v210
	s_waitcnt vmcnt(1)
	v_and_b32_e32 v223, 0xffff0000, v219
	v_lshlrev_b32_e32 v222, 16, v219
	v_mul_f32_e64 v219, |v82|, s88
	v_exp_f32_e32 v219, v219
	s_waitcnt vmcnt(0)
	v_or_b32_e32 v253, 1, v233
	v_mad_i64_i32 v[254:255], s[92:93], v253, s34, v[212:213]
	global_load_dword v246, v[254:255], off
	global_load_dword v247, v[254:255], off offset:1536
	global_load_dword v248, v[254:255], off offset:3072
	global_load_dword v249, v[254:255], off offset:-2048
	global_load_dword v250, v[254:255], off offset:-3584
	v_add_co_u32_e32 v254, vcc, 0xfffff000, v254
	s_nop 1
	v_addc_co_u32_e32 v255, vcc, -1, v255, vcc
	global_load_dword v251, v[254:255], off offset:-1024
	v_and_b32_e32 v225, 0xffff0000, v217
	v_lshlrev_b32_e32 v224, 16, v217
	v_and_b32_e32 v215, 0xffff0000, v220
	v_add_f32_e32 v217, 1.0, v219
	v_cmp_gt_f32_e32 vcc, s89, v217
	v_lshlrev_b32_e32 v214, 16, v220
	v_max_f32_e64 v82, -v82, 0
	v_cndmask_b32_e64 v219, 0, 32, vcc
	v_ldexp_f32 v217, v217, v219
	v_log_f32_e32 v217, v217
	v_add_f32_e32 v34, v34, v211
	v_add_f32_e32 v66, v66, v208
	v_add_f32_e32 v50, v50, v209
	v_mul_f32_e32 v220, 0x3f317217, v217
	v_fma_f32 v220, v217, s90, -v220
	v_fmac_f32_e32 v220, 0x3377d1cf, v217
	v_fmac_f32_e32 v220, 0x3f317217, v217
	v_cmp_lt_f32_e64 s[6:7], |v217|, s91
	v_mul_f32_e32 v66, 0xbfb8aa3b, v66
	v_mul_f32_e32 v50, 0xbfb8aa3b, v50
	v_cndmask_b32_e64 v217, v217, v220, s[6:7]
	v_cndmask_b32_e32 v220, 0, v232, vcc
	v_sub_f32_e32 v217, v217, v220
	v_add_f32_e32 v82, v82, v217
	v_mul_f32_e64 v217, |v34|, s88
	v_exp_f32_e32 v217, v217
	v_max_f32_e64 v34, -v34, 0
	v_sub_f32_e32 v82, -0.5, v82
	v_mul_f32_e32 v82, 0x3fb8aa3b, v82
	v_add_f32_e32 v217, 1.0, v217
	v_cmp_gt_f32_e32 vcc, s89, v217
	v_exp_f32_e32 v82, v82
	v_and_b32_e32 v235, 0xffff0000, v221
	v_cndmask_b32_e64 v220, 0, 32, vcc
	v_ldexp_f32 v217, v217, v220
	v_log_f32_e32 v217, v217
	v_lshlrev_b32_e32 v234, 16, v221
	v_exp_f32_e32 v221, v50
	v_pk_add_f32 v[234:235], v[234:235], v[214:215] neg_lo:[0,1] neg_hi:[0,1]
	v_mul_f32_e32 v220, 0x3f317217, v217
	v_fma_f32 v220, v217, s90, -v220
	v_fmac_f32_e32 v220, 0x3377d1cf, v217
	v_fmac_f32_e32 v220, 0x3f317217, v217
	v_cmp_lt_f32_e64 s[6:7], |v217|, s91
	v_mul_f32_e32 v82, 0xbfb8aa3b, v82
	v_pk_fma_f32 v[214:215], v[206:207], v[234:235], v[214:215]
	v_cndmask_b32_e64 v217, v217, v220, s[6:7]
	v_cndmask_b32_e32 v220, 0, v232, vcc
	v_sub_f32_e32 v217, v217, v220
	v_add_f32_e32 v34, v34, v217
	v_sub_f32_e32 v34, -0.5, v34
	v_mul_f32_e32 v34, 0x3fb8aa3b, v34
	v_exp_f32_e32 v34, v34
	v_exp_f32_e32 v220, v66
	v_mad_i64_i32 v[236:237], s[6:7], v233, s54, v[102:103]
	v_mul_f32_e32 v34, 0xbfb8aa3b, v34
	v_lshlrev_b64 v[234:235], 1, v[236:237]
	v_exp_f32_e32 v82, v82
	v_exp_f32_e32 v34, v34
	v_cvt_pk_f16_f32 v50, v214, v215
	v_lshl_add_u64 v[236:237], s[56:57], 0, v[234:235]
	v_pk_add_f32 v[220:221], v[220:221], 1.0 op_sel_hi:[1,0]
	global_store_dword v[236:237], v50, off
	v_div_scale_f32 v50, s[6:7], v221, v221, 1.0
	v_rcp_f32_e32 v66, v50
	v_sub_f32_e32 v82, 1.0, v82
	v_sub_f32_e32 v34, 1.0, v34
	v_cvt_pk_f16_f32 v34, v82, v34
	v_lshl_add_u64 v[236:237], s[62:63], 0, v[234:235]
	global_store_dword v[236:237], v34, off
	v_fma_f32 v34, -v50, v66, 1.0
	v_and_b32_e32 v219, 0xffff0000, v218
	v_lshlrev_b32_e32 v218, 16, v218
	v_fmac_f32_e32 v66, v34, v66
	v_div_scale_f32 v34, vcc, 1.0, v221, 1.0
	v_pk_add_f32 v[218:219], v[218:219], v[222:223] neg_lo:[0,1] neg_hi:[0,1]
	v_mul_f32_e32 v82, v34, v66
	v_pk_fma_f32 v[218:219], v[204:205], v[218:219], v[222:223]
	v_fma_f32 v222, -v50, v82, v34
	v_fmac_f32_e32 v82, v222, v66
	v_fma_f32 v34, -v50, v82, v34
	v_div_scale_f32 v50, s[6:7], v220, v220, 1.0
	v_rcp_f32_e32 v222, v50
	v_div_fmas_f32 v34, v34, v66, v82
	v_div_fixup_f32 v221, v34, v221, 1.0
	v_and_b32_e32 v217, 0xffff0000, v216
	v_fma_f32 v34, -v50, v222, 1.0
	v_fmac_f32_e32 v222, v34, v222
	v_div_scale_f32 v34, vcc, 1.0, v220, 1.0
	v_mul_f32_e32 v66, v34, v222
	v_fma_f32 v82, -v50, v66, v34
	v_fmac_f32_e32 v66, v82, v222
	v_fma_f32 v34, -v50, v66, v34
	v_div_fmas_f32 v34, v34, v222, v66
	v_div_fixup_f32 v220, v34, v220, 1.0
	v_pk_add_f32 v[222:223], v[220:221], -1.0 op_sel_hi:[1,0]
	v_lshlrev_b32_e32 v216, 16, v216
	v_pk_fma_f32 v[222:223], v[202:203], v[222:223], 1.0 op_sel_hi:[1,1,0]
	v_mov_b32_e32 v201, v103
	v_pk_mul_f32 v[222:223], v[222:223], v[218:219]
	v_lshl_add_u64 v[200:201], v[200:201], 2, s[58:59]
	v_pk_mul_f32 v[214:215], v[214:215], v[222:223]
	v_cvt_pk_f16_f32 v66, v222, v223
	v_fma_f32 v34, v198, v214, 0
	v_fmac_f32_e32 v34, v199, v215
	v_lshl_add_u64 v[214:215], s[64:65], 0, v[234:235]
	global_store_dword v[214:215], v66, off
	v_pk_add_f32 v[214:215], v[216:217], v[224:225] neg_lo:[0,1] neg_hi:[0,1]
	v_pk_mul_f32 v[216:217], v[194:195], v[218:219]
	v_pk_fma_f32 v[214:215], v[196:197], v[214:215], v[224:225]
	v_pk_mul_f32 v[218:219], v[216:217], v[216:217]
	v_add_f32_dpp v34, v34, v34 quad_perm:[1,0,3,2] row_mask:0xf bank_mask:0xf bound_ctrl:1
	v_add_f32_e32 v66, v218, v219
	v_cvt_pk_f16_f32 v2, v2, v18
	v_add_f32_dpp v34, v34, v34 quad_perm:[2,3,0,1] row_mask:0xf bank_mask:0xf bound_ctrl:1
	v_add_f32_dpp v66, v66, v66 quad_perm:[1,0,3,2] row_mask:0xf bank_mask:0xf bound_ctrl:1
	s_nop 0
	v_add_f32_dpp v34, v34, v34 row_half_mirror row_mask:0xf bank_mask:0xf bound_ctrl:1
	v_add_f32_dpp v66, v66, v66 quad_perm:[2,3,0,1] row_mask:0xf bank_mask:0xf bound_ctrl:1
	s_nop 0
	v_add_f32_dpp v34, v34, v34 row_mirror row_mask:0xf bank_mask:0xf bound_ctrl:1
	v_add_f32_dpp v66, v66, v66 row_half_mirror row_mask:0xf bank_mask:0xf bound_ctrl:1
	v_mov_b32_e32 v50, v34
	s_nop 1
	v_permlane16_swap_b32_e32 v34, v50
	v_add_f32_dpp v66, v66, v66 row_mirror row_mask:0xf bank_mask:0xf bound_ctrl:1
	v_mov_b32_e32 v82, v66
	s_nop 1
	v_permlane16_swap_b32_e32 v66, v82
	v_add_f32_e32 v66, v66, v82
	v_add_f32_e32 v66, 0x2b8cbccc, v66
	v_mul_f32_e32 v82, 0x4b800000, v66
	v_cmp_gt_f32_e32 vcc, s89, v66
	s_nop 1
	v_cndmask_b32_e32 v66, v66, v82, vcc
	v_rsq_f32_e32 v66, v66
	v_cvt_pk_f16_f32 v82, v214, v215
	v_lshl_add_u64 v[214:215], s[66:67], 0, v[234:235]
	global_store_dword v[214:215], v82, off
	v_mul_f32_e32 v82, 0x45800000, v66
	v_cndmask_b32_e32 v66, v66, v82, vcc
	v_pk_mul_f32 v[214:215], v[216:217], v[66:67] op_sel_hi:[1,0]
	v_lshl_add_u64 v[216:217], s[72:73], 0, v[234:235]
	v_cvt_pk_f16_f32 v66, v214, v215
	v_pk_mul_f32 v[214:215], v[220:221], v[214:215]
	global_store_dword v[216:217], v66, off
	v_cvt_pk_f16_f32 v66, v214, v215
	v_lshl_add_u64 v[214:215], s[78:79], 0, v[234:235]
	global_store_dword v[214:215], v66, off
	v_lshl_add_u64 v[214:215], s[82:83], 0, v[234:235]
	global_store_dword v[214:215], v2, off
	s_and_saveexec_b64 s[6:7], s[4:5]
	s_cbranch_execz .LBB0_454
	v_add_f32_e32 v2, v34, v50
	v_mad_i64_i32 v[214:215], s[92:93], v233, 48, v[200:201]
	global_store_dword v[214:215], v2, off
; DEVI void rwkv_prep_item(const Params& p, const int l, const int item, char* smem) {
;     ...
;     for (int r = 0; r < 16; ++r) {
;       const int t = t0 + mt * 32 + (r & 3) + 8 * (r >> 2) + 4 * hi; const bool has_prev = (t & (SEQ_ - 1)) != 0;
;       float rv[2], kv[2], vv[2], av[2], kkv[2], kpv[2], omdv[2], gv[2];
;       float ssq = 0.f, bon = 0.f;
;       const u16* pr = PA + (size_t)t * 2560 + h * 64 + 2 * l31;
;       const unsigned cr2 = *(const unsigned*)pr, ck2 = *(const unsigned*)(pr + 768), cv2 = *(const unsigned*)(pr + 1536);
;       unsigned qr2 = 0u, qk2 = 0u, qv2 = 0u;
;       if (has_prev) { qr2 = *(const unsigned*)(pr - 2560); qk2 = *(const unsigned*)(pr + 768 - 2560); qv2 = *(const unsigned*)(pr + 1536 - 2560); }
; #pragma unroll
;       for (int n = 0; n < 2; ++n) {
;         const float cr = __uint_as_float(n ? (cr2 & 0xffff0000u) : (cr2 << 16)), ck = __uint_as_float(n ? (ck2 & 0xffff0000u) : (ck2 << 16)), cv = __uint_as_float(n ? (cv2 & 0xffff0000u) : (cv2 << 16));
;         const float qr = __uint_as_float(n ? (qr2 & 0xffff0000u) : (qr2 << 16)), qk = __uint_as_float(n ? (qk2 & 0xffff0000u) : (qk2 << 16)), qv = __uint_as_float(n ? (qv2 & 0xffff0000u) : (qv2 << 16));
;         rv[n] = cr + (qr - cr) * mur[n]; kv[n] = ck + (qk - ck) * muk[n]; vv[n] = cv + (qv - cv) * muv[n];
;         const float z = -(w0c[n] + aw[n][r]);
;         const float sp = fmaxf(z, 0.f) + __logf(1.f + __expf(-fabsf(z)));
;         const float ew = __expf(-sp - 0.5f);
;         omdv[n] = 1.f - __expf(-ew);
;         av[n] = sigmoidf_(a0c[n] + aa[n][r]);
;         gv[n] = ag[n][r];
;         kkv[n] = kv[n] * kkc[n];
;         kpv[n] = kv[n] * (1.f + (av[n] - 1.f) * kac[n]);
;         ssq += kkv[n] * kkv[n];
;         bon += rv[n] * kpv[n] * rkc[n];
;       }
;       ssq = reduce32(ssq); bon = reduce32(bon);
;       const float rn = rsqrtf(ssq + 1e-12f);
;       {
;         typedef _Float16 h2 __attribute__((ext_vector_type(2)));
;         const size_t o = (size_t)t * 768 + h * 64 + 2 * l31;
;         const float kn0 = kkv[0] * rn, kn1 = kkv[1] * rn;
;         *(h2*)(RW + o) = (h2){(f16)rv[0], (f16)rv[1]};
;         *(h2*)(RW + TS + o) = (h2){(f16)omdv[0], (f16)omdv[1]};
;         *(h2*)(RW + 2 * TS + o) = (h2){(f16)kpv[0], (f16)kpv[1]};
;         *(h2*)(RW + 3 * TS + o) = (h2){(f16)vv[0], (f16)vv[1]};
;         *(h2*)(RW + 4 * TS + o) = (h2){(f16)kn0, (f16)kn1};
.LBB0_454:
	s_or_b64 exec, exec, s[6:7]
	v_or_b32_e32 v2, 1, v233
	v_mad_i64_i32 v[214:215], s[6:7], v2, s34, v[212:213]
	s_waitcnt vmcnt(7)
	v_mov_b32_e32 v18, v246
	v_mov_b32_e32 v34, v247
	v_mov_b32_e32 v50, v248
	v_mov_b32_e32 v66, v249
	v_mov_b32_e32 v82, v250
	v_add_co_u32_e32 v214, vcc, 0xfffff000, v214
	v_add_f32_e32 v35, v35, v211
	s_nop 0
	v_addc_co_u32_e32 v215, vcc, -1, v215, vcc
	v_mov_b32_e32 v216, v251
	v_or_b32_e32 v253, 2, v233
	v_mad_i64_i32 v[254:255], s[92:93], v253, s34, v[212:213]
	global_load_dword v246, v[254:255], off
	global_load_dword v247, v[254:255], off offset:1536
	global_load_dword v248, v[254:255], off offset:3072
	global_load_dword v249, v[254:255], off offset:-2048
	global_load_dword v250, v[254:255], off offset:-3584
	v_add_co_u32_e32 v254, vcc, 0xfffff000, v254
	s_nop 1
	v_addc_co_u32_e32 v255, vcc, -1, v255, vcc
	global_load_dword v251, v[254:255], off offset:-1024
	v_cvt_pk_f16_f32 v3, v3, v19
	s_nop 0
	v_and_b32_e32 v223, 0xffff0000, v18
	v_lshlrev_b32_e32 v222, 16, v18
	v_add_f32_e32 v18, v83, v210
	s_nop 0
	v_and_b32_e32 v219, 0xffff0000, v34
	v_lshlrev_b32_e32 v218, 16, v34
	v_max_f32_e64 v34, -v18, 0
	v_mul_f32_e64 v18, |v18|, s88
	v_exp_f32_e32 v18, v18
	s_nop 0
	v_and_b32_e32 v215, 0xffff0000, v50
	v_lshlrev_b32_e32 v214, 16, v50
	s_nop 0
	v_and_b32_e32 v225, 0xffff0000, v216
	v_add_f32_e32 v18, 1.0, v18
	v_cmp_gt_f32_e32 vcc, s89, v18
	v_lshlrev_b32_e32 v224, 16, v216
	v_and_b32_e32 v217, 0xffff0000, v66
	v_cndmask_b32_e64 v50, 0, 32, vcc
	v_ldexp_f32 v18, v18, v50
	v_log_f32_e32 v18, v18
	v_lshlrev_b32_e32 v216, 16, v66
	v_and_b32_e32 v221, 0xffff0000, v82
	v_lshlrev_b32_e32 v220, 16, v82
	v_mul_f32_e32 v50, 0x3f317217, v18
	v_fma_f32 v50, v18, s90, -v50
	v_fmac_f32_e32 v50, 0x3377d1cf, v18
	v_fmac_f32_e32 v50, 0x3f317217, v18
	v_cmp_lt_f32_e64 s[6:7], |v18|, s91
	s_nop 1
	v_cndmask_b32_e64 v18, v18, v50, s[6:7]
	v_cndmask_b32_e32 v50, 0, v232, vcc
	v_sub_f32_e32 v18, v18, v50
	v_max_f32_e64 v50, -v35, 0
	v_mul_f32_e64 v35, |v35|, s88
	v_exp_f32_e32 v35, v35
	v_add_f32_e32 v18, v34, v18
	v_sub_f32_e32 v18, -0.5, v18
	v_mul_f32_e32 v18, 0x3fb8aa3b, v18
	v_add_f32_e32 v35, 1.0, v35
	v_cmp_gt_f32_e32 vcc, s89, v35
	v_exp_f32_e32 v18, v18
	v_add_f32_e32 v34, v67, v208
	v_cndmask_b32_e64 v66, 0, 32, vcc
	v_ldexp_f32 v35, v35, v66
	v_log_f32_e32 v35, v35
	v_mul_f32_e32 v18, 0xbfb8aa3b, v18
	v_exp_f32_e32 v18, v18
	v_mul_f32_e32 v34, 0xbfb8aa3b, v34
	v_mul_f32_e32 v66, 0x3f317217, v35
	v_fma_f32 v66, v35, s90, -v66
	v_fmac_f32_e32 v66, 0x3377d1cf, v35
	v_fmac_f32_e32 v66, 0x3f317217, v35
	v_cmp_lt_f32_e64 s[6:7], |v35|, s91
	v_exp_f32_e32 v34, v34
	v_sub_f32_e32 v18, 1.0, v18
	v_cndmask_b32_e64 v35, v35, v66, s[6:7]
	v_cndmask_b32_e32 v66, 0, v232, vcc
	v_sub_f32_e32 v35, v35, v66
	v_add_f32_e32 v35, v50, v35
	v_sub_f32_e32 v35, -0.5, v35
	v_mul_f32_e32 v35, 0x3fb8aa3b, v35
	v_exp_f32_e32 v35, v35
	v_mad_i64_i32 v[66:67], s[6:7], v2, s54, v[102:103]
	v_lshlrev_b64 v[66:67], 1, v[66:67]
	v_mul_f32_e32 v35, 0xbfb8aa3b, v35
	v_exp_f32_e32 v35, v35
	v_lshl_add_u64 v[82:83], s[56:57], 0, v[66:67]
	v_sub_f32_e32 v234, 1.0, v35
	v_add_f32_e32 v35, v51, v209
	v_mul_f32_e32 v35, 0xbfb8aa3b, v35
	v_exp_f32_e32 v35, v35
	v_pk_add_f32 v[50:51], v[224:225], v[222:223] neg_lo:[0,1] neg_hi:[0,1]
	v_cvt_pk_f16_f32 v18, v18, v234
	v_pk_fma_f32 v[50:51], v[206:207], v[50:51], v[222:223]
	v_pk_add_f32 v[34:35], v[34:35], 1.0 op_sel_hi:[1,0]
	v_cvt_pk_f16_f32 v222, v50, v51
	global_store_dword v[82:83], v222, off
	v_lshl_add_u64 v[82:83], s[62:63], 0, v[66:67]
	global_store_dword v[82:83], v18, off
	v_pk_add_f32 v[82:83], v[220:221], v[218:219] neg_lo:[0,1] neg_hi:[0,1]
	v_div_scale_f32 v18, s[6:7], v35, v35, 1.0
	v_pk_fma_f32 v[82:83], v[204:205], v[82:83], v[218:219]
	v_rcp_f32_e32 v218, v18
	s_nop 0
	v_fma_f32 v219, -v18, v218, 1.0
	v_fmac_f32_e32 v218, v219, v218
	v_div_scale_f32 v219, vcc, 1.0, v35, 1.0
	v_mul_f32_e32 v220, v219, v218
	v_fma_f32 v221, -v18, v220, v219
	v_fmac_f32_e32 v220, v221, v218
	v_fma_f32 v18, -v18, v220, v219
	v_div_fmas_f32 v18, v18, v218, v220
	v_div_fixup_f32 v219, v18, v35, 1.0
	v_div_scale_f32 v18, s[6:7], v34, v34, 1.0
	v_rcp_f32_e32 v35, v18
	s_nop 0
	v_fma_f32 v218, -v18, v35, 1.0
	v_fmac_f32_e32 v35, v218, v35
	v_div_scale_f32 v218, vcc, 1.0, v34, 1.0
	v_mul_f32_e32 v220, v218, v35
	v_fma_f32 v221, -v18, v220, v218
	v_fmac_f32_e32 v220, v221, v35
	v_fma_f32 v18, -v18, v220, v218
	v_div_fmas_f32 v18, v18, v35, v220
	v_div_fixup_f32 v218, v18, v34, 1.0
	v_pk_add_f32 v[34:35], v[218:219], -1.0 op_sel_hi:[1,0]
	s_nop 0
	v_pk_fma_f32 v[34:35], v[202:203], v[34:35], 1.0 op_sel_hi:[1,1,0]
	s_nop 0
	v_pk_mul_f32 v[220:221], v[34:35], v[82:83]
	s_nop 0
	v_pk_mul_f32 v[34:35], v[50:51], v[220:221]
	v_lshl_add_u64 v[50:51], s[64:65], 0, v[66:67]
	v_fma_f32 v18, v198, v34, 0
	v_fmac_f32_e32 v18, v199, v35
	v_cvt_pk_f16_f32 v35, v220, v221
	global_store_dword v[50:51], v35, off
	v_pk_add_f32 v[50:51], v[216:217], v[214:215] neg_lo:[0,1] neg_hi:[0,1]
	v_add_f32_dpp v18, v18, v18 quad_perm:[1,0,3,2] row_mask:0xf bank_mask:0xf bound_ctrl:1
	v_pk_fma_f32 v[50:51], v[196:197], v[50:51], v[214:215]
	s_nop 0
	v_cvt_pk_f16_f32 v35, v50, v51
	v_lshl_add_u64 v[50:51], s[66:67], 0, v[66:67]
	global_store_dword v[50:51], v35, off
	v_pk_mul_f32 v[50:51], v[194:195], v[82:83]
	v_add_f32_dpp v18, v18, v18 quad_perm:[2,3,0,1] row_mask:0xf bank_mask:0xf bound_ctrl:1
	v_pk_mul_f32 v[82:83], v[50:51], v[50:51]
	s_nop 0
	v_add_f32_e32 v35, v82, v83
	v_add_f32_dpp v18, v18, v18 row_half_mirror row_mask:0xf bank_mask:0xf bound_ctrl:1
	s_nop 0
	v_add_f32_dpp v35, v35, v35 quad_perm:[1,0,3,2] row_mask:0xf bank_mask:0xf bound_ctrl:1
	v_add_f32_dpp v18, v18, v18 row_mirror row_mask:0xf bank_mask:0xf bound_ctrl:1
	v_mov_b32_e32 v34, v18
	v_add_f32_dpp v35, v35, v35 quad_perm:[2,3,0,1] row_mask:0xf bank_mask:0xf bound_ctrl:1
	s_nop 0
	v_permlane16_swap_b32_e32 v18, v34
	v_add_f32_dpp v35, v35, v35 row_half_mirror row_mask:0xf bank_mask:0xf bound_ctrl:1
	s_nop 1
	v_add_f32_dpp v35, v35, v35 row_mirror row_mask:0xf bank_mask:0xf bound_ctrl:1
	v_mov_b32_e32 v82, v35
	s_nop 1
	v_permlane16_swap_b32_e32 v35, v82
	v_add_f32_e32 v35, v35, v82
	v_add_f32_e32 v35, 0x2b8cbccc, v35
	v_cmp_gt_f32_e32 vcc, s89, v35
	v_mul_f32_e32 v82, 0x4b800000, v35
	s_nop 0
	v_cndmask_b32_e32 v35, v35, v82, vcc
	v_rsq_f32_e32 v35, v35
	s_nop 0
	v_mul_f32_e32 v82, 0x45800000, v35
	v_cndmask_b32_e32 v82, v35, v82, vcc
	v_pk_mul_f32 v[50:51], v[50:51], v[82:83] op_sel_hi:[1,0]
	v_lshl_add_u64 v[82:83], s[72:73], 0, v[66:67]
	v_cvt_pk_f16_f32 v35, v50, v51
	v_pk_mul_f32 v[50:51], v[218:219], v[50:51]
	global_store_dword v[82:83], v35, off
	v_cvt_pk_f16_f32 v35, v50, v51
	v_lshl_add_u64 v[50:51], s[78:79], 0, v[66:67]
	global_store_dword v[50:51], v35, off
	v_lshl_add_u64 v[50:51], s[82:83], 0, v[66:67]
	global_store_dword v[50:51], v3, off
	s_and_saveexec_b64 s[6:7], s[4:5]
	s_cbranch_execz .LBB0_456
	v_add_f32_e32 v18, v18, v34
	v_mad_i64_i32 v[2:3], s[92:93], v2, 48, v[200:201]
	global_store_dword v[2:3], v18, off
; DEVI void rwkv_prep_item(const Params& p, const int l, const int item, char* smem) {
;     ...
;     for (int r = 0; r < 16; ++r) {
;       const int t = t0 + mt * 32 + (r & 3) + 8 * (r >> 2) + 4 * hi; const bool has_prev = (t & (SEQ_ - 1)) != 0;
;       float rv[2], kv[2], vv[2], av[2], kkv[2], kpv[2], omdv[2], gv[2];
;       float ssq = 0.f, bon = 0.f;
;       const u16* pr = PA + (size_t)t * 2560 + h * 64 + 2 * l31;
;       const unsigned cr2 = *(const unsigned*)pr, ck2 = *(const unsigned*)(pr + 768), cv2 = *(const unsigned*)(pr + 1536);
;       unsigned qr2 = 0u, qk2 = 0u, qv2 = 0u;
;       if (has_prev) { qr2 = *(const unsigned*)(pr - 2560); qk2 = *(const unsigned*)(pr + 768 - 2560); qv2 = *(const unsigned*)(pr + 1536 - 2560); }
; #pragma unroll
;       for (int n = 0; n < 2; ++n) {
;         const float cr = __uint_as_float(n ? (cr2 & 0xffff0000u) : (cr2 << 16)), ck = __uint_as_float(n ? (ck2 & 0xffff0000u) : (ck2 << 16)), cv = __uint_as_float(n ? (cv2 & 0xffff0000u) : (cv2 << 16));
;         const float qr = __uint_as_float(n ? (qr2 & 0xffff0000u) : (qr2 << 16)), qk = __uint_as_float(n ? (qk2 & 0xffff0000u) : (qk2 << 16)), qv = __uint_as_float(n ? (qv2 & 0xffff0000u) : (qv2 << 16));
;         rv[n] = cr + (qr - cr) * mur[n]; kv[n] = ck + (qk - ck) * muk[n]; vv[n] = cv + (qv - cv) * muv[n];
;         const float z = -(w0c[n] + aw[n][r]);
;         const float sp = fmaxf(z, 0.f) + __logf(1.f + __expf(-fabsf(z)));
;         const float ew = __expf(-sp - 0.5f);
;         omdv[n] = 1.f - __expf(-ew);
;         av[n] = sigmoidf_(a0c[n] + aa[n][r]);
;         gv[n] = ag[n][r];
;         kkv[n] = kv[n] * kkc[n];
;         kpv[n] = kv[n] * (1.f + (av[n] - 1.f) * kac[n]);
;         ssq += kkv[n] * kkv[n];
;         bon += rv[n] * kpv[n] * rkc[n];
;       }
;       ssq = reduce32(ssq); bon = reduce32(bon);
;       const float rn = rsqrtf(ssq + 1e-12f);
;       {
;         typedef _Float16 h2 __attribute__((ext_vector_type(2)));
;         const size_t o = (size_t)t * 768 + h * 64 + 2 * l31;
;         const float kn0 = kkv[0] * rn, kn1 = kkv[1] * rn;
;         *(h2*)(RW + o) = (h2){(f16)rv[0], (f16)rv[1]};
;         *(h2*)(RW + TS + o) = (h2){(f16)omdv[0], (f16)omdv[1]};
;         *(h2*)(RW + 2 * TS + o) = (h2){(f16)kpv[0], (f16)kpv[1]};
;         *(h2*)(RW + 3 * TS + o) = (h2){(f16)vv[0], (f16)vv[1]};
;         *(h2*)(RW + 4 * TS + o) = (h2){(f16)kn0, (f16)kn1};
.LBB0_456:
	s_or_b64 exec, exec, s[6:7]
	v_or_b32_e32 v216, 2, v233
	v_mad_i64_i32 v[2:3], s[6:7], v216, s34, v[212:213]
	s_waitcnt vmcnt(7)
	v_mov_b32_e32 v18, v246
	v_mov_b32_e32 v19, v247
	v_mov_b32_e32 v50, v248
	v_mov_b32_e32 v66, v249
	v_mov_b32_e32 v67, v250
	v_add_co_u32_e32 v2, vcc, 0xfffff000, v2
	v_add_f32_e32 v36, v36, v211
	s_nop 0
	v_addc_co_u32_e32 v3, vcc, -1, v3, vcc
	v_mov_b32_e32 v51, v251
	v_or_b32_e32 v253, 3, v233
	v_mad_i64_i32 v[254:255], s[92:93], v253, s34, v[212:213]
	global_load_dword v246, v[254:255], off
	global_load_dword v247, v[254:255], off offset:1536
	global_load_dword v248, v[254:255], off offset:3072
	global_load_dword v249, v[254:255], off offset:-2048
	global_load_dword v250, v[254:255], off offset:-3584
	v_add_co_u32_e32 v254, vcc, 0xfffff000, v254
	s_nop 1
	v_addc_co_u32_e32 v255, vcc, -1, v255, vcc
	global_load_dword v251, v[254:255], off offset:-1024
	v_add_f32_e32 v52, v52, v209
	v_mul_f32_e32 v52, 0xbfb8aa3b, v52
	v_cvt_pk_f16_f32 v4, v4, v20
	s_nop 0
	v_and_b32_e32 v83, 0xffff0000, v18
	v_lshlrev_b32_e32 v82, 16, v18
	s_nop 0
	v_and_b32_e32 v35, 0xffff0000, v19
	v_lshlrev_b32_e32 v34, 16, v19
	s_nop 0
	v_and_b32_e32 v19, 0xffff0000, v66
	v_lshlrev_b32_e32 v18, 16, v66
	v_add_f32_e32 v66, v84, v210
	v_and_b32_e32 v3, 0xffff0000, v50
	v_lshlrev_b32_e32 v2, 16, v50
	s_nop 0
	v_lshlrev_b32_e32 v50, 16, v67
	s_nop 0
	v_and_b32_e32 v215, 0xffff0000, v51
	v_lshlrev_b32_e32 v214, 16, v51
	v_and_b32_e32 v51, 0xffff0000, v67
	v_max_f32_e64 v67, -v66, 0
	v_mul_f32_e64 v66, |v66|, s88
	v_exp_f32_e32 v66, v66
	v_pk_add_f32 v[214:215], v[214:215], v[82:83] neg_lo:[0,1] neg_hi:[0,1]
	v_pk_add_f32 v[50:51], v[50:51], v[34:35] neg_lo:[0,1] neg_hi:[0,1]
	v_pk_fma_f32 v[82:83], v[206:207], v[214:215], v[82:83]
	v_add_f32_e32 v66, 1.0, v66
	v_cmp_gt_f32_e32 vcc, s89, v66
	v_pk_fma_f32 v[50:51], v[204:205], v[50:51], v[34:35]
	v_pk_add_f32 v[18:19], v[18:19], v[2:3] neg_lo:[0,1] neg_hi:[0,1]
	v_cndmask_b32_e64 v84, 0, 32, vcc
	v_ldexp_f32 v66, v66, v84
	v_log_f32_e32 v66, v66
	v_pk_fma_f32 v[2:3], v[196:197], v[18:19], v[2:3]
	v_mul_f32_e32 v84, 0x3f317217, v66
	v_fma_f32 v84, v66, s90, -v84
	v_fmac_f32_e32 v84, 0x3377d1cf, v66
	v_fmac_f32_e32 v84, 0x3f317217, v66
	v_cmp_lt_f32_e64 s[6:7], |v66|, s91
	v_cvt_pk_f16_f32 v18, v2, v3
	s_nop 0
	v_cndmask_b32_e64 v66, v66, v84, s[6:7]
	v_cndmask_b32_e32 v84, 0, v232, vcc
	v_sub_f32_e32 v66, v66, v84
	v_add_f32_e32 v66, v67, v66
	v_sub_f32_e32 v66, -0.5, v66
	v_mul_f32_e32 v66, 0x3fb8aa3b, v66
	v_exp_f32_e32 v66, v66
	v_max_f32_e64 v67, -v36, 0
	v_mul_f32_e64 v36, |v36|, s88
	v_exp_f32_e32 v36, v36
	v_mul_f32_e32 v66, 0xbfb8aa3b, v66
	v_exp_f32_e32 v66, v66
	v_add_f32_e32 v36, 1.0, v36
	v_cmp_gt_f32_e32 vcc, s89, v36
	v_sub_f32_e32 v84, 1.0, v66
	v_add_f32_e32 v66, v68, v208
	v_cndmask_b32_e64 v68, 0, 32, vcc
	v_ldexp_f32 v36, v36, v68
	v_log_f32_e32 v36, v36
	v_mul_f32_e32 v66, 0xbfb8aa3b, v66
	v_exp_f32_e32 v66, v66
	v_mul_f32_e32 v68, 0x3f317217, v36
	v_fma_f32 v68, v36, s90, -v68
	v_fmac_f32_e32 v68, 0x3377d1cf, v36
	v_fmac_f32_e32 v68, 0x3f317217, v36
	v_cmp_lt_f32_e64 s[6:7], |v36|, s91
	s_nop 1
	v_cndmask_b32_e64 v36, v36, v68, s[6:7]
	v_cndmask_b32_e32 v68, 0, v232, vcc
	v_sub_f32_e32 v36, v36, v68
	v_add_f32_e32 v36, v67, v36
	v_sub_f32_e32 v36, -0.5, v36
	v_mul_f32_e32 v36, 0x3fb8aa3b, v36
	v_exp_f32_e32 v36, v36
	v_exp_f32_e32 v67, v52
	v_mad_i64_i32 v[218:219], s[6:7], v216, s54, v[102:103]
	v_mul_f32_e32 v36, 0xbfb8aa3b, v36
	v_exp_f32_e32 v36, v36
	v_lshlrev_b64 v[214:215], 1, v[218:219]
	v_cvt_pk_f16_f32 v52, v82, v83
	v_lshl_add_u64 v[218:219], s[56:57], 0, v[214:215]
	v_sub_f32_e32 v36, 1.0, v36
	global_store_dword v[218:219], v52, off
	v_cvt_pk_f16_f32 v36, v84, v36
	v_lshl_add_u64 v[218:219], s[62:63], 0, v[214:215]
	v_pk_add_f32 v[34:35], v[66:67], 1.0 op_sel_hi:[1,0]
	global_store_dword v[218:219], v36, off
	v_div_scale_f32 v36, s[6:7], v35, v35, 1.0
	v_rcp_f32_e32 v52, v36
	v_lshl_add_u64 v[2:3], s[66:67], 0, v[214:215]
	global_store_dword v[2:3], v18, off
	v_pk_mul_f32 v[2:3], v[194:195], v[50:51]
	v_fma_f32 v66, -v36, v52, 1.0
	v_fmac_f32_e32 v52, v66, v52
	v_div_scale_f32 v66, vcc, 1.0, v35, 1.0
	v_mul_f32_e32 v67, v66, v52
	v_fma_f32 v68, -v36, v67, v66
	v_fmac_f32_e32 v67, v68, v52
	v_fma_f32 v36, -v36, v67, v66
	v_div_fmas_f32 v36, v36, v52, v67
	v_div_fixup_f32 v67, v36, v35, 1.0
	v_div_scale_f32 v35, s[6:7], v34, v34, 1.0
	v_rcp_f32_e32 v36, v35
	v_pk_mul_f32 v[18:19], v[2:3], v[2:3]
	v_fma_f32 v52, -v35, v36, 1.0
	v_add_f32_e32 v18, v18, v19
	v_fmac_f32_e32 v36, v52, v36
	v_div_scale_f32 v52, vcc, 1.0, v34, 1.0
	v_add_f32_dpp v18, v18, v18 quad_perm:[1,0,3,2] row_mask:0xf bank_mask:0xf bound_ctrl:1
	v_mul_f32_e32 v66, v52, v36
	v_fma_f32 v68, -v35, v66, v52
	v_add_f32_dpp v18, v18, v18 quad_perm:[2,3,0,1] row_mask:0xf bank_mask:0xf bound_ctrl:1
	v_fmac_f32_e32 v66, v68, v36
	v_fma_f32 v35, -v35, v66, v52
	v_add_f32_dpp v18, v18, v18 row_half_mirror row_mask:0xf bank_mask:0xf bound_ctrl:1
	v_div_fmas_f32 v35, v35, v36, v66
	v_div_fixup_f32 v66, v35, v34, 1.0
	v_add_f32_dpp v18, v18, v18 row_mirror row_mask:0xf bank_mask:0xf bound_ctrl:1
	v_mov_b32_e32 v19, v18
	s_nop 1
	v_permlane16_swap_b32_e32 v18, v19
	v_add_f32_e32 v18, v18, v19
	v_add_f32_e32 v18, 0x2b8cbccc, v18
	v_pk_add_f32 v[34:35], v[66:67], -1.0 op_sel_hi:[1,0]
	v_cmp_gt_f32_e32 vcc, s89, v18
	v_mul_f32_e32 v19, 0x4b800000, v18
	v_pk_fma_f32 v[34:35], v[202:203], v[34:35], 1.0 op_sel_hi:[1,1,0]
	v_cndmask_b32_e32 v18, v18, v19, vcc
	v_pk_mul_f32 v[218:219], v[34:35], v[50:51]
	v_rsq_f32_e32 v18, v18
	v_pk_mul_f32 v[34:35], v[82:83], v[218:219]
	v_cvt_pk_f16_f32 v36, v218, v219
	v_fma_f32 v34, v198, v34, 0
	v_fmac_f32_e32 v34, v199, v35
	v_mul_f32_e32 v19, 0x45800000, v18
	v_cndmask_b32_e32 v18, v18, v19, vcc
	v_add_f32_dpp v34, v34, v34 quad_perm:[1,0,3,2] row_mask:0xf bank_mask:0xf bound_ctrl:1
	v_lshl_add_u64 v[82:83], s[64:65], 0, v[214:215]
	v_pk_mul_f32 v[2:3], v[2:3], v[18:19] op_sel_hi:[1,0]
	v_add_f32_dpp v34, v34, v34 quad_perm:[2,3,0,1] row_mask:0xf bank_mask:0xf bound_ctrl:1
	global_store_dword v[82:83], v36, off
	v_cvt_pk_f16_f32 v36, v2, v3
	v_add_f32_dpp v34, v34, v34 row_half_mirror row_mask:0xf bank_mask:0xf bound_ctrl:1
	v_lshl_add_u64 v[18:19], s[72:73], 0, v[214:215]
	v_pk_mul_f32 v[2:3], v[66:67], v[2:3]
	v_add_f32_dpp v34, v34, v34 row_mirror row_mask:0xf bank_mask:0xf bound_ctrl:1
	v_mov_b32_e32 v35, v34
	global_store_dword v[18:19], v36, off
	v_cvt_pk_f16_f32 v18, v2, v3
	v_lshl_add_u64 v[2:3], s[78:79], 0, v[214:215]
	v_permlane16_swap_b32_e32 v34, v35
	global_store_dword v[2:3], v18, off
	v_lshl_add_u64 v[2:3], s[82:83], 0, v[214:215]
	global_store_dword v[2:3], v4, off
	s_and_saveexec_b64 s[6:7], s[4:5]
	s_cbranch_execz .LBB0_458
	v_add_f32_e32 v4, v34, v35
	v_mad_i64_i32 v[2:3], s[92:93], v216, 48, v[200:201]
	global_store_dword v[2:3], v4, off
; DEVI void rwkv_prep_item(const Params& p, const int l, const int item, char* smem) {
;     ...
;     for (int r = 0; r < 16; ++r) {
;       const int t = t0 + mt * 32 + (r & 3) + 8 * (r >> 2) + 4 * hi; const bool has_prev = (t & (SEQ_ - 1)) != 0;
;       float rv[2], kv[2], vv[2], av[2], kkv[2], kpv[2], omdv[2], gv[2];
;       float ssq = 0.f, bon = 0.f;
;       const u16* pr = PA + (size_t)t * 2560 + h * 64 + 2 * l31;
;       const unsigned cr2 = *(const unsigned*)pr, ck2 = *(const unsigned*)(pr + 768), cv2 = *(const unsigned*)(pr + 1536);
;       unsigned qr2 = 0u, qk2 = 0u, qv2 = 0u;
;       if (has_prev) { qr2 = *(const unsigned*)(pr - 2560); qk2 = *(const unsigned*)(pr + 768 - 2560); qv2 = *(const unsigned*)(pr + 1536 - 2560); }
; #pragma unroll
;       for (int n = 0; n < 2; ++n) {
;         const float cr = __uint_as_float(n ? (cr2 & 0xffff0000u) : (cr2 << 16)), ck = __uint_as_float(n ? (ck2 & 0xffff0000u) : (ck2 << 16)), cv = __uint_as_float(n ? (cv2 & 0xffff0000u) : (cv2 << 16));
;         const float qr = __uint_as_float(n ? (qr2 & 0xffff0000u) : (qr2 << 16)), qk = __uint_as_float(n ? (qk2 & 0xffff0000u) : (qk2 << 16)), qv = __uint_as_float(n ? (qv2 & 0xffff0000u) : (qv2 << 16));
;         rv[n] = cr + (qr - cr) * mur[n]; kv[n] = ck + (qk - ck) * muk[n]; vv[n] = cv + (qv - cv) * muv[n];
;         const float z = -(w0c[n] + aw[n][r]);
;         const float sp = fmaxf(z, 0.f) + __logf(1.f + __expf(-fabsf(z)));
;         const float ew = __expf(-sp - 0.5f);
;         omdv[n] = 1.f - __expf(-ew);
;         av[n] = sigmoidf_(a0c[n] + aa[n][r]);
;         gv[n] = ag[n][r];
;         kkv[n] = kv[n] * kkc[n];
;         kpv[n] = kv[n] * (1.f + (av[n] - 1.f) * kac[n]);
;         ssq += kkv[n] * kkv[n];
;         bon += rv[n] * kpv[n] * rkc[n];
;       }
;       ssq = reduce32(ssq); bon = reduce32(bon);
;       const float rn = rsqrtf(ssq + 1e-12f);
;       {
;         typedef _Float16 h2 __attribute__((ext_vector_type(2)));
;         const size_t o = (size_t)t * 768 + h * 64 + 2 * l31;
;         const float kn0 = kkv[0] * rn, kn1 = kkv[1] * rn;
;         *(h2*)(RW + o) = (h2){(f16)rv[0], (f16)rv[1]};
;         *(h2*)(RW + TS + o) = (h2){(f16)omdv[0], (f16)omdv[1]};
;         *(h2*)(RW + 2 * TS + o) = (h2){(f16)kpv[0], (f16)kpv[1]};
;         *(h2*)(RW + 3 * TS + o) = (h2){(f16)vv[0], (f16)vv[1]};
;         *(h2*)(RW + 4 * TS + o) = (h2){(f16)kn0, (f16)kn1};
.LBB0_458:
	s_or_b64 exec, exec, s[6:7]
	v_or_b32_e32 v4, 3, v233
	v_mad_i64_i32 v[2:3], s[6:7], v4, s34, v[212:213]
	s_waitcnt vmcnt(7)
	v_mov_b32_e32 v18, v246
	v_mov_b32_e32 v19, v247
	v_mov_b32_e32 v20, v248
	v_mov_b32_e32 v36, v249
	v_mov_b32_e32 v50, v250
	v_add_co_u32_e32 v2, vcc, 0xfffff000, v2
	v_add_f32_e32 v37, v37, v211
	s_nop 0
	v_addc_co_u32_e32 v3, vcc, -1, v3, vcc
	v_mov_b32_e32 v51, v251
	v_or_b32_e32 v253, 8, v233
	v_mad_i64_i32 v[254:255], s[92:93], v253, s34, v[212:213]
	global_load_dword v246, v[254:255], off
	global_load_dword v247, v[254:255], off offset:1536
	global_load_dword v248, v[254:255], off offset:3072
	global_load_dword v249, v[254:255], off offset:-2048
	global_load_dword v250, v[254:255], off offset:-3584
	v_add_co_u32_e32 v254, vcc, 0xfffff000, v254
	s_nop 1
	v_addc_co_u32_e32 v255, vcc, -1, v255, vcc
	global_load_dword v251, v[254:255], off offset:-1024
	v_cvt_pk_f16_f32 v5, v5, v21
	s_nop 0
	v_and_b32_e32 v67, 0xffff0000, v18
	v_lshlrev_b32_e32 v66, 16, v18
	s_nop 0
	v_and_b32_e32 v3, 0xffff0000, v20
	v_lshlrev_b32_e32 v2, 16, v20
	v_add_f32_e32 v20, v85, v210
	v_and_b32_e32 v35, 0xffff0000, v19
	v_lshlrev_b32_e32 v34, 16, v19
	s_nop 0
	v_and_b32_e32 v19, 0xffff0000, v36
	v_lshlrev_b32_e32 v18, 16, v36
	v_max_f32_e64 v36, -v20, 0
	v_mul_f32_e64 v20, |v20|, s88
	v_exp_f32_e32 v20, v20
	s_nop 0
	v_and_b32_e32 v83, 0xffff0000, v51
	v_lshlrev_b32_e32 v82, 16, v51
	v_and_b32_e32 v51, 0xffff0000, v50
	v_add_f32_e32 v20, 1.0, v20
	v_cmp_gt_f32_e32 vcc, s89, v20
	v_lshlrev_b32_e32 v50, 16, v50
	v_pk_add_f32 v[50:51], v[50:51], v[34:35] neg_lo:[0,1] neg_hi:[0,1]
	v_cndmask_b32_e64 v52, 0, 32, vcc
	v_ldexp_f32 v20, v20, v52
	v_log_f32_e32 v20, v20
	v_pk_fma_f32 v[50:51], v[204:205], v[50:51], v[34:35]
	v_pk_add_f32 v[18:19], v[18:19], v[2:3] neg_lo:[0,1] neg_hi:[0,1]
	v_mul_f32_e32 v52, 0x3f317217, v20
	v_fma_f32 v52, v20, s90, -v52
	v_fmac_f32_e32 v52, 0x3377d1cf, v20
	v_fmac_f32_e32 v52, 0x3f317217, v20
	v_cmp_lt_f32_e64 s[6:7], |v20|, s91
	v_pk_fma_f32 v[2:3], v[196:197], v[18:19], v[2:3]
	s_nop 0
	v_cndmask_b32_e64 v20, v20, v52, s[6:7]
	v_cndmask_b32_e32 v52, 0, v232, vcc
	v_sub_f32_e32 v20, v20, v52
	v_max_f32_e64 v52, -v37, 0
	v_mul_f32_e64 v37, |v37|, s88
	v_exp_f32_e32 v37, v37
	v_add_f32_e32 v20, v36, v20
	v_sub_f32_e32 v20, -0.5, v20
	v_mul_f32_e32 v20, 0x3fb8aa3b, v20
	v_add_f32_e32 v37, 1.0, v37
	v_cmp_gt_f32_e32 vcc, s89, v37
	v_exp_f32_e32 v20, v20
	v_add_f32_e32 v36, v69, v208
	v_cndmask_b32_e64 v68, 0, 32, vcc
	v_ldexp_f32 v37, v37, v68
	v_log_f32_e32 v37, v37
	v_mul_f32_e32 v20, 0xbfb8aa3b, v20
	v_exp_f32_e32 v20, v20
	v_mul_f32_e32 v36, 0xbfb8aa3b, v36
	v_mul_f32_e32 v68, 0x3f317217, v37
	v_fma_f32 v68, v37, s90, -v68
	v_fmac_f32_e32 v68, 0x3377d1cf, v37
	v_fmac_f32_e32 v68, 0x3f317217, v37
	v_cmp_lt_f32_e64 s[6:7], |v37|, s91
	v_exp_f32_e32 v36, v36
	v_sub_f32_e32 v20, 1.0, v20
	v_cndmask_b32_e64 v37, v37, v68, s[6:7]
	v_cndmask_b32_e32 v68, 0, v232, vcc
	v_sub_f32_e32 v37, v37, v68
	v_add_f32_e32 v37, v52, v37
	v_sub_f32_e32 v37, -0.5, v37
	v_mul_f32_e32 v37, 0x3fb8aa3b, v37
	v_exp_f32_e32 v37, v37
	v_mad_i64_i32 v[68:69], s[6:7], v4, s54, v[102:103]
	v_cvt_pk_f16_f32 v18, v2, v3
	v_mul_f32_e32 v37, 0xbfb8aa3b, v37
	v_exp_f32_e32 v37, v37
	s_nop 0
	v_sub_f32_e32 v84, 1.0, v37
	v_add_f32_e32 v37, v53, v209
	v_mul_f32_e32 v37, 0xbfb8aa3b, v37
	v_exp_f32_e32 v37, v37
	v_pk_add_f32 v[52:53], v[82:83], v[66:67] neg_lo:[0,1] neg_hi:[0,1]
	v_cvt_pk_f16_f32 v20, v20, v84
	v_pk_fma_f32 v[52:53], v[206:207], v[52:53], v[66:67]
	v_lshlrev_b64 v[66:67], 1, v[68:69]
	v_cvt_pk_f16_f32 v82, v52, v53
	v_lshl_add_u64 v[68:69], s[56:57], 0, v[66:67]
	global_store_dword v[68:69], v82, off
	v_lshl_add_u64 v[68:69], s[62:63], 0, v[66:67]
	v_pk_add_f32 v[34:35], v[36:37], 1.0 op_sel_hi:[1,0]
	global_store_dword v[68:69], v20, off
	v_div_scale_f32 v20, s[6:7], v35, v35, 1.0
	v_rcp_f32_e32 v36, v20
	v_lshl_add_u64 v[2:3], s[66:67], 0, v[66:67]
	global_store_dword v[2:3], v18, off
	v_pk_mul_f32 v[2:3], v[194:195], v[50:51]
	v_fma_f32 v37, -v20, v36, 1.0
	v_fmac_f32_e32 v36, v37, v36
	v_div_scale_f32 v37, vcc, 1.0, v35, 1.0
	v_mul_f32_e32 v68, v37, v36
	v_fma_f32 v69, -v20, v68, v37
	v_fmac_f32_e32 v68, v69, v36
	v_fma_f32 v20, -v20, v68, v37
	v_div_fmas_f32 v20, v20, v36, v68
	v_div_fixup_f32 v37, v20, v35, 1.0
	v_div_scale_f32 v20, s[6:7], v34, v34, 1.0
	v_rcp_f32_e32 v35, v20
	v_pk_mul_f32 v[18:19], v[2:3], v[2:3]
	v_fma_f32 v36, -v20, v35, 1.0
	v_add_f32_e32 v18, v18, v19
	v_fmac_f32_e32 v35, v36, v35
	v_div_scale_f32 v36, vcc, 1.0, v34, 1.0
	v_add_f32_dpp v18, v18, v18 quad_perm:[1,0,3,2] row_mask:0xf bank_mask:0xf bound_ctrl:1
	v_mul_f32_e32 v68, v36, v35
	v_fma_f32 v69, -v20, v68, v36
	v_add_f32_dpp v18, v18, v18 quad_perm:[2,3,0,1] row_mask:0xf bank_mask:0xf bound_ctrl:1
	v_fmac_f32_e32 v68, v69, v35
	v_fma_f32 v20, -v20, v68, v36
	v_add_f32_dpp v18, v18, v18 row_half_mirror row_mask:0xf bank_mask:0xf bound_ctrl:1
	v_div_fmas_f32 v20, v20, v35, v68
	v_div_fixup_f32 v36, v20, v34, 1.0
	v_add_f32_dpp v18, v18, v18 row_mirror row_mask:0xf bank_mask:0xf bound_ctrl:1
	v_mov_b32_e32 v19, v18
	s_nop 1
	v_permlane16_swap_b32_e32 v18, v19
	v_add_f32_e32 v18, v18, v19
	v_add_f32_e32 v18, 0x2b8cbccc, v18
	v_pk_add_f32 v[34:35], v[36:37], -1.0 op_sel_hi:[1,0]
	v_cmp_gt_f32_e32 vcc, s89, v18
	v_mul_f32_e32 v19, 0x4b800000, v18
	v_pk_fma_f32 v[34:35], v[202:203], v[34:35], 1.0 op_sel_hi:[1,1,0]
	v_cndmask_b32_e32 v18, v18, v19, vcc
	v_pk_mul_f32 v[68:69], v[34:35], v[50:51]
	v_rsq_f32_e32 v18, v18
	v_pk_mul_f32 v[34:35], v[52:53], v[68:69]
	v_lshl_add_u64 v[52:53], s[64:65], 0, v[66:67]
	v_fma_f32 v20, v198, v34, 0
	v_fmac_f32_e32 v20, v199, v35
	v_mul_f32_e32 v19, 0x45800000, v18
	v_cndmask_b32_e32 v18, v18, v19, vcc
	v_add_f32_dpp v20, v20, v20 quad_perm:[1,0,3,2] row_mask:0xf bank_mask:0xf bound_ctrl:1
	v_cvt_pk_f16_f32 v35, v68, v69
	v_pk_mul_f32 v[2:3], v[2:3], v[18:19] op_sel_hi:[1,0]
	v_add_f32_dpp v20, v20, v20 quad_perm:[2,3,0,1] row_mask:0xf bank_mask:0xf bound_ctrl:1
	global_store_dword v[52:53], v35, off
	v_cvt_pk_f16_f32 v35, v2, v3
	v_add_f32_dpp v20, v20, v20 row_half_mirror row_mask:0xf bank_mask:0xf bound_ctrl:1
	v_lshl_add_u64 v[18:19], s[72:73], 0, v[66:67]
	v_pk_mul_f32 v[2:3], v[36:37], v[2:3]
	v_add_f32_dpp v20, v20, v20 row_mirror row_mask:0xf bank_mask:0xf bound_ctrl:1
	v_mov_b32_e32 v34, v20
	global_store_dword v[18:19], v35, off
	v_cvt_pk_f16_f32 v18, v2, v3
	v_lshl_add_u64 v[2:3], s[78:79], 0, v[66:67]
	v_permlane16_swap_b32_e32 v20, v34
	global_store_dword v[2:3], v18, off
	v_lshl_add_u64 v[2:3], s[82:83], 0, v[66:67]
	global_store_dword v[2:3], v5, off
	s_and_saveexec_b64 s[6:7], s[4:5]
	s_cbranch_execz .LBB0_460
	v_add_f32_e32 v5, v20, v34
	v_mad_i64_i32 v[2:3], s[92:93], v4, 48, v[200:201]
	global_store_dword v[2:3], v5, off
; DEVI void rwkv_prep_item(const Params& p, const int l, const int item, char* smem) {
;     ...
;     for (int r = 0; r < 16; ++r) {
;       const int t = t0 + mt * 32 + (r & 3) + 8 * (r >> 2) + 4 * hi; const bool has_prev = (t & (SEQ_ - 1)) != 0;
;       float rv[2], kv[2], vv[2], av[2], kkv[2], kpv[2], omdv[2], gv[2];
;       float ssq = 0.f, bon = 0.f;
;       const u16* pr = PA + (size_t)t * 2560 + h * 64 + 2 * l31;
;       const unsigned cr2 = *(const unsigned*)pr, ck2 = *(const unsigned*)(pr + 768), cv2 = *(const unsigned*)(pr + 1536);
;       unsigned qr2 = 0u, qk2 = 0u, qv2 = 0u;
;       if (has_prev) { qr2 = *(const unsigned*)(pr - 2560); qk2 = *(const unsigned*)(pr + 768 - 2560); qv2 = *(const unsigned*)(pr + 1536 - 2560); }
; #pragma unroll
;       for (int n = 0; n < 2; ++n) {
;         const float cr = __uint_as_float(n ? (cr2 & 0xffff0000u) : (cr2 << 16)), ck = __uint_as_float(n ? (ck2 & 0xffff0000u) : (ck2 << 16)), cv = __uint_as_float(n ? (cv2 & 0xffff0000u) : (cv2 << 16));
;         const float qr = __uint_as_float(n ? (qr2 & 0xffff0000u) : (qr2 << 16)), qk = __uint_as_float(n ? (qk2 & 0xffff0000u) : (qk2 << 16)), qv = __uint_as_float(n ? (qv2 & 0xffff0000u) : (qv2 << 16));
;         rv[n] = cr + (qr - cr) * mur[n]; kv[n] = ck + (qk - ck) * muk[n]; vv[n] = cv + (qv - cv) * muv[n];
;         const float z = -(w0c[n] + aw[n][r]);
;         const float sp = fmaxf(z, 0.f) + __logf(1.f + __expf(-fabsf(z)));
;         const float ew = __expf(-sp - 0.5f);
;         omdv[n] = 1.f - __expf(-ew);
;         av[n] = sigmoidf_(a0c[n] + aa[n][r]);
;         gv[n] = ag[n][r];
;         kkv[n] = kv[n] * kkc[n];
;         kpv[n] = kv[n] * (1.f + (av[n] - 1.f) * kac[n]);
;         ssq += kkv[n] * kkv[n];
;         bon += rv[n] * kpv[n] * rkc[n];
;       }
;       ssq = reduce32(ssq); bon = reduce32(bon);
;       const float rn = rsqrtf(ssq + 1e-12f);
;       {
;         typedef _Float16 h2 __attribute__((ext_vector_type(2)));
;         const size_t o = (size_t)t * 768 + h * 64 + 2 * l31;
;         const float kn0 = kkv[0] * rn, kn1 = kkv[1] * rn;
;         *(h2*)(RW + o) = (h2){(f16)rv[0], (f16)rv[1]};
;         *(h2*)(RW + TS + o) = (h2){(f16)omdv[0], (f16)omdv[1]};
;         *(h2*)(RW + 2 * TS + o) = (h2){(f16)kpv[0], (f16)kpv[1]};
;         *(h2*)(RW + 3 * TS + o) = (h2){(f16)vv[0], (f16)vv[1]};
;         *(h2*)(RW + 4 * TS + o) = (h2){(f16)kn0, (f16)kn1};
.LBB0_460:
	s_or_b64 exec, exec, s[6:7]
	v_or_b32_e32 v52, 8, v233
	v_mad_i64_i32 v[2:3], s[6:7], v52, s34, v[212:213]
	s_waitcnt vmcnt(7)
	v_mov_b32_e32 v4, v246
	v_mov_b32_e32 v5, v247
	v_mov_b32_e32 v20, v248
	v_mov_b32_e32 v34, v249
	v_mov_b32_e32 v35, v250
	v_add_co_u32_e32 v2, vcc, 0xfffff000, v2
	s_nop 0
	v_and_b32_e32 v37, 0xffff0000, v4
	v_addc_co_u32_e32 v3, vcc, -1, v3, vcc
	v_mov_b32_e32 v21, v251
	v_or_b32_e32 v253, 9, v233
	v_mad_i64_i32 v[254:255], s[92:93], v253, s34, v[212:213]
	global_load_dword v246, v[254:255], off
	global_load_dword v247, v[254:255], off offset:1536
	global_load_dword v248, v[254:255], off offset:3072
	global_load_dword v249, v[254:255], off offset:-2048
	global_load_dword v250, v[254:255], off offset:-3584
	v_add_co_u32_e32 v254, vcc, 0xfffff000, v254
	s_nop 1
	v_addc_co_u32_e32 v255, vcc, -1, v255, vcc
	global_load_dword v251, v[254:255], off offset:-1024
	v_lshlrev_b32_e32 v36, 16, v4
	s_nop 0
	v_and_b32_e32 v19, 0xffff0000, v5
	v_lshlrev_b32_e32 v18, 16, v5
	s_nop 0
	v_and_b32_e32 v5, 0xffff0000, v34
	v_lshlrev_b32_e32 v4, 16, v34
	v_add_f32_e32 v34, v86, v210
	v_and_b32_e32 v3, 0xffff0000, v20
	v_lshlrev_b32_e32 v2, 16, v20
	s_nop 0
	v_lshlrev_b32_e32 v20, 16, v35
	v_pk_add_f32 v[4:5], v[4:5], v[2:3] neg_lo:[0,1] neg_hi:[0,1]
	s_nop 0
	v_and_b32_e32 v51, 0xffff0000, v21
	v_lshlrev_b32_e32 v50, 16, v21
	v_and_b32_e32 v21, 0xffff0000, v35
	v_max_f32_e64 v35, -v34, 0
	v_mul_f32_e64 v34, |v34|, s88
	v_exp_f32_e32 v34, v34
	v_pk_add_f32 v[20:21], v[20:21], v[18:19] neg_lo:[0,1] neg_hi:[0,1]
	v_pk_add_f32 v[50:51], v[50:51], v[36:37] neg_lo:[0,1] neg_hi:[0,1]
	v_pk_fma_f32 v[20:21], v[204:205], v[20:21], v[18:19]
	v_add_f32_e32 v34, 1.0, v34
	v_cmp_gt_f32_e32 vcc, s89, v34
	v_pk_fma_f32 v[36:37], v[206:207], v[50:51], v[36:37]
	v_pk_fma_f32 v[2:3], v[196:197], v[4:5], v[2:3]
	v_cndmask_b32_e64 v53, 0, 32, vcc
	v_ldexp_f32 v34, v34, v53
	v_log_f32_e32 v34, v34
	v_cvt_pk_f16_f32 v4, v2, v3
	v_mul_f32_e32 v53, 0x3f317217, v34
	v_fma_f32 v53, v34, s90, -v53
	v_fmac_f32_e32 v53, 0x3377d1cf, v34
	v_fmac_f32_e32 v53, 0x3f317217, v34
	v_cmp_lt_f32_e64 s[6:7], |v34|, s91
	s_nop 1
	v_cndmask_b32_e64 v34, v34, v53, s[6:7]
	v_cndmask_b32_e32 v53, 0, v232, vcc
	v_sub_f32_e32 v34, v34, v53
	v_add_f32_e32 v34, v35, v34
	v_add_f32_e32 v35, v38, v211
	v_max_f32_e64 v38, -v35, 0
	v_mul_f32_e64 v35, |v35|, s88
	v_exp_f32_e32 v35, v35
	v_sub_f32_e32 v34, -0.5, v34
	v_mul_f32_e32 v34, 0x3fb8aa3b, v34
	v_exp_f32_e32 v34, v34
	v_add_f32_e32 v35, 1.0, v35
	v_cmp_gt_f32_e32 vcc, s89, v35
	v_mul_f32_e32 v34, 0xbfb8aa3b, v34
	s_nop 0
	v_cndmask_b32_e64 v66, 0, 32, vcc
	v_ldexp_f32 v35, v35, v66
	v_log_f32_e32 v35, v35
	v_exp_f32_e32 v34, v34
	v_mul_f32_e32 v66, 0x3f317217, v35
	v_fma_f32 v66, v35, s90, -v66
	v_fmac_f32_e32 v66, 0x3377d1cf, v35
	v_fmac_f32_e32 v66, 0x3f317217, v35
	v_cmp_lt_f32_e64 s[6:7], |v35|, s91
	v_sub_f32_e32 v53, 1.0, v34
	v_add_f32_e32 v34, v70, v208
	v_cndmask_b32_e64 v35, v35, v66, s[6:7]
	v_cndmask_b32_e32 v66, 0, v232, vcc
	v_sub_f32_e32 v35, v35, v66
	v_add_f32_e32 v35, v38, v35
	v_sub_f32_e32 v35, -0.5, v35
	v_mul_f32_e32 v35, 0x3fb8aa3b, v35
	v_exp_f32_e32 v35, v35
	v_mul_f32_e32 v34, 0xbfb8aa3b, v34
	v_exp_f32_e32 v34, v34
	v_mad_i64_i32 v[66:67], s[6:7], v52, s54, v[102:103]
	v_mul_f32_e32 v35, 0xbfb8aa3b, v35
	v_exp_f32_e32 v35, v35
	v_lshlrev_b64 v[50:51], 1, v[66:67]
	v_lshl_add_u64 v[66:67], s[56:57], 0, v[50:51]
	v_lshl_add_u64 v[2:3], s[66:67], 0, v[50:51]
	v_sub_f32_e32 v38, 1.0, v35
	v_add_f32_e32 v35, v54, v209
	v_mul_f32_e32 v35, 0xbfb8aa3b, v35
	v_exp_f32_e32 v35, v35
	v_cvt_pk_f16_f32 v54, v36, v37
	global_store_dword v[66:67], v54, off
	v_cvt_pk_f16_f32 v38, v53, v38
	v_pk_add_f32 v[18:19], v[34:35], 1.0 op_sel_hi:[1,0]
	v_lshl_add_u64 v[66:67], s[62:63], 0, v[50:51]
	v_div_scale_f32 v34, s[6:7], v19, v19, 1.0
	v_rcp_f32_e32 v35, v34
	global_store_dword v[66:67], v38, off
	global_store_dword v[2:3], v4, off
	v_pk_mul_f32 v[2:3], v[194:195], v[20:21]
	v_fma_f32 v38, -v34, v35, 1.0
	v_fmac_f32_e32 v35, v38, v35
	v_div_scale_f32 v38, vcc, 1.0, v19, 1.0
	v_mul_f32_e32 v53, v38, v35
	v_fma_f32 v54, -v34, v53, v38
	v_fmac_f32_e32 v53, v54, v35
	v_fma_f32 v34, -v34, v53, v38
	v_div_fmas_f32 v34, v34, v35, v53
	v_div_fixup_f32 v35, v34, v19, 1.0
	v_div_scale_f32 v19, s[6:7], v18, v18, 1.0
	v_rcp_f32_e32 v34, v19
	v_pk_mul_f32 v[4:5], v[2:3], v[2:3]
	v_fma_f32 v38, -v19, v34, 1.0
	v_add_f32_e32 v4, v4, v5
	v_fmac_f32_e32 v34, v38, v34
	v_div_scale_f32 v38, vcc, 1.0, v18, 1.0
	v_add_f32_dpp v4, v4, v4 quad_perm:[1,0,3,2] row_mask:0xf bank_mask:0xf bound_ctrl:1
	v_mul_f32_e32 v53, v38, v34
	v_fma_f32 v54, -v19, v53, v38
	v_add_f32_dpp v4, v4, v4 quad_perm:[2,3,0,1] row_mask:0xf bank_mask:0xf bound_ctrl:1
	v_fmac_f32_e32 v53, v54, v34
	v_fma_f32 v19, -v19, v53, v38
	v_add_f32_dpp v4, v4, v4 row_half_mirror row_mask:0xf bank_mask:0xf bound_ctrl:1
	v_div_fmas_f32 v19, v19, v34, v53
	v_div_fixup_f32 v34, v19, v18, 1.0
	v_add_f32_dpp v4, v4, v4 row_mirror row_mask:0xf bank_mask:0xf bound_ctrl:1
	v_mov_b32_e32 v5, v4
	s_nop 1
	v_permlane16_swap_b32_e32 v4, v5
	v_add_f32_e32 v4, v4, v5
	v_add_f32_e32 v4, 0x2b8cbccc, v4
	v_pk_add_f32 v[18:19], v[34:35], -1.0 op_sel_hi:[1,0]
	v_cmp_gt_f32_e32 vcc, s89, v4
	v_mul_f32_e32 v5, 0x4b800000, v4
	v_pk_fma_f32 v[18:19], v[202:203], v[18:19], 1.0 op_sel_hi:[1,1,0]
	v_cndmask_b32_e32 v4, v4, v5, vcc
	v_pk_mul_f32 v[66:67], v[18:19], v[20:21]
	v_rsq_f32_e32 v4, v4
	v_pk_mul_f32 v[18:19], v[36:37], v[66:67]
	v_cvt_pk_f16_f32 v38, v66, v67
	v_fma_f32 v18, v198, v18, 0
	v_fmac_f32_e32 v18, v199, v19
	v_mul_f32_e32 v5, 0x45800000, v4
	v_cndmask_b32_e32 v4, v4, v5, vcc
	v_add_f32_dpp v18, v18, v18 quad_perm:[1,0,3,2] row_mask:0xf bank_mask:0xf bound_ctrl:1
	v_pk_mul_f32 v[2:3], v[2:3], v[4:5] op_sel_hi:[1,0]
	v_lshl_add_u64 v[4:5], s[72:73], 0, v[50:51]
	v_add_f32_dpp v18, v18, v18 quad_perm:[2,3,0,1] row_mask:0xf bank_mask:0xf bound_ctrl:1
	v_cvt_pk_f16_f32 v20, v2, v3
	v_pk_mul_f32 v[2:3], v[34:35], v[2:3]
	v_add_f32_dpp v18, v18, v18 row_half_mirror row_mask:0xf bank_mask:0xf bound_ctrl:1
	global_store_dword v[4:5], v20, off
	v_cvt_pk_f16_f32 v4, v2, v3
	v_add_f32_dpp v18, v18, v18 row_mirror row_mask:0xf bank_mask:0xf bound_ctrl:1
	v_mov_b32_e32 v19, v18
	v_lshl_add_u64 v[2:3], s[78:79], 0, v[50:51]
	s_nop 0
	v_permlane16_swap_b32_e32 v18, v19
	v_lshl_add_u64 v[36:37], s[64:65], 0, v[50:51]
	global_store_dword v[2:3], v4, off
	v_cvt_pk_f16_f32 v4, v6, v22
	v_lshl_add_u64 v[2:3], s[82:83], 0, v[50:51]
	global_store_dword v[36:37], v38, off
	global_store_dword v[2:3], v4, off
	s_and_saveexec_b64 s[6:7], s[4:5]
	s_cbranch_execz .LBB0_462
	v_add_f32_e32 v4, v18, v19
	v_mad_i64_i32 v[2:3], s[92:93], v52, 48, v[200:201]
	global_store_dword v[2:3], v4, off
; DEVI void rwkv_prep_item(const Params& p, const int l, const int item, char* smem) {
;     ...
;     for (int r = 0; r < 16; ++r) {
;       const int t = t0 + mt * 32 + (r & 3) + 8 * (r >> 2) + 4 * hi; const bool has_prev = (t & (SEQ_ - 1)) != 0;
;       float rv[2], kv[2], vv[2], av[2], kkv[2], kpv[2], omdv[2], gv[2];
;       float ssq = 0.f, bon = 0.f;
;       const u16* pr = PA + (size_t)t * 2560 + h * 64 + 2 * l31;
;       const unsigned cr2 = *(const unsigned*)pr, ck2 = *(const unsigned*)(pr + 768), cv2 = *(const unsigned*)(pr + 1536);
;       unsigned qr2 = 0u, qk2 = 0u, qv2 = 0u;
;       if (has_prev) { qr2 = *(const unsigned*)(pr - 2560); qk2 = *(const unsigned*)(pr + 768 - 2560); qv2 = *(const unsigned*)(pr + 1536 - 2560); }
; #pragma unroll
;       for (int n = 0; n < 2; ++n) {
;         const float cr = __uint_as_float(n ? (cr2 & 0xffff0000u) : (cr2 << 16)), ck = __uint_as_float(n ? (ck2 & 0xffff0000u) : (ck2 << 16)), cv = __uint_as_float(n ? (cv2 & 0xffff0000u) : (cv2 << 16));
;         const float qr = __uint_as_float(n ? (qr2 & 0xffff0000u) : (qr2 << 16)), qk = __uint_as_float(n ? (qk2 & 0xffff0000u) : (qk2 << 16)), qv = __uint_as_float(n ? (qv2 & 0xffff0000u) : (qv2 << 16));
;         rv[n] = cr + (qr - cr) * mur[n]; kv[n] = ck + (qk - ck) * muk[n]; vv[n] = cv + (qv - cv) * muv[n];
;         const float z = -(w0c[n] + aw[n][r]);
;         const float sp = fmaxf(z, 0.f) + __logf(1.f + __expf(-fabsf(z)));
;         const float ew = __expf(-sp - 0.5f);
;         omdv[n] = 1.f - __expf(-ew);
;         av[n] = sigmoidf_(a0c[n] + aa[n][r]);
;         gv[n] = ag[n][r];
;         kkv[n] = kv[n] * kkc[n];
;         kpv[n] = kv[n] * (1.f + (av[n] - 1.f) * kac[n]);
;         ssq += kkv[n] * kkv[n];
;         bon += rv[n] * kpv[n] * rkc[n];
;       }
;       ssq = reduce32(ssq); bon = reduce32(bon);
;       const float rn = rsqrtf(ssq + 1e-12f);
;       {
;         typedef _Float16 h2 __attribute__((ext_vector_type(2)));
;         const size_t o = (size_t)t * 768 + h * 64 + 2 * l31;
;         const float kn0 = kkv[0] * rn, kn1 = kkv[1] * rn;
;         *(h2*)(RW + o) = (h2){(f16)rv[0], (f16)rv[1]};
;         *(h2*)(RW + TS + o) = (h2){(f16)omdv[0], (f16)omdv[1]};
;         *(h2*)(RW + 2 * TS + o) = (h2){(f16)kpv[0], (f16)kpv[1]};
;         *(h2*)(RW + 3 * TS + o) = (h2){(f16)vv[0], (f16)vv[1]};
;         *(h2*)(RW + 4 * TS + o) = (h2){(f16)kn0, (f16)kn1};
.LBB0_462:
	s_or_b64 exec, exec, s[6:7]
	v_or_b32_e32 v6, 9, v233
	v_mad_i64_i32 v[2:3], s[6:7], v6, s34, v[212:213]
	s_waitcnt vmcnt(7)
	v_mov_b32_e32 v4, v246
	v_mov_b32_e32 v5, v247
	v_mov_b32_e32 v20, v248
	v_mov_b32_e32 v22, v249
	v_mov_b32_e32 v34, v250
	v_add_co_u32_e32 v2, vcc, 0xfffff000, v2
	s_nop 0
	v_and_b32_e32 v37, 0xffff0000, v4
	v_addc_co_u32_e32 v3, vcc, -1, v3, vcc
	v_mov_b32_e32 v21, v251
	v_or_b32_e32 v253, 10, v233
	v_mad_i64_i32 v[254:255], s[92:93], v253, s34, v[212:213]
	global_load_dword v246, v[254:255], off
	global_load_dword v247, v[254:255], off offset:1536
	global_load_dword v248, v[254:255], off offset:3072
	global_load_dword v249, v[254:255], off offset:-2048
	global_load_dword v250, v[254:255], off offset:-3584
	v_add_co_u32_e32 v254, vcc, 0xfffff000, v254
	s_nop 1
	v_addc_co_u32_e32 v255, vcc, -1, v255, vcc
	global_load_dword v251, v[254:255], off offset:-1024
	v_lshlrev_b32_e32 v36, 16, v4
	s_nop 0
	v_and_b32_e32 v19, 0xffff0000, v5
	v_lshlrev_b32_e32 v18, 16, v5
	s_nop 0
	v_and_b32_e32 v5, 0xffff0000, v22
	v_lshlrev_b32_e32 v4, 16, v22
	v_add_f32_e32 v22, v87, v210
	v_and_b32_e32 v3, 0xffff0000, v20
	v_lshlrev_b32_e32 v2, 16, v20
	s_nop 0
	v_lshlrev_b32_e32 v20, 16, v34
	v_pk_add_f32 v[4:5], v[4:5], v[2:3] neg_lo:[0,1] neg_hi:[0,1]
	s_nop 0
	v_and_b32_e32 v51, 0xffff0000, v21
	v_lshlrev_b32_e32 v50, 16, v21
	v_and_b32_e32 v21, 0xffff0000, v34
	v_max_f32_e64 v34, -v22, 0
	v_mul_f32_e64 v22, |v22|, s88
	v_exp_f32_e32 v22, v22
	v_pk_add_f32 v[50:51], v[50:51], v[36:37] neg_lo:[0,1] neg_hi:[0,1]
	v_pk_add_f32 v[20:21], v[20:21], v[18:19] neg_lo:[0,1] neg_hi:[0,1]
	v_pk_fma_f32 v[36:37], v[206:207], v[50:51], v[36:37]
	v_add_f32_e32 v22, 1.0, v22
	v_cmp_gt_f32_e32 vcc, s89, v22
	v_cvt_pk_f16_f32 v53, v36, v37
	v_pk_fma_f32 v[20:21], v[204:205], v[20:21], v[18:19]
	v_cndmask_b32_e64 v35, 0, 32, vcc
	v_ldexp_f32 v22, v22, v35
	v_log_f32_e32 v22, v22
	v_pk_fma_f32 v[2:3], v[196:197], v[4:5], v[2:3]
	v_mul_f32_e32 v35, 0x3f317217, v22
	v_fma_f32 v35, v22, s90, -v35
	v_fmac_f32_e32 v35, 0x3377d1cf, v22
	v_fmac_f32_e32 v35, 0x3f317217, v22
	v_cmp_lt_f32_e64 s[6:7], |v22|, s91
	v_cvt_pk_f16_f32 v4, v2, v3
	s_nop 0
	v_cndmask_b32_e64 v22, v22, v35, s[6:7]
	v_cndmask_b32_e32 v35, 0, v232, vcc
	v_sub_f32_e32 v22, v22, v35
	v_add_f32_e32 v35, v39, v211
	v_max_f32_e64 v38, -v35, 0
	v_mul_f32_e64 v35, |v35|, s88
	v_exp_f32_e32 v35, v35
	v_add_f32_e32 v22, v34, v22
	v_sub_f32_e32 v22, -0.5, v22
	v_mul_f32_e32 v22, 0x3fb8aa3b, v22
	v_add_f32_e32 v35, 1.0, v35
	v_cmp_gt_f32_e32 vcc, s89, v35
	v_exp_f32_e32 v22, v22
	v_add_f32_e32 v34, v71, v208
	v_cndmask_b32_e64 v39, 0, 32, vcc
	v_ldexp_f32 v35, v35, v39
	v_log_f32_e32 v35, v35
	v_mul_f32_e32 v22, 0xbfb8aa3b, v22
	v_exp_f32_e32 v22, v22
	v_mul_f32_e32 v34, 0xbfb8aa3b, v34
	v_mul_f32_e32 v39, 0x3f317217, v35
	v_fma_f32 v39, v35, s90, -v39
	v_fmac_f32_e32 v39, 0x3377d1cf, v35
	v_fmac_f32_e32 v39, 0x3f317217, v35
	v_cmp_lt_f32_e64 s[6:7], |v35|, s91
	v_exp_f32_e32 v34, v34
	v_sub_f32_e32 v22, 1.0, v22
	v_cndmask_b32_e64 v35, v35, v39, s[6:7]
	v_cndmask_b32_e32 v39, 0, v232, vcc
	v_sub_f32_e32 v35, v35, v39
	v_add_f32_e32 v35, v38, v35
	v_sub_f32_e32 v35, -0.5, v35
	v_mul_f32_e32 v35, 0x3fb8aa3b, v35
	v_exp_f32_e32 v35, v35
	v_mad_i64_i32 v[38:39], s[6:7], v6, s54, v[102:103]
	v_lshlrev_b64 v[38:39], 1, v[38:39]
	v_mul_f32_e32 v35, 0xbfb8aa3b, v35
	v_exp_f32_e32 v35, v35
	v_lshl_add_u64 v[50:51], s[56:57], 0, v[38:39]
	global_store_dword v[50:51], v53, off
	v_lshl_add_u64 v[50:51], s[62:63], 0, v[38:39]
	v_sub_f32_e32 v52, 1.0, v35
	v_add_f32_e32 v35, v55, v209
	v_mul_f32_e32 v35, 0xbfb8aa3b, v35
	v_exp_f32_e32 v35, v35
	v_cvt_pk_f16_f32 v22, v22, v52
	global_store_dword v[50:51], v22, off
	v_lshl_add_u64 v[2:3], s[66:67], 0, v[38:39]
	v_pk_add_f32 v[18:19], v[34:35], 1.0 op_sel_hi:[1,0]
	global_store_dword v[2:3], v4, off
	v_div_scale_f32 v22, s[6:7], v19, v19, 1.0
	v_rcp_f32_e32 v34, v22
	v_pk_mul_f32 v[2:3], v[194:195], v[20:21]
	v_fma_f32 v35, -v22, v34, 1.0
	v_fmac_f32_e32 v34, v35, v34
	v_div_scale_f32 v35, vcc, 1.0, v19, 1.0
	v_mul_f32_e32 v50, v35, v34
	v_fma_f32 v51, -v22, v50, v35
	v_fmac_f32_e32 v50, v51, v34
	v_fma_f32 v22, -v22, v50, v35
	v_div_fmas_f32 v22, v22, v34, v50
	v_div_fixup_f32 v35, v22, v19, 1.0
	v_div_scale_f32 v19, s[6:7], v18, v18, 1.0
	v_rcp_f32_e32 v22, v19
	v_pk_mul_f32 v[4:5], v[2:3], v[2:3]
	v_fma_f32 v34, -v19, v22, 1.0
	v_add_f32_e32 v4, v4, v5
	v_fmac_f32_e32 v22, v34, v22
	v_div_scale_f32 v34, vcc, 1.0, v18, 1.0
	v_add_f32_dpp v4, v4, v4 quad_perm:[1,0,3,2] row_mask:0xf bank_mask:0xf bound_ctrl:1
	v_mul_f32_e32 v50, v34, v22
	v_fma_f32 v51, -v19, v50, v34
	v_add_f32_dpp v4, v4, v4 quad_perm:[2,3,0,1] row_mask:0xf bank_mask:0xf bound_ctrl:1
	v_fmac_f32_e32 v50, v51, v22
	v_fma_f32 v19, -v19, v50, v34
	v_add_f32_dpp v4, v4, v4 row_half_mirror row_mask:0xf bank_mask:0xf bound_ctrl:1
	v_div_fmas_f32 v19, v19, v22, v50
	v_div_fixup_f32 v34, v19, v18, 1.0
	v_add_f32_dpp v4, v4, v4 row_mirror row_mask:0xf bank_mask:0xf bound_ctrl:1
	v_mov_b32_e32 v5, v4
	s_nop 1
	v_permlane16_swap_b32_e32 v4, v5
	v_add_f32_e32 v4, v4, v5
	v_add_f32_e32 v4, 0x2b8cbccc, v4
	v_pk_add_f32 v[18:19], v[34:35], -1.0 op_sel_hi:[1,0]
	v_cmp_gt_f32_e32 vcc, s89, v4
	v_mul_f32_e32 v5, 0x4b800000, v4
	v_pk_fma_f32 v[18:19], v[202:203], v[18:19], 1.0 op_sel_hi:[1,1,0]
	v_cndmask_b32_e32 v4, v4, v5, vcc
	v_pk_mul_f32 v[50:51], v[18:19], v[20:21]
	v_rsq_f32_e32 v4, v4
	v_pk_mul_f32 v[18:19], v[36:37], v[50:51]
	v_cvt_pk_f16_f32 v22, v50, v51
	v_fma_f32 v18, v198, v18, 0
	v_fmac_f32_e32 v18, v199, v19
	v_mul_f32_e32 v5, 0x45800000, v4
	v_cndmask_b32_e32 v4, v4, v5, vcc
	v_add_f32_dpp v18, v18, v18 quad_perm:[1,0,3,2] row_mask:0xf bank_mask:0xf bound_ctrl:1
	v_pk_mul_f32 v[2:3], v[2:3], v[4:5] op_sel_hi:[1,0]
	v_lshl_add_u64 v[4:5], s[72:73], 0, v[38:39]
	v_add_f32_dpp v18, v18, v18 quad_perm:[2,3,0,1] row_mask:0xf bank_mask:0xf bound_ctrl:1
	v_cvt_pk_f16_f32 v20, v2, v3
	v_pk_mul_f32 v[2:3], v[34:35], v[2:3]
	v_add_f32_dpp v18, v18, v18 row_half_mirror row_mask:0xf bank_mask:0xf bound_ctrl:1
	global_store_dword v[4:5], v20, off
	v_cvt_pk_f16_f32 v4, v2, v3
	v_add_f32_dpp v18, v18, v18 row_mirror row_mask:0xf bank_mask:0xf bound_ctrl:1
	v_mov_b32_e32 v19, v18
	v_lshl_add_u64 v[2:3], s[78:79], 0, v[38:39]
	s_nop 0
	v_permlane16_swap_b32_e32 v18, v19
	v_lshl_add_u64 v[36:37], s[64:65], 0, v[38:39]
	global_store_dword v[2:3], v4, off
	v_cvt_pk_f16_f32 v4, v7, v23
	v_lshl_add_u64 v[2:3], s[82:83], 0, v[38:39]
	global_store_dword v[36:37], v22, off
	global_store_dword v[2:3], v4, off
	s_and_saveexec_b64 s[6:7], s[4:5]
	s_cbranch_execz .LBB0_464
	v_add_f32_e32 v4, v18, v19
	v_mad_i64_i32 v[2:3], s[92:93], v6, 48, v[200:201]
	global_store_dword v[2:3], v4, off
; DEVI void rwkv_prep_item(const Params& p, const int l, const int item, char* smem) {
;     ...
;     for (int r = 0; r < 16; ++r) {
;       const int t = t0 + mt * 32 + (r & 3) + 8 * (r >> 2) + 4 * hi; const bool has_prev = (t & (SEQ_ - 1)) != 0;
;       float rv[2], kv[2], vv[2], av[2], kkv[2], kpv[2], omdv[2], gv[2];
;       float ssq = 0.f, bon = 0.f;
;       const u16* pr = PA + (size_t)t * 2560 + h * 64 + 2 * l31;
;       const unsigned cr2 = *(const unsigned*)pr, ck2 = *(const unsigned*)(pr + 768), cv2 = *(const unsigned*)(pr + 1536);
;       unsigned qr2 = 0u, qk2 = 0u, qv2 = 0u;
;       if (has_prev) { qr2 = *(const unsigned*)(pr - 2560); qk2 = *(const unsigned*)(pr + 768 - 2560); qv2 = *(const unsigned*)(pr + 1536 - 2560); }
; #pragma unroll
;       for (int n = 0; n < 2; ++n) {
;         const float cr = __uint_as_float(n ? (cr2 & 0xffff0000u) : (cr2 << 16)), ck = __uint_as_float(n ? (ck2 & 0xffff0000u) : (ck2 << 16)), cv = __uint_as_float(n ? (cv2 & 0xffff0000u) : (cv2 << 16));
;         const float qr = __uint_as_float(n ? (qr2 & 0xffff0000u) : (qr2 << 16)), qk = __uint_as_float(n ? (qk2 & 0xffff0000u) : (qk2 << 16)), qv = __uint_as_float(n ? (qv2 & 0xffff0000u) : (qv2 << 16));
;         rv[n] = cr + (qr - cr) * mur[n]; kv[n] = ck + (qk - ck) * muk[n]; vv[n] = cv + (qv - cv) * muv[n];
;         const float z = -(w0c[n] + aw[n][r]);
;         const float sp = fmaxf(z, 0.f) + __logf(1.f + __expf(-fabsf(z)));
;         const float ew = __expf(-sp - 0.5f);
;         omdv[n] = 1.f - __expf(-ew);
;         av[n] = sigmoidf_(a0c[n] + aa[n][r]);
;         gv[n] = ag[n][r];
;         kkv[n] = kv[n] * kkc[n];
;         kpv[n] = kv[n] * (1.f + (av[n] - 1.f) * kac[n]);
;         ssq += kkv[n] * kkv[n];
;         bon += rv[n] * kpv[n] * rkc[n];
;       }
;       ssq = reduce32(ssq); bon = reduce32(bon);
;       const float rn = rsqrtf(ssq + 1e-12f);
;       {
;         typedef _Float16 h2 __attribute__((ext_vector_type(2)));
;         const size_t o = (size_t)t * 768 + h * 64 + 2 * l31;
;         const float kn0 = kkv[0] * rn, kn1 = kkv[1] * rn;
;         *(h2*)(RW + o) = (h2){(f16)rv[0], (f16)rv[1]};
;         *(h2*)(RW + TS + o) = (h2){(f16)omdv[0], (f16)omdv[1]};
;         *(h2*)(RW + 2 * TS + o) = (h2){(f16)kpv[0], (f16)kpv[1]};
;         *(h2*)(RW + 3 * TS + o) = (h2){(f16)vv[0], (f16)vv[1]};
;         *(h2*)(RW + 4 * TS + o) = (h2){(f16)kn0, (f16)kn1};
.LBB0_464:
	s_or_b64 exec, exec, s[6:7]
	v_or_b32_e32 v36, 10, v233
	v_mad_i64_i32 v[2:3], s[6:7], v36, s34, v[212:213]
	s_waitcnt vmcnt(7)
	v_mov_b32_e32 v4, v246
	v_mov_b32_e32 v5, v247
	v_mov_b32_e32 v18, v248
	v_mov_b32_e32 v20, v249
	v_mov_b32_e32 v21, v250
	v_add_co_u32_e32 v2, vcc, 0xfffff000, v2
	s_nop 0
	v_and_b32_e32 v23, 0xffff0000, v4
	v_addc_co_u32_e32 v3, vcc, -1, v3, vcc
	v_mov_b32_e32 v19, v251
	v_or_b32_e32 v253, 11, v233
	v_mad_i64_i32 v[254:255], s[92:93], v253, s34, v[212:213]
	global_load_dword v246, v[254:255], off
	global_load_dword v247, v[254:255], off offset:1536
	global_load_dword v248, v[254:255], off offset:3072
	global_load_dword v249, v[254:255], off offset:-2048
	global_load_dword v250, v[254:255], off offset:-3584
	v_add_co_u32_e32 v254, vcc, 0xfffff000, v254
	s_nop 1
	v_addc_co_u32_e32 v255, vcc, -1, v255, vcc
	global_load_dword v251, v[254:255], off offset:-1024
	v_lshlrev_b32_e32 v22, 16, v4
	s_nop 0
	v_and_b32_e32 v7, 0xffff0000, v5
	v_lshlrev_b32_e32 v6, 16, v5
	s_nop 0
	v_and_b32_e32 v5, 0xffff0000, v20
	v_lshlrev_b32_e32 v4, 16, v20
	v_add_f32_e32 v20, v88, v210
	v_and_b32_e32 v3, 0xffff0000, v18
	v_lshlrev_b32_e32 v2, 16, v18
	s_nop 0
	v_lshlrev_b32_e32 v18, 16, v21
	v_pk_add_f32 v[4:5], v[4:5], v[2:3] neg_lo:[0,1] neg_hi:[0,1]
	s_nop 0
	v_and_b32_e32 v35, 0xffff0000, v19
	v_lshlrev_b32_e32 v34, 16, v19
	v_and_b32_e32 v19, 0xffff0000, v21
	v_max_f32_e64 v21, -v20, 0
	v_mul_f32_e64 v20, |v20|, s88
	v_exp_f32_e32 v20, v20
	v_pk_add_f32 v[18:19], v[18:19], v[6:7] neg_lo:[0,1] neg_hi:[0,1]
	v_pk_add_f32 v[34:35], v[34:35], v[22:23] neg_lo:[0,1] neg_hi:[0,1]
	v_pk_fma_f32 v[18:19], v[204:205], v[18:19], v[6:7]
	v_add_f32_e32 v20, 1.0, v20
	v_cmp_gt_f32_e32 vcc, s89, v20
	v_pk_fma_f32 v[22:23], v[206:207], v[34:35], v[22:23]
	v_pk_fma_f32 v[2:3], v[196:197], v[4:5], v[2:3]
	v_cndmask_b32_e64 v37, 0, 32, vcc
	v_ldexp_f32 v20, v20, v37
	v_log_f32_e32 v20, v20
	v_cvt_pk_f16_f32 v50, v22, v23
	v_cvt_pk_f16_f32 v4, v2, v3
	v_mul_f32_e32 v37, 0x3f317217, v20
	v_fma_f32 v37, v20, s90, -v37
	v_fmac_f32_e32 v37, 0x3377d1cf, v20
	v_fmac_f32_e32 v37, 0x3f317217, v20
	v_cmp_lt_f32_e64 s[6:7], |v20|, s91
	s_nop 1
	v_cndmask_b32_e64 v20, v20, v37, s[6:7]
	v_cndmask_b32_e32 v37, 0, v232, vcc
	v_sub_f32_e32 v20, v20, v37
	v_add_f32_e32 v20, v21, v20
	v_add_f32_e32 v21, v40, v211
	v_max_f32_e64 v38, -v21, 0
	v_mul_f32_e64 v21, |v21|, s88
	v_exp_f32_e32 v21, v21
	v_sub_f32_e32 v20, -0.5, v20
	v_mul_f32_e32 v20, 0x3fb8aa3b, v20
	v_exp_f32_e32 v20, v20
	v_add_f32_e32 v21, 1.0, v21
	v_cmp_gt_f32_e32 vcc, s89, v21
	v_mul_f32_e32 v20, 0xbfb8aa3b, v20
	s_nop 0
	v_cndmask_b32_e64 v39, 0, 32, vcc
	v_ldexp_f32 v21, v21, v39
	v_log_f32_e32 v21, v21
	v_exp_f32_e32 v20, v20
	v_mul_f32_e32 v39, 0x3f317217, v21
	v_fma_f32 v39, v21, s90, -v39
	v_fmac_f32_e32 v39, 0x3377d1cf, v21
	v_fmac_f32_e32 v39, 0x3f317217, v21
	v_cmp_lt_f32_e64 s[6:7], |v21|, s91
	v_sub_f32_e32 v37, 1.0, v20
	v_add_f32_e32 v20, v72, v208
	v_cndmask_b32_e64 v21, v21, v39, s[6:7]
	v_cndmask_b32_e32 v39, 0, v232, vcc
	v_sub_f32_e32 v21, v21, v39
	v_add_f32_e32 v21, v38, v21
	v_sub_f32_e32 v21, -0.5, v21
	v_mul_f32_e32 v21, 0x3fb8aa3b, v21
	v_exp_f32_e32 v21, v21
	v_mul_f32_e32 v20, 0xbfb8aa3b, v20
	v_exp_f32_e32 v20, v20
	v_mad_i64_i32 v[38:39], s[6:7], v36, s54, v[102:103]
	v_mul_f32_e32 v21, 0xbfb8aa3b, v21
	v_exp_f32_e32 v21, v21
	v_lshlrev_b64 v[34:35], 1, v[38:39]
	v_lshl_add_u64 v[38:39], s[56:57], 0, v[34:35]
	global_store_dword v[38:39], v50, off
	v_sub_f32_e32 v40, 1.0, v21
	v_add_f32_e32 v21, v56, v209
	v_mul_f32_e32 v21, 0xbfb8aa3b, v21
	v_exp_f32_e32 v21, v21
	v_cvt_pk_f16_f32 v37, v37, v40
	v_lshl_add_u64 v[38:39], s[62:63], 0, v[34:35]
	global_store_dword v[38:39], v37, off
	v_pk_add_f32 v[6:7], v[20:21], 1.0 op_sel_hi:[1,0]
	v_lshl_add_u64 v[2:3], s[66:67], 0, v[34:35]
	v_div_scale_f32 v20, s[6:7], v7, v7, 1.0
	v_rcp_f32_e32 v21, v20
	global_store_dword v[2:3], v4, off
	v_pk_mul_f32 v[2:3], v[194:195], v[18:19]
	v_fma_f32 v37, -v20, v21, 1.0
	v_fmac_f32_e32 v21, v37, v21
	v_div_scale_f32 v37, vcc, 1.0, v7, 1.0
	v_mul_f32_e32 v38, v37, v21
	v_fma_f32 v39, -v20, v38, v37
	v_fmac_f32_e32 v38, v39, v21
	v_fma_f32 v20, -v20, v38, v37
	v_div_fmas_f32 v20, v20, v21, v38
	v_div_fixup_f32 v21, v20, v7, 1.0
	v_div_scale_f32 v7, s[6:7], v6, v6, 1.0
	v_rcp_f32_e32 v20, v7
	v_pk_mul_f32 v[4:5], v[2:3], v[2:3]
	v_fma_f32 v37, -v7, v20, 1.0
	v_add_f32_e32 v4, v4, v5
	v_fmac_f32_e32 v20, v37, v20
	v_div_scale_f32 v37, vcc, 1.0, v6, 1.0
	v_add_f32_dpp v4, v4, v4 quad_perm:[1,0,3,2] row_mask:0xf bank_mask:0xf bound_ctrl:1
	v_mul_f32_e32 v38, v37, v20
	v_fma_f32 v39, -v7, v38, v37
	v_add_f32_dpp v4, v4, v4 quad_perm:[2,3,0,1] row_mask:0xf bank_mask:0xf bound_ctrl:1
	v_fmac_f32_e32 v38, v39, v20
	v_fma_f32 v7, -v7, v38, v37
	v_add_f32_dpp v4, v4, v4 row_half_mirror row_mask:0xf bank_mask:0xf bound_ctrl:1
	v_div_fmas_f32 v7, v7, v20, v38
	v_div_fixup_f32 v20, v7, v6, 1.0
	v_add_f32_dpp v4, v4, v4 row_mirror row_mask:0xf bank_mask:0xf bound_ctrl:1
	v_mov_b32_e32 v5, v4
	s_nop 1
	v_permlane16_swap_b32_e32 v4, v5
	v_add_f32_e32 v4, v4, v5
	v_add_f32_e32 v4, 0x2b8cbccc, v4
	v_pk_add_f32 v[6:7], v[20:21], -1.0 op_sel_hi:[1,0]
	v_cmp_gt_f32_e32 vcc, s89, v4
	v_mul_f32_e32 v5, 0x4b800000, v4
	v_pk_fma_f32 v[6:7], v[202:203], v[6:7], 1.0 op_sel_hi:[1,1,0]
	v_cndmask_b32_e32 v4, v4, v5, vcc
	v_pk_mul_f32 v[38:39], v[6:7], v[18:19]
	v_rsq_f32_e32 v4, v4
	v_pk_mul_f32 v[6:7], v[22:23], v[38:39]
	v_cvt_pk_f16_f32 v37, v38, v39
	v_fma_f32 v6, v198, v6, 0
	v_fmac_f32_e32 v6, v199, v7
	v_mul_f32_e32 v5, 0x45800000, v4
	v_cndmask_b32_e32 v4, v4, v5, vcc
	v_add_f32_dpp v6, v6, v6 quad_perm:[1,0,3,2] row_mask:0xf bank_mask:0xf bound_ctrl:1
	v_pk_mul_f32 v[2:3], v[2:3], v[4:5] op_sel_hi:[1,0]
	v_lshl_add_u64 v[4:5], s[72:73], 0, v[34:35]
	v_add_f32_dpp v6, v6, v6 quad_perm:[2,3,0,1] row_mask:0xf bank_mask:0xf bound_ctrl:1
	v_cvt_pk_f16_f32 v18, v2, v3
	v_pk_mul_f32 v[2:3], v[20:21], v[2:3]
	v_add_f32_dpp v6, v6, v6 row_half_mirror row_mask:0xf bank_mask:0xf bound_ctrl:1
	global_store_dword v[4:5], v18, off
	v_cvt_pk_f16_f32 v4, v2, v3
	v_add_f32_dpp v6, v6, v6 row_mirror row_mask:0xf bank_mask:0xf bound_ctrl:1
	v_mov_b32_e32 v7, v6
	v_lshl_add_u64 v[2:3], s[78:79], 0, v[34:35]
	s_nop 0
	v_permlane16_swap_b32_e32 v6, v7
	v_lshl_add_u64 v[22:23], s[64:65], 0, v[34:35]
	global_store_dword v[2:3], v4, off
	v_cvt_pk_f16_f32 v4, v8, v24
	v_lshl_add_u64 v[2:3], s[82:83], 0, v[34:35]
	global_store_dword v[22:23], v37, off
	global_store_dword v[2:3], v4, off
	s_and_saveexec_b64 s[6:7], s[4:5]
	s_cbranch_execz .LBB0_466
	v_add_f32_e32 v4, v6, v7
	v_mad_i64_i32 v[2:3], s[92:93], v36, 48, v[200:201]
	global_store_dword v[2:3], v4, off
; DEVI void rwkv_prep_item(const Params& p, const int l, const int item, char* smem) {
;     ...
;     for (int r = 0; r < 16; ++r) {
;       const int t = t0 + mt * 32 + (r & 3) + 8 * (r >> 2) + 4 * hi; const bool has_prev = (t & (SEQ_ - 1)) != 0;
;       float rv[2], kv[2], vv[2], av[2], kkv[2], kpv[2], omdv[2], gv[2];
;       float ssq = 0.f, bon = 0.f;
;       const u16* pr = PA + (size_t)t * 2560 + h * 64 + 2 * l31;
;       const unsigned cr2 = *(const unsigned*)pr, ck2 = *(const unsigned*)(pr + 768), cv2 = *(const unsigned*)(pr + 1536);
;       unsigned qr2 = 0u, qk2 = 0u, qv2 = 0u;
;       if (has_prev) { qr2 = *(const unsigned*)(pr - 2560); qk2 = *(const unsigned*)(pr + 768 - 2560); qv2 = *(const unsigned*)(pr + 1536 - 2560); }
; #pragma unroll
;       for (int n = 0; n < 2; ++n) {
;         const float cr = __uint_as_float(n ? (cr2 & 0xffff0000u) : (cr2 << 16)), ck = __uint_as_float(n ? (ck2 & 0xffff0000u) : (ck2 << 16)), cv = __uint_as_float(n ? (cv2 & 0xffff0000u) : (cv2 << 16));
;         const float qr = __uint_as_float(n ? (qr2 & 0xffff0000u) : (qr2 << 16)), qk = __uint_as_float(n ? (qk2 & 0xffff0000u) : (qk2 << 16)), qv = __uint_as_float(n ? (qv2 & 0xffff0000u) : (qv2 << 16));
;         rv[n] = cr + (qr - cr) * mur[n]; kv[n] = ck + (qk - ck) * muk[n]; vv[n] = cv + (qv - cv) * muv[n];
;         const float z = -(w0c[n] + aw[n][r]);
;         const float sp = fmaxf(z, 0.f) + __logf(1.f + __expf(-fabsf(z)));
;         const float ew = __expf(-sp - 0.5f);
;         omdv[n] = 1.f - __expf(-ew);
;         av[n] = sigmoidf_(a0c[n] + aa[n][r]);
;         gv[n] = ag[n][r];
;         kkv[n] = kv[n] * kkc[n];
;         kpv[n] = kv[n] * (1.f + (av[n] - 1.f) * kac[n]);
;         ssq += kkv[n] * kkv[n];
;         bon += rv[n] * kpv[n] * rkc[n];
;       }
;       ssq = reduce32(ssq); bon = reduce32(bon);
;       const float rn = rsqrtf(ssq + 1e-12f);
;       {
;         typedef _Float16 h2 __attribute__((ext_vector_type(2)));
;         const size_t o = (size_t)t * 768 + h * 64 + 2 * l31;
;         const float kn0 = kkv[0] * rn, kn1 = kkv[1] * rn;
;         *(h2*)(RW + o) = (h2){(f16)rv[0], (f16)rv[1]};
;         *(h2*)(RW + TS + o) = (h2){(f16)omdv[0], (f16)omdv[1]};
;         *(h2*)(RW + 2 * TS + o) = (h2){(f16)kpv[0], (f16)kpv[1]};
;         *(h2*)(RW + 3 * TS + o) = (h2){(f16)vv[0], (f16)vv[1]};
;         *(h2*)(RW + 4 * TS + o) = (h2){(f16)kn0, (f16)kn1};
.LBB0_466:
	s_or_b64 exec, exec, s[6:7]
	v_or_b32_e32 v8, 11, v233
	v_mad_i64_i32 v[2:3], s[6:7], v8, s34, v[212:213]
	s_waitcnt vmcnt(7)
	v_mov_b32_e32 v4, v246
	v_mov_b32_e32 v5, v247
	v_mov_b32_e32 v18, v248
	v_mov_b32_e32 v20, v249
	v_mov_b32_e32 v21, v250
	v_add_co_u32_e32 v2, vcc, 0xfffff000, v2
	s_nop 0
	v_and_b32_e32 v23, 0xffff0000, v4
	v_addc_co_u32_e32 v3, vcc, -1, v3, vcc
	v_mov_b32_e32 v19, v251
	v_or_b32_e32 v253, 16, v233
	v_mad_i64_i32 v[254:255], s[92:93], v253, s34, v[212:213]
	global_load_dword v246, v[254:255], off
	global_load_dword v247, v[254:255], off offset:1536
	global_load_dword v248, v[254:255], off offset:3072
	global_load_dword v249, v[254:255], off offset:-2048
	global_load_dword v250, v[254:255], off offset:-3584
	v_add_co_u32_e32 v254, vcc, 0xfffff000, v254
	s_nop 1
	v_addc_co_u32_e32 v255, vcc, -1, v255, vcc
	global_load_dword v251, v[254:255], off offset:-1024
	v_lshlrev_b32_e32 v22, 16, v4
	s_nop 0
	v_and_b32_e32 v7, 0xffff0000, v5
	v_lshlrev_b32_e32 v6, 16, v5
	s_nop 0
	v_and_b32_e32 v5, 0xffff0000, v20
	v_lshlrev_b32_e32 v4, 16, v20
	v_add_f32_e32 v20, v89, v210
	v_and_b32_e32 v3, 0xffff0000, v18
	v_lshlrev_b32_e32 v2, 16, v18
	s_nop 0
	v_lshlrev_b32_e32 v18, 16, v21
	v_pk_add_f32 v[4:5], v[4:5], v[2:3] neg_lo:[0,1] neg_hi:[0,1]
	s_nop 0
	v_and_b32_e32 v35, 0xffff0000, v19
	v_lshlrev_b32_e32 v34, 16, v19
	v_and_b32_e32 v19, 0xffff0000, v21
	v_max_f32_e64 v21, -v20, 0
	v_mul_f32_e64 v20, |v20|, s88
	v_exp_f32_e32 v20, v20
	v_pk_add_f32 v[18:19], v[18:19], v[6:7] neg_lo:[0,1] neg_hi:[0,1]
	v_pk_add_f32 v[34:35], v[34:35], v[22:23] neg_lo:[0,1] neg_hi:[0,1]
	v_pk_fma_f32 v[18:19], v[204:205], v[18:19], v[6:7]
	v_add_f32_e32 v20, 1.0, v20
	v_cmp_gt_f32_e32 vcc, s89, v20
	v_pk_fma_f32 v[22:23], v[206:207], v[34:35], v[22:23]
	v_pk_fma_f32 v[2:3], v[196:197], v[4:5], v[2:3]
	v_cndmask_b32_e64 v24, 0, 32, vcc
	v_ldexp_f32 v20, v20, v24
	v_log_f32_e32 v20, v20
	v_cvt_pk_f16_f32 v39, v22, v23
	v_cvt_pk_f16_f32 v4, v2, v3
	v_mul_f32_e32 v24, 0x3f317217, v20
	v_fma_f32 v24, v20, s90, -v24
	v_fmac_f32_e32 v24, 0x3377d1cf, v20
	v_fmac_f32_e32 v24, 0x3f317217, v20
	v_cmp_lt_f32_e64 s[6:7], |v20|, s91
	s_nop 1
	v_cndmask_b32_e64 v20, v20, v24, s[6:7]
	v_cndmask_b32_e32 v24, 0, v232, vcc
	v_sub_f32_e32 v20, v20, v24
	v_add_f32_e32 v20, v21, v20
	v_add_f32_e32 v21, v41, v211
	v_max_f32_e64 v36, -v21, 0
	v_mul_f32_e64 v21, |v21|, s88
	v_exp_f32_e32 v21, v21
	v_sub_f32_e32 v20, -0.5, v20
	v_mul_f32_e32 v20, 0x3fb8aa3b, v20
	v_exp_f32_e32 v20, v20
	v_add_f32_e32 v21, 1.0, v21
	v_cmp_gt_f32_e32 vcc, s89, v21
	v_mul_f32_e32 v20, 0xbfb8aa3b, v20
	s_nop 0
	v_cndmask_b32_e64 v37, 0, 32, vcc
	v_ldexp_f32 v21, v21, v37
	v_log_f32_e32 v21, v21
	v_exp_f32_e32 v20, v20
	v_mul_f32_e32 v37, 0x3f317217, v21
	v_fma_f32 v37, v21, s90, -v37
	v_fmac_f32_e32 v37, 0x3377d1cf, v21
	v_fmac_f32_e32 v37, 0x3f317217, v21
	v_cmp_lt_f32_e64 s[6:7], |v21|, s91
	v_sub_f32_e32 v24, 1.0, v20
	v_add_f32_e32 v20, v73, v208
	v_cndmask_b32_e64 v21, v21, v37, s[6:7]
	v_cndmask_b32_e32 v37, 0, v232, vcc
	v_sub_f32_e32 v21, v21, v37
	v_add_f32_e32 v21, v36, v21
	v_sub_f32_e32 v21, -0.5, v21
	v_mul_f32_e32 v21, 0x3fb8aa3b, v21
	v_exp_f32_e32 v21, v21
	v_mul_f32_e32 v20, 0xbfb8aa3b, v20
	v_exp_f32_e32 v20, v20
	v_mad_i64_i32 v[36:37], s[6:7], v8, s54, v[102:103]
	v_mul_f32_e32 v21, 0xbfb8aa3b, v21
	v_exp_f32_e32 v21, v21
	v_lshlrev_b64 v[34:35], 1, v[36:37]
	v_lshl_add_u64 v[36:37], s[56:57], 0, v[34:35]
	global_store_dword v[36:37], v39, off
	v_sub_f32_e32 v38, 1.0, v21
	v_add_f32_e32 v21, v57, v209
	v_mul_f32_e32 v21, 0xbfb8aa3b, v21
	v_exp_f32_e32 v21, v21
	v_cvt_pk_f16_f32 v24, v24, v38
	v_lshl_add_u64 v[36:37], s[62:63], 0, v[34:35]
	global_store_dword v[36:37], v24, off
	v_pk_add_f32 v[6:7], v[20:21], 1.0 op_sel_hi:[1,0]
	v_lshl_add_u64 v[2:3], s[66:67], 0, v[34:35]
	v_div_scale_f32 v20, s[6:7], v7, v7, 1.0
	v_rcp_f32_e32 v21, v20
	global_store_dword v[2:3], v4, off
	v_pk_mul_f32 v[2:3], v[194:195], v[18:19]
	v_fma_f32 v24, -v20, v21, 1.0
	v_fmac_f32_e32 v21, v24, v21
	v_div_scale_f32 v24, vcc, 1.0, v7, 1.0
	v_mul_f32_e32 v36, v24, v21
	v_fma_f32 v37, -v20, v36, v24
	v_fmac_f32_e32 v36, v37, v21
	v_fma_f32 v20, -v20, v36, v24
	v_div_fmas_f32 v20, v20, v21, v36
	v_div_fixup_f32 v21, v20, v7, 1.0
	v_div_scale_f32 v7, s[6:7], v6, v6, 1.0
	v_rcp_f32_e32 v20, v7
	v_pk_mul_f32 v[4:5], v[2:3], v[2:3]
	v_fma_f32 v24, -v7, v20, 1.0
	v_add_f32_e32 v4, v4, v5
	v_fmac_f32_e32 v20, v24, v20
	v_div_scale_f32 v24, vcc, 1.0, v6, 1.0
	v_add_f32_dpp v4, v4, v4 quad_perm:[1,0,3,2] row_mask:0xf bank_mask:0xf bound_ctrl:1
	v_mul_f32_e32 v36, v24, v20
	v_fma_f32 v37, -v7, v36, v24
	v_add_f32_dpp v4, v4, v4 quad_perm:[2,3,0,1] row_mask:0xf bank_mask:0xf bound_ctrl:1
	v_fmac_f32_e32 v36, v37, v20
	v_fma_f32 v7, -v7, v36, v24
	v_add_f32_dpp v4, v4, v4 row_half_mirror row_mask:0xf bank_mask:0xf bound_ctrl:1
	v_div_fmas_f32 v7, v7, v20, v36
	v_div_fixup_f32 v20, v7, v6, 1.0
	v_add_f32_dpp v4, v4, v4 row_mirror row_mask:0xf bank_mask:0xf bound_ctrl:1
	v_mov_b32_e32 v5, v4
	s_nop 1
	v_permlane16_swap_b32_e32 v4, v5
	v_add_f32_e32 v4, v4, v5
	v_add_f32_e32 v4, 0x2b8cbccc, v4
	v_pk_add_f32 v[6:7], v[20:21], -1.0 op_sel_hi:[1,0]
	v_cmp_gt_f32_e32 vcc, s89, v4
	v_mul_f32_e32 v5, 0x4b800000, v4
	v_pk_fma_f32 v[6:7], v[202:203], v[6:7], 1.0 op_sel_hi:[1,1,0]
	v_cndmask_b32_e32 v4, v4, v5, vcc
	v_pk_mul_f32 v[36:37], v[6:7], v[18:19]
	v_rsq_f32_e32 v4, v4
	v_pk_mul_f32 v[6:7], v[22:23], v[36:37]
	v_cvt_pk_f16_f32 v24, v36, v37
	v_fma_f32 v6, v198, v6, 0
	v_fmac_f32_e32 v6, v199, v7
	v_mul_f32_e32 v5, 0x45800000, v4
	v_cndmask_b32_e32 v4, v4, v5, vcc
	v_add_f32_dpp v6, v6, v6 quad_perm:[1,0,3,2] row_mask:0xf bank_mask:0xf bound_ctrl:1
	v_pk_mul_f32 v[2:3], v[2:3], v[4:5] op_sel_hi:[1,0]
	v_lshl_add_u64 v[4:5], s[72:73], 0, v[34:35]
	v_add_f32_dpp v6, v6, v6 quad_perm:[2,3,0,1] row_mask:0xf bank_mask:0xf bound_ctrl:1
	v_cvt_pk_f16_f32 v18, v2, v3
	v_pk_mul_f32 v[2:3], v[20:21], v[2:3]
	v_add_f32_dpp v6, v6, v6 row_half_mirror row_mask:0xf bank_mask:0xf bound_ctrl:1
	global_store_dword v[4:5], v18, off
	v_cvt_pk_f16_f32 v4, v2, v3
	v_add_f32_dpp v6, v6, v6 row_mirror row_mask:0xf bank_mask:0xf bound_ctrl:1
	v_mov_b32_e32 v7, v6
	v_lshl_add_u64 v[2:3], s[78:79], 0, v[34:35]
	s_nop 0
	v_permlane16_swap_b32_e32 v6, v7
	v_lshl_add_u64 v[22:23], s[64:65], 0, v[34:35]
	global_store_dword v[2:3], v4, off
	v_cvt_pk_f16_f32 v4, v9, v25
	v_lshl_add_u64 v[2:3], s[82:83], 0, v[34:35]
	global_store_dword v[22:23], v24, off
	global_store_dword v[2:3], v4, off
	s_and_saveexec_b64 s[6:7], s[4:5]
	s_cbranch_execz .LBB0_468
	v_add_f32_e32 v4, v6, v7
	v_mad_i64_i32 v[2:3], s[92:93], v8, 48, v[200:201]
	global_store_dword v[2:3], v4, off
; DEVI void rwkv_prep_item(const Params& p, const int l, const int item, char* smem) {
;     ...
;     for (int r = 0; r < 16; ++r) {
;       const int t = t0 + mt * 32 + (r & 3) + 8 * (r >> 2) + 4 * hi; const bool has_prev = (t & (SEQ_ - 1)) != 0;
;       float rv[2], kv[2], vv[2], av[2], kkv[2], kpv[2], omdv[2], gv[2];
;       float ssq = 0.f, bon = 0.f;
;       const u16* pr = PA + (size_t)t * 2560 + h * 64 + 2 * l31;
;       const unsigned cr2 = *(const unsigned*)pr, ck2 = *(const unsigned*)(pr + 768), cv2 = *(const unsigned*)(pr + 1536);
;       unsigned qr2 = 0u, qk2 = 0u, qv2 = 0u;
;       if (has_prev) { qr2 = *(const unsigned*)(pr - 2560); qk2 = *(const unsigned*)(pr + 768 - 2560); qv2 = *(const unsigned*)(pr + 1536 - 2560); }
; #pragma unroll
;       for (int n = 0; n < 2; ++n) {
;         const float cr = __uint_as_float(n ? (cr2 & 0xffff0000u) : (cr2 << 16)), ck = __uint_as_float(n ? (ck2 & 0xffff0000u) : (ck2 << 16)), cv = __uint_as_float(n ? (cv2 & 0xffff0000u) : (cv2 << 16));
;         const float qr = __uint_as_float(n ? (qr2 & 0xffff0000u) : (qr2 << 16)), qk = __uint_as_float(n ? (qk2 & 0xffff0000u) : (qk2 << 16)), qv = __uint_as_float(n ? (qv2 & 0xffff0000u) : (qv2 << 16));
;         rv[n] = cr + (qr - cr) * mur[n]; kv[n] = ck + (qk - ck) * muk[n]; vv[n] = cv + (qv - cv) * muv[n];
;         const float z = -(w0c[n] + aw[n][r]);
;         const float sp = fmaxf(z, 0.f) + __logf(1.f + __expf(-fabsf(z)));
;         const float ew = __expf(-sp - 0.5f);
;         omdv[n] = 1.f - __expf(-ew);
;         av[n] = sigmoidf_(a0c[n] + aa[n][r]);
;         gv[n] = ag[n][r];
;         kkv[n] = kv[n] * kkc[n];
;         kpv[n] = kv[n] * (1.f + (av[n] - 1.f) * kac[n]);
;         ssq += kkv[n] * kkv[n];
;         bon += rv[n] * kpv[n] * rkc[n];
;       }
;       ssq = reduce32(ssq); bon = reduce32(bon);
;       const float rn = rsqrtf(ssq + 1e-12f);
;       {
;         typedef _Float16 h2 __attribute__((ext_vector_type(2)));
;         const size_t o = (size_t)t * 768 + h * 64 + 2 * l31;
;         const float kn0 = kkv[0] * rn, kn1 = kkv[1] * rn;
;         *(h2*)(RW + o) = (h2){(f16)rv[0], (f16)rv[1]};
;         *(h2*)(RW + TS + o) = (h2){(f16)omdv[0], (f16)omdv[1]};
;         *(h2*)(RW + 2 * TS + o) = (h2){(f16)kpv[0], (f16)kpv[1]};
;         *(h2*)(RW + 3 * TS + o) = (h2){(f16)vv[0], (f16)vv[1]};
;         *(h2*)(RW + 4 * TS + o) = (h2){(f16)kn0, (f16)kn1};
.LBB0_468:
	s_or_b64 exec, exec, s[6:7]
	v_or_b32_e32 v24, 16, v233
	v_mad_i64_i32 v[2:3], s[6:7], v24, s34, v[212:213]
	s_waitcnt vmcnt(7)
	v_mov_b32_e32 v4, v246
	v_mov_b32_e32 v5, v247
	v_mov_b32_e32 v8, v248
	v_mov_b32_e32 v18, v249
	v_mov_b32_e32 v19, v250
	v_add_co_u32_e32 v2, vcc, 0xfffff000, v2
	s_nop 0
	v_and_b32_e32 v21, 0xffff0000, v4
	v_addc_co_u32_e32 v3, vcc, -1, v3, vcc
	v_mov_b32_e32 v9, v251
	v_or_b32_e32 v253, 17, v233
	v_mad_i64_i32 v[254:255], s[92:93], v253, s34, v[212:213]
	global_load_dword v246, v[254:255], off
	global_load_dword v247, v[254:255], off offset:1536
	global_load_dword v248, v[254:255], off offset:3072
	global_load_dword v249, v[254:255], off offset:-2048
	global_load_dword v250, v[254:255], off offset:-3584
	v_add_co_u32_e32 v254, vcc, 0xfffff000, v254
	s_nop 1
	v_addc_co_u32_e32 v255, vcc, -1, v255, vcc
	global_load_dword v251, v[254:255], off offset:-1024
	v_lshlrev_b32_e32 v20, 16, v4
	s_nop 0
	v_and_b32_e32 v7, 0xffff0000, v5
	v_lshlrev_b32_e32 v6, 16, v5
	s_nop 0
	v_and_b32_e32 v5, 0xffff0000, v18
	v_lshlrev_b32_e32 v4, 16, v18
	v_add_f32_e32 v18, v90, v210
	v_and_b32_e32 v3, 0xffff0000, v8
	v_lshlrev_b32_e32 v2, 16, v8
	s_nop 0
	v_lshlrev_b32_e32 v8, 16, v19
	v_pk_add_f32 v[4:5], v[4:5], v[2:3] neg_lo:[0,1] neg_hi:[0,1]
	s_nop 0
	v_and_b32_e32 v23, 0xffff0000, v9
	v_lshlrev_b32_e32 v22, 16, v9
	v_and_b32_e32 v9, 0xffff0000, v19
	v_max_f32_e64 v19, -v18, 0
	v_mul_f32_e64 v18, |v18|, s88
	v_exp_f32_e32 v18, v18
	v_pk_add_f32 v[8:9], v[8:9], v[6:7] neg_lo:[0,1] neg_hi:[0,1]
	v_pk_add_f32 v[22:23], v[22:23], v[20:21] neg_lo:[0,1] neg_hi:[0,1]
	v_pk_fma_f32 v[8:9], v[204:205], v[8:9], v[6:7]
	v_add_f32_e32 v18, 1.0, v18
	v_cmp_gt_f32_e32 vcc, s89, v18
	v_pk_fma_f32 v[20:21], v[206:207], v[22:23], v[20:21]
	v_pk_fma_f32 v[2:3], v[196:197], v[4:5], v[2:3]
	v_cndmask_b32_e64 v25, 0, 32, vcc
	v_ldexp_f32 v18, v18, v25
	v_log_f32_e32 v18, v18
	v_cvt_pk_f16_f32 v37, v20, v21
	v_cvt_pk_f16_f32 v4, v2, v3
	v_mul_f32_e32 v25, 0x3f317217, v18
	v_fma_f32 v25, v18, s90, -v25
	v_fmac_f32_e32 v25, 0x3377d1cf, v18
	v_fmac_f32_e32 v25, 0x3f317217, v18
	v_cmp_lt_f32_e64 s[6:7], |v18|, s91
	s_nop 1
	v_cndmask_b32_e64 v18, v18, v25, s[6:7]
	v_cndmask_b32_e32 v25, 0, v232, vcc
	v_sub_f32_e32 v18, v18, v25
	v_add_f32_e32 v18, v19, v18
	v_add_f32_e32 v19, v42, v211
	v_max_f32_e64 v34, -v19, 0
	v_mul_f32_e64 v19, |v19|, s88
	v_exp_f32_e32 v19, v19
	v_sub_f32_e32 v18, -0.5, v18
	v_mul_f32_e32 v18, 0x3fb8aa3b, v18
	v_exp_f32_e32 v18, v18
	v_add_f32_e32 v19, 1.0, v19
	v_cmp_gt_f32_e32 vcc, s89, v19
	v_mul_f32_e32 v18, 0xbfb8aa3b, v18
	s_nop 0
	v_cndmask_b32_e64 v35, 0, 32, vcc
	v_ldexp_f32 v19, v19, v35
	v_log_f32_e32 v19, v19
	v_exp_f32_e32 v18, v18
	v_mul_f32_e32 v35, 0x3f317217, v19
	v_fma_f32 v35, v19, s90, -v35
	v_fmac_f32_e32 v35, 0x3377d1cf, v19
	v_fmac_f32_e32 v35, 0x3f317217, v19
	v_cmp_lt_f32_e64 s[6:7], |v19|, s91
	v_sub_f32_e32 v25, 1.0, v18
	v_add_f32_e32 v18, v74, v208
	v_cndmask_b32_e64 v19, v19, v35, s[6:7]
	v_cndmask_b32_e32 v35, 0, v232, vcc
	v_sub_f32_e32 v19, v19, v35
	v_add_f32_e32 v19, v34, v19
	v_sub_f32_e32 v19, -0.5, v19
	v_mul_f32_e32 v19, 0x3fb8aa3b, v19
	v_exp_f32_e32 v19, v19
	v_mul_f32_e32 v18, 0xbfb8aa3b, v18
	v_exp_f32_e32 v18, v18
	v_mad_i64_i32 v[34:35], s[6:7], v24, s54, v[102:103]
	v_mul_f32_e32 v19, 0xbfb8aa3b, v19
	v_exp_f32_e32 v19, v19
	v_lshlrev_b64 v[22:23], 1, v[34:35]
	v_lshl_add_u64 v[34:35], s[56:57], 0, v[22:23]
	global_store_dword v[34:35], v37, off
	v_sub_f32_e32 v36, 1.0, v19
	v_add_f32_e32 v19, v58, v209
	v_mul_f32_e32 v19, 0xbfb8aa3b, v19
	v_exp_f32_e32 v19, v19
	v_cvt_pk_f16_f32 v25, v25, v36
	v_lshl_add_u64 v[34:35], s[62:63], 0, v[22:23]
	global_store_dword v[34:35], v25, off
	v_pk_add_f32 v[6:7], v[18:19], 1.0 op_sel_hi:[1,0]
	v_lshl_add_u64 v[2:3], s[66:67], 0, v[22:23]
	v_div_scale_f32 v18, s[6:7], v7, v7, 1.0
	v_rcp_f32_e32 v19, v18
	global_store_dword v[2:3], v4, off
	v_pk_mul_f32 v[2:3], v[194:195], v[8:9]
	v_fma_f32 v25, -v18, v19, 1.0
	v_fmac_f32_e32 v19, v25, v19
	v_div_scale_f32 v25, vcc, 1.0, v7, 1.0
	v_mul_f32_e32 v34, v25, v19
	v_fma_f32 v35, -v18, v34, v25
	v_fmac_f32_e32 v34, v35, v19
	v_fma_f32 v18, -v18, v34, v25
	v_div_fmas_f32 v18, v18, v19, v34
	v_div_fixup_f32 v19, v18, v7, 1.0
	v_div_scale_f32 v7, s[6:7], v6, v6, 1.0
	v_rcp_f32_e32 v18, v7
	v_pk_mul_f32 v[4:5], v[2:3], v[2:3]
	v_fma_f32 v25, -v7, v18, 1.0
	v_add_f32_e32 v4, v4, v5
	v_fmac_f32_e32 v18, v25, v18
	v_div_scale_f32 v25, vcc, 1.0, v6, 1.0
	v_add_f32_dpp v4, v4, v4 quad_perm:[1,0,3,2] row_mask:0xf bank_mask:0xf bound_ctrl:1
	v_mul_f32_e32 v34, v25, v18
	v_fma_f32 v35, -v7, v34, v25
	v_add_f32_dpp v4, v4, v4 quad_perm:[2,3,0,1] row_mask:0xf bank_mask:0xf bound_ctrl:1
	v_fmac_f32_e32 v34, v35, v18
	v_fma_f32 v7, -v7, v34, v25
	v_add_f32_dpp v4, v4, v4 row_half_mirror row_mask:0xf bank_mask:0xf bound_ctrl:1
	v_div_fmas_f32 v7, v7, v18, v34
	v_div_fixup_f32 v18, v7, v6, 1.0
	v_add_f32_dpp v4, v4, v4 row_mirror row_mask:0xf bank_mask:0xf bound_ctrl:1
	v_mov_b32_e32 v5, v4
	s_nop 1
	v_permlane16_swap_b32_e32 v4, v5
	v_add_f32_e32 v4, v4, v5
	v_add_f32_e32 v4, 0x2b8cbccc, v4
	v_pk_add_f32 v[6:7], v[18:19], -1.0 op_sel_hi:[1,0]
	v_cmp_gt_f32_e32 vcc, s89, v4
	v_mul_f32_e32 v5, 0x4b800000, v4
	v_pk_fma_f32 v[6:7], v[202:203], v[6:7], 1.0 op_sel_hi:[1,1,0]
	v_cndmask_b32_e32 v4, v4, v5, vcc
	v_pk_mul_f32 v[34:35], v[6:7], v[8:9]
	v_rsq_f32_e32 v4, v4
	v_pk_mul_f32 v[6:7], v[20:21], v[34:35]
	v_cvt_pk_f16_f32 v25, v34, v35
	v_fma_f32 v6, v198, v6, 0
	v_fmac_f32_e32 v6, v199, v7
	v_mul_f32_e32 v5, 0x45800000, v4
	v_cndmask_b32_e32 v4, v4, v5, vcc
	v_add_f32_dpp v6, v6, v6 quad_perm:[1,0,3,2] row_mask:0xf bank_mask:0xf bound_ctrl:1
	v_pk_mul_f32 v[2:3], v[2:3], v[4:5] op_sel_hi:[1,0]
	v_lshl_add_u64 v[4:5], s[72:73], 0, v[22:23]
	v_add_f32_dpp v6, v6, v6 quad_perm:[2,3,0,1] row_mask:0xf bank_mask:0xf bound_ctrl:1
	v_cvt_pk_f16_f32 v8, v2, v3
	v_pk_mul_f32 v[2:3], v[18:19], v[2:3]
	v_add_f32_dpp v6, v6, v6 row_half_mirror row_mask:0xf bank_mask:0xf bound_ctrl:1
	global_store_dword v[4:5], v8, off
	v_cvt_pk_f16_f32 v4, v2, v3
	v_add_f32_dpp v6, v6, v6 row_mirror row_mask:0xf bank_mask:0xf bound_ctrl:1
	v_mov_b32_e32 v7, v6
	v_lshl_add_u64 v[2:3], s[78:79], 0, v[22:23]
	s_nop 0
	v_permlane16_swap_b32_e32 v6, v7
	v_lshl_add_u64 v[20:21], s[64:65], 0, v[22:23]
	global_store_dword v[2:3], v4, off
	v_cvt_pk_f16_f32 v4, v10, v26
	v_lshl_add_u64 v[2:3], s[82:83], 0, v[22:23]
	global_store_dword v[20:21], v25, off
	global_store_dword v[2:3], v4, off
	s_and_saveexec_b64 s[6:7], s[4:5]
	s_cbranch_execz .LBB0_470
	v_add_f32_e32 v4, v6, v7
	v_mad_i64_i32 v[2:3], s[92:93], v24, 48, v[200:201]
	global_store_dword v[2:3], v4, off
; DEVI void rwkv_prep_item(const Params& p, const int l, const int item, char* smem) {
;     ...
;     for (int r = 0; r < 16; ++r) {
;       const int t = t0 + mt * 32 + (r & 3) + 8 * (r >> 2) + 4 * hi; const bool has_prev = (t & (SEQ_ - 1)) != 0;
;       float rv[2], kv[2], vv[2], av[2], kkv[2], kpv[2], omdv[2], gv[2];
;       float ssq = 0.f, bon = 0.f;
;       const u16* pr = PA + (size_t)t * 2560 + h * 64 + 2 * l31;
;       const unsigned cr2 = *(const unsigned*)pr, ck2 = *(const unsigned*)(pr + 768), cv2 = *(const unsigned*)(pr + 1536);
;       unsigned qr2 = 0u, qk2 = 0u, qv2 = 0u;
;       if (has_prev) { qr2 = *(const unsigned*)(pr - 2560); qk2 = *(const unsigned*)(pr + 768 - 2560); qv2 = *(const unsigned*)(pr + 1536 - 2560); }
; #pragma unroll
;       for (int n = 0; n < 2; ++n) {
;         const float cr = __uint_as_float(n ? (cr2 & 0xffff0000u) : (cr2 << 16)), ck = __uint_as_float(n ? (ck2 & 0xffff0000u) : (ck2 << 16)), cv = __uint_as_float(n ? (cv2 & 0xffff0000u) : (cv2 << 16));
;         const float qr = __uint_as_float(n ? (qr2 & 0xffff0000u) : (qr2 << 16)), qk = __uint_as_float(n ? (qk2 & 0xffff0000u) : (qk2 << 16)), qv = __uint_as_float(n ? (qv2 & 0xffff0000u) : (qv2 << 16));
;         rv[n] = cr + (qr - cr) * mur[n]; kv[n] = ck + (qk - ck) * muk[n]; vv[n] = cv + (qv - cv) * muv[n];
;         const float z = -(w0c[n] + aw[n][r]);
;         const float sp = fmaxf(z, 0.f) + __logf(1.f + __expf(-fabsf(z)));
;         const float ew = __expf(-sp - 0.5f);
;         omdv[n] = 1.f - __expf(-ew);
;         av[n] = sigmoidf_(a0c[n] + aa[n][r]);
;         gv[n] = ag[n][r];
;         kkv[n] = kv[n] * kkc[n];
;         kpv[n] = kv[n] * (1.f + (av[n] - 1.f) * kac[n]);
;         ssq += kkv[n] * kkv[n];
;         bon += rv[n] * kpv[n] * rkc[n];
;       }
;       ssq = reduce32(ssq); bon = reduce32(bon);
;       const float rn = rsqrtf(ssq + 1e-12f);
;       {
;         typedef _Float16 h2 __attribute__((ext_vector_type(2)));
;         const size_t o = (size_t)t * 768 + h * 64 + 2 * l31;
;         const float kn0 = kkv[0] * rn, kn1 = kkv[1] * rn;
;         *(h2*)(RW + o) = (h2){(f16)rv[0], (f16)rv[1]};
;         *(h2*)(RW + TS + o) = (h2){(f16)omdv[0], (f16)omdv[1]};
;         *(h2*)(RW + 2 * TS + o) = (h2){(f16)kpv[0], (f16)kpv[1]};
;         *(h2*)(RW + 3 * TS + o) = (h2){(f16)vv[0], (f16)vv[1]};
;         *(h2*)(RW + 4 * TS + o) = (h2){(f16)kn0, (f16)kn1};
.LBB0_470:
	s_or_b64 exec, exec, s[6:7]
	v_or_b32_e32 v10, 17, v233
	v_mad_i64_i32 v[2:3], s[6:7], v10, s34, v[212:213]
	s_waitcnt vmcnt(7)
	v_mov_b32_e32 v4, v246
	v_mov_b32_e32 v5, v247
	v_mov_b32_e32 v8, v248
	v_mov_b32_e32 v18, v249
	v_mov_b32_e32 v19, v250
	v_add_co_u32_e32 v2, vcc, 0xfffff000, v2
	s_nop 0
	v_and_b32_e32 v21, 0xffff0000, v4
	v_addc_co_u32_e32 v3, vcc, -1, v3, vcc
	v_mov_b32_e32 v9, v251
	v_or_b32_e32 v253, 18, v233
	v_mad_i64_i32 v[254:255], s[92:93], v253, s34, v[212:213]
	global_load_dword v246, v[254:255], off
	global_load_dword v247, v[254:255], off offset:1536
	global_load_dword v248, v[254:255], off offset:3072
	global_load_dword v249, v[254:255], off offset:-2048
	global_load_dword v250, v[254:255], off offset:-3584
	v_add_co_u32_e32 v254, vcc, 0xfffff000, v254
	s_nop 1
	v_addc_co_u32_e32 v255, vcc, -1, v255, vcc
	global_load_dword v251, v[254:255], off offset:-1024
	v_lshlrev_b32_e32 v20, 16, v4
	s_nop 0
	v_and_b32_e32 v7, 0xffff0000, v5
	v_lshlrev_b32_e32 v6, 16, v5
	s_nop 0
	v_and_b32_e32 v5, 0xffff0000, v18
	v_lshlrev_b32_e32 v4, 16, v18
	v_add_f32_e32 v18, v91, v210
	v_and_b32_e32 v3, 0xffff0000, v8
	v_lshlrev_b32_e32 v2, 16, v8
	s_nop 0
	v_lshlrev_b32_e32 v8, 16, v19
	v_pk_add_f32 v[4:5], v[4:5], v[2:3] neg_lo:[0,1] neg_hi:[0,1]
	s_nop 0
	v_and_b32_e32 v23, 0xffff0000, v9
	v_lshlrev_b32_e32 v22, 16, v9
	v_and_b32_e32 v9, 0xffff0000, v19
	v_max_f32_e64 v19, -v18, 0
	v_mul_f32_e64 v18, |v18|, s88
	v_exp_f32_e32 v18, v18
	v_pk_add_f32 v[8:9], v[8:9], v[6:7] neg_lo:[0,1] neg_hi:[0,1]
	v_pk_add_f32 v[22:23], v[22:23], v[20:21] neg_lo:[0,1] neg_hi:[0,1]
	v_pk_fma_f32 v[8:9], v[204:205], v[8:9], v[6:7]
	v_add_f32_e32 v18, 1.0, v18
	v_cmp_gt_f32_e32 vcc, s89, v18
	v_pk_fma_f32 v[20:21], v[206:207], v[22:23], v[20:21]
	v_pk_fma_f32 v[2:3], v[196:197], v[4:5], v[2:3]
	v_cndmask_b32_e64 v24, 0, 32, vcc
	v_ldexp_f32 v18, v18, v24
	v_log_f32_e32 v18, v18
	v_cvt_pk_f16_f32 v35, v20, v21
	v_cvt_pk_f16_f32 v4, v2, v3
	v_mul_f32_e32 v24, 0x3f317217, v18
	v_fma_f32 v24, v18, s90, -v24
	v_fmac_f32_e32 v24, 0x3377d1cf, v18
	v_fmac_f32_e32 v24, 0x3f317217, v18
	v_cmp_lt_f32_e64 s[6:7], |v18|, s91
	s_nop 1
	v_cndmask_b32_e64 v18, v18, v24, s[6:7]
	v_cndmask_b32_e32 v24, 0, v232, vcc
	v_sub_f32_e32 v18, v18, v24
	v_add_f32_e32 v18, v19, v18
	v_add_f32_e32 v19, v43, v211
	v_max_f32_e64 v24, -v19, 0
	v_mul_f32_e64 v19, |v19|, s88
	v_exp_f32_e32 v19, v19
	v_sub_f32_e32 v18, -0.5, v18
	v_mul_f32_e32 v18, 0x3fb8aa3b, v18
	v_exp_f32_e32 v18, v18
	v_add_f32_e32 v19, 1.0, v19
	v_cmp_gt_f32_e32 vcc, s89, v19
	v_mul_f32_e32 v18, 0xbfb8aa3b, v18
	s_nop 0
	v_cndmask_b32_e64 v25, 0, 32, vcc
	v_ldexp_f32 v19, v19, v25
	v_log_f32_e32 v19, v19
	v_exp_f32_e32 v18, v18
	v_mul_f32_e32 v25, 0x3f317217, v19
	v_fma_f32 v25, v19, s90, -v25
	v_fmac_f32_e32 v25, 0x3377d1cf, v19
	v_fmac_f32_e32 v25, 0x3f317217, v19
	v_cmp_lt_f32_e64 s[6:7], |v19|, s91
	v_sub_f32_e32 v26, 1.0, v18
	v_add_f32_e32 v18, v75, v208
	v_cndmask_b32_e64 v19, v19, v25, s[6:7]
	v_cndmask_b32_e32 v25, 0, v232, vcc
	v_sub_f32_e32 v19, v19, v25
	v_add_f32_e32 v19, v24, v19
	v_sub_f32_e32 v19, -0.5, v19
	v_mul_f32_e32 v19, 0x3fb8aa3b, v19
	v_exp_f32_e32 v19, v19
	v_mul_f32_e32 v18, 0xbfb8aa3b, v18
	v_exp_f32_e32 v18, v18
	v_mad_i64_i32 v[24:25], s[6:7], v10, s54, v[102:103]
	v_mul_f32_e32 v19, 0xbfb8aa3b, v19
	v_exp_f32_e32 v19, v19
	v_lshlrev_b64 v[22:23], 1, v[24:25]
	v_lshl_add_u64 v[24:25], s[56:57], 0, v[22:23]
	global_store_dword v[24:25], v35, off
	v_sub_f32_e32 v34, 1.0, v19
	v_add_f32_e32 v19, v59, v209
	v_mul_f32_e32 v19, 0xbfb8aa3b, v19
	v_exp_f32_e32 v19, v19
	v_cvt_pk_f16_f32 v26, v26, v34
	v_lshl_add_u64 v[24:25], s[62:63], 0, v[22:23]
	global_store_dword v[24:25], v26, off
	v_pk_add_f32 v[6:7], v[18:19], 1.0 op_sel_hi:[1,0]
	v_lshl_add_u64 v[2:3], s[66:67], 0, v[22:23]
	v_div_scale_f32 v18, s[6:7], v7, v7, 1.0
	v_rcp_f32_e32 v19, v18
	global_store_dword v[2:3], v4, off
	v_pk_mul_f32 v[2:3], v[194:195], v[8:9]
	v_fma_f32 v24, -v18, v19, 1.0
	v_fmac_f32_e32 v19, v24, v19
	v_div_scale_f32 v24, vcc, 1.0, v7, 1.0
	v_mul_f32_e32 v25, v24, v19
	v_fma_f32 v26, -v18, v25, v24
	v_fmac_f32_e32 v25, v26, v19
	v_fma_f32 v18, -v18, v25, v24
	v_div_fmas_f32 v18, v18, v19, v25
	v_div_fixup_f32 v19, v18, v7, 1.0
	v_div_scale_f32 v7, s[6:7], v6, v6, 1.0
	v_rcp_f32_e32 v18, v7
	v_pk_mul_f32 v[4:5], v[2:3], v[2:3]
	v_fma_f32 v24, -v7, v18, 1.0
	v_add_f32_e32 v4, v4, v5
	v_fmac_f32_e32 v18, v24, v18
	v_div_scale_f32 v24, vcc, 1.0, v6, 1.0
	v_add_f32_dpp v4, v4, v4 quad_perm:[1,0,3,2] row_mask:0xf bank_mask:0xf bound_ctrl:1
	v_mul_f32_e32 v25, v24, v18
	v_fma_f32 v26, -v7, v25, v24
	v_add_f32_dpp v4, v4, v4 quad_perm:[2,3,0,1] row_mask:0xf bank_mask:0xf bound_ctrl:1
	v_fmac_f32_e32 v25, v26, v18
	v_fma_f32 v7, -v7, v25, v24
	v_add_f32_dpp v4, v4, v4 row_half_mirror row_mask:0xf bank_mask:0xf bound_ctrl:1
	v_div_fmas_f32 v7, v7, v18, v25
	v_div_fixup_f32 v18, v7, v6, 1.0
	v_add_f32_dpp v4, v4, v4 row_mirror row_mask:0xf bank_mask:0xf bound_ctrl:1
	v_mov_b32_e32 v5, v4
	s_nop 1
	v_permlane16_swap_b32_e32 v4, v5
	v_add_f32_e32 v4, v4, v5
	v_add_f32_e32 v4, 0x2b8cbccc, v4
	v_pk_add_f32 v[6:7], v[18:19], -1.0 op_sel_hi:[1,0]
	v_cmp_gt_f32_e32 vcc, s89, v4
	v_mul_f32_e32 v5, 0x4b800000, v4
	v_pk_fma_f32 v[6:7], v[202:203], v[6:7], 1.0 op_sel_hi:[1,1,0]
	v_cndmask_b32_e32 v4, v4, v5, vcc
	v_pk_mul_f32 v[24:25], v[6:7], v[8:9]
	v_rsq_f32_e32 v4, v4
	v_pk_mul_f32 v[6:7], v[20:21], v[24:25]
	v_cvt_pk_f16_f32 v24, v24, v25
	v_fma_f32 v6, v198, v6, 0
	v_fmac_f32_e32 v6, v199, v7
	v_mul_f32_e32 v5, 0x45800000, v4
	v_cndmask_b32_e32 v4, v4, v5, vcc
	v_add_f32_dpp v6, v6, v6 quad_perm:[1,0,3,2] row_mask:0xf bank_mask:0xf bound_ctrl:1
	v_pk_mul_f32 v[2:3], v[2:3], v[4:5] op_sel_hi:[1,0]
	v_lshl_add_u64 v[4:5], s[72:73], 0, v[22:23]
	v_add_f32_dpp v6, v6, v6 quad_perm:[2,3,0,1] row_mask:0xf bank_mask:0xf bound_ctrl:1
	v_cvt_pk_f16_f32 v8, v2, v3
	v_pk_mul_f32 v[2:3], v[18:19], v[2:3]
	v_add_f32_dpp v6, v6, v6 row_half_mirror row_mask:0xf bank_mask:0xf bound_ctrl:1
	global_store_dword v[4:5], v8, off
	v_cvt_pk_f16_f32 v4, v2, v3
	v_add_f32_dpp v6, v6, v6 row_mirror row_mask:0xf bank_mask:0xf bound_ctrl:1
	v_mov_b32_e32 v7, v6
	v_lshl_add_u64 v[2:3], s[78:79], 0, v[22:23]
	s_nop 0
	v_permlane16_swap_b32_e32 v6, v7
	v_lshl_add_u64 v[20:21], s[64:65], 0, v[22:23]
	global_store_dword v[2:3], v4, off
	v_cvt_pk_f16_f32 v4, v11, v27
	v_lshl_add_u64 v[2:3], s[82:83], 0, v[22:23]
	global_store_dword v[20:21], v24, off
	global_store_dword v[2:3], v4, off
	s_and_saveexec_b64 s[6:7], s[4:5]
	s_cbranch_execz .LBB0_472
	v_add_f32_e32 v4, v6, v7
	v_mad_i64_i32 v[2:3], s[92:93], v10, 48, v[200:201]
	global_store_dword v[2:3], v4, off
; DEVI void rwkv_prep_item(const Params& p, const int l, const int item, char* smem) {
;     ...
;     for (int r = 0; r < 16; ++r) {
;       const int t = t0 + mt * 32 + (r & 3) + 8 * (r >> 2) + 4 * hi; const bool has_prev = (t & (SEQ_ - 1)) != 0;
;       float rv[2], kv[2], vv[2], av[2], kkv[2], kpv[2], omdv[2], gv[2];
;       float ssq = 0.f, bon = 0.f;
;       const u16* pr = PA + (size_t)t * 2560 + h * 64 + 2 * l31;
;       const unsigned cr2 = *(const unsigned*)pr, ck2 = *(const unsigned*)(pr + 768), cv2 = *(const unsigned*)(pr + 1536);
;       unsigned qr2 = 0u, qk2 = 0u, qv2 = 0u;
;       if (has_prev) { qr2 = *(const unsigned*)(pr - 2560); qk2 = *(const unsigned*)(pr + 768 - 2560); qv2 = *(const unsigned*)(pr + 1536 - 2560); }
; #pragma unroll
;       for (int n = 0; n < 2; ++n) {
;         const float cr = __uint_as_float(n ? (cr2 & 0xffff0000u) : (cr2 << 16)), ck = __uint_as_float(n ? (ck2 & 0xffff0000u) : (ck2 << 16)), cv = __uint_as_float(n ? (cv2 & 0xffff0000u) : (cv2 << 16));
;         const float qr = __uint_as_float(n ? (qr2 & 0xffff0000u) : (qr2 << 16)), qk = __uint_as_float(n ? (qk2 & 0xffff0000u) : (qk2 << 16)), qv = __uint_as_float(n ? (qv2 & 0xffff0000u) : (qv2 << 16));
;         rv[n] = cr + (qr - cr) * mur[n]; kv[n] = ck + (qk - ck) * muk[n]; vv[n] = cv + (qv - cv) * muv[n];
;         const float z = -(w0c[n] + aw[n][r]);
;         const float sp = fmaxf(z, 0.f) + __logf(1.f + __expf(-fabsf(z)));
;         const float ew = __expf(-sp - 0.5f);
;         omdv[n] = 1.f - __expf(-ew);
;         av[n] = sigmoidf_(a0c[n] + aa[n][r]);
;         gv[n] = ag[n][r];
;         kkv[n] = kv[n] * kkc[n];
;         kpv[n] = kv[n] * (1.f + (av[n] - 1.f) * kac[n]);
;         ssq += kkv[n] * kkv[n];
;         bon += rv[n] * kpv[n] * rkc[n];
;       }
;       ssq = reduce32(ssq); bon = reduce32(bon);
;       const float rn = rsqrtf(ssq + 1e-12f);
;       {
;         typedef _Float16 h2 __attribute__((ext_vector_type(2)));
;         const size_t o = (size_t)t * 768 + h * 64 + 2 * l31;
;         const float kn0 = kkv[0] * rn, kn1 = kkv[1] * rn;
;         *(h2*)(RW + o) = (h2){(f16)rv[0], (f16)rv[1]};
;         *(h2*)(RW + TS + o) = (h2){(f16)omdv[0], (f16)omdv[1]};
;         *(h2*)(RW + 2 * TS + o) = (h2){(f16)kpv[0], (f16)kpv[1]};
;         *(h2*)(RW + 3 * TS + o) = (h2){(f16)vv[0], (f16)vv[1]};
;         *(h2*)(RW + 4 * TS + o) = (h2){(f16)kn0, (f16)kn1};
.LBB0_472:
	s_or_b64 exec, exec, s[6:7]
	v_or_b32_e32 v22, 18, v233
	v_mad_i64_i32 v[2:3], s[6:7], v22, s34, v[212:213]
	s_waitcnt vmcnt(7)
	v_mov_b32_e32 v4, v246
	v_mov_b32_e32 v5, v247
	v_mov_b32_e32 v8, v248
	v_mov_b32_e32 v10, v249
	v_mov_b32_e32 v11, v250
	v_add_co_u32_e32 v2, vcc, 0xfffff000, v2
	s_nop 0
	v_and_b32_e32 v19, 0xffff0000, v4
	v_addc_co_u32_e32 v3, vcc, -1, v3, vcc
	v_mov_b32_e32 v9, v251
	v_or_b32_e32 v253, 19, v233
	v_mad_i64_i32 v[254:255], s[92:93], v253, s34, v[212:213]
	global_load_dword v246, v[254:255], off
	global_load_dword v247, v[254:255], off offset:1536
	global_load_dword v248, v[254:255], off offset:3072
	global_load_dword v249, v[254:255], off offset:-2048
	global_load_dword v250, v[254:255], off offset:-3584
	v_add_co_u32_e32 v254, vcc, 0xfffff000, v254
	s_nop 1
	v_addc_co_u32_e32 v255, vcc, -1, v255, vcc
	global_load_dword v251, v[254:255], off offset:-1024
	v_lshlrev_b32_e32 v18, 16, v4
	s_nop 0
	v_and_b32_e32 v7, 0xffff0000, v5
	v_lshlrev_b32_e32 v6, 16, v5
	s_nop 0
	v_and_b32_e32 v5, 0xffff0000, v10
	v_lshlrev_b32_e32 v4, 16, v10
	v_add_f32_e32 v10, v92, v210
	v_and_b32_e32 v3, 0xffff0000, v8
	v_lshlrev_b32_e32 v2, 16, v8
	s_nop 0
	v_lshlrev_b32_e32 v8, 16, v11
	v_pk_add_f32 v[4:5], v[4:5], v[2:3] neg_lo:[0,1] neg_hi:[0,1]
	s_nop 0
	v_and_b32_e32 v21, 0xffff0000, v9
	v_lshlrev_b32_e32 v20, 16, v9
	v_and_b32_e32 v9, 0xffff0000, v11
	v_max_f32_e64 v11, -v10, 0
	v_mul_f32_e64 v10, |v10|, s88
	v_exp_f32_e32 v10, v10
	v_pk_add_f32 v[8:9], v[8:9], v[6:7] neg_lo:[0,1] neg_hi:[0,1]
	v_pk_add_f32 v[20:21], v[20:21], v[18:19] neg_lo:[0,1] neg_hi:[0,1]
	v_pk_fma_f32 v[8:9], v[204:205], v[8:9], v[6:7]
	v_add_f32_e32 v10, 1.0, v10
	v_cmp_gt_f32_e32 vcc, s89, v10
	v_pk_fma_f32 v[18:19], v[206:207], v[20:21], v[18:19]
	v_pk_fma_f32 v[2:3], v[196:197], v[4:5], v[2:3]
	v_cndmask_b32_e64 v23, 0, 32, vcc
	v_ldexp_f32 v10, v10, v23
	v_log_f32_e32 v10, v10
	v_cvt_pk_f16_f32 v27, v18, v19
	v_cvt_pk_f16_f32 v4, v2, v3
	v_mul_f32_e32 v23, 0x3f317217, v10
	v_fma_f32 v23, v10, s90, -v23
	v_fmac_f32_e32 v23, 0x3377d1cf, v10
	v_fmac_f32_e32 v23, 0x3f317217, v10
	v_cmp_lt_f32_e64 s[6:7], |v10|, s91
	s_nop 1
	v_cndmask_b32_e64 v10, v10, v23, s[6:7]
	v_cndmask_b32_e32 v23, 0, v232, vcc
	v_sub_f32_e32 v10, v10, v23
	v_add_f32_e32 v10, v11, v10
	v_add_f32_e32 v11, v44, v211
	v_max_f32_e64 v24, -v11, 0
	v_mul_f32_e64 v11, |v11|, s88
	v_exp_f32_e32 v11, v11
	v_sub_f32_e32 v10, -0.5, v10
	v_mul_f32_e32 v10, 0x3fb8aa3b, v10
	v_exp_f32_e32 v10, v10
	v_add_f32_e32 v11, 1.0, v11
	v_cmp_gt_f32_e32 vcc, s89, v11
	v_mul_f32_e32 v10, 0xbfb8aa3b, v10
	s_nop 0
	v_cndmask_b32_e64 v25, 0, 32, vcc
	v_ldexp_f32 v11, v11, v25
	v_log_f32_e32 v11, v11
	v_exp_f32_e32 v10, v10
	v_mul_f32_e32 v25, 0x3f317217, v11
	v_fma_f32 v25, v11, s90, -v25
	v_fmac_f32_e32 v25, 0x3377d1cf, v11
	v_fmac_f32_e32 v25, 0x3f317217, v11
	v_cmp_lt_f32_e64 s[6:7], |v11|, s91
	v_sub_f32_e32 v23, 1.0, v10
	v_add_f32_e32 v10, v76, v208
	v_cndmask_b32_e64 v11, v11, v25, s[6:7]
	v_cndmask_b32_e32 v25, 0, v232, vcc
	v_sub_f32_e32 v11, v11, v25
	v_add_f32_e32 v11, v24, v11
	v_sub_f32_e32 v11, -0.5, v11
	v_mul_f32_e32 v11, 0x3fb8aa3b, v11
	v_exp_f32_e32 v11, v11
	v_mul_f32_e32 v10, 0xbfb8aa3b, v10
	v_exp_f32_e32 v10, v10
	v_mad_i64_i32 v[24:25], s[6:7], v22, s54, v[102:103]
	v_mul_f32_e32 v11, 0xbfb8aa3b, v11
	v_exp_f32_e32 v11, v11
	v_lshlrev_b64 v[20:21], 1, v[24:25]
	v_lshl_add_u64 v[24:25], s[56:57], 0, v[20:21]
	global_store_dword v[24:25], v27, off
	v_sub_f32_e32 v26, 1.0, v11
	v_add_f32_e32 v11, v60, v209
	v_mul_f32_e32 v11, 0xbfb8aa3b, v11
	v_exp_f32_e32 v11, v11
	v_cvt_pk_f16_f32 v23, v23, v26
	v_lshl_add_u64 v[24:25], s[62:63], 0, v[20:21]
	global_store_dword v[24:25], v23, off
	v_pk_add_f32 v[6:7], v[10:11], 1.0 op_sel_hi:[1,0]
	v_lshl_add_u64 v[2:3], s[66:67], 0, v[20:21]
	v_div_scale_f32 v10, s[6:7], v7, v7, 1.0
	v_rcp_f32_e32 v11, v10
	global_store_dword v[2:3], v4, off
	v_pk_mul_f32 v[2:3], v[194:195], v[8:9]
	v_fma_f32 v23, -v10, v11, 1.0
	v_fmac_f32_e32 v11, v23, v11
	v_div_scale_f32 v23, vcc, 1.0, v7, 1.0
	v_mul_f32_e32 v24, v23, v11
	v_fma_f32 v25, -v10, v24, v23
	v_fmac_f32_e32 v24, v25, v11
	v_fma_f32 v10, -v10, v24, v23
	v_div_fmas_f32 v10, v10, v11, v24
	v_div_fixup_f32 v11, v10, v7, 1.0
	v_div_scale_f32 v7, s[6:7], v6, v6, 1.0
	v_rcp_f32_e32 v10, v7
	v_pk_mul_f32 v[4:5], v[2:3], v[2:3]
	v_fma_f32 v23, -v7, v10, 1.0
	v_add_f32_e32 v4, v4, v5
	v_fmac_f32_e32 v10, v23, v10
	v_div_scale_f32 v23, vcc, 1.0, v6, 1.0
	v_add_f32_dpp v4, v4, v4 quad_perm:[1,0,3,2] row_mask:0xf bank_mask:0xf bound_ctrl:1
	v_mul_f32_e32 v24, v23, v10
	v_fma_f32 v25, -v7, v24, v23
	v_add_f32_dpp v4, v4, v4 quad_perm:[2,3,0,1] row_mask:0xf bank_mask:0xf bound_ctrl:1
	v_fmac_f32_e32 v24, v25, v10
	v_fma_f32 v7, -v7, v24, v23
	v_add_f32_dpp v4, v4, v4 row_half_mirror row_mask:0xf bank_mask:0xf bound_ctrl:1
	v_div_fmas_f32 v7, v7, v10, v24
	v_div_fixup_f32 v10, v7, v6, 1.0
	v_add_f32_dpp v4, v4, v4 row_mirror row_mask:0xf bank_mask:0xf bound_ctrl:1
	v_mov_b32_e32 v5, v4
	s_nop 1
	v_permlane16_swap_b32_e32 v4, v5
	v_add_f32_e32 v4, v4, v5
	v_add_f32_e32 v4, 0x2b8cbccc, v4
	v_pk_add_f32 v[6:7], v[10:11], -1.0 op_sel_hi:[1,0]
	v_cmp_gt_f32_e32 vcc, s89, v4
	v_mul_f32_e32 v5, 0x4b800000, v4
	v_pk_fma_f32 v[6:7], v[202:203], v[6:7], 1.0 op_sel_hi:[1,1,0]
	v_cndmask_b32_e32 v4, v4, v5, vcc
	v_pk_mul_f32 v[24:25], v[6:7], v[8:9]
	v_rsq_f32_e32 v4, v4
	v_pk_mul_f32 v[6:7], v[18:19], v[24:25]
	v_cvt_pk_f16_f32 v23, v24, v25
	v_fma_f32 v6, v198, v6, 0
	v_fmac_f32_e32 v6, v199, v7
	v_mul_f32_e32 v5, 0x45800000, v4
	v_cndmask_b32_e32 v4, v4, v5, vcc
	v_add_f32_dpp v6, v6, v6 quad_perm:[1,0,3,2] row_mask:0xf bank_mask:0xf bound_ctrl:1
	v_pk_mul_f32 v[2:3], v[2:3], v[4:5] op_sel_hi:[1,0]
	v_lshl_add_u64 v[4:5], s[72:73], 0, v[20:21]
	v_add_f32_dpp v6, v6, v6 quad_perm:[2,3,0,1] row_mask:0xf bank_mask:0xf bound_ctrl:1
	v_cvt_pk_f16_f32 v8, v2, v3
	v_pk_mul_f32 v[2:3], v[10:11], v[2:3]
	v_add_f32_dpp v6, v6, v6 row_half_mirror row_mask:0xf bank_mask:0xf bound_ctrl:1
	global_store_dword v[4:5], v8, off
	v_cvt_pk_f16_f32 v4, v2, v3
	v_add_f32_dpp v6, v6, v6 row_mirror row_mask:0xf bank_mask:0xf bound_ctrl:1
	v_mov_b32_e32 v7, v6
	v_lshl_add_u64 v[2:3], s[78:79], 0, v[20:21]
	s_nop 0
	v_permlane16_swap_b32_e32 v6, v7
	v_lshl_add_u64 v[18:19], s[64:65], 0, v[20:21]
	global_store_dword v[2:3], v4, off
	v_cvt_pk_f16_f32 v4, v12, v28
	v_lshl_add_u64 v[2:3], s[82:83], 0, v[20:21]
	global_store_dword v[18:19], v23, off
	global_store_dword v[2:3], v4, off
	s_and_saveexec_b64 s[6:7], s[4:5]
	s_cbranch_execz .LBB0_474
	v_add_f32_e32 v4, v6, v7
	v_mad_i64_i32 v[2:3], s[92:93], v22, 48, v[200:201]
	global_store_dword v[2:3], v4, off
; DEVI void rwkv_prep_item(const Params& p, const int l, const int item, char* smem) {
;     ...
;     for (int r = 0; r < 16; ++r) {
;       const int t = t0 + mt * 32 + (r & 3) + 8 * (r >> 2) + 4 * hi; const bool has_prev = (t & (SEQ_ - 1)) != 0;
;       float rv[2], kv[2], vv[2], av[2], kkv[2], kpv[2], omdv[2], gv[2];
;       float ssq = 0.f, bon = 0.f;
;       const u16* pr = PA + (size_t)t * 2560 + h * 64 + 2 * l31;
;       const unsigned cr2 = *(const unsigned*)pr, ck2 = *(const unsigned*)(pr + 768), cv2 = *(const unsigned*)(pr + 1536);
;       unsigned qr2 = 0u, qk2 = 0u, qv2 = 0u;
;       if (has_prev) { qr2 = *(const unsigned*)(pr - 2560); qk2 = *(const unsigned*)(pr + 768 - 2560); qv2 = *(const unsigned*)(pr + 1536 - 2560); }
; #pragma unroll
;       for (int n = 0; n < 2; ++n) {
;         const float cr = __uint_as_float(n ? (cr2 & 0xffff0000u) : (cr2 << 16)), ck = __uint_as_float(n ? (ck2 & 0xffff0000u) : (ck2 << 16)), cv = __uint_as_float(n ? (cv2 & 0xffff0000u) : (cv2 << 16));
;         const float qr = __uint_as_float(n ? (qr2 & 0xffff0000u) : (qr2 << 16)), qk = __uint_as_float(n ? (qk2 & 0xffff0000u) : (qk2 << 16)), qv = __uint_as_float(n ? (qv2 & 0xffff0000u) : (qv2 << 16));
;         rv[n] = cr + (qr - cr) * mur[n]; kv[n] = ck + (qk - ck) * muk[n]; vv[n] = cv + (qv - cv) * muv[n];
;         const float z = -(w0c[n] + aw[n][r]);
;         const float sp = fmaxf(z, 0.f) + __logf(1.f + __expf(-fabsf(z)));
;         const float ew = __expf(-sp - 0.5f);
;         omdv[n] = 1.f - __expf(-ew);
;         av[n] = sigmoidf_(a0c[n] + aa[n][r]);
;         gv[n] = ag[n][r];
;         kkv[n] = kv[n] * kkc[n];
;         kpv[n] = kv[n] * (1.f + (av[n] - 1.f) * kac[n]);
;         ssq += kkv[n] * kkv[n];
;         bon += rv[n] * kpv[n] * rkc[n];
;       }
;       ssq = reduce32(ssq); bon = reduce32(bon);
;       const float rn = rsqrtf(ssq + 1e-12f);
;       {
;         typedef _Float16 h2 __attribute__((ext_vector_type(2)));
;         const size_t o = (size_t)t * 768 + h * 64 + 2 * l31;
;         const float kn0 = kkv[0] * rn, kn1 = kkv[1] * rn;
;         *(h2*)(RW + o) = (h2){(f16)rv[0], (f16)rv[1]};
;         *(h2*)(RW + TS + o) = (h2){(f16)omdv[0], (f16)omdv[1]};
;         *(h2*)(RW + 2 * TS + o) = (h2){(f16)kpv[0], (f16)kpv[1]};
;         *(h2*)(RW + 3 * TS + o) = (h2){(f16)vv[0], (f16)vv[1]};
;         *(h2*)(RW + 4 * TS + o) = (h2){(f16)kn0, (f16)kn1};
.LBB0_474:
	s_or_b64 exec, exec, s[6:7]
	v_or_b32_e32 v12, 19, v233
	v_mad_i64_i32 v[2:3], s[6:7], v12, s34, v[212:213]
	s_waitcnt vmcnt(7)
	v_mov_b32_e32 v4, v246
	v_mov_b32_e32 v5, v247
	v_mov_b32_e32 v8, v248
	v_mov_b32_e32 v10, v249
	v_mov_b32_e32 v11, v250
	v_add_co_u32_e32 v2, vcc, 0xfffff000, v2
	s_nop 0
	v_and_b32_e32 v19, 0xffff0000, v4
	v_addc_co_u32_e32 v3, vcc, -1, v3, vcc
	v_mov_b32_e32 v9, v251
	v_or_b32_e32 v253, 24, v233
	v_mad_i64_i32 v[254:255], s[92:93], v253, s34, v[212:213]
	global_load_dword v246, v[254:255], off
	global_load_dword v247, v[254:255], off offset:1536
	global_load_dword v248, v[254:255], off offset:3072
	global_load_dword v249, v[254:255], off offset:-2048
	global_load_dword v250, v[254:255], off offset:-3584
	v_add_co_u32_e32 v254, vcc, 0xfffff000, v254
	s_nop 1
	v_addc_co_u32_e32 v255, vcc, -1, v255, vcc
	global_load_dword v251, v[254:255], off offset:-1024
	v_lshlrev_b32_e32 v18, 16, v4
	s_nop 0
	v_and_b32_e32 v7, 0xffff0000, v5
	v_lshlrev_b32_e32 v6, 16, v5
	s_nop 0
	v_and_b32_e32 v5, 0xffff0000, v10
	v_lshlrev_b32_e32 v4, 16, v10
	v_add_f32_e32 v10, v93, v210
	v_and_b32_e32 v3, 0xffff0000, v8
	v_lshlrev_b32_e32 v2, 16, v8
	s_nop 0
	v_lshlrev_b32_e32 v8, 16, v11
	v_pk_add_f32 v[4:5], v[4:5], v[2:3] neg_lo:[0,1] neg_hi:[0,1]
	s_nop 0
	v_and_b32_e32 v21, 0xffff0000, v9
	v_lshlrev_b32_e32 v20, 16, v9
	v_and_b32_e32 v9, 0xffff0000, v11
	v_max_f32_e64 v11, -v10, 0
	v_mul_f32_e64 v10, |v10|, s88
	v_exp_f32_e32 v10, v10
	v_pk_add_f32 v[8:9], v[8:9], v[6:7] neg_lo:[0,1] neg_hi:[0,1]
	v_pk_add_f32 v[20:21], v[20:21], v[18:19] neg_lo:[0,1] neg_hi:[0,1]
	v_pk_fma_f32 v[8:9], v[204:205], v[8:9], v[6:7]
	v_add_f32_e32 v10, 1.0, v10
	v_cmp_gt_f32_e32 vcc, s89, v10
	v_pk_fma_f32 v[18:19], v[206:207], v[20:21], v[18:19]
	v_pk_fma_f32 v[2:3], v[196:197], v[4:5], v[2:3]
	v_cndmask_b32_e64 v22, 0, 32, vcc
	v_ldexp_f32 v10, v10, v22
	v_log_f32_e32 v10, v10
	v_cvt_pk_f16_f32 v26, v18, v19
	v_cvt_pk_f16_f32 v4, v2, v3
	v_mul_f32_e32 v22, 0x3f317217, v10
	v_fma_f32 v22, v10, s90, -v22
	v_fmac_f32_e32 v22, 0x3377d1cf, v10
	v_fmac_f32_e32 v22, 0x3f317217, v10
	v_cmp_lt_f32_e64 s[6:7], |v10|, s91
	s_nop 1
	v_cndmask_b32_e64 v10, v10, v22, s[6:7]
	v_cndmask_b32_e32 v22, 0, v232, vcc
	v_sub_f32_e32 v10, v10, v22
	v_add_f32_e32 v10, v11, v10
	v_add_f32_e32 v11, v45, v211
	v_max_f32_e64 v22, -v11, 0
	v_mul_f32_e64 v11, |v11|, s88
	v_exp_f32_e32 v11, v11
	v_sub_f32_e32 v10, -0.5, v10
	v_mul_f32_e32 v10, 0x3fb8aa3b, v10
	v_exp_f32_e32 v10, v10
	v_add_f32_e32 v11, 1.0, v11
	v_cmp_gt_f32_e32 vcc, s89, v11
	v_mul_f32_e32 v10, 0xbfb8aa3b, v10
	s_nop 0
	v_cndmask_b32_e64 v23, 0, 32, vcc
	v_ldexp_f32 v11, v11, v23
	v_log_f32_e32 v11, v11
	v_exp_f32_e32 v10, v10
	v_mul_f32_e32 v23, 0x3f317217, v11
	v_fma_f32 v23, v11, s90, -v23
	v_fmac_f32_e32 v23, 0x3377d1cf, v11
	v_fmac_f32_e32 v23, 0x3f317217, v11
	v_cmp_lt_f32_e64 s[6:7], |v11|, s91
	v_sub_f32_e32 v24, 1.0, v10
	v_add_f32_e32 v10, v77, v208
	v_cndmask_b32_e64 v11, v11, v23, s[6:7]
	v_cndmask_b32_e32 v23, 0, v232, vcc
	v_sub_f32_e32 v11, v11, v23
	v_add_f32_e32 v11, v22, v11
	v_sub_f32_e32 v11, -0.5, v11
	v_mul_f32_e32 v11, 0x3fb8aa3b, v11
	v_exp_f32_e32 v11, v11
	v_mul_f32_e32 v10, 0xbfb8aa3b, v10
	v_exp_f32_e32 v10, v10
	v_mad_i64_i32 v[22:23], s[6:7], v12, s54, v[102:103]
	v_mul_f32_e32 v11, 0xbfb8aa3b, v11
	v_exp_f32_e32 v11, v11
	v_lshlrev_b64 v[20:21], 1, v[22:23]
	v_lshl_add_u64 v[22:23], s[56:57], 0, v[20:21]
	global_store_dword v[22:23], v26, off
	v_sub_f32_e32 v25, 1.0, v11
	v_add_f32_e32 v11, v61, v209
	v_mul_f32_e32 v11, 0xbfb8aa3b, v11
	v_exp_f32_e32 v11, v11
	v_cvt_pk_f16_f32 v24, v24, v25
	v_lshl_add_u64 v[22:23], s[62:63], 0, v[20:21]
	global_store_dword v[22:23], v24, off
	v_pk_add_f32 v[6:7], v[10:11], 1.0 op_sel_hi:[1,0]
	v_lshl_add_u64 v[2:3], s[66:67], 0, v[20:21]
	v_div_scale_f32 v10, s[6:7], v7, v7, 1.0
	v_rcp_f32_e32 v11, v10
	global_store_dword v[2:3], v4, off
	v_pk_mul_f32 v[2:3], v[194:195], v[8:9]
	v_fma_f32 v22, -v10, v11, 1.0
	v_fmac_f32_e32 v11, v22, v11
	v_div_scale_f32 v22, vcc, 1.0, v7, 1.0
	v_mul_f32_e32 v23, v22, v11
	v_fma_f32 v24, -v10, v23, v22
	v_fmac_f32_e32 v23, v24, v11
	v_fma_f32 v10, -v10, v23, v22
	v_div_fmas_f32 v10, v10, v11, v23
	v_div_fixup_f32 v11, v10, v7, 1.0
	v_div_scale_f32 v7, s[6:7], v6, v6, 1.0
	v_rcp_f32_e32 v10, v7
	v_pk_mul_f32 v[4:5], v[2:3], v[2:3]
	v_fma_f32 v22, -v7, v10, 1.0
	v_add_f32_e32 v4, v4, v5
	v_fmac_f32_e32 v10, v22, v10
	v_div_scale_f32 v22, vcc, 1.0, v6, 1.0
	v_add_f32_dpp v4, v4, v4 quad_perm:[1,0,3,2] row_mask:0xf bank_mask:0xf bound_ctrl:1
	v_mul_f32_e32 v23, v22, v10
	v_fma_f32 v24, -v7, v23, v22
	v_add_f32_dpp v4, v4, v4 quad_perm:[2,3,0,1] row_mask:0xf bank_mask:0xf bound_ctrl:1
	v_fmac_f32_e32 v23, v24, v10
	v_fma_f32 v7, -v7, v23, v22
	v_add_f32_dpp v4, v4, v4 row_half_mirror row_mask:0xf bank_mask:0xf bound_ctrl:1
	v_div_fmas_f32 v7, v7, v10, v23
	v_div_fixup_f32 v10, v7, v6, 1.0
	v_add_f32_dpp v4, v4, v4 row_mirror row_mask:0xf bank_mask:0xf bound_ctrl:1
	v_mov_b32_e32 v5, v4
	s_nop 1
	v_permlane16_swap_b32_e32 v4, v5
	v_add_f32_e32 v4, v4, v5
	v_add_f32_e32 v4, 0x2b8cbccc, v4
	v_pk_add_f32 v[6:7], v[10:11], -1.0 op_sel_hi:[1,0]
	v_cmp_gt_f32_e32 vcc, s89, v4
	v_mul_f32_e32 v5, 0x4b800000, v4
	v_pk_fma_f32 v[6:7], v[202:203], v[6:7], 1.0 op_sel_hi:[1,1,0]
	v_cndmask_b32_e32 v4, v4, v5, vcc
	v_pk_mul_f32 v[22:23], v[6:7], v[8:9]
	v_rsq_f32_e32 v4, v4
	v_pk_mul_f32 v[6:7], v[18:19], v[22:23]
	v_cvt_pk_f16_f32 v22, v22, v23
	v_fma_f32 v6, v198, v6, 0
	v_fmac_f32_e32 v6, v199, v7
	v_mul_f32_e32 v5, 0x45800000, v4
	v_cndmask_b32_e32 v4, v4, v5, vcc
	v_add_f32_dpp v6, v6, v6 quad_perm:[1,0,3,2] row_mask:0xf bank_mask:0xf bound_ctrl:1
	v_pk_mul_f32 v[2:3], v[2:3], v[4:5] op_sel_hi:[1,0]
	v_lshl_add_u64 v[4:5], s[72:73], 0, v[20:21]
	v_add_f32_dpp v6, v6, v6 quad_perm:[2,3,0,1] row_mask:0xf bank_mask:0xf bound_ctrl:1
	v_cvt_pk_f16_f32 v8, v2, v3
	v_pk_mul_f32 v[2:3], v[10:11], v[2:3]
	v_add_f32_dpp v6, v6, v6 row_half_mirror row_mask:0xf bank_mask:0xf bound_ctrl:1
	global_store_dword v[4:5], v8, off
	v_cvt_pk_f16_f32 v4, v2, v3
	v_add_f32_dpp v6, v6, v6 row_mirror row_mask:0xf bank_mask:0xf bound_ctrl:1
	v_mov_b32_e32 v7, v6
	v_lshl_add_u64 v[2:3], s[78:79], 0, v[20:21]
	s_nop 0
	v_permlane16_swap_b32_e32 v6, v7
	v_lshl_add_u64 v[18:19], s[64:65], 0, v[20:21]
	global_store_dword v[2:3], v4, off
	v_cvt_pk_f16_f32 v4, v13, v29
	v_lshl_add_u64 v[2:3], s[82:83], 0, v[20:21]
	global_store_dword v[18:19], v22, off
	global_store_dword v[2:3], v4, off
	s_and_saveexec_b64 s[6:7], s[4:5]
	s_cbranch_execz .LBB0_476
	v_add_f32_e32 v4, v6, v7
	v_mad_i64_i32 v[2:3], s[92:93], v12, 48, v[200:201]
	global_store_dword v[2:3], v4, off
; DEVI void rwkv_prep_item(const Params& p, const int l, const int item, char* smem) {
;     ...
;     for (int r = 0; r < 16; ++r) {
;       const int t = t0 + mt * 32 + (r & 3) + 8 * (r >> 2) + 4 * hi; const bool has_prev = (t & (SEQ_ - 1)) != 0;
;       float rv[2], kv[2], vv[2], av[2], kkv[2], kpv[2], omdv[2], gv[2];
;       float ssq = 0.f, bon = 0.f;
;       const u16* pr = PA + (size_t)t * 2560 + h * 64 + 2 * l31;
;       const unsigned cr2 = *(const unsigned*)pr, ck2 = *(const unsigned*)(pr + 768), cv2 = *(const unsigned*)(pr + 1536);
;       unsigned qr2 = 0u, qk2 = 0u, qv2 = 0u;
;       if (has_prev) { qr2 = *(const unsigned*)(pr - 2560); qk2 = *(const unsigned*)(pr + 768 - 2560); qv2 = *(const unsigned*)(pr + 1536 - 2560); }
; #pragma unroll
;       for (int n = 0; n < 2; ++n) {
;         const float cr = __uint_as_float(n ? (cr2 & 0xffff0000u) : (cr2 << 16)), ck = __uint_as_float(n ? (ck2 & 0xffff0000u) : (ck2 << 16)), cv = __uint_as_float(n ? (cv2 & 0xffff0000u) : (cv2 << 16));
;         const float qr = __uint_as_float(n ? (qr2 & 0xffff0000u) : (qr2 << 16)), qk = __uint_as_float(n ? (qk2 & 0xffff0000u) : (qk2 << 16)), qv = __uint_as_float(n ? (qv2 & 0xffff0000u) : (qv2 << 16));
;         rv[n] = cr + (qr - cr) * mur[n]; kv[n] = ck + (qk - ck) * muk[n]; vv[n] = cv + (qv - cv) * muv[n];
;         const float z = -(w0c[n] + aw[n][r]);
;         const float sp = fmaxf(z, 0.f) + __logf(1.f + __expf(-fabsf(z)));
;         const float ew = __expf(-sp - 0.5f);
;         omdv[n] = 1.f - __expf(-ew);
;         av[n] = sigmoidf_(a0c[n] + aa[n][r]);
;         gv[n] = ag[n][r];
;         kkv[n] = kv[n] * kkc[n];
;         kpv[n] = kv[n] * (1.f + (av[n] - 1.f) * kac[n]);
;         ssq += kkv[n] * kkv[n];
;         bon += rv[n] * kpv[n] * rkc[n];
;       }
;       ssq = reduce32(ssq); bon = reduce32(bon);
;       const float rn = rsqrtf(ssq + 1e-12f);
;       {
;         typedef _Float16 h2 __attribute__((ext_vector_type(2)));
;         const size_t o = (size_t)t * 768 + h * 64 + 2 * l31;
;         const float kn0 = kkv[0] * rn, kn1 = kkv[1] * rn;
;         *(h2*)(RW + o) = (h2){(f16)rv[0], (f16)rv[1]};
;         *(h2*)(RW + TS + o) = (h2){(f16)omdv[0], (f16)omdv[1]};
;         *(h2*)(RW + 2 * TS + o) = (h2){(f16)kpv[0], (f16)kpv[1]};
;         *(h2*)(RW + 3 * TS + o) = (h2){(f16)vv[0], (f16)vv[1]};
;         *(h2*)(RW + 4 * TS + o) = (h2){(f16)kn0, (f16)kn1};
.LBB0_476:
	s_or_b64 exec, exec, s[6:7]
	v_or_b32_e32 v20, 24, v233
	v_mad_i64_i32 v[2:3], s[6:7], v20, s34, v[212:213]
	s_waitcnt vmcnt(7)
	v_mov_b32_e32 v4, v246
	v_mov_b32_e32 v5, v247
	v_mov_b32_e32 v8, v248
	v_mov_b32_e32 v10, v249
	v_mov_b32_e32 v11, v250
	v_add_co_u32_e32 v2, vcc, 0xfffff000, v2
	s_nop 0
	v_and_b32_e32 v13, 0xffff0000, v4
	v_addc_co_u32_e32 v3, vcc, -1, v3, vcc
	v_mov_b32_e32 v9, v251
	v_or_b32_e32 v253, 25, v233
	v_mad_i64_i32 v[254:255], s[92:93], v253, s34, v[212:213]
	global_load_dword v246, v[254:255], off
	global_load_dword v247, v[254:255], off offset:1536
	global_load_dword v248, v[254:255], off offset:3072
	global_load_dword v249, v[254:255], off offset:-2048
	global_load_dword v250, v[254:255], off offset:-3584
	v_add_co_u32_e32 v254, vcc, 0xfffff000, v254
	s_nop 1
	v_addc_co_u32_e32 v255, vcc, -1, v255, vcc
	global_load_dword v251, v[254:255], off offset:-1024
	v_lshlrev_b32_e32 v12, 16, v4
	s_nop 0
	v_and_b32_e32 v7, 0xffff0000, v5
	v_lshlrev_b32_e32 v6, 16, v5
	s_nop 0
	v_and_b32_e32 v5, 0xffff0000, v10
	v_lshlrev_b32_e32 v4, 16, v10
	v_add_f32_e32 v10, v94, v210
	v_and_b32_e32 v3, 0xffff0000, v8
	v_lshlrev_b32_e32 v2, 16, v8
	s_nop 0
	v_lshlrev_b32_e32 v8, 16, v11
	v_pk_add_f32 v[4:5], v[4:5], v[2:3] neg_lo:[0,1] neg_hi:[0,1]
	s_nop 0
	v_and_b32_e32 v19, 0xffff0000, v9
	v_lshlrev_b32_e32 v18, 16, v9
	v_and_b32_e32 v9, 0xffff0000, v11
	v_max_f32_e64 v11, -v10, 0
	v_mul_f32_e64 v10, |v10|, s88
	v_exp_f32_e32 v10, v10
	v_pk_add_f32 v[8:9], v[8:9], v[6:7] neg_lo:[0,1] neg_hi:[0,1]
	v_pk_add_f32 v[18:19], v[18:19], v[12:13] neg_lo:[0,1] neg_hi:[0,1]
	v_pk_fma_f32 v[8:9], v[204:205], v[8:9], v[6:7]
	v_add_f32_e32 v10, 1.0, v10
	v_cmp_gt_f32_e32 vcc, s89, v10
	v_pk_fma_f32 v[12:13], v[206:207], v[18:19], v[12:13]
	v_pk_fma_f32 v[2:3], v[196:197], v[4:5], v[2:3]
	v_cndmask_b32_e64 v21, 0, 32, vcc
	v_ldexp_f32 v10, v10, v21
	v_log_f32_e32 v10, v10
	v_cvt_pk_f16_f32 v25, v12, v13
	v_cvt_pk_f16_f32 v4, v2, v3
	v_mul_f32_e32 v21, 0x3f317217, v10
	v_fma_f32 v21, v10, s90, -v21
	v_fmac_f32_e32 v21, 0x3377d1cf, v10
	v_fmac_f32_e32 v21, 0x3f317217, v10
	v_cmp_lt_f32_e64 s[6:7], |v10|, s91
	s_nop 1
	v_cndmask_b32_e64 v10, v10, v21, s[6:7]
	v_cndmask_b32_e32 v21, 0, v232, vcc
	v_sub_f32_e32 v10, v10, v21
	v_add_f32_e32 v10, v11, v10
	v_add_f32_e32 v11, v46, v211
	v_max_f32_e64 v22, -v11, 0
	v_mul_f32_e64 v11, |v11|, s88
	v_exp_f32_e32 v11, v11
	v_sub_f32_e32 v10, -0.5, v10
	v_mul_f32_e32 v10, 0x3fb8aa3b, v10
	v_exp_f32_e32 v10, v10
	v_add_f32_e32 v11, 1.0, v11
	v_cmp_gt_f32_e32 vcc, s89, v11
	v_mul_f32_e32 v10, 0xbfb8aa3b, v10
	s_nop 0
	v_cndmask_b32_e64 v23, 0, 32, vcc
	v_ldexp_f32 v11, v11, v23
	v_log_f32_e32 v11, v11
	v_exp_f32_e32 v10, v10
	v_mul_f32_e32 v23, 0x3f317217, v11
	v_fma_f32 v23, v11, s90, -v23
	v_fmac_f32_e32 v23, 0x3377d1cf, v11
	v_fmac_f32_e32 v23, 0x3f317217, v11
	v_cmp_lt_f32_e64 s[6:7], |v11|, s91
	v_sub_f32_e32 v21, 1.0, v10
	v_add_f32_e32 v10, v78, v208
	v_cndmask_b32_e64 v11, v11, v23, s[6:7]
	v_cndmask_b32_e32 v23, 0, v232, vcc
	v_sub_f32_e32 v11, v11, v23
	v_add_f32_e32 v11, v22, v11
	v_sub_f32_e32 v11, -0.5, v11
	v_mul_f32_e32 v11, 0x3fb8aa3b, v11
	v_exp_f32_e32 v11, v11
	v_mul_f32_e32 v10, 0xbfb8aa3b, v10
	v_exp_f32_e32 v10, v10
	v_mad_i64_i32 v[22:23], s[6:7], v20, s54, v[102:103]
	v_mul_f32_e32 v11, 0xbfb8aa3b, v11
	v_exp_f32_e32 v11, v11
	v_lshlrev_b64 v[18:19], 1, v[22:23]
	v_lshl_add_u64 v[22:23], s[56:57], 0, v[18:19]
	global_store_dword v[22:23], v25, off
	v_sub_f32_e32 v24, 1.0, v11
	v_add_f32_e32 v11, v62, v209
	v_mul_f32_e32 v11, 0xbfb8aa3b, v11
	v_exp_f32_e32 v11, v11
	v_cvt_pk_f16_f32 v21, v21, v24
	v_lshl_add_u64 v[22:23], s[62:63], 0, v[18:19]
	global_store_dword v[22:23], v21, off
	v_pk_add_f32 v[6:7], v[10:11], 1.0 op_sel_hi:[1,0]
	v_lshl_add_u64 v[2:3], s[66:67], 0, v[18:19]
	v_div_scale_f32 v10, s[6:7], v7, v7, 1.0
	v_rcp_f32_e32 v11, v10
	global_store_dword v[2:3], v4, off
	v_pk_mul_f32 v[2:3], v[194:195], v[8:9]
	v_fma_f32 v21, -v10, v11, 1.0
	v_fmac_f32_e32 v11, v21, v11
	v_div_scale_f32 v21, vcc, 1.0, v7, 1.0
	v_mul_f32_e32 v22, v21, v11
	v_fma_f32 v23, -v10, v22, v21
	v_fmac_f32_e32 v22, v23, v11
	v_fma_f32 v10, -v10, v22, v21
	v_div_fmas_f32 v10, v10, v11, v22
	v_div_fixup_f32 v11, v10, v7, 1.0
	v_div_scale_f32 v7, s[6:7], v6, v6, 1.0
	v_rcp_f32_e32 v10, v7
	v_pk_mul_f32 v[4:5], v[2:3], v[2:3]
	v_fma_f32 v21, -v7, v10, 1.0
	v_add_f32_e32 v4, v4, v5
	v_fmac_f32_e32 v10, v21, v10
	v_div_scale_f32 v21, vcc, 1.0, v6, 1.0
	v_add_f32_dpp v4, v4, v4 quad_perm:[1,0,3,2] row_mask:0xf bank_mask:0xf bound_ctrl:1
	v_mul_f32_e32 v22, v21, v10
	v_fma_f32 v23, -v7, v22, v21
	v_add_f32_dpp v4, v4, v4 quad_perm:[2,3,0,1] row_mask:0xf bank_mask:0xf bound_ctrl:1
	v_fmac_f32_e32 v22, v23, v10
	v_fma_f32 v7, -v7, v22, v21
	v_add_f32_dpp v4, v4, v4 row_half_mirror row_mask:0xf bank_mask:0xf bound_ctrl:1
	v_div_fmas_f32 v7, v7, v10, v22
	v_div_fixup_f32 v10, v7, v6, 1.0
	v_add_f32_dpp v4, v4, v4 row_mirror row_mask:0xf bank_mask:0xf bound_ctrl:1
	v_mov_b32_e32 v5, v4
	s_nop 1
	v_permlane16_swap_b32_e32 v4, v5
	v_add_f32_e32 v4, v4, v5
	v_add_f32_e32 v4, 0x2b8cbccc, v4
	v_pk_add_f32 v[6:7], v[10:11], -1.0 op_sel_hi:[1,0]
	v_cmp_gt_f32_e32 vcc, s89, v4
	v_mul_f32_e32 v5, 0x4b800000, v4
	v_pk_fma_f32 v[6:7], v[202:203], v[6:7], 1.0 op_sel_hi:[1,1,0]
	v_cndmask_b32_e32 v4, v4, v5, vcc
	v_pk_mul_f32 v[22:23], v[6:7], v[8:9]
	v_rsq_f32_e32 v4, v4
	v_pk_mul_f32 v[6:7], v[12:13], v[22:23]
	v_cvt_pk_f16_f32 v21, v22, v23
	v_fma_f32 v6, v198, v6, 0
	v_fmac_f32_e32 v6, v199, v7
	v_mul_f32_e32 v5, 0x45800000, v4
	v_cndmask_b32_e32 v4, v4, v5, vcc
	v_add_f32_dpp v6, v6, v6 quad_perm:[1,0,3,2] row_mask:0xf bank_mask:0xf bound_ctrl:1
	v_pk_mul_f32 v[2:3], v[2:3], v[4:5] op_sel_hi:[1,0]
	v_lshl_add_u64 v[4:5], s[72:73], 0, v[18:19]
	v_add_f32_dpp v6, v6, v6 quad_perm:[2,3,0,1] row_mask:0xf bank_mask:0xf bound_ctrl:1
	v_cvt_pk_f16_f32 v8, v2, v3
	v_pk_mul_f32 v[2:3], v[10:11], v[2:3]
	v_add_f32_dpp v6, v6, v6 row_half_mirror row_mask:0xf bank_mask:0xf bound_ctrl:1
	global_store_dword v[4:5], v8, off
	v_cvt_pk_f16_f32 v4, v2, v3
	v_add_f32_dpp v6, v6, v6 row_mirror row_mask:0xf bank_mask:0xf bound_ctrl:1
	v_mov_b32_e32 v7, v6
	v_lshl_add_u64 v[2:3], s[78:79], 0, v[18:19]
	s_nop 0
	v_permlane16_swap_b32_e32 v6, v7
	v_lshl_add_u64 v[12:13], s[64:65], 0, v[18:19]
	global_store_dword v[2:3], v4, off
	v_cvt_pk_f16_f32 v4, v14, v30
	v_lshl_add_u64 v[2:3], s[82:83], 0, v[18:19]
	global_store_dword v[12:13], v21, off
	global_store_dword v[2:3], v4, off
	s_and_saveexec_b64 s[6:7], s[4:5]
	s_cbranch_execz .LBB0_478
	v_add_f32_e32 v4, v6, v7
	v_mad_i64_i32 v[2:3], s[92:93], v20, 48, v[200:201]
	global_store_dword v[2:3], v4, off
; DEVI void rwkv_prep_item(const Params& p, const int l, const int item, char* smem) {
;     ...
;     for (int r = 0; r < 16; ++r) {
;       const int t = t0 + mt * 32 + (r & 3) + 8 * (r >> 2) + 4 * hi; const bool has_prev = (t & (SEQ_ - 1)) != 0;
;       float rv[2], kv[2], vv[2], av[2], kkv[2], kpv[2], omdv[2], gv[2];
;       float ssq = 0.f, bon = 0.f;
;       const u16* pr = PA + (size_t)t * 2560 + h * 64 + 2 * l31;
;       const unsigned cr2 = *(const unsigned*)pr, ck2 = *(const unsigned*)(pr + 768), cv2 = *(const unsigned*)(pr + 1536);
;       unsigned qr2 = 0u, qk2 = 0u, qv2 = 0u;
;       if (has_prev) { qr2 = *(const unsigned*)(pr - 2560); qk2 = *(const unsigned*)(pr + 768 - 2560); qv2 = *(const unsigned*)(pr + 1536 - 2560); }
; #pragma unroll
;       for (int n = 0; n < 2; ++n) {
;         const float cr = __uint_as_float(n ? (cr2 & 0xffff0000u) : (cr2 << 16)), ck = __uint_as_float(n ? (ck2 & 0xffff0000u) : (ck2 << 16)), cv = __uint_as_float(n ? (cv2 & 0xffff0000u) : (cv2 << 16));
;         const float qr = __uint_as_float(n ? (qr2 & 0xffff0000u) : (qr2 << 16)), qk = __uint_as_float(n ? (qk2 & 0xffff0000u) : (qk2 << 16)), qv = __uint_as_float(n ? (qv2 & 0xffff0000u) : (qv2 << 16));
;         rv[n] = cr + (qr - cr) * mur[n]; kv[n] = ck + (qk - ck) * muk[n]; vv[n] = cv + (qv - cv) * muv[n];
;         const float z = -(w0c[n] + aw[n][r]);
;         const float sp = fmaxf(z, 0.f) + __logf(1.f + __expf(-fabsf(z)));
;         const float ew = __expf(-sp - 0.5f);
;         omdv[n] = 1.f - __expf(-ew);
;         av[n] = sigmoidf_(a0c[n] + aa[n][r]);
;         gv[n] = ag[n][r];
;         kkv[n] = kv[n] * kkc[n];
;         kpv[n] = kv[n] * (1.f + (av[n] - 1.f) * kac[n]);
;         ssq += kkv[n] * kkv[n];
;         bon += rv[n] * kpv[n] * rkc[n];
;       }
;       ssq = reduce32(ssq); bon = reduce32(bon);
;       const float rn = rsqrtf(ssq + 1e-12f);
;       {
;         typedef _Float16 h2 __attribute__((ext_vector_type(2)));
;         const size_t o = (size_t)t * 768 + h * 64 + 2 * l31;
;         const float kn0 = kkv[0] * rn, kn1 = kkv[1] * rn;
;         *(h2*)(RW + o) = (h2){(f16)rv[0], (f16)rv[1]};
;         *(h2*)(RW + TS + o) = (h2){(f16)omdv[0], (f16)omdv[1]};
;         *(h2*)(RW + 2 * TS + o) = (h2){(f16)kpv[0], (f16)kpv[1]};
;         *(h2*)(RW + 3 * TS + o) = (h2){(f16)vv[0], (f16)vv[1]};
;         *(h2*)(RW + 4 * TS + o) = (h2){(f16)kn0, (f16)kn1};
.LBB0_478:
	s_or_b64 exec, exec, s[6:7]
	v_or_b32_e32 v14, 25, v233
	v_mad_i64_i32 v[2:3], s[6:7], v14, s34, v[212:213]
	s_waitcnt vmcnt(7)
	v_mov_b32_e32 v4, v246
	v_mov_b32_e32 v5, v247
	v_mov_b32_e32 v8, v248
	v_mov_b32_e32 v10, v249
	v_mov_b32_e32 v11, v250
	v_add_co_u32_e32 v2, vcc, 0xfffff000, v2
	s_nop 0
	v_and_b32_e32 v13, 0xffff0000, v4
	v_addc_co_u32_e32 v3, vcc, -1, v3, vcc
	v_mov_b32_e32 v9, v251
	v_or_b32_e32 v253, 26, v233
	v_mad_i64_i32 v[254:255], s[92:93], v253, s34, v[212:213]
	global_load_dword v246, v[254:255], off
	global_load_dword v247, v[254:255], off offset:1536
	global_load_dword v248, v[254:255], off offset:3072
	global_load_dword v249, v[254:255], off offset:-2048
	global_load_dword v250, v[254:255], off offset:-3584
	v_add_co_u32_e32 v254, vcc, 0xfffff000, v254
	s_nop 1
	v_addc_co_u32_e32 v255, vcc, -1, v255, vcc
	global_load_dword v251, v[254:255], off offset:-1024
	v_lshlrev_b32_e32 v12, 16, v4
	s_nop 0
	v_and_b32_e32 v7, 0xffff0000, v5
	v_lshlrev_b32_e32 v6, 16, v5
	s_nop 0
	v_and_b32_e32 v5, 0xffff0000, v10
	v_lshlrev_b32_e32 v4, 16, v10
	v_add_f32_e32 v10, v95, v210
	v_and_b32_e32 v3, 0xffff0000, v8
	v_lshlrev_b32_e32 v2, 16, v8
	s_nop 0
	v_lshlrev_b32_e32 v8, 16, v11
	v_pk_add_f32 v[4:5], v[4:5], v[2:3] neg_lo:[0,1] neg_hi:[0,1]
	s_nop 0
	v_and_b32_e32 v19, 0xffff0000, v9
	v_lshlrev_b32_e32 v18, 16, v9
	v_and_b32_e32 v9, 0xffff0000, v11
	v_max_f32_e64 v11, -v10, 0
	v_mul_f32_e64 v10, |v10|, s88
	v_exp_f32_e32 v10, v10
	v_pk_add_f32 v[8:9], v[8:9], v[6:7] neg_lo:[0,1] neg_hi:[0,1]
	v_pk_add_f32 v[18:19], v[18:19], v[12:13] neg_lo:[0,1] neg_hi:[0,1]
	v_pk_fma_f32 v[8:9], v[204:205], v[8:9], v[6:7]
	v_add_f32_e32 v10, 1.0, v10
	v_cmp_gt_f32_e32 vcc, s89, v10
	v_pk_fma_f32 v[12:13], v[206:207], v[18:19], v[12:13]
	v_pk_fma_f32 v[2:3], v[196:197], v[4:5], v[2:3]
	v_cndmask_b32_e64 v20, 0, 32, vcc
	v_ldexp_f32 v10, v10, v20
	v_log_f32_e32 v10, v10
	v_cvt_pk_f16_f32 v24, v12, v13
	v_cvt_pk_f16_f32 v4, v2, v3
	v_mul_f32_e32 v20, 0x3f317217, v10
	v_fma_f32 v20, v10, s90, -v20
	v_fmac_f32_e32 v20, 0x3377d1cf, v10
	v_fmac_f32_e32 v20, 0x3f317217, v10
	v_cmp_lt_f32_e64 s[6:7], |v10|, s91
	s_nop 1
	v_cndmask_b32_e64 v10, v10, v20, s[6:7]
	v_cndmask_b32_e32 v20, 0, v232, vcc
	v_sub_f32_e32 v10, v10, v20
	v_add_f32_e32 v10, v11, v10
	v_add_f32_e32 v11, v47, v211
	v_max_f32_e64 v20, -v11, 0
	v_mul_f32_e64 v11, |v11|, s88
	v_exp_f32_e32 v11, v11
	v_sub_f32_e32 v10, -0.5, v10
	v_mul_f32_e32 v10, 0x3fb8aa3b, v10
	v_exp_f32_e32 v10, v10
	v_add_f32_e32 v11, 1.0, v11
	v_cmp_gt_f32_e32 vcc, s89, v11
	v_mul_f32_e32 v10, 0xbfb8aa3b, v10
	s_nop 0
	v_cndmask_b32_e64 v21, 0, 32, vcc
	v_ldexp_f32 v11, v11, v21
	v_log_f32_e32 v11, v11
	v_exp_f32_e32 v10, v10
	v_mul_f32_e32 v21, 0x3f317217, v11
	v_fma_f32 v21, v11, s90, -v21
	v_fmac_f32_e32 v21, 0x3377d1cf, v11
	v_fmac_f32_e32 v21, 0x3f317217, v11
	v_cmp_lt_f32_e64 s[6:7], |v11|, s91
	v_sub_f32_e32 v22, 1.0, v10
	v_add_f32_e32 v10, v79, v208
	v_cndmask_b32_e64 v11, v11, v21, s[6:7]
	v_cndmask_b32_e32 v21, 0, v232, vcc
	v_sub_f32_e32 v11, v11, v21
	v_add_f32_e32 v11, v20, v11
	v_sub_f32_e32 v11, -0.5, v11
	v_mul_f32_e32 v11, 0x3fb8aa3b, v11
	v_exp_f32_e32 v11, v11
	v_mul_f32_e32 v10, 0xbfb8aa3b, v10
	v_exp_f32_e32 v10, v10
	v_mad_i64_i32 v[20:21], s[6:7], v14, s54, v[102:103]
	v_mul_f32_e32 v11, 0xbfb8aa3b, v11
	v_exp_f32_e32 v11, v11
	v_lshlrev_b64 v[18:19], 1, v[20:21]
	v_lshl_add_u64 v[20:21], s[56:57], 0, v[18:19]
	global_store_dword v[20:21], v24, off
	v_sub_f32_e32 v23, 1.0, v11
	v_add_f32_e32 v11, v63, v209
	v_mul_f32_e32 v11, 0xbfb8aa3b, v11
	v_exp_f32_e32 v11, v11
	v_cvt_pk_f16_f32 v22, v22, v23
	v_lshl_add_u64 v[20:21], s[62:63], 0, v[18:19]
	global_store_dword v[20:21], v22, off
	v_pk_add_f32 v[6:7], v[10:11], 1.0 op_sel_hi:[1,0]
	v_lshl_add_u64 v[2:3], s[66:67], 0, v[18:19]
	v_div_scale_f32 v10, s[6:7], v7, v7, 1.0
	v_rcp_f32_e32 v11, v10
	global_store_dword v[2:3], v4, off
	v_pk_mul_f32 v[2:3], v[194:195], v[8:9]
	v_fma_f32 v20, -v10, v11, 1.0
	v_fmac_f32_e32 v11, v20, v11
	v_div_scale_f32 v20, vcc, 1.0, v7, 1.0
	v_mul_f32_e32 v21, v20, v11
	v_fma_f32 v22, -v10, v21, v20
	v_fmac_f32_e32 v21, v22, v11
	v_fma_f32 v10, -v10, v21, v20
	v_div_fmas_f32 v10, v10, v11, v21
	v_div_fixup_f32 v11, v10, v7, 1.0
	v_div_scale_f32 v7, s[6:7], v6, v6, 1.0
	v_rcp_f32_e32 v10, v7
	v_pk_mul_f32 v[4:5], v[2:3], v[2:3]
	v_fma_f32 v20, -v7, v10, 1.0
	v_add_f32_e32 v4, v4, v5
	v_fmac_f32_e32 v10, v20, v10
	v_div_scale_f32 v20, vcc, 1.0, v6, 1.0
	v_add_f32_dpp v4, v4, v4 quad_perm:[1,0,3,2] row_mask:0xf bank_mask:0xf bound_ctrl:1
	v_mul_f32_e32 v21, v20, v10
	v_fma_f32 v22, -v7, v21, v20
	v_add_f32_dpp v4, v4, v4 quad_perm:[2,3,0,1] row_mask:0xf bank_mask:0xf bound_ctrl:1
	v_fmac_f32_e32 v21, v22, v10
	v_fma_f32 v7, -v7, v21, v20
	v_add_f32_dpp v4, v4, v4 row_half_mirror row_mask:0xf bank_mask:0xf bound_ctrl:1
	v_div_fmas_f32 v7, v7, v10, v21
	v_div_fixup_f32 v10, v7, v6, 1.0
	v_add_f32_dpp v4, v4, v4 row_mirror row_mask:0xf bank_mask:0xf bound_ctrl:1
	v_mov_b32_e32 v5, v4
	s_nop 1
	v_permlane16_swap_b32_e32 v4, v5
	v_add_f32_e32 v4, v4, v5
	v_add_f32_e32 v4, 0x2b8cbccc, v4
	v_pk_add_f32 v[6:7], v[10:11], -1.0 op_sel_hi:[1,0]
	v_cmp_gt_f32_e32 vcc, s89, v4
	v_mul_f32_e32 v5, 0x4b800000, v4
	v_pk_fma_f32 v[6:7], v[202:203], v[6:7], 1.0 op_sel_hi:[1,1,0]
	v_cndmask_b32_e32 v4, v4, v5, vcc
	v_pk_mul_f32 v[20:21], v[6:7], v[8:9]
	v_rsq_f32_e32 v4, v4
	v_pk_mul_f32 v[6:7], v[12:13], v[20:21]
	v_cvt_pk_f16_f32 v20, v20, v21
	v_fma_f32 v6, v198, v6, 0
	v_fmac_f32_e32 v6, v199, v7
	v_mul_f32_e32 v5, 0x45800000, v4
	v_cndmask_b32_e32 v4, v4, v5, vcc
	v_add_f32_dpp v6, v6, v6 quad_perm:[1,0,3,2] row_mask:0xf bank_mask:0xf bound_ctrl:1
	v_pk_mul_f32 v[2:3], v[2:3], v[4:5] op_sel_hi:[1,0]
	v_lshl_add_u64 v[4:5], s[72:73], 0, v[18:19]
	v_add_f32_dpp v6, v6, v6 quad_perm:[2,3,0,1] row_mask:0xf bank_mask:0xf bound_ctrl:1
	v_cvt_pk_f16_f32 v8, v2, v3
	v_pk_mul_f32 v[2:3], v[10:11], v[2:3]
	v_add_f32_dpp v6, v6, v6 row_half_mirror row_mask:0xf bank_mask:0xf bound_ctrl:1
	global_store_dword v[4:5], v8, off
	v_cvt_pk_f16_f32 v4, v2, v3
	v_add_f32_dpp v6, v6, v6 row_mirror row_mask:0xf bank_mask:0xf bound_ctrl:1
	v_mov_b32_e32 v7, v6
	v_lshl_add_u64 v[2:3], s[78:79], 0, v[18:19]
	s_nop 0
	v_permlane16_swap_b32_e32 v6, v7
	v_lshl_add_u64 v[12:13], s[64:65], 0, v[18:19]
	global_store_dword v[2:3], v4, off
	v_cvt_pk_f16_f32 v4, v15, v31
	v_lshl_add_u64 v[2:3], s[82:83], 0, v[18:19]
	global_store_dword v[12:13], v20, off
	global_store_dword v[2:3], v4, off
	s_and_saveexec_b64 s[6:7], s[4:5]
	s_cbranch_execz .LBB0_480
	v_add_f32_e32 v4, v6, v7
	v_mad_i64_i32 v[2:3], s[92:93], v14, 48, v[200:201]
	global_store_dword v[2:3], v4, off
; DEVI void rwkv_prep_item(const Params& p, const int l, const int item, char* smem) {
;     ...
;     for (int r = 0; r < 16; ++r) {
;       const int t = t0 + mt * 32 + (r & 3) + 8 * (r >> 2) + 4 * hi; const bool has_prev = (t & (SEQ_ - 1)) != 0;
;       float rv[2], kv[2], vv[2], av[2], kkv[2], kpv[2], omdv[2], gv[2];
;       float ssq = 0.f, bon = 0.f;
;       const u16* pr = PA + (size_t)t * 2560 + h * 64 + 2 * l31;
;       const unsigned cr2 = *(const unsigned*)pr, ck2 = *(const unsigned*)(pr + 768), cv2 = *(const unsigned*)(pr + 1536);
;       unsigned qr2 = 0u, qk2 = 0u, qv2 = 0u;
;       if (has_prev) { qr2 = *(const unsigned*)(pr - 2560); qk2 = *(const unsigned*)(pr + 768 - 2560); qv2 = *(const unsigned*)(pr + 1536 - 2560); }
; #pragma unroll
;       for (int n = 0; n < 2; ++n) {
;         const float cr = __uint_as_float(n ? (cr2 & 0xffff0000u) : (cr2 << 16)), ck = __uint_as_float(n ? (ck2 & 0xffff0000u) : (ck2 << 16)), cv = __uint_as_float(n ? (cv2 & 0xffff0000u) : (cv2 << 16));
;         const float qr = __uint_as_float(n ? (qr2 & 0xffff0000u) : (qr2 << 16)), qk = __uint_as_float(n ? (qk2 & 0xffff0000u) : (qk2 << 16)), qv = __uint_as_float(n ? (qv2 & 0xffff0000u) : (qv2 << 16));
;         rv[n] = cr + (qr - cr) * mur[n]; kv[n] = ck + (qk - ck) * muk[n]; vv[n] = cv + (qv - cv) * muv[n];
;         const float z = -(w0c[n] + aw[n][r]);
;         const float sp = fmaxf(z, 0.f) + __logf(1.f + __expf(-fabsf(z)));
;         const float ew = __expf(-sp - 0.5f);
;         omdv[n] = 1.f - __expf(-ew);
;         av[n] = sigmoidf_(a0c[n] + aa[n][r]);
;         gv[n] = ag[n][r];
;         kkv[n] = kv[n] * kkc[n];
;         kpv[n] = kv[n] * (1.f + (av[n] - 1.f) * kac[n]);
;         ssq += kkv[n] * kkv[n];
;         bon += rv[n] * kpv[n] * rkc[n];
;       }
;       ssq = reduce32(ssq); bon = reduce32(bon);
;       const float rn = rsqrtf(ssq + 1e-12f);
;       {
;         typedef _Float16 h2 __attribute__((ext_vector_type(2)));
;         const size_t o = (size_t)t * 768 + h * 64 + 2 * l31;
;         const float kn0 = kkv[0] * rn, kn1 = kkv[1] * rn;
;         *(h2*)(RW + o) = (h2){(f16)rv[0], (f16)rv[1]};
;         *(h2*)(RW + TS + o) = (h2){(f16)omdv[0], (f16)omdv[1]};
;         *(h2*)(RW + 2 * TS + o) = (h2){(f16)kpv[0], (f16)kpv[1]};
;         *(h2*)(RW + 3 * TS + o) = (h2){(f16)vv[0], (f16)vv[1]};
;         *(h2*)(RW + 4 * TS + o) = (h2){(f16)kn0, (f16)kn1};
.LBB0_480:
	s_or_b64 exec, exec, s[6:7]
	v_or_b32_e32 v18, 26, v233
	v_mad_i64_i32 v[2:3], s[6:7], v18, s34, v[212:213]
	s_waitcnt vmcnt(7)
	v_mov_b32_e32 v4, v246
	v_mov_b32_e32 v5, v247
	v_mov_b32_e32 v8, v248
	v_mov_b32_e32 v10, v249
	v_mov_b32_e32 v11, v250
	v_add_co_u32_e32 v2, vcc, 0xfffff000, v2
	s_nop 0
	v_and_b32_e32 v13, 0xffff0000, v4
	v_addc_co_u32_e32 v3, vcc, -1, v3, vcc
	v_mov_b32_e32 v9, v251
	v_or_b32_e32 v253, 27, v233
	v_mad_i64_i32 v[254:255], s[92:93], v253, s34, v[212:213]
	global_load_dword v246, v[254:255], off
	global_load_dword v247, v[254:255], off offset:1536
	global_load_dword v248, v[254:255], off offset:3072
	global_load_dword v249, v[254:255], off offset:-2048
	global_load_dword v250, v[254:255], off offset:-3584
	v_add_co_u32_e32 v254, vcc, 0xfffff000, v254
	s_nop 1
	v_addc_co_u32_e32 v255, vcc, -1, v255, vcc
	global_load_dword v251, v[254:255], off offset:-1024
	v_lshlrev_b32_e32 v12, 16, v4
	s_nop 0
	v_and_b32_e32 v7, 0xffff0000, v5
	v_lshlrev_b32_e32 v6, 16, v5
	s_nop 0
	v_and_b32_e32 v5, 0xffff0000, v10
	v_lshlrev_b32_e32 v4, 16, v10
	v_add_f32_e32 v10, v96, v210
	v_and_b32_e32 v3, 0xffff0000, v8
	v_lshlrev_b32_e32 v2, 16, v8
	s_nop 0
	v_lshlrev_b32_e32 v8, 16, v11
	v_pk_add_f32 v[4:5], v[4:5], v[2:3] neg_lo:[0,1] neg_hi:[0,1]
	s_nop 0
	v_and_b32_e32 v15, 0xffff0000, v9
	v_lshlrev_b32_e32 v14, 16, v9
	v_and_b32_e32 v9, 0xffff0000, v11
	v_max_f32_e64 v11, -v10, 0
	v_mul_f32_e64 v10, |v10|, s88
	v_exp_f32_e32 v10, v10
	v_pk_add_f32 v[8:9], v[8:9], v[6:7] neg_lo:[0,1] neg_hi:[0,1]
	v_pk_add_f32 v[14:15], v[14:15], v[12:13] neg_lo:[0,1] neg_hi:[0,1]
	v_pk_fma_f32 v[8:9], v[204:205], v[8:9], v[6:7]
	v_add_f32_e32 v10, 1.0, v10
	v_cmp_gt_f32_e32 vcc, s89, v10
	v_pk_fma_f32 v[12:13], v[206:207], v[14:15], v[12:13]
	v_pk_fma_f32 v[2:3], v[196:197], v[4:5], v[2:3]
	v_cndmask_b32_e64 v19, 0, 32, vcc
	v_ldexp_f32 v10, v10, v19
	v_log_f32_e32 v10, v10
	v_cvt_pk_f16_f32 v23, v12, v13
	v_cvt_pk_f16_f32 v4, v2, v3
	v_mul_f32_e32 v19, 0x3f317217, v10
	v_fma_f32 v19, v10, s90, -v19
	v_fmac_f32_e32 v19, 0x3377d1cf, v10
	v_fmac_f32_e32 v19, 0x3f317217, v10
	v_cmp_lt_f32_e64 s[6:7], |v10|, s91
	s_nop 1
	v_cndmask_b32_e64 v10, v10, v19, s[6:7]
	v_cndmask_b32_e32 v19, 0, v232, vcc
	v_sub_f32_e32 v10, v10, v19
	v_add_f32_e32 v10, v11, v10
	v_add_f32_e32 v11, v48, v211
	v_max_f32_e64 v20, -v11, 0
	v_mul_f32_e64 v11, |v11|, s88
	v_exp_f32_e32 v11, v11
	v_sub_f32_e32 v10, -0.5, v10
	v_mul_f32_e32 v10, 0x3fb8aa3b, v10
	v_exp_f32_e32 v10, v10
	v_add_f32_e32 v11, 1.0, v11
	v_cmp_gt_f32_e32 vcc, s89, v11
	v_mul_f32_e32 v10, 0xbfb8aa3b, v10
	s_nop 0
	v_cndmask_b32_e64 v21, 0, 32, vcc
	v_ldexp_f32 v11, v11, v21
	v_log_f32_e32 v11, v11
	v_exp_f32_e32 v10, v10
	v_mul_f32_e32 v21, 0x3f317217, v11
	v_fma_f32 v21, v11, s90, -v21
	v_fmac_f32_e32 v21, 0x3377d1cf, v11
	v_fmac_f32_e32 v21, 0x3f317217, v11
	v_cmp_lt_f32_e64 s[6:7], |v11|, s91
	v_sub_f32_e32 v19, 1.0, v10
	v_add_f32_e32 v10, v80, v208
	v_cndmask_b32_e64 v11, v11, v21, s[6:7]
	v_cndmask_b32_e32 v21, 0, v232, vcc
	v_sub_f32_e32 v11, v11, v21
	v_add_f32_e32 v11, v20, v11
	v_sub_f32_e32 v11, -0.5, v11
	v_mul_f32_e32 v11, 0x3fb8aa3b, v11
	v_exp_f32_e32 v11, v11
	v_mul_f32_e32 v10, 0xbfb8aa3b, v10
	v_exp_f32_e32 v10, v10
	v_mad_i64_i32 v[20:21], s[6:7], v18, s54, v[102:103]
	v_mul_f32_e32 v11, 0xbfb8aa3b, v11
	v_exp_f32_e32 v11, v11
	v_lshlrev_b64 v[14:15], 1, v[20:21]
	v_lshl_add_u64 v[20:21], s[56:57], 0, v[14:15]
	global_store_dword v[20:21], v23, off
	v_sub_f32_e32 v22, 1.0, v11
	v_add_f32_e32 v11, v64, v209
	v_mul_f32_e32 v11, 0xbfb8aa3b, v11
	v_exp_f32_e32 v11, v11
	v_cvt_pk_f16_f32 v19, v19, v22
	v_lshl_add_u64 v[20:21], s[62:63], 0, v[14:15]
	global_store_dword v[20:21], v19, off
	v_pk_add_f32 v[6:7], v[10:11], 1.0 op_sel_hi:[1,0]
	v_lshl_add_u64 v[2:3], s[66:67], 0, v[14:15]
	v_div_scale_f32 v10, s[6:7], v7, v7, 1.0
	v_rcp_f32_e32 v11, v10
	global_store_dword v[2:3], v4, off
	v_pk_mul_f32 v[2:3], v[194:195], v[8:9]
	v_fma_f32 v19, -v10, v11, 1.0
	v_fmac_f32_e32 v11, v19, v11
	v_div_scale_f32 v19, vcc, 1.0, v7, 1.0
	v_mul_f32_e32 v20, v19, v11
	v_fma_f32 v21, -v10, v20, v19
	v_fmac_f32_e32 v20, v21, v11
	v_fma_f32 v10, -v10, v20, v19
	v_div_fmas_f32 v10, v10, v11, v20
	v_div_fixup_f32 v11, v10, v7, 1.0
	v_div_scale_f32 v7, s[6:7], v6, v6, 1.0
	v_rcp_f32_e32 v10, v7
	v_pk_mul_f32 v[4:5], v[2:3], v[2:3]
	v_fma_f32 v19, -v7, v10, 1.0
	v_add_f32_e32 v4, v4, v5
	v_fmac_f32_e32 v10, v19, v10
	v_div_scale_f32 v19, vcc, 1.0, v6, 1.0
	v_add_f32_dpp v4, v4, v4 quad_perm:[1,0,3,2] row_mask:0xf bank_mask:0xf bound_ctrl:1
	v_mul_f32_e32 v20, v19, v10
	v_fma_f32 v21, -v7, v20, v19
	v_add_f32_dpp v4, v4, v4 quad_perm:[2,3,0,1] row_mask:0xf bank_mask:0xf bound_ctrl:1
	v_fmac_f32_e32 v20, v21, v10
	v_fma_f32 v7, -v7, v20, v19
	v_add_f32_dpp v4, v4, v4 row_half_mirror row_mask:0xf bank_mask:0xf bound_ctrl:1
	v_div_fmas_f32 v7, v7, v10, v20
	v_div_fixup_f32 v10, v7, v6, 1.0
	v_add_f32_dpp v4, v4, v4 row_mirror row_mask:0xf bank_mask:0xf bound_ctrl:1
	v_mov_b32_e32 v5, v4
	s_nop 1
	v_permlane16_swap_b32_e32 v4, v5
	v_add_f32_e32 v4, v4, v5
	v_add_f32_e32 v4, 0x2b8cbccc, v4
	v_pk_add_f32 v[6:7], v[10:11], -1.0 op_sel_hi:[1,0]
	v_cmp_gt_f32_e32 vcc, s89, v4
	v_mul_f32_e32 v5, 0x4b800000, v4
	v_pk_fma_f32 v[6:7], v[202:203], v[6:7], 1.0 op_sel_hi:[1,1,0]
	v_cndmask_b32_e32 v4, v4, v5, vcc
	v_pk_mul_f32 v[20:21], v[6:7], v[8:9]
	v_rsq_f32_e32 v4, v4
	v_pk_mul_f32 v[6:7], v[12:13], v[20:21]
	v_cvt_pk_f16_f32 v19, v20, v21
	v_fma_f32 v6, v198, v6, 0
	v_fmac_f32_e32 v6, v199, v7
	v_mul_f32_e32 v5, 0x45800000, v4
	v_cndmask_b32_e32 v4, v4, v5, vcc
	v_add_f32_dpp v6, v6, v6 quad_perm:[1,0,3,2] row_mask:0xf bank_mask:0xf bound_ctrl:1
	v_pk_mul_f32 v[2:3], v[2:3], v[4:5] op_sel_hi:[1,0]
	v_lshl_add_u64 v[4:5], s[72:73], 0, v[14:15]
	v_add_f32_dpp v6, v6, v6 quad_perm:[2,3,0,1] row_mask:0xf bank_mask:0xf bound_ctrl:1
	v_cvt_pk_f16_f32 v8, v2, v3
	v_pk_mul_f32 v[2:3], v[10:11], v[2:3]
	v_add_f32_dpp v6, v6, v6 row_half_mirror row_mask:0xf bank_mask:0xf bound_ctrl:1
	global_store_dword v[4:5], v8, off
	v_cvt_pk_f16_f32 v4, v2, v3
	v_add_f32_dpp v6, v6, v6 row_mirror row_mask:0xf bank_mask:0xf bound_ctrl:1
	v_mov_b32_e32 v7, v6
	v_lshl_add_u64 v[2:3], s[78:79], 0, v[14:15]
	s_nop 0
	v_permlane16_swap_b32_e32 v6, v7
	v_lshl_add_u64 v[12:13], s[64:65], 0, v[14:15]
	global_store_dword v[2:3], v4, off
	v_cvt_pk_f16_f32 v4, v16, v32
	v_lshl_add_u64 v[2:3], s[82:83], 0, v[14:15]
	global_store_dword v[12:13], v19, off
	global_store_dword v[2:3], v4, off
	s_and_saveexec_b64 s[6:7], s[4:5]
	s_cbranch_execz .LBB0_482
	v_add_f32_e32 v4, v6, v7
	v_mad_i64_i32 v[2:3], s[92:93], v18, 48, v[200:201]
	global_store_dword v[2:3], v4, off
; DEVI void rwkv_prep_item(const Params& p, const int l, const int item, char* smem) {
;     ...
;     for (int r = 0; r < 16; ++r) {
;       const int t = t0 + mt * 32 + (r & 3) + 8 * (r >> 2) + 4 * hi; const bool has_prev = (t & (SEQ_ - 1)) != 0;
;       float rv[2], kv[2], vv[2], av[2], kkv[2], kpv[2], omdv[2], gv[2];
;       float ssq = 0.f, bon = 0.f;
;       const u16* pr = PA + (size_t)t * 2560 + h * 64 + 2 * l31;
;       const unsigned cr2 = *(const unsigned*)pr, ck2 = *(const unsigned*)(pr + 768), cv2 = *(const unsigned*)(pr + 1536);
;       unsigned qr2 = 0u, qk2 = 0u, qv2 = 0u;
;       if (has_prev) { qr2 = *(const unsigned*)(pr - 2560); qk2 = *(const unsigned*)(pr + 768 - 2560); qv2 = *(const unsigned*)(pr + 1536 - 2560); }
; #pragma unroll
;       for (int n = 0; n < 2; ++n) {
;         const float cr = __uint_as_float(n ? (cr2 & 0xffff0000u) : (cr2 << 16)), ck = __uint_as_float(n ? (ck2 & 0xffff0000u) : (ck2 << 16)), cv = __uint_as_float(n ? (cv2 & 0xffff0000u) : (cv2 << 16));
;         const float qr = __uint_as_float(n ? (qr2 & 0xffff0000u) : (qr2 << 16)), qk = __uint_as_float(n ? (qk2 & 0xffff0000u) : (qk2 << 16)), qv = __uint_as_float(n ? (qv2 & 0xffff0000u) : (qv2 << 16));
;         rv[n] = cr + (qr - cr) * mur[n]; kv[n] = ck + (qk - ck) * muk[n]; vv[n] = cv + (qv - cv) * muv[n];
;         const float z = -(w0c[n] + aw[n][r]);
;         const float sp = fmaxf(z, 0.f) + __logf(1.f + __expf(-fabsf(z)));
;         const float ew = __expf(-sp - 0.5f);
;         omdv[n] = 1.f - __expf(-ew);
;         av[n] = sigmoidf_(a0c[n] + aa[n][r]);
;         gv[n] = ag[n][r];
;         kkv[n] = kv[n] * kkc[n];
;         kpv[n] = kv[n] * (1.f + (av[n] - 1.f) * kac[n]);
;         ssq += kkv[n] * kkv[n];
;         bon += rv[n] * kpv[n] * rkc[n];
;       }
;       ssq = reduce32(ssq); bon = reduce32(bon);
;       const float rn = rsqrtf(ssq + 1e-12f);
;       {
;         typedef _Float16 h2 __attribute__((ext_vector_type(2)));
;         const size_t o = (size_t)t * 768 + h * 64 + 2 * l31;
;         const float kn0 = kkv[0] * rn, kn1 = kkv[1] * rn;
;         *(h2*)(RW + o) = (h2){(f16)rv[0], (f16)rv[1]};
;         *(h2*)(RW + TS + o) = (h2){(f16)omdv[0], (f16)omdv[1]};
;         *(h2*)(RW + 2 * TS + o) = (h2){(f16)kpv[0], (f16)kpv[1]};
;         *(h2*)(RW + 3 * TS + o) = (h2){(f16)vv[0], (f16)vv[1]};
;         *(h2*)(RW + 4 * TS + o) = (h2){(f16)kn0, (f16)kn1};
.LBB0_482:
	s_or_b64 exec, exec, s[6:7]
	v_or_b32_e32 v2, 27, v233
	v_mad_i64_i32 v[4:5], s[6:7], v2, s34, v[212:213]
	v_add_co_u32_e32 v6, vcc, 0xfffff000, v4
	s_waitcnt vmcnt(7)
	v_mov_b32_e32 v3, v246
	s_nop 0
	v_addc_co_u32_e32 v7, vcc, -1, v5, vcc
	v_mov_b32_e32 v12, v247
	v_mov_b32_e32 v14, v248
	v_mov_b32_e32 v16, v250
	v_mov_b32_e32 v20, v251
	v_mov_b32_e32 v22, v249
	v_add_f32_e32 v4, v97, v210
	v_add_f32_e32 v5, v81, v208
	v_add_f32_e32 v6, v49, v211
	v_max_f32_e64 v8, -v4, 0
	v_mul_f32_e64 v4, |v4|, s88
	v_mul_f32_e32 v9, 0xbfb8aa3b, v5
	v_max_f32_e64 v10, -v6, 0
	v_mul_f32_e64 v5, |v6|, s88
	v_exp_f32_e32 v6, v4
	v_exp_f32_e32 v11, v5
	v_mad_i64_i32 v[4:5], s[6:7], v2, s54, v[102:103]
	v_add_f32_e32 v6, 1.0, v6
	v_add_f32_e32 v11, 1.0, v11
	v_cmp_gt_f32_e32 vcc, s89, v6
	v_cmp_gt_f32_e64 s[6:7], s89, v11
	v_add_f32_e32 v7, v65, v209
	v_cndmask_b32_e64 v13, 0, 32, vcc
	v_cndmask_b32_e64 v15, 0, 32, s[6:7]
	v_ldexp_f32 v6, v6, v13
	v_ldexp_f32 v11, v11, v15
	v_log_f32_e32 v6, v6
	v_log_f32_e32 v11, v11
	v_cndmask_b32_e32 v13, 0, v232, vcc
	v_cndmask_b32_e64 v15, 0, v232, s[6:7]
	v_mul_f32_e32 v18, 0x3f317217, v6
	v_mul_f32_e32 v19, 0x3f317217, v11
	v_fma_f32 v18, v6, s90, -v18
	v_fma_f32 v19, v11, s90, -v19
	v_fmac_f32_e32 v18, 0x3377d1cf, v6
	v_fmac_f32_e32 v19, 0x3377d1cf, v11
	v_fmac_f32_e32 v18, 0x3f317217, v6
	v_cmp_lt_f32_e64 vcc, |v6|, s91
	v_fmac_f32_e32 v19, 0x3f317217, v11
	v_mul_f32_e32 v7, 0xbfb8aa3b, v7
	v_cndmask_b32_e32 v6, v6, v18, vcc
	v_cmp_lt_f32_e64 vcc, |v11|, s91
	v_sub_f32_e32 v6, v6, v13
	v_add_f32_e32 v6, v8, v6
	v_cndmask_b32_e32 v11, v11, v19, vcc
	v_sub_f32_e32 v11, v11, v15
	v_add_f32_e32 v8, v10, v11
	v_sub_f32_e32 v6, -0.5, v6
	v_sub_f32_e32 v8, -0.5, v8
	v_mul_f32_e32 v6, 0x3fb8aa3b, v6
	v_mul_f32_e32 v8, 0x3fb8aa3b, v8
	v_exp_f32_e32 v10, v6
	v_exp_f32_e32 v8, v8
	v_exp_f32_e32 v6, v9
	v_exp_f32_e32 v7, v7
	v_mul_f32_e32 v9, 0xbfb8aa3b, v10
	v_mul_f32_e32 v8, 0xbfb8aa3b, v8
	v_exp_f32_e32 v10, v9
	v_exp_f32_e32 v11, v8
	v_lshlrev_b64 v[8:9], 1, v[4:5]
	v_lshl_add_u64 v[4:5], s[56:57], 0, v[8:9]
	v_sub_f32_e32 v10, 1.0, v10
	v_sub_f32_e32 v11, 1.0, v11
	v_cvt_pk_f16_f32 v24, v10, v11
	v_pk_add_f32 v[6:7], v[6:7], 1.0 op_sel_hi:[1,0]
	s_nop 0
	v_and_b32_e32 v11, 0xffff0000, v3
	v_lshlrev_b32_e32 v10, 16, v3
	s_nop 0
	v_and_b32_e32 v13, 0xffff0000, v12
	s_nop 0
	v_and_b32_e32 v21, 0xffff0000, v20
	v_lshlrev_b32_e32 v20, 16, v20
	v_pk_add_f32 v[20:21], v[20:21], v[10:11] neg_lo:[0,1] neg_hi:[0,1]
	v_and_b32_e32 v19, 0xffff0000, v16
	v_pk_fma_f32 v[10:11], v[206:207], v[20:21], v[10:11]
	v_lshlrev_b32_e32 v18, 16, v16
	v_cvt_pk_f16_f32 v3, v10, v11
	global_store_dword v[4:5], v3, off
	v_div_scale_f32 v3, s[6:7], v7, v7, 1.0
	v_rcp_f32_e32 v16, v3
	v_lshlrev_b32_e32 v12, 16, v12
	v_lshl_add_u64 v[4:5], s[62:63], 0, v[8:9]
	global_store_dword v[4:5], v24, off
	v_pk_add_f32 v[4:5], v[18:19], v[12:13] neg_lo:[0,1] neg_hi:[0,1]
	v_and_b32_e32 v15, 0xffff0000, v14
	v_pk_fma_f32 v[12:13], v[204:205], v[4:5], v[12:13]
	v_fma_f32 v4, -v3, v16, 1.0
	v_fmac_f32_e32 v16, v4, v16
	v_div_scale_f32 v4, vcc, 1.0, v7, 1.0
	v_mul_f32_e32 v5, v4, v16
	v_fma_f32 v18, -v3, v5, v4
	v_fmac_f32_e32 v5, v18, v16
	v_fma_f32 v3, -v3, v5, v4
	v_div_scale_f32 v4, s[6:7], v6, v6, 1.0
	v_rcp_f32_e32 v18, v4
	v_div_fmas_f32 v3, v3, v16, v5
	v_div_fixup_f32 v7, v3, v7, 1.0
	v_lshlrev_b32_e32 v14, 16, v14
	v_fma_f32 v3, -v4, v18, 1.0
	v_fmac_f32_e32 v18, v3, v18
	v_div_scale_f32 v3, vcc, 1.0, v6, 1.0
	v_mul_f32_e32 v5, v3, v18
	v_fma_f32 v16, -v4, v5, v3
	v_fmac_f32_e32 v5, v16, v18
	v_fma_f32 v3, -v4, v5, v3
	v_div_fmas_f32 v3, v3, v18, v5
	v_div_fixup_f32 v6, v3, v6, 1.0
	v_pk_add_f32 v[4:5], v[6:7], -1.0 op_sel_hi:[1,0]
	s_nop 0
	v_and_b32_e32 v23, 0xffff0000, v22
	v_pk_fma_f32 v[4:5], v[202:203], v[4:5], 1.0 op_sel_hi:[1,1,0]
	v_lshlrev_b32_e32 v22, 16, v22
	v_pk_mul_f32 v[18:19], v[4:5], v[12:13]
	v_pk_mul_f32 v[12:13], v[194:195], v[12:13]
	v_pk_mul_f32 v[4:5], v[10:11], v[18:19]
	v_lshl_add_u64 v[10:11], s[64:65], 0, v[8:9]
	v_fma_f32 v3, v198, v4, 0
	v_fmac_f32_e32 v3, v199, v5
	v_cvt_pk_f16_f32 v5, v18, v19
	global_store_dword v[10:11], v5, off
	v_pk_add_f32 v[10:11], v[22:23], v[14:15] neg_lo:[0,1] neg_hi:[0,1]
	v_add_f32_dpp v3, v3, v3 quad_perm:[1,0,3,2] row_mask:0xf bank_mask:0xf bound_ctrl:1
	v_pk_fma_f32 v[10:11], v[196:197], v[10:11], v[14:15]
	v_pk_mul_f32 v[14:15], v[12:13], v[12:13]
	v_add_f32_dpp v3, v3, v3 quad_perm:[2,3,0,1] row_mask:0xf bank_mask:0xf bound_ctrl:1
	v_add_f32_e32 v5, v14, v15
	s_nop 0
	v_add_f32_dpp v3, v3, v3 row_half_mirror row_mask:0xf bank_mask:0xf bound_ctrl:1
	v_add_f32_dpp v5, v5, v5 quad_perm:[1,0,3,2] row_mask:0xf bank_mask:0xf bound_ctrl:1
	s_nop 0
	v_add_f32_dpp v3, v3, v3 row_mirror row_mask:0xf bank_mask:0xf bound_ctrl:1
	v_add_f32_dpp v5, v5, v5 quad_perm:[2,3,0,1] row_mask:0xf bank_mask:0xf bound_ctrl:1
	v_mov_b32_e32 v4, v3
	s_nop 1
	v_permlane16_swap_b32_e32 v3, v4
	v_add_f32_dpp v5, v5, v5 row_half_mirror row_mask:0xf bank_mask:0xf bound_ctrl:1
	s_nop 1
	v_add_f32_dpp v5, v5, v5 row_mirror row_mask:0xf bank_mask:0xf bound_ctrl:1
	v_mov_b32_e32 v14, v5
	s_nop 1
	v_permlane16_swap_b32_e32 v5, v14
	v_add_f32_e32 v5, v5, v14
	v_add_f32_e32 v5, 0x2b8cbccc, v5
	v_mul_f32_e32 v14, 0x4b800000, v5
	v_cmp_gt_f32_e32 vcc, s89, v5
	s_nop 1
	v_cndmask_b32_e32 v5, v5, v14, vcc
	v_rsq_f32_e32 v5, v5
	v_cvt_pk_f16_f32 v14, v10, v11
	v_lshl_add_u64 v[10:11], s[66:67], 0, v[8:9]
	global_store_dword v[10:11], v14, off
	v_mul_f32_e32 v10, 0x45800000, v5
	v_cndmask_b32_e32 v10, v5, v10, vcc
	v_pk_mul_f32 v[10:11], v[12:13], v[10:11] op_sel_hi:[1,0]
	v_lshl_add_u64 v[12:13], s[72:73], 0, v[8:9]
	v_cvt_pk_f16_f32 v5, v10, v11
	v_pk_mul_f32 v[6:7], v[6:7], v[10:11]
	global_store_dword v[12:13], v5, off
	v_cvt_pk_f16_f32 v5, v6, v7
	v_lshl_add_u64 v[6:7], s[78:79], 0, v[8:9]
	global_store_dword v[6:7], v5, off
	v_cvt_pk_f16_f32 v5, v17, v33
	v_lshl_add_u64 v[6:7], s[82:83], 0, v[8:9]
	global_store_dword v[6:7], v5, off
	s_and_saveexec_b64 s[6:7], s[4:5]
	s_cbranch_execz .LBB0_449
	v_add_f32_e32 v4, v3, v4
	v_mad_i64_i32 v[2:3], s[92:93], v2, 48, v[200:201]
	global_store_dword v[2:3], v4, off
	s_branch .LBB0_449

; DEVI void rwkv_scan_item(const Params& p, const int item, char* smem) {
;     ...
;   if (wid >= 4) load_chunk(0, 0);
;   __syncthreads();
;   const int rsub = lane >> 4, kp = lane & 15;
;   const int row16 = (wid & 3) * 4 + rsub;
;   f32x2 Sa = {0.f, 0.f}, Sb = {0.f, 0.f};
;     ...
;   for (int c = 0; c < NC; ++c) {
;     if (wid >= 4) {
;       if (c + 1 < NC) load_chunk(c + 1, (c + 1) & 1);
;       if (c >= 1) store_y(c - 1);
;     } else {
;       const float* sb = buf + (c & 1) * 12288 + kp * 4;
;       float* yb = ybuf + (c & 1) * 2048 + row16 * 4 + (kp >> 2);
;       const int vofs = 320 + rq * 16 + row16 - kp * 4;
.LBB0_512:
	s_or_b64 exec, exec, s[64:65]
	s_lshl_b32 s58, s36, 2
	s_lshl_b32 s64, s73, 4
	s_and_b32 s58, s58, 0xc0
	s_and_b32 s66, s64, 48
	s_lshl_b64 s[64:65], s[62:63], 1
	s_lshl_b64 s[62:63], s[62:63], 2
	s_add_u32 s62, s34, s62
	v_lshl_add_u64 v[68:69], v[50:51], 0, s[64:65]
	v_lshl_add_u64 v[70:71], v[52:53], 0, s[64:65]
	v_lshl_add_u64 v[72:73], v[54:55], 0, s[64:65]
	v_lshl_add_u64 v[74:75], v[56:57], 0, s[64:65]
	v_lshl_add_u64 v[76:77], v[58:59], 0, s[64:65]
	v_lshl_add_u64 v[78:79], v[60:61], 0, s[64:65]
	s_addc_u32 s63, s35, s63
	s_lshl_b32 s64, s66, 2
	s_add_u32 s62, s62, s64
	s_addc_u32 s63, s63, 0
	v_mov_b32_e32 v26, v45
	v_mov_b32_e32 v27, v45
	v_lshl_add_u64 v[66:67], s[62:63], 0, v[44:45]
	v_add_u32_e32 v63, s66, v92
	v_add_u32_e32 v96, s58, v94
	s_mov_b32 s78, 0
	s_mov_b64 s[62:63], 0
	v_mov_b64_e32 v[28:29], v[26:27]
	v_mov_b32_e32 v100, v45
	v_mov_b32_e32 v101, v45
	v_mov_b32_e32 v102, v45
	v_mov_b32_e32 v103, v45
	s_waitcnt lgkmcnt(0)
	s_barrier
	s_branch .LBB0_514

; DEVI void rwkv_scan_item(const Params& p, const int item, char* smem) {
;     ...
;   for (int c = 0; c < NC; ++c) {
;     if (wid >= 4) {
;       if (c + 1 < NC) load_chunk(c + 1, (c + 1) & 1);
;       if (c >= 1) store_y(c - 1);
;     } else {
;       const float* sb = buf + (c & 1) * 12288 + kp * 4;
;       float* yb = ybuf + (c & 1) * 2048 + row16 * 4 + (kp >> 2);
;       const int vofs = 320 + rq * 16 + row16 - kp * 4;
;       f32x4 kkA, wA, kaA, kA, rA, kkB, wB, kaB, kB, rB; float vA, vB;
;       RW_LD(0, A)
; #pragma unroll 2
;       for (int s = 0; s < 32; s += 2) {
;         RW_LD(s + 1, B)
;         __builtin_amdgcn_sched_barrier(0);
;         RW_STEP(s, A)
;         __builtin_amdgcn_sched_barrier(0);
;         if (s + 2 < 32) RW_LD(s + 2, A)
;         __builtin_amdgcn_sched_barrier(0);
;         RW_STEP(s + 1, B)
;         __builtin_amdgcn_sched_barrier(0);
;       }
.LBB0_514:
	s_and_saveexec_b64 s[64:65], s[2:3]
	s_xor_b64 s[64:65], exec, s[64:65]
	s_cbranch_execz .LBB0_519
	s_and_b32 s58, s78, 1
	s_mul_i32 s58, s58, 0xc000
	v_add_u32_e32 v98, s58, v81
	ds_read_b128 v[2:5], v98
	v_lshl_add_u32 v99, v63, 2, v98
	ds_read_b32 v22, v99 offset:1280
	ds_read_b128 v[14:17], v98 offset:768
	ds_read_b128 v[6:9], v98 offset:256
	ds_read_b128 v[10:13], v98 offset:512
	ds_read_b128 v[18:21], v98 offset:1024
	s_and_b32 s58, s78, 1
	s_lshl_b32 s58, s58, 13
	s_add_i32 s58, s58, 0x18010
	v_add_u32_e32 v97, s58, v93
	s_waitcnt lgkmcnt(0)
	v_pk_mul_f32 v[104:105], v[100:101], v[2:3]
	s_nop 0
	v_pk_fma_f32 v[104:105], v[102:103], v[4:5], v[104:105]
	s_nop 0
	v_add_f32_e32 v104, v104, v105
	ds_read_b32 v40, v99 offset:2816
	ds_read_b128 v[36:39], v98 offset:2304
	v_add_f32_dpp v104, v104, v104 quad_perm:[1,0,3,2] row_mask:0xf bank_mask:0xf bound_ctrl:1
	ds_read_b128 v[24:27], v98 offset:1536
	ds_read_b128 v[28:31], v98 offset:1792
	v_add_f32_dpp v104, v104, v104 quad_perm:[2,3,0,1] row_mask:0xf bank_mask:0xf bound_ctrl:1
	v_pk_mul_f32 v[14:15], v[14:15], v[22:23] op_sel_hi:[1,0]
	v_pk_mul_f32 v[16:17], v[16:17], v[22:23] op_sel_hi:[1,0]
	v_add_f32_dpp v104, v104, v104 row_half_mirror row_mask:0xf bank_mask:0xf bound_ctrl:1
	s_waitcnt lgkmcnt(5)
	v_pk_fma_f32 v[14:15], v[100:101], v[6:7], v[14:15]
	v_pk_fma_f32 v[16:17], v[102:103], v[8:9], v[16:17]
	v_add_f32_dpp v104, v104, v104 row_mirror row_mask:0xf bank_mask:0xf bound_ctrl:1
	v_pk_fma_f32 v[100:101], v[10:11], v[104:105], v[14:15] op_sel_hi:[1,0,1] neg_lo:[0,1,0] neg_hi:[0,1,0]
	v_pk_fma_f32 v[102:103], v[12:13], v[104:105], v[16:17] op_sel_hi:[1,0,1] neg_lo:[0,1,0] neg_hi:[0,1,0]
	v_pk_mul_f32 v[106:107], v[100:101], v[18:19]
	ds_read_b128 v[32:35], v98 offset:2048
	v_pk_fma_f32 v[106:107], v[102:103], v[20:21], v[106:107]
	s_waitcnt lgkmcnt(2)
	v_pk_mul_f32 v[104:105], v[100:101], v[24:25]
	v_add_f32_e32 v106, v106, v107
	ds_read_b128 v[84:87], v98 offset:2560
	v_pk_fma_f32 v[104:105], v[102:103], v[26:27], v[104:105]
	v_add_f32_dpp v106, v106, v106 quad_perm:[1,0,3,2] row_mask:0xf bank_mask:0xf bound_ctrl:1
	v_add_f32_e32 v104, v104, v105
	s_nop 0
	v_add_f32_dpp v106, v106, v106 quad_perm:[2,3,0,1] row_mask:0xf bank_mask:0xf bound_ctrl:1
	ds_write_b32 v97, v106 offset:0
	ds_read_b32 v22, v99 offset:4352
	ds_read_b128 v[14:17], v98 offset:3840
	v_add_f32_dpp v104, v104, v104 quad_perm:[1,0,3,2] row_mask:0xf bank_mask:0xf bound_ctrl:1
	ds_read_b128 v[2:5], v98 offset:3072
	ds_read_b128 v[6:9], v98 offset:3328
	v_add_f32_dpp v104, v104, v104 quad_perm:[2,3,0,1] row_mask:0xf bank_mask:0xf bound_ctrl:1
	v_pk_mul_f32 v[36:37], v[36:37], v[40:41] op_sel_hi:[1,0]
	v_pk_mul_f32 v[38:39], v[38:39], v[40:41] op_sel_hi:[1,0]
	v_add_f32_dpp v104, v104, v104 row_half_mirror row_mask:0xf bank_mask:0xf bound_ctrl:1
	s_waitcnt lgkmcnt(5)
	v_pk_fma_f32 v[36:37], v[100:101], v[28:29], v[36:37]
	v_pk_fma_f32 v[38:39], v[102:103], v[30:31], v[38:39]
	v_add_f32_dpp v104, v104, v104 row_mirror row_mask:0xf bank_mask:0xf bound_ctrl:1
	v_pk_fma_f32 v[100:101], v[32:33], v[104:105], v[36:37] op_sel_hi:[1,0,1] neg_lo:[0,1,0] neg_hi:[0,1,0]
	v_pk_fma_f32 v[102:103], v[34:35], v[104:105], v[38:39] op_sel_hi:[1,0,1] neg_lo:[0,1,0] neg_hi:[0,1,0]
	v_pk_mul_f32 v[106:107], v[100:101], v[84:85]
	ds_read_b128 v[10:13], v98 offset:3584
	v_pk_fma_f32 v[106:107], v[102:103], v[86:87], v[106:107]
	s_waitcnt lgkmcnt(2)
	v_pk_mul_f32 v[104:105], v[100:101], v[2:3]
	v_add_f32_e32 v106, v106, v107
	ds_read_b128 v[18:21], v98 offset:4096
	v_pk_fma_f32 v[104:105], v[102:103], v[4:5], v[104:105]
	v_add_f32_dpp v106, v106, v106 quad_perm:[1,0,3,2] row_mask:0xf bank_mask:0xf bound_ctrl:1
	v_add_f32_e32 v104, v104, v105
	s_nop 0
	v_add_f32_dpp v106, v106, v106 quad_perm:[2,3,0,1] row_mask:0xf bank_mask:0xf bound_ctrl:1
	ds_write_b32 v97, v106 offset:256
	ds_read_b32 v40, v99 offset:5888
	ds_read_b128 v[36:39], v98 offset:5376
	v_add_f32_dpp v104, v104, v104 quad_perm:[1,0,3,2] row_mask:0xf bank_mask:0xf bound_ctrl:1
	ds_read_b128 v[24:27], v98 offset:4608
	ds_read_b128 v[28:31], v98 offset:4864
	v_add_f32_dpp v104, v104, v104 quad_perm:[2,3,0,1] row_mask:0xf bank_mask:0xf bound_ctrl:1
	v_pk_mul_f32 v[14:15], v[14:15], v[22:23] op_sel_hi:[1,0]
	v_pk_mul_f32 v[16:17], v[16:17], v[22:23] op_sel_hi:[1,0]
	v_add_f32_dpp v104, v104, v104 row_half_mirror row_mask:0xf bank_mask:0xf bound_ctrl:1
	s_waitcnt lgkmcnt(5)
	v_pk_fma_f32 v[14:15], v[100:101], v[6:7], v[14:15]
	v_pk_fma_f32 v[16:17], v[102:103], v[8:9], v[16:17]
	v_add_f32_dpp v104, v104, v104 row_mirror row_mask:0xf bank_mask:0xf bound_ctrl:1
	v_pk_fma_f32 v[100:101], v[10:11], v[104:105], v[14:15] op_sel_hi:[1,0,1] neg_lo:[0,1,0] neg_hi:[0,1,0]
	v_pk_fma_f32 v[102:103], v[12:13], v[104:105], v[16:17] op_sel_hi:[1,0,1] neg_lo:[0,1,0] neg_hi:[0,1,0]
	v_pk_mul_f32 v[106:107], v[100:101], v[18:19]
	ds_read_b128 v[32:35], v98 offset:5120
	v_pk_fma_f32 v[106:107], v[102:103], v[20:21], v[106:107]
	s_waitcnt lgkmcnt(2)
	v_pk_mul_f32 v[104:105], v[100:101], v[24:25]
	v_add_f32_e32 v106, v106, v107
	ds_read_b128 v[84:87], v98 offset:5632
	v_pk_fma_f32 v[104:105], v[102:103], v[26:27], v[104:105]
	v_add_f32_dpp v106, v106, v106 quad_perm:[1,0,3,2] row_mask:0xf bank_mask:0xf bound_ctrl:1
	v_add_f32_e32 v104, v104, v105
	s_nop 0
	v_add_f32_dpp v106, v106, v106 quad_perm:[2,3,0,1] row_mask:0xf bank_mask:0xf bound_ctrl:1
	ds_write_b32 v97, v106 offset:512
	ds_read_b32 v22, v99 offset:7424
	ds_read_b128 v[14:17], v98 offset:6912
	v_add_f32_dpp v104, v104, v104 quad_perm:[1,0,3,2] row_mask:0xf bank_mask:0xf bound_ctrl:1
	ds_read_b128 v[2:5], v98 offset:6144
	ds_read_b128 v[6:9], v98 offset:6400
	v_add_f32_dpp v104, v104, v104 quad_perm:[2,3,0,1] row_mask:0xf bank_mask:0xf bound_ctrl:1
	v_pk_mul_f32 v[36:37], v[36:37], v[40:41] op_sel_hi:[1,0]
	v_pk_mul_f32 v[38:39], v[38:39], v[40:41] op_sel_hi:[1,0]
	v_add_f32_dpp v104, v104, v104 row_half_mirror row_mask:0xf bank_mask:0xf bound_ctrl:1
	s_waitcnt lgkmcnt(5)
; DEVI void rwkv_scan_item(const Params& p, const int item, char* smem) {
;     ...
;   for (int c = 0; c < NC; ++c) {
;     if (wid >= 4) {
;       if (c + 1 < NC) load_chunk(c + 1, (c + 1) & 1);
;       if (c >= 1) store_y(c - 1);
;     } else {
;       const float* sb = buf + (c & 1) * 12288 + kp * 4;
;       float* yb = ybuf + (c & 1) * 2048 + row16 * 4 + (kp >> 2);
;       const int vofs = 320 + rq * 16 + row16 - kp * 4;
;       f32x4 kkA, wA, kaA, kA, rA, kkB, wB, kaB, kB, rB; float vA, vB;
;       RW_LD(0, A)
; #pragma unroll 2
;       for (int s = 0; s < 32; s += 2) {
;         RW_LD(s + 1, B)
;         __builtin_amdgcn_sched_barrier(0);
;         RW_STEP(s, A)
;         __builtin_amdgcn_sched_barrier(0);
;         if (s + 2 < 32) RW_LD(s + 2, A)
;         __builtin_amdgcn_sched_barrier(0);
;         RW_STEP(s + 1, B)
;         __builtin_amdgcn_sched_barrier(0);
;       }
	v_pk_fma_f32 v[36:37], v[100:101], v[28:29], v[36:37]
	v_pk_fma_f32 v[38:39], v[102:103], v[30:31], v[38:39]
	v_add_f32_dpp v104, v104, v104 row_mirror row_mask:0xf bank_mask:0xf bound_ctrl:1
	v_pk_fma_f32 v[100:101], v[32:33], v[104:105], v[36:37] op_sel_hi:[1,0,1] neg_lo:[0,1,0] neg_hi:[0,1,0]
	v_pk_fma_f32 v[102:103], v[34:35], v[104:105], v[38:39] op_sel_hi:[1,0,1] neg_lo:[0,1,0] neg_hi:[0,1,0]
	v_pk_mul_f32 v[106:107], v[100:101], v[84:85]
	ds_read_b128 v[10:13], v98 offset:6656
	v_pk_fma_f32 v[106:107], v[102:103], v[86:87], v[106:107]
	s_waitcnt lgkmcnt(2)
	v_pk_mul_f32 v[104:105], v[100:101], v[2:3]
	v_add_f32_e32 v106, v106, v107
	ds_read_b128 v[18:21], v98 offset:7168
	v_pk_fma_f32 v[104:105], v[102:103], v[4:5], v[104:105]
	v_add_f32_dpp v106, v106, v106 quad_perm:[1,0,3,2] row_mask:0xf bank_mask:0xf bound_ctrl:1
	v_add_f32_e32 v104, v104, v105
	s_nop 0
	v_add_f32_dpp v106, v106, v106 quad_perm:[2,3,0,1] row_mask:0xf bank_mask:0xf bound_ctrl:1
	ds_write_b32 v97, v106 offset:768
	ds_read_b32 v40, v99 offset:8960
	ds_read_b128 v[36:39], v98 offset:8448
	v_add_f32_dpp v104, v104, v104 quad_perm:[1,0,3,2] row_mask:0xf bank_mask:0xf bound_ctrl:1
	ds_read_b128 v[24:27], v98 offset:7680
	ds_read_b128 v[28:31], v98 offset:7936
	v_add_f32_dpp v104, v104, v104 quad_perm:[2,3,0,1] row_mask:0xf bank_mask:0xf bound_ctrl:1
	v_pk_mul_f32 v[14:15], v[14:15], v[22:23] op_sel_hi:[1,0]
	v_pk_mul_f32 v[16:17], v[16:17], v[22:23] op_sel_hi:[1,0]
	v_add_f32_dpp v104, v104, v104 row_half_mirror row_mask:0xf bank_mask:0xf bound_ctrl:1
	s_waitcnt lgkmcnt(5)
	v_pk_fma_f32 v[14:15], v[100:101], v[6:7], v[14:15]
	v_pk_fma_f32 v[16:17], v[102:103], v[8:9], v[16:17]
	v_add_f32_dpp v104, v104, v104 row_mirror row_mask:0xf bank_mask:0xf bound_ctrl:1
	v_pk_fma_f32 v[100:101], v[10:11], v[104:105], v[14:15] op_sel_hi:[1,0,1] neg_lo:[0,1,0] neg_hi:[0,1,0]
	v_pk_fma_f32 v[102:103], v[12:13], v[104:105], v[16:17] op_sel_hi:[1,0,1] neg_lo:[0,1,0] neg_hi:[0,1,0]
	v_pk_mul_f32 v[106:107], v[100:101], v[18:19]
	ds_read_b128 v[32:35], v98 offset:8192
	v_pk_fma_f32 v[106:107], v[102:103], v[20:21], v[106:107]
	s_waitcnt lgkmcnt(2)
	v_pk_mul_f32 v[104:105], v[100:101], v[24:25]
	v_add_f32_e32 v106, v106, v107
	ds_read_b128 v[84:87], v98 offset:8704
	v_pk_fma_f32 v[104:105], v[102:103], v[26:27], v[104:105]
	v_add_f32_dpp v106, v106, v106 quad_perm:[1,0,3,2] row_mask:0xf bank_mask:0xf bound_ctrl:1
	v_add_f32_e32 v104, v104, v105
	s_nop 0
	v_add_f32_dpp v106, v106, v106 quad_perm:[2,3,0,1] row_mask:0xf bank_mask:0xf bound_ctrl:1
	ds_write_b32 v97, v106 offset:1024
	ds_read_b32 v22, v99 offset:10496
	ds_read_b128 v[14:17], v98 offset:9984
	v_add_f32_dpp v104, v104, v104 quad_perm:[1,0,3,2] row_mask:0xf bank_mask:0xf bound_ctrl:1
	ds_read_b128 v[2:5], v98 offset:9216
	ds_read_b128 v[6:9], v98 offset:9472
	v_add_f32_dpp v104, v104, v104 quad_perm:[2,3,0,1] row_mask:0xf bank_mask:0xf bound_ctrl:1
	v_pk_mul_f32 v[36:37], v[36:37], v[40:41] op_sel_hi:[1,0]
	v_pk_mul_f32 v[38:39], v[38:39], v[40:41] op_sel_hi:[1,0]
	v_add_f32_dpp v104, v104, v104 row_half_mirror row_mask:0xf bank_mask:0xf bound_ctrl:1
	s_waitcnt lgkmcnt(5)
	v_pk_fma_f32 v[36:37], v[100:101], v[28:29], v[36:37]
	v_pk_fma_f32 v[38:39], v[102:103], v[30:31], v[38:39]
	v_add_f32_dpp v104, v104, v104 row_mirror row_mask:0xf bank_mask:0xf bound_ctrl:1
	v_pk_fma_f32 v[100:101], v[32:33], v[104:105], v[36:37] op_sel_hi:[1,0,1] neg_lo:[0,1,0] neg_hi:[0,1,0]
	v_pk_fma_f32 v[102:103], v[34:35], v[104:105], v[38:39] op_sel_hi:[1,0,1] neg_lo:[0,1,0] neg_hi:[0,1,0]
	v_pk_mul_f32 v[106:107], v[100:101], v[84:85]
	ds_read_b128 v[10:13], v98 offset:9728
	v_pk_fma_f32 v[106:107], v[102:103], v[86:87], v[106:107]
	s_waitcnt lgkmcnt(2)
	v_pk_mul_f32 v[104:105], v[100:101], v[2:3]
	v_add_f32_e32 v106, v106, v107
	ds_read_b128 v[18:21], v98 offset:10240
	v_pk_fma_f32 v[104:105], v[102:103], v[4:5], v[104:105]
	v_add_f32_dpp v106, v106, v106 quad_perm:[1,0,3,2] row_mask:0xf bank_mask:0xf bound_ctrl:1
	v_add_f32_e32 v104, v104, v105
	s_nop 0
	v_add_f32_dpp v106, v106, v106 quad_perm:[2,3,0,1] row_mask:0xf bank_mask:0xf bound_ctrl:1
	ds_write_b32 v97, v106 offset:1280
	ds_read_b32 v40, v99 offset:12032
	ds_read_b128 v[36:39], v98 offset:11520
	v_add_f32_dpp v104, v104, v104 quad_perm:[1,0,3,2] row_mask:0xf bank_mask:0xf bound_ctrl:1
	ds_read_b128 v[24:27], v98 offset:10752
	ds_read_b128 v[28:31], v98 offset:11008
	v_add_f32_dpp v104, v104, v104 quad_perm:[2,3,0,1] row_mask:0xf bank_mask:0xf bound_ctrl:1
	v_pk_mul_f32 v[14:15], v[14:15], v[22:23] op_sel_hi:[1,0]
	v_pk_mul_f32 v[16:17], v[16:17], v[22:23] op_sel_hi:[1,0]
	v_add_f32_dpp v104, v104, v104 row_half_mirror row_mask:0xf bank_mask:0xf bound_ctrl:1
	s_waitcnt lgkmcnt(5)
	v_pk_fma_f32 v[14:15], v[100:101], v[6:7], v[14:15]
	v_pk_fma_f32 v[16:17], v[102:103], v[8:9], v[16:17]
	v_add_f32_dpp v104, v104, v104 row_mirror row_mask:0xf bank_mask:0xf bound_ctrl:1
	v_pk_fma_f32 v[100:101], v[10:11], v[104:105], v[14:15] op_sel_hi:[1,0,1] neg_lo:[0,1,0] neg_hi:[0,1,0]
	v_pk_fma_f32 v[102:103], v[12:13], v[104:105], v[16:17] op_sel_hi:[1,0,1] neg_lo:[0,1,0] neg_hi:[0,1,0]
	v_pk_mul_f32 v[106:107], v[100:101], v[18:19]
	ds_read_b128 v[32:35], v98 offset:11264
	v_pk_fma_f32 v[106:107], v[102:103], v[20:21], v[106:107]
	s_waitcnt lgkmcnt(2)
; DEVI void rwkv_scan_item(const Params& p, const int item, char* smem) {
;     ...
;   for (int c = 0; c < NC; ++c) {
;     if (wid >= 4) {
;       if (c + 1 < NC) load_chunk(c + 1, (c + 1) & 1);
;       if (c >= 1) store_y(c - 1);
;     } else {
;       const float* sb = buf + (c & 1) * 12288 + kp * 4;
;       float* yb = ybuf + (c & 1) * 2048 + row16 * 4 + (kp >> 2);
;       const int vofs = 320 + rq * 16 + row16 - kp * 4;
;       f32x4 kkA, wA, kaA, kA, rA, kkB, wB, kaB, kB, rB; float vA, vB;
;       RW_LD(0, A)
; #pragma unroll 2
;       for (int s = 0; s < 32; s += 2) {
;         RW_LD(s + 1, B)
;         __builtin_amdgcn_sched_barrier(0);
;         RW_STEP(s, A)
;         __builtin_amdgcn_sched_barrier(0);
;         if (s + 2 < 32) RW_LD(s + 2, A)
;         __builtin_amdgcn_sched_barrier(0);
;         RW_STEP(s + 1, B)
;         __builtin_amdgcn_sched_barrier(0);
;       }
	v_pk_mul_f32 v[104:105], v[100:101], v[24:25]
	v_add_f32_e32 v106, v106, v107
	ds_read_b128 v[84:87], v98 offset:11776
	v_pk_fma_f32 v[104:105], v[102:103], v[26:27], v[104:105]
	v_add_f32_dpp v106, v106, v106 quad_perm:[1,0,3,2] row_mask:0xf bank_mask:0xf bound_ctrl:1
	v_add_f32_e32 v104, v104, v105
	s_nop 0
	v_add_f32_dpp v106, v106, v106 quad_perm:[2,3,0,1] row_mask:0xf bank_mask:0xf bound_ctrl:1
	ds_write_b32 v97, v106 offset:1536
	ds_read_b32 v22, v99 offset:13568
	ds_read_b128 v[14:17], v98 offset:13056
	v_add_f32_dpp v104, v104, v104 quad_perm:[1,0,3,2] row_mask:0xf bank_mask:0xf bound_ctrl:1
	ds_read_b128 v[2:5], v98 offset:12288
	ds_read_b128 v[6:9], v98 offset:12544
	v_add_f32_dpp v104, v104, v104 quad_perm:[2,3,0,1] row_mask:0xf bank_mask:0xf bound_ctrl:1
	v_pk_mul_f32 v[36:37], v[36:37], v[40:41] op_sel_hi:[1,0]
	v_pk_mul_f32 v[38:39], v[38:39], v[40:41] op_sel_hi:[1,0]
	v_add_f32_dpp v104, v104, v104 row_half_mirror row_mask:0xf bank_mask:0xf bound_ctrl:1
	s_waitcnt lgkmcnt(5)
	v_pk_fma_f32 v[36:37], v[100:101], v[28:29], v[36:37]
	v_pk_fma_f32 v[38:39], v[102:103], v[30:31], v[38:39]
	v_add_f32_dpp v104, v104, v104 row_mirror row_mask:0xf bank_mask:0xf bound_ctrl:1
	v_pk_fma_f32 v[100:101], v[32:33], v[104:105], v[36:37] op_sel_hi:[1,0,1] neg_lo:[0,1,0] neg_hi:[0,1,0]
	v_pk_fma_f32 v[102:103], v[34:35], v[104:105], v[38:39] op_sel_hi:[1,0,1] neg_lo:[0,1,0] neg_hi:[0,1,0]
	v_pk_mul_f32 v[106:107], v[100:101], v[84:85]
	ds_read_b128 v[10:13], v98 offset:12800
	v_pk_fma_f32 v[106:107], v[102:103], v[86:87], v[106:107]
	s_waitcnt lgkmcnt(2)
	v_pk_mul_f32 v[104:105], v[100:101], v[2:3]
	v_add_f32_e32 v106, v106, v107
	ds_read_b128 v[18:21], v98 offset:13312
	v_pk_fma_f32 v[104:105], v[102:103], v[4:5], v[104:105]
	v_add_f32_dpp v106, v106, v106 quad_perm:[1,0,3,2] row_mask:0xf bank_mask:0xf bound_ctrl:1
	v_add_f32_e32 v104, v104, v105
	s_nop 0
	v_add_f32_dpp v106, v106, v106 quad_perm:[2,3,0,1] row_mask:0xf bank_mask:0xf bound_ctrl:1
	ds_write_b32 v97, v106 offset:1792
	ds_read_b32 v40, v99 offset:15104
	ds_read_b128 v[36:39], v98 offset:14592
	v_add_f32_dpp v104, v104, v104 quad_perm:[1,0,3,2] row_mask:0xf bank_mask:0xf bound_ctrl:1
	ds_read_b128 v[24:27], v98 offset:13824
	ds_read_b128 v[28:31], v98 offset:14080
	v_add_f32_dpp v104, v104, v104 quad_perm:[2,3,0,1] row_mask:0xf bank_mask:0xf bound_ctrl:1
	v_pk_mul_f32 v[14:15], v[14:15], v[22:23] op_sel_hi:[1,0]
	v_pk_mul_f32 v[16:17], v[16:17], v[22:23] op_sel_hi:[1,0]
	v_add_f32_dpp v104, v104, v104 row_half_mirror row_mask:0xf bank_mask:0xf bound_ctrl:1
	s_waitcnt lgkmcnt(5)
	v_pk_fma_f32 v[14:15], v[100:101], v[6:7], v[14:15]
	v_pk_fma_f32 v[16:17], v[102:103], v[8:9], v[16:17]
	v_add_f32_dpp v104, v104, v104 row_mirror row_mask:0xf bank_mask:0xf bound_ctrl:1
	v_pk_fma_f32 v[100:101], v[10:11], v[104:105], v[14:15] op_sel_hi:[1,0,1] neg_lo:[0,1,0] neg_hi:[0,1,0]
	v_pk_fma_f32 v[102:103], v[12:13], v[104:105], v[16:17] op_sel_hi:[1,0,1] neg_lo:[0,1,0] neg_hi:[0,1,0]
	v_pk_mul_f32 v[106:107], v[100:101], v[18:19]
	ds_read_b128 v[32:35], v98 offset:14336
	v_pk_fma_f32 v[106:107], v[102:103], v[20:21], v[106:107]
	s_waitcnt lgkmcnt(2)
	v_pk_mul_f32 v[104:105], v[100:101], v[24:25]
	v_add_f32_e32 v106, v106, v107
	ds_read_b128 v[84:87], v98 offset:14848
	v_pk_fma_f32 v[104:105], v[102:103], v[26:27], v[104:105]
	v_add_f32_dpp v106, v106, v106 quad_perm:[1,0,3,2] row_mask:0xf bank_mask:0xf bound_ctrl:1
	v_add_f32_e32 v104, v104, v105
	s_nop 0
	v_add_f32_dpp v106, v106, v106 quad_perm:[2,3,0,1] row_mask:0xf bank_mask:0xf bound_ctrl:1
	ds_write_b32 v97, v106 offset:2048
	ds_read_b32 v22, v99 offset:16640
	ds_read_b128 v[14:17], v98 offset:16128
	v_add_f32_dpp v104, v104, v104 quad_perm:[1,0,3,2] row_mask:0xf bank_mask:0xf bound_ctrl:1
	ds_read_b128 v[2:5], v98 offset:15360
	ds_read_b128 v[6:9], v98 offset:15616
	v_add_f32_dpp v104, v104, v104 quad_perm:[2,3,0,1] row_mask:0xf bank_mask:0xf bound_ctrl:1
	v_pk_mul_f32 v[36:37], v[36:37], v[40:41] op_sel_hi:[1,0]
	v_pk_mul_f32 v[38:39], v[38:39], v[40:41] op_sel_hi:[1,0]
	v_add_f32_dpp v104, v104, v104 row_half_mirror row_mask:0xf bank_mask:0xf bound_ctrl:1
	s_waitcnt lgkmcnt(5)
	v_pk_fma_f32 v[36:37], v[100:101], v[28:29], v[36:37]
	v_pk_fma_f32 v[38:39], v[102:103], v[30:31], v[38:39]
	v_add_f32_dpp v104, v104, v104 row_mirror row_mask:0xf bank_mask:0xf bound_ctrl:1
	v_pk_fma_f32 v[100:101], v[32:33], v[104:105], v[36:37] op_sel_hi:[1,0,1] neg_lo:[0,1,0] neg_hi:[0,1,0]
	v_pk_fma_f32 v[102:103], v[34:35], v[104:105], v[38:39] op_sel_hi:[1,0,1] neg_lo:[0,1,0] neg_hi:[0,1,0]
	v_pk_mul_f32 v[106:107], v[100:101], v[84:85]
	ds_read_b128 v[10:13], v98 offset:15872
	v_pk_fma_f32 v[106:107], v[102:103], v[86:87], v[106:107]
	s_waitcnt lgkmcnt(2)
	v_pk_mul_f32 v[104:105], v[100:101], v[2:3]
	v_add_f32_e32 v106, v106, v107
	ds_read_b128 v[18:21], v98 offset:16384
	v_pk_fma_f32 v[104:105], v[102:103], v[4:5], v[104:105]
	v_add_f32_dpp v106, v106, v106 quad_perm:[1,0,3,2] row_mask:0xf bank_mask:0xf bound_ctrl:1
	v_add_f32_e32 v104, v104, v105
	s_nop 0
	v_add_f32_dpp v106, v106, v106 quad_perm:[2,3,0,1] row_mask:0xf bank_mask:0xf bound_ctrl:1
	ds_write_b32 v97, v106 offset:2304
	ds_read_b32 v40, v99 offset:18176
	ds_read_b128 v[36:39], v98 offset:17664
	v_add_f32_dpp v104, v104, v104 quad_perm:[1,0,3,2] row_mask:0xf bank_mask:0xf bound_ctrl:1
	ds_read_b128 v[24:27], v98 offset:16896
	ds_read_b128 v[28:31], v98 offset:17152
	v_add_f32_dpp v104, v104, v104 quad_perm:[2,3,0,1] row_mask:0xf bank_mask:0xf bound_ctrl:1
	v_pk_mul_f32 v[14:15], v[14:15], v[22:23] op_sel_hi:[1,0]
	v_pk_mul_f32 v[16:17], v[16:17], v[22:23] op_sel_hi:[1,0]
	v_add_f32_dpp v104, v104, v104 row_half_mirror row_mask:0xf bank_mask:0xf bound_ctrl:1
	s_waitcnt lgkmcnt(5)
; DEVI void rwkv_scan_item(const Params& p, const int item, char* smem) {
;     ...
;   for (int c = 0; c < NC; ++c) {
;     if (wid >= 4) {
;       if (c + 1 < NC) load_chunk(c + 1, (c + 1) & 1);
;       if (c >= 1) store_y(c - 1);
;     } else {
;       const float* sb = buf + (c & 1) * 12288 + kp * 4;
;       float* yb = ybuf + (c & 1) * 2048 + row16 * 4 + (kp >> 2);
;       const int vofs = 320 + rq * 16 + row16 - kp * 4;
;       f32x4 kkA, wA, kaA, kA, rA, kkB, wB, kaB, kB, rB; float vA, vB;
;       RW_LD(0, A)
; #pragma unroll 2
;       for (int s = 0; s < 32; s += 2) {
;         RW_LD(s + 1, B)
;         __builtin_amdgcn_sched_barrier(0);
;         RW_STEP(s, A)
;         __builtin_amdgcn_sched_barrier(0);
;         if (s + 2 < 32) RW_LD(s + 2, A)
;         __builtin_amdgcn_sched_barrier(0);
;         RW_STEP(s + 1, B)
;         __builtin_amdgcn_sched_barrier(0);
;       }
	v_pk_fma_f32 v[14:15], v[100:101], v[6:7], v[14:15]
	v_pk_fma_f32 v[16:17], v[102:103], v[8:9], v[16:17]
	v_add_f32_dpp v104, v104, v104 row_mirror row_mask:0xf bank_mask:0xf bound_ctrl:1
	v_pk_fma_f32 v[100:101], v[10:11], v[104:105], v[14:15] op_sel_hi:[1,0,1] neg_lo:[0,1,0] neg_hi:[0,1,0]
	v_pk_fma_f32 v[102:103], v[12:13], v[104:105], v[16:17] op_sel_hi:[1,0,1] neg_lo:[0,1,0] neg_hi:[0,1,0]
	v_pk_mul_f32 v[106:107], v[100:101], v[18:19]
	ds_read_b128 v[32:35], v98 offset:17408
	v_pk_fma_f32 v[106:107], v[102:103], v[20:21], v[106:107]
	s_waitcnt lgkmcnt(2)
	v_pk_mul_f32 v[104:105], v[100:101], v[24:25]
	v_add_f32_e32 v106, v106, v107
	ds_read_b128 v[84:87], v98 offset:17920
	v_pk_fma_f32 v[104:105], v[102:103], v[26:27], v[104:105]
	v_add_f32_dpp v106, v106, v106 quad_perm:[1,0,3,2] row_mask:0xf bank_mask:0xf bound_ctrl:1
	v_add_f32_e32 v104, v104, v105
	s_nop 0
	v_add_f32_dpp v106, v106, v106 quad_perm:[2,3,0,1] row_mask:0xf bank_mask:0xf bound_ctrl:1
	ds_write_b32 v97, v106 offset:2560
	ds_read_b32 v22, v99 offset:19712
	ds_read_b128 v[14:17], v98 offset:19200
	v_add_f32_dpp v104, v104, v104 quad_perm:[1,0,3,2] row_mask:0xf bank_mask:0xf bound_ctrl:1
	ds_read_b128 v[2:5], v98 offset:18432
	ds_read_b128 v[6:9], v98 offset:18688
	v_add_f32_dpp v104, v104, v104 quad_perm:[2,3,0,1] row_mask:0xf bank_mask:0xf bound_ctrl:1
	v_pk_mul_f32 v[36:37], v[36:37], v[40:41] op_sel_hi:[1,0]
	v_pk_mul_f32 v[38:39], v[38:39], v[40:41] op_sel_hi:[1,0]
	v_add_f32_dpp v104, v104, v104 row_half_mirror row_mask:0xf bank_mask:0xf bound_ctrl:1
	s_waitcnt lgkmcnt(5)
	v_pk_fma_f32 v[36:37], v[100:101], v[28:29], v[36:37]
	v_pk_fma_f32 v[38:39], v[102:103], v[30:31], v[38:39]
	v_add_f32_dpp v104, v104, v104 row_mirror row_mask:0xf bank_mask:0xf bound_ctrl:1
	v_pk_fma_f32 v[100:101], v[32:33], v[104:105], v[36:37] op_sel_hi:[1,0,1] neg_lo:[0,1,0] neg_hi:[0,1,0]
	v_pk_fma_f32 v[102:103], v[34:35], v[104:105], v[38:39] op_sel_hi:[1,0,1] neg_lo:[0,1,0] neg_hi:[0,1,0]
	v_pk_mul_f32 v[106:107], v[100:101], v[84:85]
	ds_read_b128 v[10:13], v98 offset:18944
	v_pk_fma_f32 v[106:107], v[102:103], v[86:87], v[106:107]
	s_waitcnt lgkmcnt(2)
	v_pk_mul_f32 v[104:105], v[100:101], v[2:3]
	v_add_f32_e32 v106, v106, v107
	ds_read_b128 v[18:21], v98 offset:19456
	v_pk_fma_f32 v[104:105], v[102:103], v[4:5], v[104:105]
	v_add_f32_dpp v106, v106, v106 quad_perm:[1,0,3,2] row_mask:0xf bank_mask:0xf bound_ctrl:1
	v_add_f32_e32 v104, v104, v105
	s_nop 0
	v_add_f32_dpp v106, v106, v106 quad_perm:[2,3,0,1] row_mask:0xf bank_mask:0xf bound_ctrl:1
	ds_write_b32 v97, v106 offset:2816
	ds_read_b32 v40, v99 offset:21248
	ds_read_b128 v[36:39], v98 offset:20736
	v_add_f32_dpp v104, v104, v104 quad_perm:[1,0,3,2] row_mask:0xf bank_mask:0xf bound_ctrl:1
	ds_read_b128 v[24:27], v98 offset:19968
	ds_read_b128 v[28:31], v98 offset:20224
	v_add_f32_dpp v104, v104, v104 quad_perm:[2,3,0,1] row_mask:0xf bank_mask:0xf bound_ctrl:1
	v_pk_mul_f32 v[14:15], v[14:15], v[22:23] op_sel_hi:[1,0]
	v_pk_mul_f32 v[16:17], v[16:17], v[22:23] op_sel_hi:[1,0]
	v_add_f32_dpp v104, v104, v104 row_half_mirror row_mask:0xf bank_mask:0xf bound_ctrl:1
	s_waitcnt lgkmcnt(5)
	v_pk_fma_f32 v[14:15], v[100:101], v[6:7], v[14:15]
	v_pk_fma_f32 v[16:17], v[102:103], v[8:9], v[16:17]
	v_add_f32_dpp v104, v104, v104 row_mirror row_mask:0xf bank_mask:0xf bound_ctrl:1
	v_pk_fma_f32 v[100:101], v[10:11], v[104:105], v[14:15] op_sel_hi:[1,0,1] neg_lo:[0,1,0] neg_hi:[0,1,0]
	v_pk_fma_f32 v[102:103], v[12:13], v[104:105], v[16:17] op_sel_hi:[1,0,1] neg_lo:[0,1,0] neg_hi:[0,1,0]
	v_pk_mul_f32 v[106:107], v[100:101], v[18:19]
	ds_read_b128 v[32:35], v98 offset:20480
	v_pk_fma_f32 v[106:107], v[102:103], v[20:21], v[106:107]
	s_waitcnt lgkmcnt(2)
	v_pk_mul_f32 v[104:105], v[100:101], v[24:25]
	v_add_f32_e32 v106, v106, v107
	ds_read_b128 v[84:87], v98 offset:20992
	v_pk_fma_f32 v[104:105], v[102:103], v[26:27], v[104:105]
	v_add_f32_dpp v106, v106, v106 quad_perm:[1,0,3,2] row_mask:0xf bank_mask:0xf bound_ctrl:1
	v_add_f32_e32 v104, v104, v105
	s_nop 0
	v_add_f32_dpp v106, v106, v106 quad_perm:[2,3,0,1] row_mask:0xf bank_mask:0xf bound_ctrl:1
	ds_write_b32 v97, v106 offset:3072
	ds_read_b32 v22, v99 offset:22784
	ds_read_b128 v[14:17], v98 offset:22272
	v_add_f32_dpp v104, v104, v104 quad_perm:[1,0,3,2] row_mask:0xf bank_mask:0xf bound_ctrl:1
	ds_read_b128 v[2:5], v98 offset:21504
	ds_read_b128 v[6:9], v98 offset:21760
	v_add_f32_dpp v104, v104, v104 quad_perm:[2,3,0,1] row_mask:0xf bank_mask:0xf bound_ctrl:1
	v_pk_mul_f32 v[36:37], v[36:37], v[40:41] op_sel_hi:[1,0]
	v_pk_mul_f32 v[38:39], v[38:39], v[40:41] op_sel_hi:[1,0]
	v_add_f32_dpp v104, v104, v104 row_half_mirror row_mask:0xf bank_mask:0xf bound_ctrl:1
	s_waitcnt lgkmcnt(5)
	v_pk_fma_f32 v[36:37], v[100:101], v[28:29], v[36:37]
	v_pk_fma_f32 v[38:39], v[102:103], v[30:31], v[38:39]
	v_add_f32_dpp v104, v104, v104 row_mirror row_mask:0xf bank_mask:0xf bound_ctrl:1
	v_pk_fma_f32 v[100:101], v[32:33], v[104:105], v[36:37] op_sel_hi:[1,0,1] neg_lo:[0,1,0] neg_hi:[0,1,0]
	v_pk_fma_f32 v[102:103], v[34:35], v[104:105], v[38:39] op_sel_hi:[1,0,1] neg_lo:[0,1,0] neg_hi:[0,1,0]
	v_pk_mul_f32 v[106:107], v[100:101], v[84:85]
	ds_read_b128 v[10:13], v98 offset:22016
	v_pk_fma_f32 v[106:107], v[102:103], v[86:87], v[106:107]
	s_waitcnt lgkmcnt(2)
; DEVI void rwkv_scan_item(const Params& p, const int item, char* smem) {
;     ...
;   for (int c = 0; c < NC; ++c) {
;     if (wid >= 4) {
;       if (c + 1 < NC) load_chunk(c + 1, (c + 1) & 1);
;       if (c >= 1) store_y(c - 1);
;     } else {
;       const float* sb = buf + (c & 1) * 12288 + kp * 4;
;       float* yb = ybuf + (c & 1) * 2048 + row16 * 4 + (kp >> 2);
;       const int vofs = 320 + rq * 16 + row16 - kp * 4;
;       f32x4 kkA, wA, kaA, kA, rA, kkB, wB, kaB, kB, rB; float vA, vB;
;       RW_LD(0, A)
; #pragma unroll 2
;       for (int s = 0; s < 32; s += 2) {
;         RW_LD(s + 1, B)
;         __builtin_amdgcn_sched_barrier(0);
;         RW_STEP(s, A)
;         __builtin_amdgcn_sched_barrier(0);
;         if (s + 2 < 32) RW_LD(s + 2, A)
;         __builtin_amdgcn_sched_barrier(0);
;         RW_STEP(s + 1, B)
;         __builtin_amdgcn_sched_barrier(0);
;       }
	v_pk_mul_f32 v[104:105], v[100:101], v[2:3]
	v_add_f32_e32 v106, v106, v107
	ds_read_b128 v[18:21], v98 offset:22528
	v_pk_fma_f32 v[104:105], v[102:103], v[4:5], v[104:105]
	v_add_f32_dpp v106, v106, v106 quad_perm:[1,0,3,2] row_mask:0xf bank_mask:0xf bound_ctrl:1
	v_add_f32_e32 v104, v104, v105
	s_nop 0
	v_add_f32_dpp v106, v106, v106 quad_perm:[2,3,0,1] row_mask:0xf bank_mask:0xf bound_ctrl:1
	ds_write_b32 v97, v106 offset:3328
	ds_read_b32 v40, v99 offset:24320
	ds_read_b128 v[36:39], v98 offset:23808
	v_add_f32_dpp v104, v104, v104 quad_perm:[1,0,3,2] row_mask:0xf bank_mask:0xf bound_ctrl:1
	ds_read_b128 v[24:27], v98 offset:23040
	ds_read_b128 v[28:31], v98 offset:23296
	v_add_f32_dpp v104, v104, v104 quad_perm:[2,3,0,1] row_mask:0xf bank_mask:0xf bound_ctrl:1
	v_pk_mul_f32 v[14:15], v[14:15], v[22:23] op_sel_hi:[1,0]
	v_pk_mul_f32 v[16:17], v[16:17], v[22:23] op_sel_hi:[1,0]
	v_add_f32_dpp v104, v104, v104 row_half_mirror row_mask:0xf bank_mask:0xf bound_ctrl:1
	s_waitcnt lgkmcnt(5)
	v_pk_fma_f32 v[14:15], v[100:101], v[6:7], v[14:15]
	v_pk_fma_f32 v[16:17], v[102:103], v[8:9], v[16:17]
	v_add_f32_dpp v104, v104, v104 row_mirror row_mask:0xf bank_mask:0xf bound_ctrl:1
	v_pk_fma_f32 v[100:101], v[10:11], v[104:105], v[14:15] op_sel_hi:[1,0,1] neg_lo:[0,1,0] neg_hi:[0,1,0]
	v_pk_fma_f32 v[102:103], v[12:13], v[104:105], v[16:17] op_sel_hi:[1,0,1] neg_lo:[0,1,0] neg_hi:[0,1,0]
	v_pk_mul_f32 v[106:107], v[100:101], v[18:19]
	ds_read_b128 v[32:35], v98 offset:23552
	v_pk_fma_f32 v[106:107], v[102:103], v[20:21], v[106:107]
	s_waitcnt lgkmcnt(2)
	v_pk_mul_f32 v[104:105], v[100:101], v[24:25]
	v_add_f32_e32 v106, v106, v107
	ds_read_b128 v[84:87], v98 offset:24064
	v_pk_fma_f32 v[104:105], v[102:103], v[26:27], v[104:105]
	v_add_f32_dpp v106, v106, v106 quad_perm:[1,0,3,2] row_mask:0xf bank_mask:0xf bound_ctrl:1
	v_add_f32_e32 v104, v104, v105
	s_nop 0
	v_add_f32_dpp v106, v106, v106 quad_perm:[2,3,0,1] row_mask:0xf bank_mask:0xf bound_ctrl:1
	ds_write_b32 v97, v106 offset:3584
	ds_read_b32 v22, v99 offset:25856
	ds_read_b128 v[14:17], v98 offset:25344
	v_add_f32_dpp v104, v104, v104 quad_perm:[1,0,3,2] row_mask:0xf bank_mask:0xf bound_ctrl:1
	ds_read_b128 v[2:5], v98 offset:24576
	ds_read_b128 v[6:9], v98 offset:24832
	v_add_f32_dpp v104, v104, v104 quad_perm:[2,3,0,1] row_mask:0xf bank_mask:0xf bound_ctrl:1
	v_pk_mul_f32 v[36:37], v[36:37], v[40:41] op_sel_hi:[1,0]
	v_pk_mul_f32 v[38:39], v[38:39], v[40:41] op_sel_hi:[1,0]
	v_add_f32_dpp v104, v104, v104 row_half_mirror row_mask:0xf bank_mask:0xf bound_ctrl:1
	s_waitcnt lgkmcnt(5)
	v_pk_fma_f32 v[36:37], v[100:101], v[28:29], v[36:37]
	v_pk_fma_f32 v[38:39], v[102:103], v[30:31], v[38:39]
	v_add_f32_dpp v104, v104, v104 row_mirror row_mask:0xf bank_mask:0xf bound_ctrl:1
	v_pk_fma_f32 v[100:101], v[32:33], v[104:105], v[36:37] op_sel_hi:[1,0,1] neg_lo:[0,1,0] neg_hi:[0,1,0]
	v_pk_fma_f32 v[102:103], v[34:35], v[104:105], v[38:39] op_sel_hi:[1,0,1] neg_lo:[0,1,0] neg_hi:[0,1,0]
	v_pk_mul_f32 v[106:107], v[100:101], v[84:85]
	ds_read_b128 v[10:13], v98 offset:25088
	v_pk_fma_f32 v[106:107], v[102:103], v[86:87], v[106:107]
	s_waitcnt lgkmcnt(2)
	v_pk_mul_f32 v[104:105], v[100:101], v[2:3]
	v_add_f32_e32 v106, v106, v107
	ds_read_b128 v[18:21], v98 offset:25600
	v_pk_fma_f32 v[104:105], v[102:103], v[4:5], v[104:105]
	v_add_f32_dpp v106, v106, v106 quad_perm:[1,0,3,2] row_mask:0xf bank_mask:0xf bound_ctrl:1
	v_add_f32_e32 v104, v104, v105
	s_nop 0
	v_add_f32_dpp v106, v106, v106 quad_perm:[2,3,0,1] row_mask:0xf bank_mask:0xf bound_ctrl:1
	ds_write_b32 v97, v106 offset:3840
	ds_read_b32 v40, v99 offset:27392
	ds_read_b128 v[36:39], v98 offset:26880
	v_add_f32_dpp v104, v104, v104 quad_perm:[1,0,3,2] row_mask:0xf bank_mask:0xf bound_ctrl:1
	ds_read_b128 v[24:27], v98 offset:26112
	ds_read_b128 v[28:31], v98 offset:26368
	v_add_f32_dpp v104, v104, v104 quad_perm:[2,3,0,1] row_mask:0xf bank_mask:0xf bound_ctrl:1
	v_pk_mul_f32 v[14:15], v[14:15], v[22:23] op_sel_hi:[1,0]
	v_pk_mul_f32 v[16:17], v[16:17], v[22:23] op_sel_hi:[1,0]
	v_add_f32_dpp v104, v104, v104 row_half_mirror row_mask:0xf bank_mask:0xf bound_ctrl:1
	s_waitcnt lgkmcnt(5)
	v_pk_fma_f32 v[14:15], v[100:101], v[6:7], v[14:15]
	v_pk_fma_f32 v[16:17], v[102:103], v[8:9], v[16:17]
	v_add_f32_dpp v104, v104, v104 row_mirror row_mask:0xf bank_mask:0xf bound_ctrl:1
	v_pk_fma_f32 v[100:101], v[10:11], v[104:105], v[14:15] op_sel_hi:[1,0,1] neg_lo:[0,1,0] neg_hi:[0,1,0]
	v_pk_fma_f32 v[102:103], v[12:13], v[104:105], v[16:17] op_sel_hi:[1,0,1] neg_lo:[0,1,0] neg_hi:[0,1,0]
	v_pk_mul_f32 v[106:107], v[100:101], v[18:19]
	ds_read_b128 v[32:35], v98 offset:26624
	v_pk_fma_f32 v[106:107], v[102:103], v[20:21], v[106:107]
	s_waitcnt lgkmcnt(2)
	v_pk_mul_f32 v[104:105], v[100:101], v[24:25]
	v_add_f32_e32 v106, v106, v107
	ds_read_b128 v[84:87], v98 offset:27136
	v_pk_fma_f32 v[104:105], v[102:103], v[26:27], v[104:105]
	v_add_f32_dpp v106, v106, v106 quad_perm:[1,0,3,2] row_mask:0xf bank_mask:0xf bound_ctrl:1
	v_add_f32_e32 v104, v104, v105
	s_nop 0
	v_add_f32_dpp v106, v106, v106 quad_perm:[2,3,0,1] row_mask:0xf bank_mask:0xf bound_ctrl:1
	ds_write_b32 v97, v106 offset:4096
	ds_read_b32 v22, v99 offset:28928
	ds_read_b128 v[14:17], v98 offset:28416
	v_add_f32_dpp v104, v104, v104 quad_perm:[1,0,3,2] row_mask:0xf bank_mask:0xf bound_ctrl:1
	ds_read_b128 v[2:5], v98 offset:27648
	ds_read_b128 v[6:9], v98 offset:27904
	v_add_f32_dpp v104, v104, v104 quad_perm:[2,3,0,1] row_mask:0xf bank_mask:0xf bound_ctrl:1
	v_pk_mul_f32 v[36:37], v[36:37], v[40:41] op_sel_hi:[1,0]
	v_pk_mul_f32 v[38:39], v[38:39], v[40:41] op_sel_hi:[1,0]
	v_add_f32_dpp v104, v104, v104 row_half_mirror row_mask:0xf bank_mask:0xf bound_ctrl:1
	s_waitcnt lgkmcnt(5)
; DEVI void rwkv_scan_item(const Params& p, const int item, char* smem) {
;     ...
;   for (int c = 0; c < NC; ++c) {
;     if (wid >= 4) {
;       if (c + 1 < NC) load_chunk(c + 1, (c + 1) & 1);
;       if (c >= 1) store_y(c - 1);
;     } else {
;       const float* sb = buf + (c & 1) * 12288 + kp * 4;
;       float* yb = ybuf + (c & 1) * 2048 + row16 * 4 + (kp >> 2);
;       const int vofs = 320 + rq * 16 + row16 - kp * 4;
;       f32x4 kkA, wA, kaA, kA, rA, kkB, wB, kaB, kB, rB; float vA, vB;
;       RW_LD(0, A)
; #pragma unroll 2
;       for (int s = 0; s < 32; s += 2) {
;         RW_LD(s + 1, B)
;         __builtin_amdgcn_sched_barrier(0);
;         RW_STEP(s, A)
;         __builtin_amdgcn_sched_barrier(0);
;         if (s + 2 < 32) RW_LD(s + 2, A)
;         __builtin_amdgcn_sched_barrier(0);
;         RW_STEP(s + 1, B)
;         __builtin_amdgcn_sched_barrier(0);
;       }
	v_pk_fma_f32 v[36:37], v[100:101], v[28:29], v[36:37]
	v_pk_fma_f32 v[38:39], v[102:103], v[30:31], v[38:39]
	v_add_f32_dpp v104, v104, v104 row_mirror row_mask:0xf bank_mask:0xf bound_ctrl:1
	v_pk_fma_f32 v[100:101], v[32:33], v[104:105], v[36:37] op_sel_hi:[1,0,1] neg_lo:[0,1,0] neg_hi:[0,1,0]
	v_pk_fma_f32 v[102:103], v[34:35], v[104:105], v[38:39] op_sel_hi:[1,0,1] neg_lo:[0,1,0] neg_hi:[0,1,0]
	v_pk_mul_f32 v[106:107], v[100:101], v[84:85]
	ds_read_b128 v[10:13], v98 offset:28160
	v_pk_fma_f32 v[106:107], v[102:103], v[86:87], v[106:107]
	s_waitcnt lgkmcnt(2)
	v_pk_mul_f32 v[104:105], v[100:101], v[2:3]
	v_add_f32_e32 v106, v106, v107
	ds_read_b128 v[18:21], v98 offset:28672
	v_pk_fma_f32 v[104:105], v[102:103], v[4:5], v[104:105]
	v_add_f32_dpp v106, v106, v106 quad_perm:[1,0,3,2] row_mask:0xf bank_mask:0xf bound_ctrl:1
	v_add_f32_e32 v104, v104, v105
	s_nop 0
	v_add_f32_dpp v106, v106, v106 quad_perm:[2,3,0,1] row_mask:0xf bank_mask:0xf bound_ctrl:1
	ds_write_b32 v97, v106 offset:4352
	ds_read_b32 v40, v99 offset:30464
	ds_read_b128 v[36:39], v98 offset:29952
	v_add_f32_dpp v104, v104, v104 quad_perm:[1,0,3,2] row_mask:0xf bank_mask:0xf bound_ctrl:1
	ds_read_b128 v[24:27], v98 offset:29184
	ds_read_b128 v[28:31], v98 offset:29440
	v_add_f32_dpp v104, v104, v104 quad_perm:[2,3,0,1] row_mask:0xf bank_mask:0xf bound_ctrl:1
	v_pk_mul_f32 v[14:15], v[14:15], v[22:23] op_sel_hi:[1,0]
	v_pk_mul_f32 v[16:17], v[16:17], v[22:23] op_sel_hi:[1,0]
	v_add_f32_dpp v104, v104, v104 row_half_mirror row_mask:0xf bank_mask:0xf bound_ctrl:1
	s_waitcnt lgkmcnt(5)
	v_pk_fma_f32 v[14:15], v[100:101], v[6:7], v[14:15]
	v_pk_fma_f32 v[16:17], v[102:103], v[8:9], v[16:17]
	v_add_f32_dpp v104, v104, v104 row_mirror row_mask:0xf bank_mask:0xf bound_ctrl:1
	v_pk_fma_f32 v[100:101], v[10:11], v[104:105], v[14:15] op_sel_hi:[1,0,1] neg_lo:[0,1,0] neg_hi:[0,1,0]
	v_pk_fma_f32 v[102:103], v[12:13], v[104:105], v[16:17] op_sel_hi:[1,0,1] neg_lo:[0,1,0] neg_hi:[0,1,0]
	v_pk_mul_f32 v[106:107], v[100:101], v[18:19]
	ds_read_b128 v[32:35], v98 offset:29696
	v_pk_fma_f32 v[106:107], v[102:103], v[20:21], v[106:107]
	s_waitcnt lgkmcnt(2)
	v_pk_mul_f32 v[104:105], v[100:101], v[24:25]
	v_add_f32_e32 v106, v106, v107
	ds_read_b128 v[84:87], v98 offset:30208
	v_pk_fma_f32 v[104:105], v[102:103], v[26:27], v[104:105]
	v_add_f32_dpp v106, v106, v106 quad_perm:[1,0,3,2] row_mask:0xf bank_mask:0xf bound_ctrl:1
	v_add_f32_e32 v104, v104, v105
	s_nop 0
	v_add_f32_dpp v106, v106, v106 quad_perm:[2,3,0,1] row_mask:0xf bank_mask:0xf bound_ctrl:1
	ds_write_b32 v97, v106 offset:4608
	ds_read_b32 v22, v99 offset:32000
	ds_read_b128 v[14:17], v98 offset:31488
	v_add_f32_dpp v104, v104, v104 quad_perm:[1,0,3,2] row_mask:0xf bank_mask:0xf bound_ctrl:1
	ds_read_b128 v[2:5], v98 offset:30720
	ds_read_b128 v[6:9], v98 offset:30976
	v_add_f32_dpp v104, v104, v104 quad_perm:[2,3,0,1] row_mask:0xf bank_mask:0xf bound_ctrl:1
	v_pk_mul_f32 v[36:37], v[36:37], v[40:41] op_sel_hi:[1,0]
	v_pk_mul_f32 v[38:39], v[38:39], v[40:41] op_sel_hi:[1,0]
	v_add_f32_dpp v104, v104, v104 row_half_mirror row_mask:0xf bank_mask:0xf bound_ctrl:1
	s_waitcnt lgkmcnt(5)
	v_pk_fma_f32 v[36:37], v[100:101], v[28:29], v[36:37]
	v_pk_fma_f32 v[38:39], v[102:103], v[30:31], v[38:39]
	v_add_f32_dpp v104, v104, v104 row_mirror row_mask:0xf bank_mask:0xf bound_ctrl:1
	v_pk_fma_f32 v[100:101], v[32:33], v[104:105], v[36:37] op_sel_hi:[1,0,1] neg_lo:[0,1,0] neg_hi:[0,1,0]
	v_pk_fma_f32 v[102:103], v[34:35], v[104:105], v[38:39] op_sel_hi:[1,0,1] neg_lo:[0,1,0] neg_hi:[0,1,0]
	v_pk_mul_f32 v[106:107], v[100:101], v[84:85]
	ds_read_b128 v[10:13], v98 offset:31232
	v_pk_fma_f32 v[106:107], v[102:103], v[86:87], v[106:107]
	s_waitcnt lgkmcnt(2)
	v_pk_mul_f32 v[104:105], v[100:101], v[2:3]
	v_add_f32_e32 v106, v106, v107
	ds_read_b128 v[18:21], v98 offset:31744
	v_pk_fma_f32 v[104:105], v[102:103], v[4:5], v[104:105]
	v_add_f32_dpp v106, v106, v106 quad_perm:[1,0,3,2] row_mask:0xf bank_mask:0xf bound_ctrl:1
	v_add_f32_e32 v104, v104, v105
	s_nop 0
	v_add_f32_dpp v106, v106, v106 quad_perm:[2,3,0,1] row_mask:0xf bank_mask:0xf bound_ctrl:1
	ds_write_b32 v97, v106 offset:4864
	ds_read_b32 v40, v99 offset:33536
	ds_read_b128 v[36:39], v98 offset:33024
	v_add_f32_dpp v104, v104, v104 quad_perm:[1,0,3,2] row_mask:0xf bank_mask:0xf bound_ctrl:1
	ds_read_b128 v[24:27], v98 offset:32256
	ds_read_b128 v[28:31], v98 offset:32512
	v_add_f32_dpp v104, v104, v104 quad_perm:[2,3,0,1] row_mask:0xf bank_mask:0xf bound_ctrl:1
	v_pk_mul_f32 v[14:15], v[14:15], v[22:23] op_sel_hi:[1,0]
	v_pk_mul_f32 v[16:17], v[16:17], v[22:23] op_sel_hi:[1,0]
	v_add_f32_dpp v104, v104, v104 row_half_mirror row_mask:0xf bank_mask:0xf bound_ctrl:1
	s_waitcnt lgkmcnt(5)
	v_pk_fma_f32 v[14:15], v[100:101], v[6:7], v[14:15]
	v_pk_fma_f32 v[16:17], v[102:103], v[8:9], v[16:17]
	v_add_f32_dpp v104, v104, v104 row_mirror row_mask:0xf bank_mask:0xf bound_ctrl:1
	v_pk_fma_f32 v[100:101], v[10:11], v[104:105], v[14:15] op_sel_hi:[1,0,1] neg_lo:[0,1,0] neg_hi:[0,1,0]
	v_pk_fma_f32 v[102:103], v[12:13], v[104:105], v[16:17] op_sel_hi:[1,0,1] neg_lo:[0,1,0] neg_hi:[0,1,0]
	v_pk_mul_f32 v[106:107], v[100:101], v[18:19]
	ds_read_b128 v[32:35], v98 offset:32768
	v_pk_fma_f32 v[106:107], v[102:103], v[20:21], v[106:107]
	s_waitcnt lgkmcnt(2)
; DEVI void rwkv_scan_item(const Params& p, const int item, char* smem) {
;     ...
;   for (int c = 0; c < NC; ++c) {
;     if (wid >= 4) {
;       if (c + 1 < NC) load_chunk(c + 1, (c + 1) & 1);
;       if (c >= 1) store_y(c - 1);
;     } else {
;       const float* sb = buf + (c & 1) * 12288 + kp * 4;
;       float* yb = ybuf + (c & 1) * 2048 + row16 * 4 + (kp >> 2);
;       const int vofs = 320 + rq * 16 + row16 - kp * 4;
;       f32x4 kkA, wA, kaA, kA, rA, kkB, wB, kaB, kB, rB; float vA, vB;
;       RW_LD(0, A)
; #pragma unroll 2
;       for (int s = 0; s < 32; s += 2) {
;         RW_LD(s + 1, B)
;         __builtin_amdgcn_sched_barrier(0);
;         RW_STEP(s, A)
;         __builtin_amdgcn_sched_barrier(0);
;         if (s + 2 < 32) RW_LD(s + 2, A)
;         __builtin_amdgcn_sched_barrier(0);
;         RW_STEP(s + 1, B)
;         __builtin_amdgcn_sched_barrier(0);
;       }
	v_pk_mul_f32 v[104:105], v[100:101], v[24:25]
	v_add_f32_e32 v106, v106, v107
	ds_read_b128 v[84:87], v98 offset:33280
	v_pk_fma_f32 v[104:105], v[102:103], v[26:27], v[104:105]
	v_add_f32_dpp v106, v106, v106 quad_perm:[1,0,3,2] row_mask:0xf bank_mask:0xf bound_ctrl:1
	v_add_f32_e32 v104, v104, v105
	s_nop 0
	v_add_f32_dpp v106, v106, v106 quad_perm:[2,3,0,1] row_mask:0xf bank_mask:0xf bound_ctrl:1
	ds_write_b32 v97, v106 offset:5120
	ds_read_b32 v22, v99 offset:35072
	ds_read_b128 v[14:17], v98 offset:34560
	v_add_f32_dpp v104, v104, v104 quad_perm:[1,0,3,2] row_mask:0xf bank_mask:0xf bound_ctrl:1
	ds_read_b128 v[2:5], v98 offset:33792
	ds_read_b128 v[6:9], v98 offset:34048
	v_add_f32_dpp v104, v104, v104 quad_perm:[2,3,0,1] row_mask:0xf bank_mask:0xf bound_ctrl:1
	v_pk_mul_f32 v[36:37], v[36:37], v[40:41] op_sel_hi:[1,0]
	v_pk_mul_f32 v[38:39], v[38:39], v[40:41] op_sel_hi:[1,0]
	v_add_f32_dpp v104, v104, v104 row_half_mirror row_mask:0xf bank_mask:0xf bound_ctrl:1
	s_waitcnt lgkmcnt(5)
	v_pk_fma_f32 v[36:37], v[100:101], v[28:29], v[36:37]
	v_pk_fma_f32 v[38:39], v[102:103], v[30:31], v[38:39]
	v_add_f32_dpp v104, v104, v104 row_mirror row_mask:0xf bank_mask:0xf bound_ctrl:1
	v_pk_fma_f32 v[100:101], v[32:33], v[104:105], v[36:37] op_sel_hi:[1,0,1] neg_lo:[0,1,0] neg_hi:[0,1,0]
	v_pk_fma_f32 v[102:103], v[34:35], v[104:105], v[38:39] op_sel_hi:[1,0,1] neg_lo:[0,1,0] neg_hi:[0,1,0]
	v_pk_mul_f32 v[106:107], v[100:101], v[84:85]
	ds_read_b128 v[10:13], v98 offset:34304
	v_pk_fma_f32 v[106:107], v[102:103], v[86:87], v[106:107]
	s_waitcnt lgkmcnt(2)
	v_pk_mul_f32 v[104:105], v[100:101], v[2:3]
	v_add_f32_e32 v106, v106, v107
	ds_read_b128 v[18:21], v98 offset:34816
	v_pk_fma_f32 v[104:105], v[102:103], v[4:5], v[104:105]
	v_add_f32_dpp v106, v106, v106 quad_perm:[1,0,3,2] row_mask:0xf bank_mask:0xf bound_ctrl:1
	v_add_f32_e32 v104, v104, v105
	s_nop 0
	v_add_f32_dpp v106, v106, v106 quad_perm:[2,3,0,1] row_mask:0xf bank_mask:0xf bound_ctrl:1
	ds_write_b32 v97, v106 offset:5376
	ds_read_b32 v40, v99 offset:36608
	ds_read_b128 v[36:39], v98 offset:36096
	v_add_f32_dpp v104, v104, v104 quad_perm:[1,0,3,2] row_mask:0xf bank_mask:0xf bound_ctrl:1
	ds_read_b128 v[24:27], v98 offset:35328
	ds_read_b128 v[28:31], v98 offset:35584
	v_add_f32_dpp v104, v104, v104 quad_perm:[2,3,0,1] row_mask:0xf bank_mask:0xf bound_ctrl:1
	v_pk_mul_f32 v[14:15], v[14:15], v[22:23] op_sel_hi:[1,0]
	v_pk_mul_f32 v[16:17], v[16:17], v[22:23] op_sel_hi:[1,0]
	v_add_f32_dpp v104, v104, v104 row_half_mirror row_mask:0xf bank_mask:0xf bound_ctrl:1
	s_waitcnt lgkmcnt(5)
	v_pk_fma_f32 v[14:15], v[100:101], v[6:7], v[14:15]
	v_pk_fma_f32 v[16:17], v[102:103], v[8:9], v[16:17]
	v_add_f32_dpp v104, v104, v104 row_mirror row_mask:0xf bank_mask:0xf bound_ctrl:1
	v_pk_fma_f32 v[100:101], v[10:11], v[104:105], v[14:15] op_sel_hi:[1,0,1] neg_lo:[0,1,0] neg_hi:[0,1,0]
	v_pk_fma_f32 v[102:103], v[12:13], v[104:105], v[16:17] op_sel_hi:[1,0,1] neg_lo:[0,1,0] neg_hi:[0,1,0]
	v_pk_mul_f32 v[106:107], v[100:101], v[18:19]
	ds_read_b128 v[32:35], v98 offset:35840
	v_pk_fma_f32 v[106:107], v[102:103], v[20:21], v[106:107]
	s_waitcnt lgkmcnt(2)
	v_pk_mul_f32 v[104:105], v[100:101], v[24:25]
	v_add_f32_e32 v106, v106, v107
	ds_read_b128 v[84:87], v98 offset:36352
	v_pk_fma_f32 v[104:105], v[102:103], v[26:27], v[104:105]
	v_add_f32_dpp v106, v106, v106 quad_perm:[1,0,3,2] row_mask:0xf bank_mask:0xf bound_ctrl:1
	v_add_f32_e32 v104, v104, v105
	s_nop 0
	v_add_f32_dpp v106, v106, v106 quad_perm:[2,3,0,1] row_mask:0xf bank_mask:0xf bound_ctrl:1
	ds_write_b32 v97, v106 offset:5632
	ds_read_b32 v22, v99 offset:38144
	ds_read_b128 v[14:17], v98 offset:37632
	v_add_f32_dpp v104, v104, v104 quad_perm:[1,0,3,2] row_mask:0xf bank_mask:0xf bound_ctrl:1
	ds_read_b128 v[2:5], v98 offset:36864
	ds_read_b128 v[6:9], v98 offset:37120
	v_add_f32_dpp v104, v104, v104 quad_perm:[2,3,0,1] row_mask:0xf bank_mask:0xf bound_ctrl:1
	v_pk_mul_f32 v[36:37], v[36:37], v[40:41] op_sel_hi:[1,0]
	v_pk_mul_f32 v[38:39], v[38:39], v[40:41] op_sel_hi:[1,0]
	v_add_f32_dpp v104, v104, v104 row_half_mirror row_mask:0xf bank_mask:0xf bound_ctrl:1
	s_waitcnt lgkmcnt(5)
	v_pk_fma_f32 v[36:37], v[100:101], v[28:29], v[36:37]
	v_pk_fma_f32 v[38:39], v[102:103], v[30:31], v[38:39]
	v_add_f32_dpp v104, v104, v104 row_mirror row_mask:0xf bank_mask:0xf bound_ctrl:1
	v_pk_fma_f32 v[100:101], v[32:33], v[104:105], v[36:37] op_sel_hi:[1,0,1] neg_lo:[0,1,0] neg_hi:[0,1,0]
	v_pk_fma_f32 v[102:103], v[34:35], v[104:105], v[38:39] op_sel_hi:[1,0,1] neg_lo:[0,1,0] neg_hi:[0,1,0]
	v_pk_mul_f32 v[106:107], v[100:101], v[84:85]
	ds_read_b128 v[10:13], v98 offset:37376
	v_pk_fma_f32 v[106:107], v[102:103], v[86:87], v[106:107]
	s_waitcnt lgkmcnt(2)
	v_pk_mul_f32 v[104:105], v[100:101], v[2:3]
	v_add_f32_e32 v106, v106, v107
	ds_read_b128 v[18:21], v98 offset:37888
	v_pk_fma_f32 v[104:105], v[102:103], v[4:5], v[104:105]
	v_add_f32_dpp v106, v106, v106 quad_perm:[1,0,3,2] row_mask:0xf bank_mask:0xf bound_ctrl:1
	v_add_f32_e32 v104, v104, v105
	s_nop 0
	v_add_f32_dpp v106, v106, v106 quad_perm:[2,3,0,1] row_mask:0xf bank_mask:0xf bound_ctrl:1
	ds_write_b32 v97, v106 offset:5888
	ds_read_b32 v40, v99 offset:39680
	ds_read_b128 v[36:39], v98 offset:39168
	v_add_f32_dpp v104, v104, v104 quad_perm:[1,0,3,2] row_mask:0xf bank_mask:0xf bound_ctrl:1
	ds_read_b128 v[24:27], v98 offset:38400
	ds_read_b128 v[28:31], v98 offset:38656
	v_add_f32_dpp v104, v104, v104 quad_perm:[2,3,0,1] row_mask:0xf bank_mask:0xf bound_ctrl:1
	v_pk_mul_f32 v[14:15], v[14:15], v[22:23] op_sel_hi:[1,0]
	v_pk_mul_f32 v[16:17], v[16:17], v[22:23] op_sel_hi:[1,0]
	v_add_f32_dpp v104, v104, v104 row_half_mirror row_mask:0xf bank_mask:0xf bound_ctrl:1
	s_waitcnt lgkmcnt(5)
; DEVI void rwkv_scan_item(const Params& p, const int item, char* smem) {
;     ...
;   for (int c = 0; c < NC; ++c) {
;     if (wid >= 4) {
;       if (c + 1 < NC) load_chunk(c + 1, (c + 1) & 1);
;       if (c >= 1) store_y(c - 1);
;     } else {
;       const float* sb = buf + (c & 1) * 12288 + kp * 4;
;       float* yb = ybuf + (c & 1) * 2048 + row16 * 4 + (kp >> 2);
;       const int vofs = 320 + rq * 16 + row16 - kp * 4;
;       f32x4 kkA, wA, kaA, kA, rA, kkB, wB, kaB, kB, rB; float vA, vB;
;       RW_LD(0, A)
; #pragma unroll 2
;       for (int s = 0; s < 32; s += 2) {
;         RW_LD(s + 1, B)
;         __builtin_amdgcn_sched_barrier(0);
;         RW_STEP(s, A)
;         __builtin_amdgcn_sched_barrier(0);
;         if (s + 2 < 32) RW_LD(s + 2, A)
;         __builtin_amdgcn_sched_barrier(0);
;         RW_STEP(s + 1, B)
;         __builtin_amdgcn_sched_barrier(0);
;       }
	v_pk_fma_f32 v[14:15], v[100:101], v[6:7], v[14:15]
	v_pk_fma_f32 v[16:17], v[102:103], v[8:9], v[16:17]
	v_add_f32_dpp v104, v104, v104 row_mirror row_mask:0xf bank_mask:0xf bound_ctrl:1
	v_pk_fma_f32 v[100:101], v[10:11], v[104:105], v[14:15] op_sel_hi:[1,0,1] neg_lo:[0,1,0] neg_hi:[0,1,0]
	v_pk_fma_f32 v[102:103], v[12:13], v[104:105], v[16:17] op_sel_hi:[1,0,1] neg_lo:[0,1,0] neg_hi:[0,1,0]
	v_pk_mul_f32 v[106:107], v[100:101], v[18:19]
	ds_read_b128 v[32:35], v98 offset:38912
	v_pk_fma_f32 v[106:107], v[102:103], v[20:21], v[106:107]
	s_waitcnt lgkmcnt(2)
	v_pk_mul_f32 v[104:105], v[100:101], v[24:25]
	v_add_f32_e32 v106, v106, v107
	ds_read_b128 v[84:87], v98 offset:39424
	v_pk_fma_f32 v[104:105], v[102:103], v[26:27], v[104:105]
	v_add_f32_dpp v106, v106, v106 quad_perm:[1,0,3,2] row_mask:0xf bank_mask:0xf bound_ctrl:1
	v_add_f32_e32 v104, v104, v105
	s_nop 0
	v_add_f32_dpp v106, v106, v106 quad_perm:[2,3,0,1] row_mask:0xf bank_mask:0xf bound_ctrl:1
	ds_write_b32 v97, v106 offset:6144
	ds_read_b32 v22, v99 offset:41216
	ds_read_b128 v[14:17], v98 offset:40704
	v_add_f32_dpp v104, v104, v104 quad_perm:[1,0,3,2] row_mask:0xf bank_mask:0xf bound_ctrl:1
	ds_read_b128 v[2:5], v98 offset:39936
	ds_read_b128 v[6:9], v98 offset:40192
	v_add_f32_dpp v104, v104, v104 quad_perm:[2,3,0,1] row_mask:0xf bank_mask:0xf bound_ctrl:1
	v_pk_mul_f32 v[36:37], v[36:37], v[40:41] op_sel_hi:[1,0]
	v_pk_mul_f32 v[38:39], v[38:39], v[40:41] op_sel_hi:[1,0]
	v_add_f32_dpp v104, v104, v104 row_half_mirror row_mask:0xf bank_mask:0xf bound_ctrl:1
	s_waitcnt lgkmcnt(5)
	v_pk_fma_f32 v[36:37], v[100:101], v[28:29], v[36:37]
	v_pk_fma_f32 v[38:39], v[102:103], v[30:31], v[38:39]
	v_add_f32_dpp v104, v104, v104 row_mirror row_mask:0xf bank_mask:0xf bound_ctrl:1
	v_pk_fma_f32 v[100:101], v[32:33], v[104:105], v[36:37] op_sel_hi:[1,0,1] neg_lo:[0,1,0] neg_hi:[0,1,0]
	v_pk_fma_f32 v[102:103], v[34:35], v[104:105], v[38:39] op_sel_hi:[1,0,1] neg_lo:[0,1,0] neg_hi:[0,1,0]
	v_pk_mul_f32 v[106:107], v[100:101], v[84:85]
	ds_read_b128 v[10:13], v98 offset:40448
	v_pk_fma_f32 v[106:107], v[102:103], v[86:87], v[106:107]
	s_waitcnt lgkmcnt(2)
	v_pk_mul_f32 v[104:105], v[100:101], v[2:3]
	v_add_f32_e32 v106, v106, v107
	ds_read_b128 v[18:21], v98 offset:40960
	v_pk_fma_f32 v[104:105], v[102:103], v[4:5], v[104:105]
	v_add_f32_dpp v106, v106, v106 quad_perm:[1,0,3,2] row_mask:0xf bank_mask:0xf bound_ctrl:1
	v_add_f32_e32 v104, v104, v105
	s_nop 0
	v_add_f32_dpp v106, v106, v106 quad_perm:[2,3,0,1] row_mask:0xf bank_mask:0xf bound_ctrl:1
	ds_write_b32 v97, v106 offset:6400
	ds_read_b32 v40, v99 offset:42752
	ds_read_b128 v[36:39], v98 offset:42240
	v_add_f32_dpp v104, v104, v104 quad_perm:[1,0,3,2] row_mask:0xf bank_mask:0xf bound_ctrl:1
	ds_read_b128 v[24:27], v98 offset:41472
	ds_read_b128 v[28:31], v98 offset:41728
	v_add_f32_dpp v104, v104, v104 quad_perm:[2,3,0,1] row_mask:0xf bank_mask:0xf bound_ctrl:1
	v_pk_mul_f32 v[14:15], v[14:15], v[22:23] op_sel_hi:[1,0]
	v_pk_mul_f32 v[16:17], v[16:17], v[22:23] op_sel_hi:[1,0]
	v_add_f32_dpp v104, v104, v104 row_half_mirror row_mask:0xf bank_mask:0xf bound_ctrl:1
	s_waitcnt lgkmcnt(5)
	v_pk_fma_f32 v[14:15], v[100:101], v[6:7], v[14:15]
	v_pk_fma_f32 v[16:17], v[102:103], v[8:9], v[16:17]
	v_add_f32_dpp v104, v104, v104 row_mirror row_mask:0xf bank_mask:0xf bound_ctrl:1
	v_pk_fma_f32 v[100:101], v[10:11], v[104:105], v[14:15] op_sel_hi:[1,0,1] neg_lo:[0,1,0] neg_hi:[0,1,0]
	v_pk_fma_f32 v[102:103], v[12:13], v[104:105], v[16:17] op_sel_hi:[1,0,1] neg_lo:[0,1,0] neg_hi:[0,1,0]
	v_pk_mul_f32 v[106:107], v[100:101], v[18:19]
	ds_read_b128 v[32:35], v98 offset:41984
	v_pk_fma_f32 v[106:107], v[102:103], v[20:21], v[106:107]
	s_waitcnt lgkmcnt(2)
	v_pk_mul_f32 v[104:105], v[100:101], v[24:25]
	v_add_f32_e32 v106, v106, v107
	ds_read_b128 v[84:87], v98 offset:42496
	v_pk_fma_f32 v[104:105], v[102:103], v[26:27], v[104:105]
	v_add_f32_dpp v106, v106, v106 quad_perm:[1,0,3,2] row_mask:0xf bank_mask:0xf bound_ctrl:1
	v_add_f32_e32 v104, v104, v105
	s_nop 0
	v_add_f32_dpp v106, v106, v106 quad_perm:[2,3,0,1] row_mask:0xf bank_mask:0xf bound_ctrl:1
	ds_write_b32 v97, v106 offset:6656
	ds_read_b32 v22, v99 offset:44288
	ds_read_b128 v[14:17], v98 offset:43776
	v_add_f32_dpp v104, v104, v104 quad_perm:[1,0,3,2] row_mask:0xf bank_mask:0xf bound_ctrl:1
	ds_read_b128 v[2:5], v98 offset:43008
	ds_read_b128 v[6:9], v98 offset:43264
	v_add_f32_dpp v104, v104, v104 quad_perm:[2,3,0,1] row_mask:0xf bank_mask:0xf bound_ctrl:1
	v_pk_mul_f32 v[36:37], v[36:37], v[40:41] op_sel_hi:[1,0]
	v_pk_mul_f32 v[38:39], v[38:39], v[40:41] op_sel_hi:[1,0]
	v_add_f32_dpp v104, v104, v104 row_half_mirror row_mask:0xf bank_mask:0xf bound_ctrl:1
	s_waitcnt lgkmcnt(5)
	v_pk_fma_f32 v[36:37], v[100:101], v[28:29], v[36:37]
	v_pk_fma_f32 v[38:39], v[102:103], v[30:31], v[38:39]
	v_add_f32_dpp v104, v104, v104 row_mirror row_mask:0xf bank_mask:0xf bound_ctrl:1
	v_pk_fma_f32 v[100:101], v[32:33], v[104:105], v[36:37] op_sel_hi:[1,0,1] neg_lo:[0,1,0] neg_hi:[0,1,0]
	v_pk_fma_f32 v[102:103], v[34:35], v[104:105], v[38:39] op_sel_hi:[1,0,1] neg_lo:[0,1,0] neg_hi:[0,1,0]
	v_pk_mul_f32 v[106:107], v[100:101], v[84:85]
	ds_read_b128 v[10:13], v98 offset:43520
	v_pk_fma_f32 v[106:107], v[102:103], v[86:87], v[106:107]
	s_waitcnt lgkmcnt(2)
; DEVI void rwkv_scan_item(const Params& p, const int item, char* smem) {
;     ...
;   for (int c = 0; c < NC; ++c) {
;     if (wid >= 4) {
;       if (c + 1 < NC) load_chunk(c + 1, (c + 1) & 1);
;       if (c >= 1) store_y(c - 1);
;     } else {
;       const float* sb = buf + (c & 1) * 12288 + kp * 4;
;       float* yb = ybuf + (c & 1) * 2048 + row16 * 4 + (kp >> 2);
;       const int vofs = 320 + rq * 16 + row16 - kp * 4;
;       f32x4 kkA, wA, kaA, kA, rA, kkB, wB, kaB, kB, rB; float vA, vB;
;       RW_LD(0, A)
; #pragma unroll 2
;       for (int s = 0; s < 32; s += 2) {
;         RW_LD(s + 1, B)
;         __builtin_amdgcn_sched_barrier(0);
;         RW_STEP(s, A)
;         __builtin_amdgcn_sched_barrier(0);
;         if (s + 2 < 32) RW_LD(s + 2, A)
;         __builtin_amdgcn_sched_barrier(0);
;         RW_STEP(s + 1, B)
;         __builtin_amdgcn_sched_barrier(0);
;       }
	v_pk_mul_f32 v[104:105], v[100:101], v[2:3]
	v_add_f32_e32 v106, v106, v107
	ds_read_b128 v[18:21], v98 offset:44032
	v_pk_fma_f32 v[104:105], v[102:103], v[4:5], v[104:105]
	v_add_f32_dpp v106, v106, v106 quad_perm:[1,0,3,2] row_mask:0xf bank_mask:0xf bound_ctrl:1
	v_add_f32_e32 v104, v104, v105
	s_nop 0
	v_add_f32_dpp v106, v106, v106 quad_perm:[2,3,0,1] row_mask:0xf bank_mask:0xf bound_ctrl:1
	ds_write_b32 v97, v106 offset:6912
	ds_read_b32 v40, v99 offset:45824
	ds_read_b128 v[36:39], v98 offset:45312
	v_add_f32_dpp v104, v104, v104 quad_perm:[1,0,3,2] row_mask:0xf bank_mask:0xf bound_ctrl:1
	ds_read_b128 v[24:27], v98 offset:44544
	ds_read_b128 v[28:31], v98 offset:44800
	v_add_f32_dpp v104, v104, v104 quad_perm:[2,3,0,1] row_mask:0xf bank_mask:0xf bound_ctrl:1
	v_pk_mul_f32 v[14:15], v[14:15], v[22:23] op_sel_hi:[1,0]
	v_pk_mul_f32 v[16:17], v[16:17], v[22:23] op_sel_hi:[1,0]
	v_add_f32_dpp v104, v104, v104 row_half_mirror row_mask:0xf bank_mask:0xf bound_ctrl:1
	s_waitcnt lgkmcnt(5)
	v_pk_fma_f32 v[14:15], v[100:101], v[6:7], v[14:15]
	v_pk_fma_f32 v[16:17], v[102:103], v[8:9], v[16:17]
	v_add_f32_dpp v104, v104, v104 row_mirror row_mask:0xf bank_mask:0xf bound_ctrl:1
	v_pk_fma_f32 v[100:101], v[10:11], v[104:105], v[14:15] op_sel_hi:[1,0,1] neg_lo:[0,1,0] neg_hi:[0,1,0]
	v_pk_fma_f32 v[102:103], v[12:13], v[104:105], v[16:17] op_sel_hi:[1,0,1] neg_lo:[0,1,0] neg_hi:[0,1,0]
	v_pk_mul_f32 v[106:107], v[100:101], v[18:19]
	ds_read_b128 v[32:35], v98 offset:45056
	v_pk_fma_f32 v[106:107], v[102:103], v[20:21], v[106:107]
	s_waitcnt lgkmcnt(2)
	v_pk_mul_f32 v[104:105], v[100:101], v[24:25]
	v_add_f32_e32 v106, v106, v107
	ds_read_b128 v[84:87], v98 offset:45568
	v_pk_fma_f32 v[104:105], v[102:103], v[26:27], v[104:105]
	v_add_f32_dpp v106, v106, v106 quad_perm:[1,0,3,2] row_mask:0xf bank_mask:0xf bound_ctrl:1
	v_add_f32_e32 v104, v104, v105
	s_nop 0
	v_add_f32_dpp v106, v106, v106 quad_perm:[2,3,0,1] row_mask:0xf bank_mask:0xf bound_ctrl:1
	ds_write_b32 v97, v106 offset:7168
	ds_read_b32 v22, v99 offset:47360
	ds_read_b128 v[14:17], v98 offset:46848
	v_add_f32_dpp v104, v104, v104 quad_perm:[1,0,3,2] row_mask:0xf bank_mask:0xf bound_ctrl:1
	ds_read_b128 v[2:5], v98 offset:46080
	ds_read_b128 v[6:9], v98 offset:46336
	v_add_f32_dpp v104, v104, v104 quad_perm:[2,3,0,1] row_mask:0xf bank_mask:0xf bound_ctrl:1
	v_pk_mul_f32 v[36:37], v[36:37], v[40:41] op_sel_hi:[1,0]
	v_pk_mul_f32 v[38:39], v[38:39], v[40:41] op_sel_hi:[1,0]
	v_add_f32_dpp v104, v104, v104 row_half_mirror row_mask:0xf bank_mask:0xf bound_ctrl:1
	s_waitcnt lgkmcnt(5)
	v_pk_fma_f32 v[36:37], v[100:101], v[28:29], v[36:37]
	v_pk_fma_f32 v[38:39], v[102:103], v[30:31], v[38:39]
	v_add_f32_dpp v104, v104, v104 row_mirror row_mask:0xf bank_mask:0xf bound_ctrl:1
	v_pk_fma_f32 v[100:101], v[32:33], v[104:105], v[36:37] op_sel_hi:[1,0,1] neg_lo:[0,1,0] neg_hi:[0,1,0]
	v_pk_fma_f32 v[102:103], v[34:35], v[104:105], v[38:39] op_sel_hi:[1,0,1] neg_lo:[0,1,0] neg_hi:[0,1,0]
	v_pk_mul_f32 v[106:107], v[100:101], v[84:85]
	ds_read_b128 v[10:13], v98 offset:46592
	v_pk_fma_f32 v[106:107], v[102:103], v[86:87], v[106:107]
	s_waitcnt lgkmcnt(2)
	v_pk_mul_f32 v[104:105], v[100:101], v[2:3]
	v_add_f32_e32 v106, v106, v107
	ds_read_b128 v[18:21], v98 offset:47104
	v_pk_fma_f32 v[104:105], v[102:103], v[4:5], v[104:105]
	v_add_f32_dpp v106, v106, v106 quad_perm:[1,0,3,2] row_mask:0xf bank_mask:0xf bound_ctrl:1
	v_add_f32_e32 v104, v104, v105
	s_nop 0
	v_add_f32_dpp v106, v106, v106 quad_perm:[2,3,0,1] row_mask:0xf bank_mask:0xf bound_ctrl:1
	ds_write_b32 v97, v106 offset:7424
	ds_read_b32 v40, v99 offset:48896
	ds_read_b128 v[36:39], v98 offset:48384
	v_add_f32_dpp v104, v104, v104 quad_perm:[1,0,3,2] row_mask:0xf bank_mask:0xf bound_ctrl:1
	ds_read_b128 v[24:27], v98 offset:47616
	ds_read_b128 v[28:31], v98 offset:47872
	v_add_f32_dpp v104, v104, v104 quad_perm:[2,3,0,1] row_mask:0xf bank_mask:0xf bound_ctrl:1
	v_pk_mul_f32 v[14:15], v[14:15], v[22:23] op_sel_hi:[1,0]
	v_pk_mul_f32 v[16:17], v[16:17], v[22:23] op_sel_hi:[1,0]
	v_add_f32_dpp v104, v104, v104 row_half_mirror row_mask:0xf bank_mask:0xf bound_ctrl:1
	s_waitcnt lgkmcnt(5)
	v_pk_fma_f32 v[14:15], v[100:101], v[6:7], v[14:15]
	v_pk_fma_f32 v[16:17], v[102:103], v[8:9], v[16:17]
	v_add_f32_dpp v104, v104, v104 row_mirror row_mask:0xf bank_mask:0xf bound_ctrl:1
	v_pk_fma_f32 v[100:101], v[10:11], v[104:105], v[14:15] op_sel_hi:[1,0,1] neg_lo:[0,1,0] neg_hi:[0,1,0]
	v_pk_fma_f32 v[102:103], v[12:13], v[104:105], v[16:17] op_sel_hi:[1,0,1] neg_lo:[0,1,0] neg_hi:[0,1,0]
	v_pk_mul_f32 v[106:107], v[100:101], v[18:19]
	ds_read_b128 v[32:35], v98 offset:48128
	v_pk_fma_f32 v[106:107], v[102:103], v[20:21], v[106:107]
	s_waitcnt lgkmcnt(2)
	v_pk_mul_f32 v[104:105], v[100:101], v[24:25]
	v_add_f32_e32 v106, v106, v107
	ds_read_b128 v[84:87], v98 offset:48640
	v_pk_fma_f32 v[104:105], v[102:103], v[26:27], v[104:105]
	v_add_f32_dpp v106, v106, v106 quad_perm:[1,0,3,2] row_mask:0xf bank_mask:0xf bound_ctrl:1
	v_add_f32_e32 v104, v104, v105
	s_nop 0
	v_add_f32_dpp v106, v106, v106 quad_perm:[2,3,0,1] row_mask:0xf bank_mask:0xf bound_ctrl:1
	ds_write_b32 v97, v106 offset:7680
	v_add_f32_dpp v104, v104, v104 quad_perm:[1,0,3,2] row_mask:0xf bank_mask:0xf bound_ctrl:1
	v_pk_mul_f32 v[36:37], v[36:37], v[40:41] op_sel_hi:[1,0]
	v_pk_mul_f32 v[38:39], v[38:39], v[40:41] op_sel_hi:[1,0]
	v_add_f32_dpp v104, v104, v104 quad_perm:[2,3,0,1] row_mask:0xf bank_mask:0xf bound_ctrl:1
	s_waitcnt lgkmcnt(1)
	v_pk_fma_f32 v[36:37], v[100:101], v[28:29], v[36:37]
	v_pk_fma_f32 v[38:39], v[102:103], v[30:31], v[38:39]
	v_add_f32_dpp v104, v104, v104 row_half_mirror row_mask:0xf bank_mask:0xf bound_ctrl:1
	s_nop 1
	v_add_f32_dpp v104, v104, v104 row_mirror row_mask:0xf bank_mask:0xf bound_ctrl:1
	v_pk_fma_f32 v[100:101], v[32:33], v[104:105], v[36:37] op_sel_hi:[1,0,1] neg_lo:[0,1,0] neg_hi:[0,1,0]
	v_pk_fma_f32 v[102:103], v[34:35], v[104:105], v[38:39] op_sel_hi:[1,0,1] neg_lo:[0,1,0] neg_hi:[0,1,0]
	v_pk_mul_f32 v[106:107], v[100:101], v[84:85]
	s_nop 0
	v_pk_fma_f32 v[106:107], v[102:103], v[86:87], v[106:107]
	s_nop 0
	v_add_f32_e32 v106, v106, v107
	s_nop 1
	v_add_f32_dpp v106, v106, v106 quad_perm:[1,0,3,2] row_mask:0xf bank_mask:0xf bound_ctrl:1
	s_nop 1
	v_add_f32_dpp v106, v106, v106 quad_perm:[2,3,0,1] row_mask:0xf bank_mask:0xf bound_ctrl:1
	ds_write_b32 v97, v106 offset:7936
; DEVI void rwkv_scan_item(const Params& p, const int item, char* smem) {
;     ...
;   auto load_chunk = [&](int c, int stage) {
;     const size_t gofs = (tok0 + (size_t)c * 32 + lstep) * 768 + h * 64 + lpart * 8;
;     float* dst = buf + stage * 12288 + lstep * 384 + lpart * 8;
;     const int srcidx[6] = {4, 1, 5, 2, 0, 3};
; #pragma unroll
;     for (int a = 0; a < 6; ++a) {
;       const h16x8 hv = *(const h16x8*)(RW + (size_t)srcidx[a] * TS + gofs);
;       float4 f0, f1;
;       f0.x = (float)hv[0]; f0.y = (float)hv[1]; f0.z = (float)hv[2]; f0.w = (float)hv[3];
;       f1.x = (float)hv[4]; f1.y = (float)hv[5]; f1.z = (float)hv[6]; f1.w = (float)hv[7];
;       if (a == 1) { f0.x = 1.f - f0.x; f0.y = 1.f - f0.y; f0.z = 1.f - f0.z; f0.w = 1.f - f0.w; f1.x = 1.f - f1.x; f1.y = 1.f - f1.y; f1.z = 1.f - f1.z; f1.w = 1.f - f1.w; }
;       *(float4*)(dst + a * 64) = f0; *(float4*)(dst + a * 64 + 4) = f1;
;     }
;   };
;     ...
;       if (c + 1 < NC) load_chunk(c + 1, (c + 1) & 1);
.LBB0_519:
	s_andn2_saveexec_b64 s[64:65], s[64:65]
	s_cbranch_execz .LBB0_513
	s_cmpk_eq_i32 s78, 0x1ff
	s_cselect_b64 s[66:67], -1, 0
	s_and_b64 vcc, exec, s[66:67]
	s_cbranch_vccnz .LBB0_522
	s_add_i32 s66, s78, 1
	s_lshl_b32 s58, s66, 5
	v_lshl_add_u64 v[22:23], v[64:65], 0, s[58:59]
	v_mad_u64_u32 v[2:3], s[82:83], v22, s10, v[68:69]
	v_mad_u64_u32 v[6:7], s[82:83], v22, s10, v[70:71]
	v_mad_u64_u32 v[10:11], s[82:83], v22, s10, v[72:73]
	v_mad_i32_i24 v3, v23, s10, v3
	v_mad_i32_i24 v7, v23, s10, v7
	v_mad_i32_i24 v11, v23, s10, v11
	global_load_dwordx4 v[2:5], v[2:3], off
	v_mad_u64_u32 v[14:15], s[82:83], v22, s10, v[74:75]
	global_load_dwordx4 v[6:9], v[6:7], off
	v_mad_i32_i24 v15, v23, s10, v15
	global_load_dwordx4 v[10:13], v[10:11], off
	v_mad_u64_u32 v[18:19], s[82:83], v22, s10, v[76:77]
	global_load_dwordx4 v[14:17], v[14:15], off
	v_mad_u64_u32 v[24:25], s[82:83], v22, s10, v[78:79]
	v_mad_i32_i24 v19, v23, s10, v19
	v_mad_i32_i24 v25, v23, s10, v25
	global_load_dwordx4 v[18:21], v[18:19], off
	s_bitcmp1_b32 s66, 0
	global_load_dwordx4 v[22:25], v[24:25], off
	s_cselect_b32 s58, 0xc000, 0
	s_cmp_lg_u32 s78, 0
	v_add_u32_e32 v80, s58, v1
	s_cselect_b64 s[66:67], -1, 0
	s_waitcnt vmcnt(5)
	v_cvt_f32_f16_e32 v30, v2
	v_cvt_f32_f16_sdwa v31, v2 dst_sel:DWORD dst_unused:UNUSED_PAD src0_sel:WORD_1
	v_cvt_f32_f16_e32 v32, v3
	v_cvt_f32_f16_sdwa v33, v3 dst_sel:DWORD dst_unused:UNUSED_PAD src0_sel:WORD_1
	v_cvt_f32_f16_e32 v2, v4
	v_cvt_f32_f16_sdwa v3, v4 dst_sel:DWORD dst_unused:UNUSED_PAD src0_sel:WORD_1
	v_cvt_f32_f16_e32 v4, v5
	v_cvt_f32_f16_sdwa v5, v5 dst_sel:DWORD dst_unused:UNUSED_PAD src0_sel:WORD_1
	ds_write_b128 v80, v[30:33]
	ds_write_b128 v80, v[2:5] offset:16
	s_waitcnt vmcnt(4)
	v_cvt_f32_f16_e32 v98, v6
	v_cvt_f32_f16_sdwa v99, v6 dst_sel:DWORD dst_unused:UNUSED_PAD src0_sel:WORD_1
	v_cvt_f32_f16_e32 v100, v7
	v_cvt_f32_f16_sdwa v101, v7 dst_sel:DWORD dst_unused:UNUSED_PAD src0_sel:WORD_1
	v_cvt_f32_f16_e32 v102, v8
	v_cvt_f32_f16_sdwa v103, v8 dst_sel:DWORD dst_unused:UNUSED_PAD src0_sel:WORD_1
	v_cvt_f32_f16_e32 v104, v9
	v_cvt_f32_f16_sdwa v105, v9 dst_sel:DWORD dst_unused:UNUSED_PAD src0_sel:WORD_1
	v_pk_add_f32 v[2:3], v[98:99], 1.0 op_sel_hi:[1,0] neg_lo:[1,0] neg_hi:[1,0]
	v_pk_add_f32 v[4:5], v[100:101], 1.0 op_sel_hi:[1,0] neg_lo:[1,0] neg_hi:[1,0]
	v_pk_add_f32 v[30:31], v[102:103], 1.0 op_sel_hi:[1,0] neg_lo:[1,0] neg_hi:[1,0]
	v_pk_add_f32 v[32:33], v[104:105], 1.0 op_sel_hi:[1,0] neg_lo:[1,0] neg_hi:[1,0]
	ds_write_b128 v80, v[2:5] offset:256
	ds_write_b128 v80, v[30:33] offset:272
	s_waitcnt vmcnt(3)
	v_cvt_f32_f16_e32 v6, v10
	v_cvt_f32_f16_sdwa v7, v10 dst_sel:DWORD dst_unused:UNUSED_PAD src0_sel:WORD_1
	v_cvt_f32_f16_e32 v8, v11
	v_cvt_f32_f16_sdwa v9, v11 dst_sel:DWORD dst_unused:UNUSED_PAD src0_sel:WORD_1
	v_cvt_f32_f16_e32 v10, v12
	v_cvt_f32_f16_sdwa v11, v12 dst_sel:DWORD dst_unused:UNUSED_PAD src0_sel:WORD_1
	v_cvt_f32_f16_e32 v12, v13
	v_cvt_f32_f16_sdwa v13, v13 dst_sel:DWORD dst_unused:UNUSED_PAD src0_sel:WORD_1
	ds_write_b128 v80, v[6:9] offset:512
	ds_write_b128 v80, v[10:13] offset:528
	s_waitcnt vmcnt(2)
	v_cvt_f32_f16_e32 v34, v14
	v_cvt_f32_f16_sdwa v35, v14 dst_sel:DWORD dst_unused:UNUSED_PAD src0_sel:WORD_1
	v_cvt_f32_f16_e32 v36, v15
	v_cvt_f32_f16_sdwa v37, v15 dst_sel:DWORD dst_unused:UNUSED_PAD src0_sel:WORD_1
	v_cvt_f32_f16_e32 v14, v16
	v_cvt_f32_f16_sdwa v15, v16 dst_sel:DWORD dst_unused:UNUSED_PAD src0_sel:WORD_1
	v_cvt_f32_f16_e32 v16, v17
	v_cvt_f32_f16_sdwa v17, v17 dst_sel:DWORD dst_unused:UNUSED_PAD src0_sel:WORD_1
	ds_write_b128 v80, v[34:37] offset:768
	ds_write_b128 v80, v[14:17] offset:784
	s_waitcnt vmcnt(1)
	v_cvt_f32_f16_e32 v38, v18
	v_cvt_f32_f16_sdwa v39, v18 dst_sel:DWORD dst_unused:UNUSED_PAD src0_sel:WORD_1
	v_cvt_f32_f16_e32 v40, v19
	v_cvt_f32_f16_sdwa v41, v19 dst_sel:DWORD dst_unused:UNUSED_PAD src0_sel:WORD_1
	v_cvt_f32_f16_e32 v18, v20
	v_cvt_f32_f16_sdwa v19, v20 dst_sel:DWORD dst_unused:UNUSED_PAD src0_sel:WORD_1
	v_cvt_f32_f16_e32 v20, v21
	v_cvt_f32_f16_sdwa v21, v21 dst_sel:DWORD dst_unused:UNUSED_PAD src0_sel:WORD_1
	ds_write_b128 v80, v[38:41] offset:1024
	ds_write_b128 v80, v[18:21] offset:1040
	s_waitcnt vmcnt(0)
	v_cvt_f32_f16_e32 v84, v22
	v_cvt_f32_f16_sdwa v85, v22 dst_sel:DWORD dst_unused:UNUSED_PAD src0_sel:WORD_1
	v_cvt_f32_f16_e32 v86, v23
	v_cvt_f32_f16_sdwa v87, v23 dst_sel:DWORD dst_unused:UNUSED_PAD src0_sel:WORD_1
	v_cvt_f32_f16_e32 v22, v24
	v_cvt_f32_f16_sdwa v23, v24 dst_sel:DWORD dst_unused:UNUSED_PAD src0_sel:WORD_1
	v_cvt_f32_f16_e32 v24, v25
	v_cvt_f32_f16_sdwa v25, v25 dst_sel:DWORD dst_unused:UNUSED_PAD src0_sel:WORD_1
	ds_write_b128 v80, v[84:87] offset:1280
	ds_write_b128 v80, v[22:25] offset:1296

; #define WAITL() asm volatile("s_waitcnt lgkmcnt(0)" ::: "memory")
; template <int EPI> ...
;     ...
;         WAITL();
; #pragma unroll
;         for (int m = 0; m < 4; ++m)
; #pragma unroll
;           for (int n = 0; n < 2; ++n)
; #pragma unroll
;             for (int j = 0; j < 4; ++j) ep[(m * 16 + fq * 4 + j) * 32 + n * 16 + fr] = acc[ai][bj][m][n][j];
;         WAITL();
;         const int grow0 = brow + ai * 128 + wr * 64, gcol0 = bcol + bj * 128 + wc * 32;
;         if (EPI == 1) {
;           const size_t idx0 = (size_t)(grow0 + (lane >> 3)) * 2048 + gcol0 + (lane & 7) * 4;
;           const float* xp = xin + idx0; float* op = xout + idx0; const float* lp = ep + (lane >> 3) * 32 + (lane & 7) * 4;
; #pragma unroll
;           for (int i = 0; i < 8; ++i) {
;             const float4 v = *(const float4*)(lp + i * 256);
;             float4 x = *(const float4*)xp;
;             x.x += v.x; x.y += v.y; x.z += v.z; x.w += v.w;
;             *(float4*)op = x;
;             xp += 16384; op += 16384;
;             asm volatile("" : "+v"(xp), "+v"(op));
;           }
.LBB0_659:
	s_and_b32 s35, s37, 0x7fffff8
	v_or_b32_e32 v142, s66, v156
	v_or_b32_e32 v132, s35, v139
	v_ashrrev_i32_e32 v143, 31, v142
	s_waitcnt lgkmcnt(0)
	ds_write2_b32 v158, v114, v126 offset1:16
	ds_write2_b32 v158, v115, v127 offset0:32 offset1:48
	ds_write2_b32 v158, v116, v128 offset0:64 offset1:80
	ds_write2_b32 v158, v117, v129 offset0:96 offset1:112
	v_add_u32_e32 v114, 0x800, v158
	v_lshlrev_b32_e32 v140, 5, v132
	v_lshlrev_b64 v[142:143], 11, v[142:143]
	ds_write2_b32 v114, v106, v122 offset1:16
	ds_write2_b32 v114, v107, v123 offset0:32 offset1:48
	ds_write2_b32 v114, v108, v124 offset0:64 offset1:80
	ds_write2_b32 v114, v109, v125 offset0:96 offset1:112
	v_add_u32_e32 v106, 0x1000, v158
	v_or_b32_e32 v142, v142, v138
	ds_write2_b32 v106, v102, v118 offset1:16
	ds_write2_b32 v106, v103, v119 offset0:32 offset1:48
	ds_write2_b32 v106, v104, v120 offset0:64 offset1:80
	ds_write2_b32 v106, v105, v121 offset0:96 offset1:112
	v_add_u32_e32 v102, 0x1800, v158
	v_ashrrev_i32_e32 v141, 31, v140
	ds_write2_b32 v102, v98, v110 offset1:16
	ds_write2_b32 v102, v99, v111 offset0:32 offset1:48
	ds_write2_b32 v102, v100, v112 offset0:64 offset1:80
	ds_write2_b32 v102, v101, v113 offset0:96 offset1:112
	v_lshl_add_u64 v[98:99], v[142:143], 0, v[140:141]
	v_lshlrev_b64 v[98:99], 2, v[98:99]
	s_waitcnt lgkmcnt(0)
	v_lshl_add_u64 v[100:101], s[68:69], 0, v[98:99]
	global_load_dwordx4 v[176:179], v[100:101], off
	v_lshl_add_u64 v[208:209], v[100:101], 0, s[58:59]
	global_load_dwordx4 v[180:183], v[208:209], off
	v_lshl_add_u64 v[208:209], v[208:209], 0, s[58:59]
	global_load_dwordx4 v[184:187], v[208:209], off
	v_lshl_add_u64 v[208:209], v[208:209], 0, s[58:59]
	global_load_dwordx4 v[188:191], v[208:209], off
	v_lshl_add_u64 v[208:209], v[208:209], 0, s[58:59]
	global_load_dwordx4 v[192:195], v[208:209], off
	v_lshl_add_u64 v[208:209], v[208:209], 0, s[58:59]
	global_load_dwordx4 v[196:199], v[208:209], off
	v_lshl_add_u64 v[208:209], v[208:209], 0, s[58:59]
	global_load_dwordx4 v[200:203], v[208:209], off
	v_lshl_add_u64 v[208:209], v[208:209], 0, s[58:59]
	global_load_dwordx4 v[204:207], v[208:209], off
	ds_read_b128 v[116:119], v157
	v_readlane_b32 s84, v252, 16
	v_readlane_b32 s88, v252, 20
	v_readlane_b32 s89, v252, 21
	v_readlane_b32 s90, v252, 22
	v_readlane_b32 s91, v252, 23
	s_mov_b64 s[64:65], s[88:89]
	s_mov_b64 s[66:67], s[90:91]
	v_lshl_add_u64 v[104:105], s[66:67], 0, v[98:99]
	v_lshl_add_u64 v[112:113], v[100:101], 0, s[58:59]
	v_lshl_add_u64 v[120:121], v[104:105], 0, s[58:59]
	s_mov_b64 s[36:37], 0x100000
	s_andn2_b64 vcc, exec, s[62:63]
	v_readlane_b32 s85, v252, 17
	v_readlane_b32 s86, v252, 18
	v_readlane_b32 s87, v252, 19
	s_waitcnt vmcnt(7) lgkmcnt(0)
	v_pk_add_f32 v[176:177], v[116:117], v[176:177]
	v_pk_add_f32 v[178:179], v[118:119], v[178:179]
	global_store_dwordx4 v[104:105], v[176:179], off
	ds_read_b128 v[116:119], v157 offset:1024
	v_lshl_add_u64 v[112:113], v[112:113], 0, s[58:59]
	v_lshl_add_u64 v[122:123], v[120:121], 0, s[58:59]
	s_waitcnt vmcnt(7) lgkmcnt(0)
	v_pk_add_f32 v[180:181], v[116:117], v[180:181]
	v_pk_add_f32 v[182:183], v[118:119], v[182:183]
	global_store_dwordx4 v[120:121], v[180:183], off
	ds_read_b128 v[116:119], v157 offset:2048
	v_lshl_add_u64 v[112:113], v[112:113], 0, s[58:59]
	v_lshl_add_u64 v[120:121], v[122:123], 0, s[58:59]
	s_waitcnt vmcnt(7) lgkmcnt(0)
	v_pk_add_f32 v[184:185], v[116:117], v[184:185]
	v_pk_add_f32 v[186:187], v[118:119], v[186:187]
	global_store_dwordx4 v[122:123], v[184:187], off
	ds_read_b128 v[116:119], v157 offset:3072
	v_lshl_add_u64 v[112:113], v[112:113], 0, s[58:59]
	v_lshl_add_u64 v[122:123], v[120:121], 0, s[58:59]
	s_waitcnt vmcnt(7) lgkmcnt(0)
	v_pk_add_f32 v[188:189], v[116:117], v[188:189]
	v_pk_add_f32 v[190:191], v[118:119], v[190:191]
	global_store_dwordx4 v[120:121], v[188:191], off
	ds_read_b128 v[116:119], v157 offset:4096
	v_lshl_add_u64 v[112:113], v[112:113], 0, s[58:59]
	v_lshl_add_u64 v[120:121], v[122:123], 0, s[58:59]
	s_waitcnt vmcnt(7) lgkmcnt(0)
	v_pk_add_f32 v[192:193], v[116:117], v[192:193]
	v_pk_add_f32 v[194:195], v[118:119], v[194:195]
	global_store_dwordx4 v[122:123], v[192:195], off
	ds_read_b128 v[116:119], v157 offset:5120
	v_lshl_add_u64 v[112:113], v[112:113], 0, s[58:59]
	v_lshl_add_u64 v[122:123], v[120:121], 0, s[58:59]
	s_waitcnt vmcnt(7) lgkmcnt(0)
	v_pk_add_f32 v[196:197], v[116:117], v[196:197]
	v_pk_add_f32 v[198:199], v[118:119], v[198:199]
	global_store_dwordx4 v[120:121], v[196:199], off
	ds_read_b128 v[116:119], v157 offset:6144
	v_lshl_add_u64 v[112:113], v[112:113], 0, s[58:59]
	v_lshl_add_u64 v[120:121], v[122:123], 0, s[58:59]
	s_waitcnt vmcnt(7) lgkmcnt(0)
	v_pk_add_f32 v[200:201], v[116:117], v[200:201]
	v_pk_add_f32 v[202:203], v[118:119], v[202:203]
	global_store_dwordx4 v[122:123], v[200:203], off
	ds_read_b128 v[116:119], v157 offset:7168
	v_lshl_add_u64 v[112:113], v[112:113], 0, s[58:59]
	v_lshl_add_u64 v[122:123], v[120:121], 0, s[58:59]
	s_waitcnt vmcnt(7) lgkmcnt(0)
	v_pk_add_f32 v[204:205], v[116:117], v[204:205]
	v_pk_add_f32 v[206:207], v[118:119], v[206:207]
	global_store_dwordx4 v[120:121], v[204:207], off
	s_waitcnt lgkmcnt(0)
	ds_write2_b32 v158, v66, v82 offset1:16
	ds_write2_b32 v158, v67, v83 offset0:32 offset1:48
	ds_write2_b32 v158, v68, v84 offset0:64 offset1:80
	ds_write2_b32 v158, v69, v85 offset0:96 offset1:112
	ds_write2_b32 v114, v70, v86 offset1:16
	ds_write2_b32 v114, v71, v87 offset0:32 offset1:48
	ds_write2_b32 v114, v72, v88 offset0:64 offset1:80
	ds_write2_b32 v114, v73, v89 offset0:96 offset1:112
	ds_write2_b32 v106, v74, v90 offset1:16
	ds_write2_b32 v106, v75, v91 offset0:32 offset1:48
	ds_write2_b32 v106, v76, v92 offset0:64 offset1:80
	ds_write2_b32 v106, v77, v93 offset0:96 offset1:112
	ds_write2_b32 v102, v78, v94 offset1:16
	ds_write2_b32 v102, v79, v95 offset0:32 offset1:48
	ds_write2_b32 v102, v80, v96 offset0:64 offset1:80
	ds_write2_b32 v102, v81, v97 offset0:96 offset1:112
	s_waitcnt lgkmcnt(0)
; #define WAITL() asm volatile("s_waitcnt lgkmcnt(0)" ::: "memory")
; template <int EPI> ...
;     ...
;         WAITL();
; #pragma unroll
;         for (int m = 0; m < 4; ++m)
; #pragma unroll
;           for (int n = 0; n < 2; ++n)
; #pragma unroll
;             for (int j = 0; j < 4; ++j) ep[(m * 16 + fq * 4 + j) * 32 + n * 16 + fr] = acc[ai][bj][m][n][j];
;         WAITL();
;         const int grow0 = brow + ai * 128 + wr * 64, gcol0 = bcol + bj * 128 + wc * 32;
;         if (EPI == 1) {
;           const size_t idx0 = (size_t)(grow0 + (lane >> 3)) * 2048 + gcol0 + (lane & 7) * 4;
;           const float* xp = xin + idx0; float* op = xout + idx0; const float* lp = ep + (lane >> 3) * 32 + (lane & 7) * 4;
; #pragma unroll
;           for (int i = 0; i < 8; ++i) {
;             const float4 v = *(const float4*)(lp + i * 256);
;             float4 x = *(const float4*)xp;
;             x.x += v.x; x.y += v.y; x.z += v.z; x.w += v.w;
;             *(float4*)op = x;
;             xp += 16384; op += 16384;
;             asm volatile("" : "+v"(xp), "+v"(op));
;           }
	global_load_dwordx4 v[176:179], v[100:101], off offset:512
	v_lshl_add_u64 v[208:209], v[100:101], 0, s[60:61]
	global_load_dwordx4 v[180:183], v[208:209], off
	v_lshl_add_u64 v[208:209], v[208:209], 0, s[58:59]
	global_load_dwordx4 v[184:187], v[208:209], off
	v_lshl_add_u64 v[208:209], v[208:209], 0, s[58:59]
	global_load_dwordx4 v[188:191], v[208:209], off
	v_lshl_add_u64 v[208:209], v[208:209], 0, s[58:59]
	global_load_dwordx4 v[192:195], v[208:209], off
	v_lshl_add_u64 v[208:209], v[208:209], 0, s[58:59]
	global_load_dwordx4 v[196:199], v[208:209], off
	v_lshl_add_u64 v[208:209], v[208:209], 0, s[58:59]
	global_load_dwordx4 v[200:203], v[208:209], off
	v_lshl_add_u64 v[208:209], v[208:209], 0, s[58:59]
	global_load_dwordx4 v[204:207], v[208:209], off
	ds_read_b128 v[70:73], v157
	v_lshl_add_u64 v[74:75], v[100:101], 0, s[60:61]
	v_lshl_add_u64 v[76:77], v[104:105], 0, s[60:61]
	s_waitcnt vmcnt(7) lgkmcnt(0)
	v_pk_add_f32 v[176:177], v[70:71], v[176:177]
	v_pk_add_f32 v[178:179], v[72:73], v[178:179]
	global_store_dwordx4 v[104:105], v[176:179], off offset:512
	ds_read_b128 v[70:73], v157 offset:1024
	v_lshl_add_u64 v[74:75], v[74:75], 0, s[58:59]
	v_lshl_add_u64 v[78:79], v[76:77], 0, s[58:59]
	s_waitcnt vmcnt(7) lgkmcnt(0)
	v_pk_add_f32 v[180:181], v[70:71], v[180:181]
	v_pk_add_f32 v[182:183], v[72:73], v[182:183]
	global_store_dwordx4 v[76:77], v[180:183], off
	ds_read_b128 v[70:73], v157 offset:2048
	v_lshl_add_u64 v[74:75], v[74:75], 0, s[58:59]
	v_lshl_add_u64 v[76:77], v[78:79], 0, s[58:59]
	s_waitcnt vmcnt(7) lgkmcnt(0)
	v_pk_add_f32 v[184:185], v[70:71], v[184:185]
	v_pk_add_f32 v[186:187], v[72:73], v[186:187]
	global_store_dwordx4 v[78:79], v[184:187], off
	ds_read_b128 v[70:73], v157 offset:3072
	v_lshl_add_u64 v[74:75], v[74:75], 0, s[58:59]
	v_lshl_add_u64 v[78:79], v[76:77], 0, s[58:59]
	s_waitcnt vmcnt(7) lgkmcnt(0)
	v_pk_add_f32 v[188:189], v[70:71], v[188:189]
	v_pk_add_f32 v[190:191], v[72:73], v[190:191]
	global_store_dwordx4 v[76:77], v[188:191], off
	ds_read_b128 v[70:73], v157 offset:4096
	v_lshl_add_u64 v[74:75], v[74:75], 0, s[58:59]
	v_lshl_add_u64 v[76:77], v[78:79], 0, s[58:59]
	s_waitcnt vmcnt(7) lgkmcnt(0)
	v_pk_add_f32 v[192:193], v[70:71], v[192:193]
	v_pk_add_f32 v[194:195], v[72:73], v[194:195]
	global_store_dwordx4 v[78:79], v[192:195], off
	ds_read_b128 v[70:73], v157 offset:5120
	v_lshl_add_u64 v[74:75], v[74:75], 0, s[58:59]
	v_lshl_add_u64 v[78:79], v[76:77], 0, s[58:59]
	s_waitcnt vmcnt(7) lgkmcnt(0)
	v_pk_add_f32 v[196:197], v[70:71], v[196:197]
	v_pk_add_f32 v[198:199], v[72:73], v[198:199]
	global_store_dwordx4 v[76:77], v[196:199], off
	ds_read_b128 v[70:73], v157 offset:6144
	v_lshl_add_u64 v[74:75], v[74:75], 0, s[58:59]
	v_lshl_add_u64 v[76:77], v[78:79], 0, s[58:59]
	s_waitcnt vmcnt(7) lgkmcnt(0)
	v_pk_add_f32 v[200:201], v[70:71], v[200:201]
	v_pk_add_f32 v[202:203], v[72:73], v[202:203]
	global_store_dwordx4 v[78:79], v[200:203], off
	ds_read_b128 v[70:73], v157 offset:7168
	v_lshl_add_u64 v[74:75], v[74:75], 0, s[58:59]
	v_lshl_add_u64 v[82:83], v[76:77], 0, s[58:59]
	v_lshl_add_u64 v[78:79], v[98:99], 0, s[36:37]
	v_lshl_add_u64 v[80:81], s[68:69], 0, v[78:79]
	s_mov_b32 s37, s34
	s_waitcnt vmcnt(7) lgkmcnt(0)
	v_pk_add_f32 v[204:205], v[70:71], v[204:205]
	v_pk_add_f32 v[206:207], v[72:73], v[206:207]
	global_store_dwordx4 v[76:77], v[204:207], off
	s_waitcnt lgkmcnt(0)
	ds_write2_b32 v158, v34, v50 offset1:16
	ds_write2_b32 v158, v35, v51 offset0:32 offset1:48
	ds_write2_b32 v158, v36, v52 offset0:64 offset1:80
	ds_write2_b32 v158, v37, v53 offset0:96 offset1:112
	ds_write2_b32 v114, v38, v54 offset1:16
	ds_write2_b32 v114, v39, v55 offset0:32 offset1:48
	ds_write2_b32 v114, v40, v56 offset0:64 offset1:80
	ds_write2_b32 v114, v41, v57 offset0:96 offset1:112
	ds_write2_b32 v106, v42, v58 offset1:16
	ds_write2_b32 v106, v43, v59 offset0:32 offset1:48
	ds_write2_b32 v106, v44, v60 offset0:64 offset1:80
	ds_write2_b32 v106, v45, v61 offset0:96 offset1:112
	ds_write2_b32 v102, v46, v62 offset1:16
	ds_write2_b32 v102, v47, v63 offset0:32 offset1:48
	ds_write2_b32 v102, v48, v64 offset0:64 offset1:80
	ds_write2_b32 v102, v49, v65 offset0:96 offset1:112
	s_waitcnt lgkmcnt(0)
	global_load_dwordx4 v[176:179], v[80:81], off
	v_lshl_add_u64 v[208:209], v[80:81], 0, s[58:59]
	global_load_dwordx4 v[180:183], v[208:209], off
	v_lshl_add_u64 v[208:209], v[208:209], 0, s[58:59]
	global_load_dwordx4 v[184:187], v[208:209], off
	v_lshl_add_u64 v[208:209], v[208:209], 0, s[58:59]
	global_load_dwordx4 v[188:191], v[208:209], off
	v_lshl_add_u64 v[208:209], v[208:209], 0, s[58:59]
	global_load_dwordx4 v[192:195], v[208:209], off
	v_lshl_add_u64 v[208:209], v[208:209], 0, s[58:59]
	global_load_dwordx4 v[196:199], v[208:209], off
	v_lshl_add_u64 v[208:209], v[208:209], 0, s[58:59]
	global_load_dwordx4 v[200:203], v[208:209], off
	v_lshl_add_u64 v[208:209], v[208:209], 0, s[58:59]
	global_load_dwordx4 v[204:207], v[208:209], off
	ds_read_b128 v[38:41], v157
	v_lshl_add_u64 v[42:43], s[66:67], 0, v[78:79]
	v_lshl_add_u64 v[44:45], v[80:81], 0, s[58:59]
	v_lshl_add_u64 v[46:47], v[42:43], 0, s[58:59]
	s_waitcnt vmcnt(7) lgkmcnt(0)
	v_pk_add_f32 v[176:177], v[38:39], v[176:177]
	v_pk_add_f32 v[178:179], v[40:41], v[178:179]
	global_store_dwordx4 v[42:43], v[176:179], off
	ds_read_b128 v[38:41], v157 offset:1024
	v_lshl_add_u64 v[44:45], v[44:45], 0, s[58:59]
	v_lshl_add_u64 v[48:49], v[46:47], 0, s[58:59]
	s_waitcnt vmcnt(7) lgkmcnt(0)
	v_pk_add_f32 v[180:181], v[38:39], v[180:181]
	v_pk_add_f32 v[182:183], v[40:41], v[182:183]
	global_store_dwordx4 v[46:47], v[180:183], off
	ds_read_b128 v[38:41], v157 offset:2048
	v_lshl_add_u64 v[44:45], v[44:45], 0, s[58:59]
	v_lshl_add_u64 v[46:47], v[48:49], 0, s[58:59]
	s_waitcnt vmcnt(7) lgkmcnt(0)
; #define WAITL() asm volatile("s_waitcnt lgkmcnt(0)" ::: "memory")
; template <int EPI> ...
;     ...
;         WAITL();
; #pragma unroll
;         for (int m = 0; m < 4; ++m)
; #pragma unroll
;           for (int n = 0; n < 2; ++n)
; #pragma unroll
;             for (int j = 0; j < 4; ++j) ep[(m * 16 + fq * 4 + j) * 32 + n * 16 + fr] = acc[ai][bj][m][n][j];
;         WAITL();
;         const int grow0 = brow + ai * 128 + wr * 64, gcol0 = bcol + bj * 128 + wc * 32;
;         if (EPI == 1) {
;           const size_t idx0 = (size_t)(grow0 + (lane >> 3)) * 2048 + gcol0 + (lane & 7) * 4;
;           const float* xp = xin + idx0; float* op = xout + idx0; const float* lp = ep + (lane >> 3) * 32 + (lane & 7) * 4;
; #pragma unroll
;           for (int i = 0; i < 8; ++i) {
;             const float4 v = *(const float4*)(lp + i * 256);
;             float4 x = *(const float4*)xp;
;             x.x += v.x; x.y += v.y; x.z += v.z; x.w += v.w;
;             *(float4*)op = x;
;             xp += 16384; op += 16384;
;             asm volatile("" : "+v"(xp), "+v"(op));
;           }
	v_pk_add_f32 v[184:185], v[38:39], v[184:185]
	v_pk_add_f32 v[186:187], v[40:41], v[186:187]
	global_store_dwordx4 v[48:49], v[184:187], off
	ds_read_b128 v[38:41], v157 offset:3072
	v_lshl_add_u64 v[44:45], v[44:45], 0, s[58:59]
	v_lshl_add_u64 v[48:49], v[46:47], 0, s[58:59]
	s_waitcnt vmcnt(7) lgkmcnt(0)
	v_pk_add_f32 v[188:189], v[38:39], v[188:189]
	v_pk_add_f32 v[190:191], v[40:41], v[190:191]
	global_store_dwordx4 v[46:47], v[188:191], off
	ds_read_b128 v[38:41], v157 offset:4096
	v_lshl_add_u64 v[44:45], v[44:45], 0, s[58:59]
	v_lshl_add_u64 v[46:47], v[48:49], 0, s[58:59]
	s_waitcnt vmcnt(7) lgkmcnt(0)
	v_pk_add_f32 v[192:193], v[38:39], v[192:193]
	v_pk_add_f32 v[194:195], v[40:41], v[194:195]
	global_store_dwordx4 v[48:49], v[192:195], off
	ds_read_b128 v[38:41], v157 offset:5120
	v_lshl_add_u64 v[44:45], v[44:45], 0, s[58:59]
	v_lshl_add_u64 v[48:49], v[46:47], 0, s[58:59]
	s_waitcnt vmcnt(7) lgkmcnt(0)
	v_pk_add_f32 v[196:197], v[38:39], v[196:197]
	v_pk_add_f32 v[198:199], v[40:41], v[198:199]
	global_store_dwordx4 v[46:47], v[196:199], off
	ds_read_b128 v[38:41], v157 offset:6144
	v_lshl_add_u64 v[44:45], v[44:45], 0, s[58:59]
	v_lshl_add_u64 v[46:47], v[48:49], 0, s[58:59]
	s_waitcnt vmcnt(7) lgkmcnt(0)
	v_pk_add_f32 v[200:201], v[38:39], v[200:201]
	v_pk_add_f32 v[202:203], v[40:41], v[202:203]
	global_store_dwordx4 v[48:49], v[200:203], off
	ds_read_b128 v[38:41], v157 offset:7168
	v_lshl_add_u64 v[44:45], v[44:45], 0, s[58:59]
	v_lshl_add_u64 v[48:49], v[46:47], 0, s[58:59]
	s_waitcnt vmcnt(7) lgkmcnt(0)
	v_pk_add_f32 v[204:205], v[38:39], v[204:205]
	v_pk_add_f32 v[206:207], v[40:41], v[206:207]
	global_store_dwordx4 v[46:47], v[204:207], off
	s_waitcnt lgkmcnt(0)
	ds_write2_b32 v158, v2, v18 offset1:16
	ds_write2_b32 v158, v3, v19 offset0:32 offset1:48
	ds_write2_b32 v158, v4, v20 offset0:64 offset1:80
	ds_write2_b32 v158, v5, v21 offset0:96 offset1:112
	ds_write2_b32 v114, v6, v22 offset1:16
	ds_write2_b32 v114, v7, v23 offset0:32 offset1:48
	ds_write2_b32 v114, v8, v24 offset0:64 offset1:80
	ds_write2_b32 v114, v9, v25 offset0:96 offset1:112
	ds_write2_b32 v106, v10, v26 offset1:16
	ds_write2_b32 v106, v11, v27 offset0:32 offset1:48
	ds_write2_b32 v106, v12, v28 offset0:64 offset1:80
	ds_write2_b32 v106, v13, v29 offset0:96 offset1:112
	ds_write2_b32 v102, v14, v30 offset1:16
	ds_write2_b32 v102, v15, v31 offset0:32 offset1:48
	ds_write2_b32 v102, v16, v32 offset0:64 offset1:80
	ds_write2_b32 v102, v17, v33 offset0:96 offset1:112
	s_waitcnt lgkmcnt(0)
	global_load_dwordx4 v[176:179], v[80:81], off offset:512
	v_lshl_add_u64 v[208:209], v[80:81], 0, s[60:61]
	global_load_dwordx4 v[180:183], v[208:209], off
	v_lshl_add_u64 v[208:209], v[208:209], 0, s[58:59]
	global_load_dwordx4 v[184:187], v[208:209], off
	v_lshl_add_u64 v[208:209], v[208:209], 0, s[58:59]
	global_load_dwordx4 v[188:191], v[208:209], off
	v_lshl_add_u64 v[208:209], v[208:209], 0, s[58:59]
	global_load_dwordx4 v[192:195], v[208:209], off
	v_lshl_add_u64 v[208:209], v[208:209], 0, s[58:59]
	global_load_dwordx4 v[196:199], v[208:209], off
	v_lshl_add_u64 v[208:209], v[208:209], 0, s[58:59]
	global_load_dwordx4 v[200:203], v[208:209], off
	v_lshl_add_u64 v[208:209], v[208:209], 0, s[58:59]
	global_load_dwordx4 v[204:207], v[208:209], off
	ds_read_b128 v[6:9], v157
	v_lshl_add_u64 v[10:11], v[80:81], 0, s[60:61]
	v_lshl_add_u64 v[12:13], v[42:43], 0, s[60:61]
	s_waitcnt vmcnt(7) lgkmcnt(0)
	v_pk_add_f32 v[176:177], v[6:7], v[176:177]
	v_pk_add_f32 v[178:179], v[8:9], v[178:179]
	global_store_dwordx4 v[42:43], v[176:179], off offset:512
	ds_read_b128 v[6:9], v157 offset:1024
	v_lshl_add_u64 v[10:11], v[10:11], 0, s[58:59]
	v_lshl_add_u64 v[14:15], v[12:13], 0, s[58:59]
	s_waitcnt vmcnt(7) lgkmcnt(0)
	v_pk_add_f32 v[180:181], v[6:7], v[180:181]
	v_pk_add_f32 v[182:183], v[8:9], v[182:183]
	global_store_dwordx4 v[12:13], v[180:183], off
	ds_read_b128 v[6:9], v157 offset:2048
	v_lshl_add_u64 v[10:11], v[10:11], 0, s[58:59]
	v_lshl_add_u64 v[12:13], v[14:15], 0, s[58:59]
	s_waitcnt vmcnt(7) lgkmcnt(0)
	v_pk_add_f32 v[184:185], v[6:7], v[184:185]
	v_pk_add_f32 v[186:187], v[8:9], v[186:187]
	global_store_dwordx4 v[14:15], v[184:187], off
	ds_read_b128 v[6:9], v157 offset:3072
	v_lshl_add_u64 v[10:11], v[10:11], 0, s[58:59]
	v_lshl_add_u64 v[14:15], v[12:13], 0, s[58:59]
	s_waitcnt vmcnt(7) lgkmcnt(0)
	v_pk_add_f32 v[188:189], v[6:7], v[188:189]
	v_pk_add_f32 v[190:191], v[8:9], v[190:191]
	global_store_dwordx4 v[12:13], v[188:191], off
	ds_read_b128 v[6:9], v157 offset:4096
	v_lshl_add_u64 v[10:11], v[10:11], 0, s[58:59]
	v_lshl_add_u64 v[12:13], v[14:15], 0, s[58:59]
	s_waitcnt vmcnt(7) lgkmcnt(0)
	v_pk_add_f32 v[192:193], v[6:7], v[192:193]
	v_pk_add_f32 v[194:195], v[8:9], v[194:195]
	global_store_dwordx4 v[14:15], v[192:195], off
	ds_read_b128 v[6:9], v157 offset:5120
	v_lshl_add_u64 v[10:11], v[10:11], 0, s[58:59]
	v_lshl_add_u64 v[14:15], v[12:13], 0, s[58:59]
	s_waitcnt vmcnt(7) lgkmcnt(0)
	v_pk_add_f32 v[196:197], v[6:7], v[196:197]
	v_pk_add_f32 v[198:199], v[8:9], v[198:199]
	global_store_dwordx4 v[12:13], v[196:199], off
	ds_read_b128 v[6:9], v157 offset:6144
	v_lshl_add_u64 v[10:11], v[10:11], 0, s[58:59]
	v_lshl_add_u64 v[12:13], v[14:15], 0, s[58:59]
	s_waitcnt vmcnt(7) lgkmcnt(0)
	v_pk_add_f32 v[200:201], v[6:7], v[200:201]
	v_pk_add_f32 v[202:203], v[8:9], v[202:203]
	global_store_dwordx4 v[14:15], v[200:203], off
	ds_read_b128 v[6:9], v157 offset:7168
	v_lshl_add_u64 v[10:11], v[10:11], 0, s[58:59]
	v_lshl_add_u64 v[14:15], v[12:13], 0, s[58:59]
	s_waitcnt vmcnt(7) lgkmcnt(0)
	v_pk_add_f32 v[204:205], v[6:7], v[204:205]
	v_pk_add_f32 v[206:207], v[8:9], v[206:207]
	global_store_dwordx4 v[12:13], v[204:207], off
	s_waitcnt lgkmcnt(0)
	s_barrier
	s_cbranch_vccz .LBB0_676

; #define WAITL() asm volatile("s_waitcnt lgkmcnt(0)" ::: "memory")
; template <int EPI> ...
;     ...
;         WAITL();
; #pragma unroll
;         for (int m = 0; m < 4; ++m)
; #pragma unroll
;           for (int n = 0; n < 2; ++n)
; #pragma unroll
;             for (int j = 0; j < 4; ++j) ep[(m * 16 + fq * 4 + j) * 32 + n * 16 + fr] = acc[ai][bj][m][n][j];
;         WAITL();
;         const int grow0 = brow + ai * 128 + wr * 64, gcol0 = bcol + bj * 128 + wc * 32;
;         if (EPI == 1) {
;           const size_t idx0 = (size_t)(grow0 + (lane >> 3)) * 2048 + gcol0 + (lane & 7) * 4;
;           const float* xp = xin + idx0; float* op = xout + idx0; const float* lp = ep + (lane >> 3) * 32 + (lane & 7) * 4;
; #pragma unroll
;           for (int i = 0; i < 8; ++i) {
;             const float4 v = *(const float4*)(lp + i * 256);
;             float4 x = *(const float4*)xp;
;             x.x += v.x; x.y += v.y; x.z += v.z; x.w += v.w;
;             *(float4*)op = x;
;             xp += 16384; op += 16384;
;             asm volatile("" : "+v"(xp), "+v"(op));
;           }
.LBB0_770:
	s_waitcnt lgkmcnt(0)
	ds_write2_b32 v159, v114, v126 offset1:16
	ds_write2_b32 v159, v115, v127 offset0:32 offset1:48
	ds_write2_b32 v159, v116, v128 offset0:64 offset1:80
	ds_write2_b32 v159, v117, v129 offset0:96 offset1:112
	v_add_u32_e32 v114, 0x800, v159
	s_and_b32 s35, s37, 0x7fffff8
	v_or_b32_e32 v142, s64, v157
	ds_write2_b32 v114, v106, v122 offset1:16
	ds_write2_b32 v114, v107, v123 offset0:32 offset1:48
	ds_write2_b32 v114, v108, v124 offset0:64 offset1:80
	ds_write2_b32 v114, v109, v125 offset0:96 offset1:112
	v_add_u32_e32 v106, 0x1000, v159
	v_or_b32_e32 v132, s35, v146
	v_ashrrev_i32_e32 v143, 31, v142
	ds_write2_b32 v106, v102, v118 offset1:16
	ds_write2_b32 v106, v103, v119 offset0:32 offset1:48
	ds_write2_b32 v106, v104, v120 offset0:64 offset1:80
	ds_write2_b32 v106, v105, v121 offset0:96 offset1:112
	v_add_u32_e32 v102, 0x1800, v159
	v_lshlrev_b32_e32 v140, 5, v132
	ds_write2_b32 v102, v98, v110 offset1:16
	ds_write2_b32 v102, v99, v111 offset0:32 offset1:48
	ds_write2_b32 v102, v100, v112 offset0:64 offset1:80
	ds_write2_b32 v102, v101, v113 offset0:96 offset1:112
	v_lshlrev_b64 v[98:99], 13, v[142:143]
	v_ashrrev_i32_e32 v141, 31, v140
	v_lshl_add_u64 v[98:99], v[138:139], 0, v[98:99]
	s_waitcnt lgkmcnt(0)
	v_lshl_add_u64 v[98:99], v[140:141], 2, v[98:99]
	global_load_dwordx4 v[176:179], v[98:99], off
	v_lshl_add_u64 v[208:209], v[98:99], 0, s[58:59]
	global_load_dwordx4 v[180:183], v[208:209], off
	v_lshl_add_u64 v[208:209], v[208:209], 0, s[58:59]
	global_load_dwordx4 v[184:187], v[208:209], off
	v_lshl_add_u64 v[208:209], v[208:209], 0, s[58:59]
	global_load_dwordx4 v[188:191], v[208:209], off
	v_lshl_add_u64 v[208:209], v[208:209], 0, s[58:59]
	global_load_dwordx4 v[192:195], v[208:209], off
	v_lshl_add_u64 v[208:209], v[208:209], 0, s[58:59]
	global_load_dwordx4 v[196:199], v[208:209], off
	v_lshl_add_u64 v[208:209], v[208:209], 0, s[58:59]
	global_load_dwordx4 v[200:203], v[208:209], off
	v_lshl_add_u64 v[208:209], v[208:209], 0, s[58:59]
	global_load_dwordx4 v[204:207], v[208:209], off
	ds_read_b128 v[116:119], v158
	v_lshl_add_u64 v[100:101], v[98:99], 0, s[58:59]
	v_mov_b64_e32 v[104:105], v[100:101]
	s_mov_b64 s[36:37], 0x10200
	s_mov_b32 s35, 0x100000
	s_waitcnt vmcnt(7) lgkmcnt(0)
	v_pk_add_f32 v[176:177], v[116:117], v[176:177]
	v_pk_add_f32 v[178:179], v[118:119], v[178:179]
	global_store_dwordx4 v[98:99], v[176:179], off
	ds_read_b128 v[116:119], v158 offset:1024
	v_lshl_add_u64 v[100:101], v[100:101], 0, s[58:59]
	v_lshl_add_u64 v[112:113], v[104:105], 0, s[58:59]
	s_waitcnt vmcnt(7) lgkmcnt(0)
	v_pk_add_f32 v[180:181], v[116:117], v[180:181]
	v_pk_add_f32 v[182:183], v[118:119], v[182:183]
	global_store_dwordx4 v[104:105], v[180:183], off
	ds_read_b128 v[116:119], v158 offset:2048
	v_lshl_add_u64 v[100:101], v[100:101], 0, s[58:59]
	v_lshl_add_u64 v[104:105], v[112:113], 0, s[58:59]
	s_waitcnt vmcnt(7) lgkmcnt(0)
	v_pk_add_f32 v[184:185], v[116:117], v[184:185]
	v_pk_add_f32 v[186:187], v[118:119], v[186:187]
	global_store_dwordx4 v[112:113], v[184:187], off
	ds_read_b128 v[116:119], v158 offset:3072
	v_lshl_add_u64 v[100:101], v[100:101], 0, s[58:59]
	v_lshl_add_u64 v[112:113], v[104:105], 0, s[58:59]
	s_waitcnt vmcnt(7) lgkmcnt(0)
	v_pk_add_f32 v[188:189], v[116:117], v[188:189]
	v_pk_add_f32 v[190:191], v[118:119], v[190:191]
	global_store_dwordx4 v[104:105], v[188:191], off
	ds_read_b128 v[116:119], v158 offset:4096
	v_lshl_add_u64 v[100:101], v[100:101], 0, s[58:59]
	v_lshl_add_u64 v[104:105], v[112:113], 0, s[58:59]
	s_waitcnt vmcnt(7) lgkmcnt(0)
	v_pk_add_f32 v[192:193], v[116:117], v[192:193]
	v_pk_add_f32 v[194:195], v[118:119], v[194:195]
	global_store_dwordx4 v[112:113], v[192:195], off
	ds_read_b128 v[116:119], v158 offset:5120
	v_lshl_add_u64 v[100:101], v[100:101], 0, s[58:59]
	v_lshl_add_u64 v[112:113], v[104:105], 0, s[58:59]
	s_waitcnt vmcnt(7) lgkmcnt(0)
	v_pk_add_f32 v[196:197], v[116:117], v[196:197]
	v_pk_add_f32 v[198:199], v[118:119], v[198:199]
	global_store_dwordx4 v[104:105], v[196:199], off
	ds_read_b128 v[116:119], v158 offset:6144
	v_lshl_add_u64 v[100:101], v[100:101], 0, s[58:59]
	v_lshl_add_u64 v[104:105], v[112:113], 0, s[58:59]
	s_waitcnt vmcnt(7) lgkmcnt(0)
	v_pk_add_f32 v[200:201], v[116:117], v[200:201]
	v_pk_add_f32 v[202:203], v[118:119], v[202:203]
	global_store_dwordx4 v[112:113], v[200:203], off
	ds_read_b128 v[116:119], v158 offset:7168
	v_lshl_add_u64 v[100:101], v[100:101], 0, s[58:59]
	v_lshl_add_u64 v[112:113], v[104:105], 0, s[58:59]
	s_waitcnt vmcnt(7) lgkmcnt(0)
	v_pk_add_f32 v[204:205], v[116:117], v[204:205]
	v_pk_add_f32 v[206:207], v[118:119], v[206:207]
	global_store_dwordx4 v[104:105], v[204:207], off
	s_waitcnt lgkmcnt(0)
	ds_write2_b32 v159, v66, v82 offset1:16
	ds_write2_b32 v159, v67, v83 offset0:32 offset1:48
	ds_write2_b32 v159, v68, v84 offset0:64 offset1:80
	ds_write2_b32 v159, v69, v85 offset0:96 offset1:112
	ds_write2_b32 v114, v70, v86 offset1:16
	ds_write2_b32 v114, v71, v87 offset0:32 offset1:48
	ds_write2_b32 v114, v72, v88 offset0:64 offset1:80
	ds_write2_b32 v114, v73, v89 offset0:96 offset1:112
	ds_write2_b32 v106, v74, v90 offset1:16
	ds_write2_b32 v106, v75, v91 offset0:32 offset1:48
	ds_write2_b32 v106, v76, v92 offset0:64 offset1:80
	ds_write2_b32 v106, v77, v93 offset0:96 offset1:112
	ds_write2_b32 v102, v78, v94 offset1:16
	ds_write2_b32 v102, v79, v95 offset0:32 offset1:48
	ds_write2_b32 v102, v80, v96 offset0:64 offset1:80
	ds_write2_b32 v102, v81, v97 offset0:96 offset1:112
	s_waitcnt lgkmcnt(0)
; #define WAITL() asm volatile("s_waitcnt lgkmcnt(0)" ::: "memory")
; template <int EPI> ...
;     ...
;         WAITL();
; #pragma unroll
;         for (int m = 0; m < 4; ++m)
; #pragma unroll
;           for (int n = 0; n < 2; ++n)
; #pragma unroll
;             for (int j = 0; j < 4; ++j) ep[(m * 16 + fq * 4 + j) * 32 + n * 16 + fr] = acc[ai][bj][m][n][j];
;         WAITL();
;         const int grow0 = brow + ai * 128 + wr * 64, gcol0 = bcol + bj * 128 + wc * 32;
;         if (EPI == 1) {
;           const size_t idx0 = (size_t)(grow0 + (lane >> 3)) * 2048 + gcol0 + (lane & 7) * 4;
;           const float* xp = xin + idx0; float* op = xout + idx0; const float* lp = ep + (lane >> 3) * 32 + (lane & 7) * 4;
; #pragma unroll
;           for (int i = 0; i < 8; ++i) {
;             const float4 v = *(const float4*)(lp + i * 256);
;             float4 x = *(const float4*)xp;
;             x.x += v.x; x.y += v.y; x.z += v.z; x.w += v.w;
;             *(float4*)op = x;
;             xp += 16384; op += 16384;
;             asm volatile("" : "+v"(xp), "+v"(op));
;           }
	global_load_dwordx4 v[176:179], v[98:99], off offset:512
	v_lshl_add_u64 v[208:209], v[98:99], 0, s[36:37]
	global_load_dwordx4 v[180:183], v[208:209], off
	v_lshl_add_u64 v[208:209], v[208:209], 0, s[58:59]
	global_load_dwordx4 v[184:187], v[208:209], off
	v_lshl_add_u64 v[208:209], v[208:209], 0, s[58:59]
	global_load_dwordx4 v[188:191], v[208:209], off
	v_lshl_add_u64 v[208:209], v[208:209], 0, s[58:59]
	global_load_dwordx4 v[192:195], v[208:209], off
	v_lshl_add_u64 v[208:209], v[208:209], 0, s[58:59]
	global_load_dwordx4 v[196:199], v[208:209], off
	v_lshl_add_u64 v[208:209], v[208:209], 0, s[58:59]
	global_load_dwordx4 v[200:203], v[208:209], off
	v_lshl_add_u64 v[208:209], v[208:209], 0, s[58:59]
	global_load_dwordx4 v[204:207], v[208:209], off
	ds_read_b128 v[70:73], v158
	v_lshl_add_u64 v[74:75], v[98:99], 0, s[36:37]
	v_mov_b64_e32 v[76:77], v[74:75]
	s_mov_b64 s[36:37], 0x110000
	s_waitcnt vmcnt(7) lgkmcnt(0)
	v_pk_add_f32 v[176:177], v[70:71], v[176:177]
	v_pk_add_f32 v[178:179], v[72:73], v[178:179]
	global_store_dwordx4 v[98:99], v[176:179], off offset:512
	ds_read_b128 v[70:73], v158 offset:1024
	v_lshl_add_u64 v[74:75], v[74:75], 0, s[58:59]
	v_lshl_add_u64 v[78:79], v[76:77], 0, s[58:59]
	s_waitcnt vmcnt(7) lgkmcnt(0)
	v_pk_add_f32 v[180:181], v[70:71], v[180:181]
	v_pk_add_f32 v[182:183], v[72:73], v[182:183]
	global_store_dwordx4 v[76:77], v[180:183], off
	ds_read_b128 v[70:73], v158 offset:2048
	v_lshl_add_u64 v[74:75], v[74:75], 0, s[58:59]
	v_lshl_add_u64 v[76:77], v[78:79], 0, s[58:59]
	s_waitcnt vmcnt(7) lgkmcnt(0)
	v_pk_add_f32 v[184:185], v[70:71], v[184:185]
	v_pk_add_f32 v[186:187], v[72:73], v[186:187]
	global_store_dwordx4 v[78:79], v[184:187], off
	ds_read_b128 v[70:73], v158 offset:3072
	v_lshl_add_u64 v[74:75], v[74:75], 0, s[58:59]
	v_lshl_add_u64 v[78:79], v[76:77], 0, s[58:59]
	s_waitcnt vmcnt(7) lgkmcnt(0)
	v_pk_add_f32 v[188:189], v[70:71], v[188:189]
	v_pk_add_f32 v[190:191], v[72:73], v[190:191]
	global_store_dwordx4 v[76:77], v[188:191], off
	ds_read_b128 v[70:73], v158 offset:4096
	v_lshl_add_u64 v[74:75], v[74:75], 0, s[58:59]
	v_lshl_add_u64 v[76:77], v[78:79], 0, s[58:59]
	s_waitcnt vmcnt(7) lgkmcnt(0)
	v_pk_add_f32 v[192:193], v[70:71], v[192:193]
	v_pk_add_f32 v[194:195], v[72:73], v[194:195]
	global_store_dwordx4 v[78:79], v[192:195], off
	ds_read_b128 v[70:73], v158 offset:5120
	v_lshl_add_u64 v[74:75], v[74:75], 0, s[58:59]
	v_lshl_add_u64 v[78:79], v[76:77], 0, s[58:59]
	s_waitcnt vmcnt(7) lgkmcnt(0)
	v_pk_add_f32 v[196:197], v[70:71], v[196:197]
	v_pk_add_f32 v[198:199], v[72:73], v[198:199]
	global_store_dwordx4 v[76:77], v[196:199], off
	ds_read_b128 v[70:73], v158 offset:6144
	v_lshl_add_u64 v[74:75], v[74:75], 0, s[58:59]
	v_lshl_add_u64 v[76:77], v[78:79], 0, s[58:59]
	s_waitcnt vmcnt(7) lgkmcnt(0)
	v_pk_add_f32 v[200:201], v[70:71], v[200:201]
	v_pk_add_f32 v[202:203], v[72:73], v[202:203]
	global_store_dwordx4 v[78:79], v[200:203], off
	ds_read_b128 v[70:73], v158 offset:7168
	v_lshl_add_u64 v[74:75], v[74:75], 0, s[58:59]
	v_lshl_add_u64 v[80:81], v[76:77], 0, s[58:59]
	v_add_co_u32_e32 v78, vcc, s35, v98
	s_waitcnt vmcnt(7) lgkmcnt(0)
	v_pk_add_f32 v[204:205], v[70:71], v[204:205]
	v_pk_add_f32 v[206:207], v[72:73], v[206:207]
	global_store_dwordx4 v[76:77], v[204:207], off
	s_waitcnt lgkmcnt(0)
	ds_write2_b32 v159, v34, v50 offset1:16
	ds_write2_b32 v159, v35, v51 offset0:32 offset1:48
	ds_write2_b32 v159, v36, v52 offset0:64 offset1:80
	ds_write2_b32 v159, v37, v53 offset0:96 offset1:112
	ds_write2_b32 v114, v38, v54 offset1:16
	ds_write2_b32 v114, v39, v55 offset0:32 offset1:48
	ds_write2_b32 v114, v40, v56 offset0:64 offset1:80
	ds_write2_b32 v114, v41, v57 offset0:96 offset1:112
	ds_write2_b32 v106, v42, v58 offset1:16
	ds_write2_b32 v106, v43, v59 offset0:32 offset1:48
	ds_write2_b32 v106, v44, v60 offset0:64 offset1:80
	ds_write2_b32 v106, v45, v61 offset0:96 offset1:112
	ds_write2_b32 v102, v46, v62 offset1:16
	ds_write2_b32 v102, v47, v63 offset0:32 offset1:48
	ds_write2_b32 v102, v48, v64 offset0:64 offset1:80
	ds_write2_b32 v102, v49, v65 offset0:96 offset1:112
	v_addc_co_u32_e32 v79, vcc, 0, v99, vcc
	s_waitcnt lgkmcnt(0)
	global_load_dwordx4 v[176:179], v[78:79], off
	v_lshl_add_u64 v[208:209], v[98:99], 0, s[36:37]
	global_load_dwordx4 v[180:183], v[208:209], off
	v_lshl_add_u64 v[208:209], v[208:209], 0, s[58:59]
	global_load_dwordx4 v[184:187], v[208:209], off
	v_lshl_add_u64 v[208:209], v[208:209], 0, s[58:59]
	global_load_dwordx4 v[188:191], v[208:209], off
	v_lshl_add_u64 v[208:209], v[208:209], 0, s[58:59]
	global_load_dwordx4 v[192:195], v[208:209], off
	v_lshl_add_u64 v[208:209], v[208:209], 0, s[58:59]
	global_load_dwordx4 v[196:199], v[208:209], off
	v_lshl_add_u64 v[208:209], v[208:209], 0, s[58:59]
	global_load_dwordx4 v[200:203], v[208:209], off
	v_lshl_add_u64 v[208:209], v[208:209], 0, s[58:59]
	global_load_dwordx4 v[204:207], v[208:209], off
	ds_read_b128 v[38:41], v158
	v_lshl_add_u64 v[42:43], v[98:99], 0, s[36:37]
	v_mov_b64_e32 v[44:45], v[42:43]
	s_mov_b64 s[36:37], 0x110200
	s_andn2_b64 vcc, exec, s[60:61]
	s_waitcnt vmcnt(7) lgkmcnt(0)
	v_pk_add_f32 v[176:177], v[38:39], v[176:177]
	v_pk_add_f32 v[178:179], v[40:41], v[178:179]
	global_store_dwordx4 v[78:79], v[176:179], off
	ds_read_b128 v[38:41], v158 offset:1024
	v_lshl_add_u64 v[42:43], v[42:43], 0, s[58:59]
	v_lshl_add_u64 v[46:47], v[44:45], 0, s[58:59]
	s_waitcnt vmcnt(7) lgkmcnt(0)
	v_pk_add_f32 v[180:181], v[38:39], v[180:181]
	v_pk_add_f32 v[182:183], v[40:41], v[182:183]
	global_store_dwordx4 v[44:45], v[180:183], off
	ds_read_b128 v[38:41], v158 offset:2048
	v_lshl_add_u64 v[42:43], v[42:43], 0, s[58:59]
	v_lshl_add_u64 v[44:45], v[46:47], 0, s[58:59]
	s_waitcnt vmcnt(7) lgkmcnt(0)
; #define WAITL() asm volatile("s_waitcnt lgkmcnt(0)" ::: "memory")
; template <int EPI> ...
;     ...
;         WAITL();
; #pragma unroll
;         for (int m = 0; m < 4; ++m)
; #pragma unroll
;           for (int n = 0; n < 2; ++n)
; #pragma unroll
;             for (int j = 0; j < 4; ++j) ep[(m * 16 + fq * 4 + j) * 32 + n * 16 + fr] = acc[ai][bj][m][n][j];
;         WAITL();
;         const int grow0 = brow + ai * 128 + wr * 64, gcol0 = bcol + bj * 128 + wc * 32;
;         if (EPI == 1) {
;           const size_t idx0 = (size_t)(grow0 + (lane >> 3)) * 2048 + gcol0 + (lane & 7) * 4;
;           const float* xp = xin + idx0; float* op = xout + idx0; const float* lp = ep + (lane >> 3) * 32 + (lane & 7) * 4;
; #pragma unroll
;           for (int i = 0; i < 8; ++i) {
;             const float4 v = *(const float4*)(lp + i * 256);
;             float4 x = *(const float4*)xp;
;             x.x += v.x; x.y += v.y; x.z += v.z; x.w += v.w;
;             *(float4*)op = x;
;             xp += 16384; op += 16384;
;             asm volatile("" : "+v"(xp), "+v"(op));
;           }
	v_pk_add_f32 v[184:185], v[38:39], v[184:185]
	v_pk_add_f32 v[186:187], v[40:41], v[186:187]
	global_store_dwordx4 v[46:47], v[184:187], off
	ds_read_b128 v[38:41], v158 offset:3072
	v_lshl_add_u64 v[42:43], v[42:43], 0, s[58:59]
	v_lshl_add_u64 v[46:47], v[44:45], 0, s[58:59]
	s_waitcnt vmcnt(7) lgkmcnt(0)
	v_pk_add_f32 v[188:189], v[38:39], v[188:189]
	v_pk_add_f32 v[190:191], v[40:41], v[190:191]
	global_store_dwordx4 v[44:45], v[188:191], off
	ds_read_b128 v[38:41], v158 offset:4096
	v_lshl_add_u64 v[42:43], v[42:43], 0, s[58:59]
	v_lshl_add_u64 v[44:45], v[46:47], 0, s[58:59]
	s_waitcnt vmcnt(7) lgkmcnt(0)
	v_pk_add_f32 v[192:193], v[38:39], v[192:193]
	v_pk_add_f32 v[194:195], v[40:41], v[194:195]
	global_store_dwordx4 v[46:47], v[192:195], off
	ds_read_b128 v[38:41], v158 offset:5120
	v_lshl_add_u64 v[42:43], v[42:43], 0, s[58:59]
	v_lshl_add_u64 v[46:47], v[44:45], 0, s[58:59]
	s_waitcnt vmcnt(7) lgkmcnt(0)
	v_pk_add_f32 v[196:197], v[38:39], v[196:197]
	v_pk_add_f32 v[198:199], v[40:41], v[198:199]
	global_store_dwordx4 v[44:45], v[196:199], off
	ds_read_b128 v[38:41], v158 offset:6144
	v_lshl_add_u64 v[42:43], v[42:43], 0, s[58:59]
	v_lshl_add_u64 v[44:45], v[46:47], 0, s[58:59]
	s_waitcnt vmcnt(7) lgkmcnt(0)
	v_pk_add_f32 v[200:201], v[38:39], v[200:201]
	v_pk_add_f32 v[202:203], v[40:41], v[202:203]
	global_store_dwordx4 v[46:47], v[200:203], off
	ds_read_b128 v[38:41], v158 offset:7168
	v_lshl_add_u64 v[42:43], v[42:43], 0, s[58:59]
	v_lshl_add_u64 v[48:49], v[44:45], 0, s[58:59]
	v_lshl_add_u64 v[46:47], v[98:99], 0, s[4:5]
	s_waitcnt vmcnt(7) lgkmcnt(0)
	v_pk_add_f32 v[204:205], v[38:39], v[204:205]
	v_pk_add_f32 v[206:207], v[40:41], v[206:207]
	global_store_dwordx4 v[44:45], v[204:207], off
	s_waitcnt lgkmcnt(0)
	ds_write2_b32 v159, v2, v18 offset1:16
	ds_write2_b32 v159, v3, v19 offset0:32 offset1:48
	ds_write2_b32 v159, v4, v20 offset0:64 offset1:80
	ds_write2_b32 v159, v5, v21 offset0:96 offset1:112
	ds_write2_b32 v114, v6, v22 offset1:16
	ds_write2_b32 v114, v7, v23 offset0:32 offset1:48
	ds_write2_b32 v114, v8, v24 offset0:64 offset1:80
	ds_write2_b32 v114, v9, v25 offset0:96 offset1:112
	ds_write2_b32 v106, v10, v26 offset1:16
	ds_write2_b32 v106, v11, v27 offset0:32 offset1:48
	ds_write2_b32 v106, v12, v28 offset0:64 offset1:80
	ds_write2_b32 v106, v13, v29 offset0:96 offset1:112
	ds_write2_b32 v102, v14, v30 offset1:16
	ds_write2_b32 v102, v15, v31 offset0:32 offset1:48
	ds_write2_b32 v102, v16, v32 offset0:64 offset1:80
	ds_write2_b32 v102, v17, v33 offset0:96 offset1:112
	s_waitcnt lgkmcnt(0)
	global_load_dwordx4 v[176:179], v[46:47], off offset:512
	v_lshl_add_u64 v[208:209], v[98:99], 0, s[36:37]
	global_load_dwordx4 v[180:183], v[208:209], off
	v_lshl_add_u64 v[208:209], v[208:209], 0, s[58:59]
	global_load_dwordx4 v[184:187], v[208:209], off
	v_lshl_add_u64 v[208:209], v[208:209], 0, s[58:59]
	global_load_dwordx4 v[188:191], v[208:209], off
	v_lshl_add_u64 v[208:209], v[208:209], 0, s[58:59]
	global_load_dwordx4 v[192:195], v[208:209], off
	v_lshl_add_u64 v[208:209], v[208:209], 0, s[58:59]
	global_load_dwordx4 v[196:199], v[208:209], off
	v_lshl_add_u64 v[208:209], v[208:209], 0, s[58:59]
	global_load_dwordx4 v[200:203], v[208:209], off
	v_lshl_add_u64 v[208:209], v[208:209], 0, s[58:59]
	global_load_dwordx4 v[204:207], v[208:209], off
	ds_read_b128 v[6:9], v158
	v_lshl_add_u64 v[10:11], v[98:99], 0, s[36:37]
	v_mov_b64_e32 v[12:13], v[10:11]
	s_mov_b32 s37, s34
	s_waitcnt vmcnt(7) lgkmcnt(0)
	v_pk_add_f32 v[176:177], v[6:7], v[176:177]
	v_pk_add_f32 v[178:179], v[8:9], v[178:179]
	global_store_dwordx4 v[46:47], v[176:179], off offset:512
	ds_read_b128 v[6:9], v158 offset:1024
	v_lshl_add_u64 v[10:11], v[10:11], 0, s[58:59]
	v_lshl_add_u64 v[14:15], v[12:13], 0, s[58:59]
	s_waitcnt vmcnt(7) lgkmcnt(0)
	v_pk_add_f32 v[180:181], v[6:7], v[180:181]
	v_pk_add_f32 v[182:183], v[8:9], v[182:183]
	global_store_dwordx4 v[12:13], v[180:183], off
	ds_read_b128 v[6:9], v158 offset:2048
	v_lshl_add_u64 v[10:11], v[10:11], 0, s[58:59]
	v_lshl_add_u64 v[12:13], v[14:15], 0, s[58:59]
	s_waitcnt vmcnt(7) lgkmcnt(0)
	v_pk_add_f32 v[184:185], v[6:7], v[184:185]
	v_pk_add_f32 v[186:187], v[8:9], v[186:187]
	global_store_dwordx4 v[14:15], v[184:187], off
	ds_read_b128 v[6:9], v158 offset:3072
	v_lshl_add_u64 v[10:11], v[10:11], 0, s[58:59]
	v_lshl_add_u64 v[14:15], v[12:13], 0, s[58:59]
	s_waitcnt vmcnt(7) lgkmcnt(0)
	v_pk_add_f32 v[188:189], v[6:7], v[188:189]
	v_pk_add_f32 v[190:191], v[8:9], v[190:191]
	global_store_dwordx4 v[12:13], v[188:191], off
	ds_read_b128 v[6:9], v158 offset:4096
	v_lshl_add_u64 v[10:11], v[10:11], 0, s[58:59]
	v_lshl_add_u64 v[12:13], v[14:15], 0, s[58:59]
	s_waitcnt vmcnt(7) lgkmcnt(0)
	v_pk_add_f32 v[192:193], v[6:7], v[192:193]
	v_pk_add_f32 v[194:195], v[8:9], v[194:195]
	global_store_dwordx4 v[14:15], v[192:195], off
	ds_read_b128 v[6:9], v158 offset:5120
	v_lshl_add_u64 v[10:11], v[10:11], 0, s[58:59]
	v_lshl_add_u64 v[14:15], v[12:13], 0, s[58:59]
	s_waitcnt vmcnt(7) lgkmcnt(0)
	v_pk_add_f32 v[196:197], v[6:7], v[196:197]
	v_pk_add_f32 v[198:199], v[8:9], v[198:199]
	global_store_dwordx4 v[12:13], v[196:199], off
	ds_read_b128 v[6:9], v158 offset:6144
	v_lshl_add_u64 v[10:11], v[10:11], 0, s[58:59]
	v_lshl_add_u64 v[12:13], v[14:15], 0, s[58:59]
	s_waitcnt vmcnt(7) lgkmcnt(0)
	v_pk_add_f32 v[200:201], v[6:7], v[200:201]
	v_pk_add_f32 v[202:203], v[8:9], v[202:203]
	global_store_dwordx4 v[14:15], v[200:203], off
	ds_read_b128 v[6:9], v158 offset:7168
	v_lshl_add_u64 v[10:11], v[10:11], 0, s[58:59]
	v_lshl_add_u64 v[14:15], v[12:13], 0, s[58:59]
	s_waitcnt vmcnt(7) lgkmcnt(0)
	v_pk_add_f32 v[204:205], v[6:7], v[204:205]
	v_pk_add_f32 v[206:207], v[8:9], v[206:207]
	global_store_dwordx4 v[12:13], v[204:207], off
	s_waitcnt lgkmcnt(0)
	s_barrier
	s_cbranch_vccz .LBB0_787

; DEVI void rwkv_prep_item(const Params& p, const int l, const int item, char* smem) {
;     ...
;     for (int r = 0; r < 16; ++r) {
;       const int t = t0 + mt * 32 + (r & 3) + 8 * (r >> 2) + 4 * hi; const bool has_prev = (t & (SEQ_ - 1)) != 0;
;       float rv[2], kv[2], vv[2], av[2], kkv[2], kpv[2], omdv[2], gv[2];
;       float ssq = 0.f, bon = 0.f;
;       const u16* pr = PA + (size_t)t * 2560 + h * 64 + 2 * l31;
;       const unsigned cr2 = *(const unsigned*)pr, ck2 = *(const unsigned*)(pr + 768), cv2 = *(const unsigned*)(pr + 1536);
;       unsigned qr2 = 0u, qk2 = 0u, qv2 = 0u;
;       if (has_prev) { qr2 = *(const unsigned*)(pr - 2560); qk2 = *(const unsigned*)(pr + 768 - 2560); qv2 = *(const unsigned*)(pr + 1536 - 2560); }
; #pragma unroll
;       for (int n = 0; n < 2; ++n) {
;         const float cr = __uint_as_float(n ? (cr2 & 0xffff0000u) : (cr2 << 16)), ck = __uint_as_float(n ? (ck2 & 0xffff0000u) : (ck2 << 16)), cv = __uint_as_float(n ? (cv2 & 0xffff0000u) : (cv2 << 16));
;         const float qr = __uint_as_float(n ? (qr2 & 0xffff0000u) : (qr2 << 16)), qk = __uint_as_float(n ? (qk2 & 0xffff0000u) : (qk2 << 16)), qv = __uint_as_float(n ? (qv2 & 0xffff0000u) : (qv2 << 16));
;         rv[n] = cr + (qr - cr) * mur[n]; kv[n] = ck + (qk - ck) * muk[n]; vv[n] = cv + (qv - cv) * muv[n];
;         const float z = -(w0c[n] + aw[n][r]);
;         const float sp = fmaxf(z, 0.f) + __logf(1.f + __expf(-fabsf(z)));
;         const float ew = __expf(-sp - 0.5f);
;         omdv[n] = 1.f - __expf(-ew);
;         av[n] = sigmoidf_(a0c[n] + aa[n][r]);
;         gv[n] = ag[n][r];
;         kkv[n] = kv[n] * kkc[n];
;         kpv[n] = kv[n] * (1.f + (av[n] - 1.f) * kac[n]);
;         ssq += kkv[n] * kkv[n];
;         bon += rv[n] * kpv[n] * rkc[n];
;       }
;       ssq = reduce32(ssq); bon = reduce32(bon);
;       const float rn = rsqrtf(ssq + 1e-12f);
;       {
;         typedef _Float16 h2 __attribute__((ext_vector_type(2)));
;         const size_t o = (size_t)t * 768 + h * 64 + 2 * l31;
;         const float kn0 = kkv[0] * rn, kn1 = kkv[1] * rn;
;         *(h2*)(RW + o) = (h2){(f16)rv[0], (f16)rv[1]};
;         *(h2*)(RW + TS + o) = (h2){(f16)omdv[0], (f16)omdv[1]};
;         *(h2*)(RW + 2 * TS + o) = (h2){(f16)kpv[0], (f16)kpv[1]};
;         *(h2*)(RW + 3 * TS + o) = (h2){(f16)vv[0], (f16)vv[1]};
;         *(h2*)(RW + 4 * TS + o) = (h2){(f16)kn0, (f16)kn1};
.LBB0_1228:
	s_or_b64 exec, exec, s[6:7]
	s_waitcnt vmcnt(10)
	s_nop 7
	v_add_f32_e32 v82, v82, v210
	s_waitcnt vmcnt(1)
	v_and_b32_e32 v223, 0xffff0000, v219
	v_lshlrev_b32_e32 v222, 16, v219
	v_mul_f32_e64 v219, |v82|, s89
	v_exp_f32_e32 v219, v219
	s_waitcnt vmcnt(0)
	v_or_b32_e32 v253, 1, v233
	v_mad_i64_i32 v[254:255], s[86:87], v253, s88, v[212:213]
	global_load_dword v246, v[254:255], off
	global_load_dword v247, v[254:255], off offset:1536
	global_load_dword v248, v[254:255], off offset:3072
	global_load_dword v249, v[254:255], off offset:-2048
	global_load_dword v250, v[254:255], off offset:-3584
	v_add_co_u32_e32 v254, vcc, 0xfffff000, v254
	s_nop 1
	v_addc_co_u32_e32 v255, vcc, -1, v255, vcc
	global_load_dword v251, v[254:255], off offset:-1024
	v_and_b32_e32 v225, 0xffff0000, v217
	v_lshlrev_b32_e32 v224, 16, v217
	v_and_b32_e32 v215, 0xffff0000, v220
	v_add_f32_e32 v217, 1.0, v219
	v_cmp_gt_f32_e32 vcc, s90, v217
	v_lshlrev_b32_e32 v214, 16, v220
	v_max_f32_e64 v82, -v82, 0
	v_cndmask_b32_e64 v219, 0, 32, vcc
	v_ldexp_f32 v217, v217, v219
	v_log_f32_e32 v217, v217
	v_add_f32_e32 v34, v34, v211
	v_add_f32_e32 v66, v66, v208
	v_add_f32_e32 v50, v50, v209
	v_mul_f32_e32 v220, 0x3f317217, v217
	v_fma_f32 v220, v217, s91, -v220
	v_fmac_f32_e32 v220, 0x3377d1cf, v217
	v_fmac_f32_e32 v220, 0x3f317217, v217
	v_cmp_lt_f32_e64 s[6:7], |v217|, s97
	v_mul_f32_e32 v66, 0xbfb8aa3b, v66
	v_mul_f32_e32 v50, 0xbfb8aa3b, v50
	v_cndmask_b32_e64 v217, v217, v220, s[6:7]
	v_cndmask_b32_e32 v220, 0, v232, vcc
	v_sub_f32_e32 v217, v217, v220
	v_add_f32_e32 v82, v82, v217
	v_mul_f32_e64 v217, |v34|, s89
	v_exp_f32_e32 v217, v217
	v_max_f32_e64 v34, -v34, 0
	v_sub_f32_e32 v82, -0.5, v82
	v_mul_f32_e32 v82, 0x3fb8aa3b, v82
	v_add_f32_e32 v217, 1.0, v217
	v_cmp_gt_f32_e32 vcc, s90, v217
	v_exp_f32_e32 v82, v82
	v_and_b32_e32 v235, 0xffff0000, v221
	v_cndmask_b32_e64 v220, 0, 32, vcc
	v_ldexp_f32 v217, v217, v220
	v_log_f32_e32 v217, v217
	v_lshlrev_b32_e32 v234, 16, v221
	v_exp_f32_e32 v221, v50
	v_pk_add_f32 v[234:235], v[234:235], v[214:215] neg_lo:[0,1] neg_hi:[0,1]
	v_mul_f32_e32 v220, 0x3f317217, v217
	v_fma_f32 v220, v217, s91, -v220
	v_fmac_f32_e32 v220, 0x3377d1cf, v217
	v_fmac_f32_e32 v220, 0x3f317217, v217
	v_cmp_lt_f32_e64 s[6:7], |v217|, s97
	v_mul_f32_e32 v82, 0xbfb8aa3b, v82
	v_pk_fma_f32 v[214:215], v[206:207], v[234:235], v[214:215]
	v_cndmask_b32_e64 v217, v217, v220, s[6:7]
	v_cndmask_b32_e32 v220, 0, v232, vcc
	v_sub_f32_e32 v217, v217, v220
	v_add_f32_e32 v34, v34, v217
	v_sub_f32_e32 v34, -0.5, v34
	v_mul_f32_e32 v34, 0x3fb8aa3b, v34
	v_exp_f32_e32 v34, v34
	v_exp_f32_e32 v220, v66
	v_mad_i64_i32 v[236:237], s[6:7], v233, s95, v[102:103]
	v_mul_f32_e32 v34, 0xbfb8aa3b, v34
	v_lshlrev_b64 v[234:235], 1, v[236:237]
	v_exp_f32_e32 v82, v82
	v_exp_f32_e32 v34, v34
	v_cvt_pk_f16_f32 v50, v214, v215
	v_lshl_add_u64 v[236:237], s[58:59], 0, v[234:235]
	v_pk_add_f32 v[220:221], v[220:221], 1.0 op_sel_hi:[1,0]
	global_store_dword v[236:237], v50, off
	v_div_scale_f32 v50, s[6:7], v221, v221, 1.0
	v_rcp_f32_e32 v66, v50
	v_sub_f32_e32 v82, 1.0, v82
	v_sub_f32_e32 v34, 1.0, v34
	v_cvt_pk_f16_f32 v34, v82, v34
	v_lshl_add_u64 v[236:237], s[66:67], 0, v[234:235]
	global_store_dword v[236:237], v34, off
	v_fma_f32 v34, -v50, v66, 1.0
	v_and_b32_e32 v219, 0xffff0000, v218
	v_lshlrev_b32_e32 v218, 16, v218
	v_fmac_f32_e32 v66, v34, v66
	v_div_scale_f32 v34, vcc, 1.0, v221, 1.0
	v_pk_add_f32 v[218:219], v[218:219], v[222:223] neg_lo:[0,1] neg_hi:[0,1]
	v_mul_f32_e32 v82, v34, v66
	v_pk_fma_f32 v[218:219], v[204:205], v[218:219], v[222:223]
	v_fma_f32 v222, -v50, v82, v34
	v_fmac_f32_e32 v82, v222, v66
	v_fma_f32 v34, -v50, v82, v34
	v_div_scale_f32 v50, s[6:7], v220, v220, 1.0
	v_rcp_f32_e32 v222, v50
	v_div_fmas_f32 v34, v34, v66, v82
	v_div_fixup_f32 v221, v34, v221, 1.0
	v_and_b32_e32 v217, 0xffff0000, v216
	v_fma_f32 v34, -v50, v222, 1.0
	v_fmac_f32_e32 v222, v34, v222
	v_div_scale_f32 v34, vcc, 1.0, v220, 1.0
	v_mul_f32_e32 v66, v34, v222
	v_fma_f32 v82, -v50, v66, v34
	v_fmac_f32_e32 v66, v82, v222
	v_fma_f32 v34, -v50, v66, v34
	v_div_fmas_f32 v34, v34, v222, v66
	v_div_fixup_f32 v220, v34, v220, 1.0
	v_pk_add_f32 v[222:223], v[220:221], -1.0 op_sel_hi:[1,0]
	v_lshlrev_b32_e32 v216, 16, v216
	v_pk_fma_f32 v[222:223], v[202:203], v[222:223], 1.0 op_sel_hi:[1,1,0]
	v_mov_b32_e32 v201, v103
	v_pk_mul_f32 v[222:223], v[222:223], v[218:219]
	v_lshl_add_u64 v[200:201], v[200:201], 2, s[60:61]
	v_pk_mul_f32 v[214:215], v[214:215], v[222:223]
	v_cvt_pk_f16_f32 v66, v222, v223
	v_fma_f32 v34, v198, v214, 0
	v_fmac_f32_e32 v34, v199, v215
	v_lshl_add_u64 v[214:215], s[68:69], 0, v[234:235]
	global_store_dword v[214:215], v66, off
	v_pk_add_f32 v[214:215], v[216:217], v[224:225] neg_lo:[0,1] neg_hi:[0,1]
	v_pk_mul_f32 v[216:217], v[194:195], v[218:219]
	v_pk_fma_f32 v[214:215], v[196:197], v[214:215], v[224:225]
	v_pk_mul_f32 v[218:219], v[216:217], v[216:217]
	v_add_f32_dpp v34, v34, v34 quad_perm:[1,0,3,2] row_mask:0xf bank_mask:0xf bound_ctrl:1
	v_add_f32_e32 v66, v218, v219
	v_cvt_pk_f16_f32 v2, v2, v18
	v_add_f32_dpp v34, v34, v34 quad_perm:[2,3,0,1] row_mask:0xf bank_mask:0xf bound_ctrl:1
	v_add_f32_dpp v66, v66, v66 quad_perm:[1,0,3,2] row_mask:0xf bank_mask:0xf bound_ctrl:1
	s_nop 0
	v_add_f32_dpp v34, v34, v34 row_half_mirror row_mask:0xf bank_mask:0xf bound_ctrl:1
	v_add_f32_dpp v66, v66, v66 quad_perm:[2,3,0,1] row_mask:0xf bank_mask:0xf bound_ctrl:1
	s_nop 0
	v_add_f32_dpp v34, v34, v34 row_mirror row_mask:0xf bank_mask:0xf bound_ctrl:1
	v_add_f32_dpp v66, v66, v66 row_half_mirror row_mask:0xf bank_mask:0xf bound_ctrl:1
	v_mov_b32_e32 v50, v34
	s_nop 1
	v_permlane16_swap_b32_e32 v34, v50
	v_add_f32_dpp v66, v66, v66 row_mirror row_mask:0xf bank_mask:0xf bound_ctrl:1
	v_mov_b32_e32 v82, v66
	s_nop 1
	v_permlane16_swap_b32_e32 v66, v82
	v_add_f32_e32 v66, v66, v82
	v_add_f32_e32 v66, 0x2b8cbccc, v66
	v_mul_f32_e32 v82, 0x4b800000, v66
	v_cmp_gt_f32_e32 vcc, s90, v66
	s_nop 1
	v_cndmask_b32_e32 v66, v66, v82, vcc
	v_rsq_f32_e32 v66, v66
	v_cvt_pk_f16_f32 v82, v214, v215
	v_lshl_add_u64 v[214:215], s[70:71], 0, v[234:235]
	global_store_dword v[214:215], v82, off
	v_mul_f32_e32 v82, 0x45800000, v66
	v_cndmask_b32_e32 v66, v66, v82, vcc
	v_pk_mul_f32 v[214:215], v[216:217], v[66:67] op_sel_hi:[1,0]
	v_lshl_add_u64 v[216:217], s[72:73], 0, v[234:235]
	v_cvt_pk_f16_f32 v66, v214, v215
	v_pk_mul_f32 v[214:215], v[220:221], v[214:215]
	global_store_dword v[216:217], v66, off
	v_cvt_pk_f16_f32 v66, v214, v215
	v_lshl_add_u64 v[214:215], s[74:75], 0, v[234:235]
	global_store_dword v[214:215], v66, off
	v_lshl_add_u64 v[214:215], s[78:79], 0, v[234:235]
	global_store_dword v[214:215], v2, off
	s_and_saveexec_b64 s[6:7], s[4:5]
	s_cbranch_execz .LBB0_1230
	v_add_f32_e32 v2, v34, v50
	v_mad_i64_i32 v[214:215], s[86:87], v233, 48, v[200:201]
	global_store_dword v[214:215], v2, off
; DEVI void rwkv_prep_item(const Params& p, const int l, const int item, char* smem) {
;     ...
;     for (int r = 0; r < 16; ++r) {
;       const int t = t0 + mt * 32 + (r & 3) + 8 * (r >> 2) + 4 * hi; const bool has_prev = (t & (SEQ_ - 1)) != 0;
;       float rv[2], kv[2], vv[2], av[2], kkv[2], kpv[2], omdv[2], gv[2];
;       float ssq = 0.f, bon = 0.f;
;       const u16* pr = PA + (size_t)t * 2560 + h * 64 + 2 * l31;
;       const unsigned cr2 = *(const unsigned*)pr, ck2 = *(const unsigned*)(pr + 768), cv2 = *(const unsigned*)(pr + 1536);
;       unsigned qr2 = 0u, qk2 = 0u, qv2 = 0u;
;       if (has_prev) { qr2 = *(const unsigned*)(pr - 2560); qk2 = *(const unsigned*)(pr + 768 - 2560); qv2 = *(const unsigned*)(pr + 1536 - 2560); }
; #pragma unroll
;       for (int n = 0; n < 2; ++n) {
;         const float cr = __uint_as_float(n ? (cr2 & 0xffff0000u) : (cr2 << 16)), ck = __uint_as_float(n ? (ck2 & 0xffff0000u) : (ck2 << 16)), cv = __uint_as_float(n ? (cv2 & 0xffff0000u) : (cv2 << 16));
;         const float qr = __uint_as_float(n ? (qr2 & 0xffff0000u) : (qr2 << 16)), qk = __uint_as_float(n ? (qk2 & 0xffff0000u) : (qk2 << 16)), qv = __uint_as_float(n ? (qv2 & 0xffff0000u) : (qv2 << 16));
;         rv[n] = cr + (qr - cr) * mur[n]; kv[n] = ck + (qk - ck) * muk[n]; vv[n] = cv + (qv - cv) * muv[n];
;         const float z = -(w0c[n] + aw[n][r]);
;         const float sp = fmaxf(z, 0.f) + __logf(1.f + __expf(-fabsf(z)));
;         const float ew = __expf(-sp - 0.5f);
;         omdv[n] = 1.f - __expf(-ew);
;         av[n] = sigmoidf_(a0c[n] + aa[n][r]);
;         gv[n] = ag[n][r];
;         kkv[n] = kv[n] * kkc[n];
;         kpv[n] = kv[n] * (1.f + (av[n] - 1.f) * kac[n]);
;         ssq += kkv[n] * kkv[n];
;         bon += rv[n] * kpv[n] * rkc[n];
;       }
;       ssq = reduce32(ssq); bon = reduce32(bon);
;       const float rn = rsqrtf(ssq + 1e-12f);
;       {
;         typedef _Float16 h2 __attribute__((ext_vector_type(2)));
;         const size_t o = (size_t)t * 768 + h * 64 + 2 * l31;
;         const float kn0 = kkv[0] * rn, kn1 = kkv[1] * rn;
;         *(h2*)(RW + o) = (h2){(f16)rv[0], (f16)rv[1]};
;         *(h2*)(RW + TS + o) = (h2){(f16)omdv[0], (f16)omdv[1]};
;         *(h2*)(RW + 2 * TS + o) = (h2){(f16)kpv[0], (f16)kpv[1]};
;         *(h2*)(RW + 3 * TS + o) = (h2){(f16)vv[0], (f16)vv[1]};
;         *(h2*)(RW + 4 * TS + o) = (h2){(f16)kn0, (f16)kn1};
.LBB0_1230:
	s_or_b64 exec, exec, s[6:7]
	v_or_b32_e32 v2, 1, v233
	v_mad_i64_i32 v[214:215], s[6:7], v2, s88, v[212:213]
	s_waitcnt vmcnt(7)
	v_mov_b32_e32 v18, v246
	v_mov_b32_e32 v34, v247
	v_mov_b32_e32 v50, v248
	v_mov_b32_e32 v66, v249
	v_mov_b32_e32 v82, v250
	v_add_co_u32_e32 v214, vcc, 0xfffff000, v214
	v_add_f32_e32 v35, v35, v211
	s_nop 0
	v_addc_co_u32_e32 v215, vcc, -1, v215, vcc
	v_mov_b32_e32 v216, v251
	v_or_b32_e32 v253, 2, v233
	v_mad_i64_i32 v[254:255], s[86:87], v253, s88, v[212:213]
	global_load_dword v246, v[254:255], off
	global_load_dword v247, v[254:255], off offset:1536
	global_load_dword v248, v[254:255], off offset:3072
	global_load_dword v249, v[254:255], off offset:-2048
	global_load_dword v250, v[254:255], off offset:-3584
	v_add_co_u32_e32 v254, vcc, 0xfffff000, v254
	s_nop 1
	v_addc_co_u32_e32 v255, vcc, -1, v255, vcc
	global_load_dword v251, v[254:255], off offset:-1024
	v_cvt_pk_f16_f32 v3, v3, v19
	s_nop 0
	v_and_b32_e32 v223, 0xffff0000, v18
	v_lshlrev_b32_e32 v222, 16, v18
	v_add_f32_e32 v18, v83, v210
	s_nop 0
	v_and_b32_e32 v219, 0xffff0000, v34
	v_lshlrev_b32_e32 v218, 16, v34
	v_max_f32_e64 v34, -v18, 0
	v_mul_f32_e64 v18, |v18|, s89
	v_exp_f32_e32 v18, v18
	s_nop 0
	v_and_b32_e32 v215, 0xffff0000, v50
	v_lshlrev_b32_e32 v214, 16, v50
	s_nop 0
	v_and_b32_e32 v225, 0xffff0000, v216
	v_add_f32_e32 v18, 1.0, v18
	v_cmp_gt_f32_e32 vcc, s90, v18
	v_lshlrev_b32_e32 v224, 16, v216
	v_and_b32_e32 v217, 0xffff0000, v66
	v_cndmask_b32_e64 v50, 0, 32, vcc
	v_ldexp_f32 v18, v18, v50
	v_log_f32_e32 v18, v18
	v_lshlrev_b32_e32 v216, 16, v66
	v_and_b32_e32 v221, 0xffff0000, v82
	v_lshlrev_b32_e32 v220, 16, v82
	v_mul_f32_e32 v50, 0x3f317217, v18
	v_fma_f32 v50, v18, s91, -v50
	v_fmac_f32_e32 v50, 0x3377d1cf, v18
	v_fmac_f32_e32 v50, 0x3f317217, v18
	v_cmp_lt_f32_e64 s[6:7], |v18|, s97
	s_nop 1
	v_cndmask_b32_e64 v18, v18, v50, s[6:7]
	v_cndmask_b32_e32 v50, 0, v232, vcc
	v_sub_f32_e32 v18, v18, v50
	v_max_f32_e64 v50, -v35, 0
	v_mul_f32_e64 v35, |v35|, s89
	v_exp_f32_e32 v35, v35
	v_add_f32_e32 v18, v34, v18
	v_sub_f32_e32 v18, -0.5, v18
	v_mul_f32_e32 v18, 0x3fb8aa3b, v18
	v_add_f32_e32 v35, 1.0, v35
	v_cmp_gt_f32_e32 vcc, s90, v35
	v_exp_f32_e32 v18, v18
	v_add_f32_e32 v34, v67, v208
	v_cndmask_b32_e64 v66, 0, 32, vcc
	v_ldexp_f32 v35, v35, v66
	v_log_f32_e32 v35, v35
	v_mul_f32_e32 v18, 0xbfb8aa3b, v18
	v_exp_f32_e32 v18, v18
	v_mul_f32_e32 v34, 0xbfb8aa3b, v34
	v_mul_f32_e32 v66, 0x3f317217, v35
	v_fma_f32 v66, v35, s91, -v66
	v_fmac_f32_e32 v66, 0x3377d1cf, v35
	v_fmac_f32_e32 v66, 0x3f317217, v35
	v_cmp_lt_f32_e64 s[6:7], |v35|, s97
	v_exp_f32_e32 v34, v34
	v_sub_f32_e32 v18, 1.0, v18
	v_cndmask_b32_e64 v35, v35, v66, s[6:7]
	v_cndmask_b32_e32 v66, 0, v232, vcc
	v_sub_f32_e32 v35, v35, v66
	v_add_f32_e32 v35, v50, v35
	v_sub_f32_e32 v35, -0.5, v35
	v_mul_f32_e32 v35, 0x3fb8aa3b, v35
	v_exp_f32_e32 v35, v35
	v_mad_i64_i32 v[66:67], s[6:7], v2, s95, v[102:103]
	v_lshlrev_b64 v[66:67], 1, v[66:67]
	v_mul_f32_e32 v35, 0xbfb8aa3b, v35
	v_exp_f32_e32 v35, v35
	v_lshl_add_u64 v[82:83], s[58:59], 0, v[66:67]
	v_sub_f32_e32 v234, 1.0, v35
	v_add_f32_e32 v35, v51, v209
	v_mul_f32_e32 v35, 0xbfb8aa3b, v35
	v_exp_f32_e32 v35, v35
	v_pk_add_f32 v[50:51], v[224:225], v[222:223] neg_lo:[0,1] neg_hi:[0,1]
	v_cvt_pk_f16_f32 v18, v18, v234
	v_pk_fma_f32 v[50:51], v[206:207], v[50:51], v[222:223]
	v_pk_add_f32 v[34:35], v[34:35], 1.0 op_sel_hi:[1,0]
	v_cvt_pk_f16_f32 v222, v50, v51
	global_store_dword v[82:83], v222, off
	v_lshl_add_u64 v[82:83], s[66:67], 0, v[66:67]
	global_store_dword v[82:83], v18, off
	v_pk_add_f32 v[82:83], v[220:221], v[218:219] neg_lo:[0,1] neg_hi:[0,1]
	v_div_scale_f32 v18, s[6:7], v35, v35, 1.0
	v_pk_fma_f32 v[82:83], v[204:205], v[82:83], v[218:219]
	v_rcp_f32_e32 v218, v18
	s_nop 0
	v_fma_f32 v219, -v18, v218, 1.0
	v_fmac_f32_e32 v218, v219, v218
	v_div_scale_f32 v219, vcc, 1.0, v35, 1.0
	v_mul_f32_e32 v220, v219, v218
	v_fma_f32 v221, -v18, v220, v219
	v_fmac_f32_e32 v220, v221, v218
	v_fma_f32 v18, -v18, v220, v219
	v_div_fmas_f32 v18, v18, v218, v220
	v_div_fixup_f32 v219, v18, v35, 1.0
	v_div_scale_f32 v18, s[6:7], v34, v34, 1.0
	v_rcp_f32_e32 v35, v18
	s_nop 0
	v_fma_f32 v218, -v18, v35, 1.0
	v_fmac_f32_e32 v35, v218, v35
	v_div_scale_f32 v218, vcc, 1.0, v34, 1.0
	v_mul_f32_e32 v220, v218, v35
	v_fma_f32 v221, -v18, v220, v218
	v_fmac_f32_e32 v220, v221, v35
	v_fma_f32 v18, -v18, v220, v218
	v_div_fmas_f32 v18, v18, v35, v220
	v_div_fixup_f32 v218, v18, v34, 1.0
	v_pk_add_f32 v[34:35], v[218:219], -1.0 op_sel_hi:[1,0]
	s_nop 0
	v_pk_fma_f32 v[34:35], v[202:203], v[34:35], 1.0 op_sel_hi:[1,1,0]
	s_nop 0
	v_pk_mul_f32 v[220:221], v[34:35], v[82:83]
	s_nop 0
	v_pk_mul_f32 v[34:35], v[50:51], v[220:221]
	v_lshl_add_u64 v[50:51], s[68:69], 0, v[66:67]
	v_fma_f32 v18, v198, v34, 0
	v_fmac_f32_e32 v18, v199, v35
	v_cvt_pk_f16_f32 v35, v220, v221
	global_store_dword v[50:51], v35, off
	v_pk_add_f32 v[50:51], v[216:217], v[214:215] neg_lo:[0,1] neg_hi:[0,1]
	v_add_f32_dpp v18, v18, v18 quad_perm:[1,0,3,2] row_mask:0xf bank_mask:0xf bound_ctrl:1
	v_pk_fma_f32 v[50:51], v[196:197], v[50:51], v[214:215]
	s_nop 0
	v_cvt_pk_f16_f32 v35, v50, v51
	v_lshl_add_u64 v[50:51], s[70:71], 0, v[66:67]
	global_store_dword v[50:51], v35, off
	v_pk_mul_f32 v[50:51], v[194:195], v[82:83]
	v_add_f32_dpp v18, v18, v18 quad_perm:[2,3,0,1] row_mask:0xf bank_mask:0xf bound_ctrl:1
	v_pk_mul_f32 v[82:83], v[50:51], v[50:51]
	s_nop 0
	v_add_f32_e32 v35, v82, v83
	v_add_f32_dpp v18, v18, v18 row_half_mirror row_mask:0xf bank_mask:0xf bound_ctrl:1
	s_nop 0
	v_add_f32_dpp v35, v35, v35 quad_perm:[1,0,3,2] row_mask:0xf bank_mask:0xf bound_ctrl:1
	v_add_f32_dpp v18, v18, v18 row_mirror row_mask:0xf bank_mask:0xf bound_ctrl:1
	v_mov_b32_e32 v34, v18
	v_add_f32_dpp v35, v35, v35 quad_perm:[2,3,0,1] row_mask:0xf bank_mask:0xf bound_ctrl:1
	s_nop 0
	v_permlane16_swap_b32_e32 v18, v34
	v_add_f32_dpp v35, v35, v35 row_half_mirror row_mask:0xf bank_mask:0xf bound_ctrl:1
	s_nop 1
	v_add_f32_dpp v35, v35, v35 row_mirror row_mask:0xf bank_mask:0xf bound_ctrl:1
	v_mov_b32_e32 v82, v35
	s_nop 1
	v_permlane16_swap_b32_e32 v35, v82
	v_add_f32_e32 v35, v35, v82
	v_add_f32_e32 v35, 0x2b8cbccc, v35
	v_cmp_gt_f32_e32 vcc, s90, v35
	v_mul_f32_e32 v82, 0x4b800000, v35
	s_nop 0
	v_cndmask_b32_e32 v35, v35, v82, vcc
	v_rsq_f32_e32 v35, v35
	s_nop 0
	v_mul_f32_e32 v82, 0x45800000, v35
	v_cndmask_b32_e32 v82, v35, v82, vcc
	v_pk_mul_f32 v[50:51], v[50:51], v[82:83] op_sel_hi:[1,0]
	v_lshl_add_u64 v[82:83], s[72:73], 0, v[66:67]
	v_cvt_pk_f16_f32 v35, v50, v51
	v_pk_mul_f32 v[50:51], v[218:219], v[50:51]
	global_store_dword v[82:83], v35, off
	v_cvt_pk_f16_f32 v35, v50, v51
	v_lshl_add_u64 v[50:51], s[74:75], 0, v[66:67]
	global_store_dword v[50:51], v35, off
	v_lshl_add_u64 v[50:51], s[78:79], 0, v[66:67]
	global_store_dword v[50:51], v3, off
	s_and_saveexec_b64 s[6:7], s[4:5]
	s_cbranch_execz .LBB0_1232
	v_add_f32_e32 v18, v18, v34
	v_mad_i64_i32 v[2:3], s[86:87], v2, 48, v[200:201]
	global_store_dword v[2:3], v18, off
; DEVI void rwkv_prep_item(const Params& p, const int l, const int item, char* smem) {
;     ...
;     for (int r = 0; r < 16; ++r) {
;       const int t = t0 + mt * 32 + (r & 3) + 8 * (r >> 2) + 4 * hi; const bool has_prev = (t & (SEQ_ - 1)) != 0;
;       float rv[2], kv[2], vv[2], av[2], kkv[2], kpv[2], omdv[2], gv[2];
;       float ssq = 0.f, bon = 0.f;
;       const u16* pr = PA + (size_t)t * 2560 + h * 64 + 2 * l31;
;       const unsigned cr2 = *(const unsigned*)pr, ck2 = *(const unsigned*)(pr + 768), cv2 = *(const unsigned*)(pr + 1536);
;       unsigned qr2 = 0u, qk2 = 0u, qv2 = 0u;
;       if (has_prev) { qr2 = *(const unsigned*)(pr - 2560); qk2 = *(const unsigned*)(pr + 768 - 2560); qv2 = *(const unsigned*)(pr + 1536 - 2560); }
; #pragma unroll
;       for (int n = 0; n < 2; ++n) {
;         const float cr = __uint_as_float(n ? (cr2 & 0xffff0000u) : (cr2 << 16)), ck = __uint_as_float(n ? (ck2 & 0xffff0000u) : (ck2 << 16)), cv = __uint_as_float(n ? (cv2 & 0xffff0000u) : (cv2 << 16));
;         const float qr = __uint_as_float(n ? (qr2 & 0xffff0000u) : (qr2 << 16)), qk = __uint_as_float(n ? (qk2 & 0xffff0000u) : (qk2 << 16)), qv = __uint_as_float(n ? (qv2 & 0xffff0000u) : (qv2 << 16));
;         rv[n] = cr + (qr - cr) * mur[n]; kv[n] = ck + (qk - ck) * muk[n]; vv[n] = cv + (qv - cv) * muv[n];
;         const float z = -(w0c[n] + aw[n][r]);
;         const float sp = fmaxf(z, 0.f) + __logf(1.f + __expf(-fabsf(z)));
;         const float ew = __expf(-sp - 0.5f);
;         omdv[n] = 1.f - __expf(-ew);
;         av[n] = sigmoidf_(a0c[n] + aa[n][r]);
;         gv[n] = ag[n][r];
;         kkv[n] = kv[n] * kkc[n];
;         kpv[n] = kv[n] * (1.f + (av[n] - 1.f) * kac[n]);
;         ssq += kkv[n] * kkv[n];
;         bon += rv[n] * kpv[n] * rkc[n];
;       }
;       ssq = reduce32(ssq); bon = reduce32(bon);
;       const float rn = rsqrtf(ssq + 1e-12f);
;       {
;         typedef _Float16 h2 __attribute__((ext_vector_type(2)));
;         const size_t o = (size_t)t * 768 + h * 64 + 2 * l31;
;         const float kn0 = kkv[0] * rn, kn1 = kkv[1] * rn;
;         *(h2*)(RW + o) = (h2){(f16)rv[0], (f16)rv[1]};
;         *(h2*)(RW + TS + o) = (h2){(f16)omdv[0], (f16)omdv[1]};
;         *(h2*)(RW + 2 * TS + o) = (h2){(f16)kpv[0], (f16)kpv[1]};
;         *(h2*)(RW + 3 * TS + o) = (h2){(f16)vv[0], (f16)vv[1]};
;         *(h2*)(RW + 4 * TS + o) = (h2){(f16)kn0, (f16)kn1};
.LBB0_1232:
	s_or_b64 exec, exec, s[6:7]
	v_or_b32_e32 v216, 2, v233
	v_mad_i64_i32 v[2:3], s[6:7], v216, s88, v[212:213]
	s_waitcnt vmcnt(7)
	v_mov_b32_e32 v18, v246
	v_mov_b32_e32 v19, v247
	v_mov_b32_e32 v50, v248
	v_mov_b32_e32 v66, v249
	v_mov_b32_e32 v67, v250
	v_add_co_u32_e32 v2, vcc, 0xfffff000, v2
	v_add_f32_e32 v36, v36, v211
	s_nop 0
	v_addc_co_u32_e32 v3, vcc, -1, v3, vcc
	v_mov_b32_e32 v51, v251
	v_or_b32_e32 v253, 3, v233
	v_mad_i64_i32 v[254:255], s[86:87], v253, s88, v[212:213]
	global_load_dword v246, v[254:255], off
	global_load_dword v247, v[254:255], off offset:1536
	global_load_dword v248, v[254:255], off offset:3072
	global_load_dword v249, v[254:255], off offset:-2048
	global_load_dword v250, v[254:255], off offset:-3584
	v_add_co_u32_e32 v254, vcc, 0xfffff000, v254
	s_nop 1
	v_addc_co_u32_e32 v255, vcc, -1, v255, vcc
	global_load_dword v251, v[254:255], off offset:-1024
	v_add_f32_e32 v52, v52, v209
	v_mul_f32_e32 v52, 0xbfb8aa3b, v52
	v_cvt_pk_f16_f32 v4, v4, v20
	s_nop 0
	v_and_b32_e32 v83, 0xffff0000, v18
	v_lshlrev_b32_e32 v82, 16, v18
	s_nop 0
	v_and_b32_e32 v35, 0xffff0000, v19
	v_lshlrev_b32_e32 v34, 16, v19
	s_nop 0
	v_and_b32_e32 v19, 0xffff0000, v66
	v_lshlrev_b32_e32 v18, 16, v66
	v_add_f32_e32 v66, v84, v210
	v_and_b32_e32 v3, 0xffff0000, v50
	v_lshlrev_b32_e32 v2, 16, v50
	s_nop 0
	v_lshlrev_b32_e32 v50, 16, v67
	s_nop 0
	v_and_b32_e32 v215, 0xffff0000, v51
	v_lshlrev_b32_e32 v214, 16, v51
	v_and_b32_e32 v51, 0xffff0000, v67
	v_max_f32_e64 v67, -v66, 0
	v_mul_f32_e64 v66, |v66|, s89
	v_exp_f32_e32 v66, v66
	v_pk_add_f32 v[214:215], v[214:215], v[82:83] neg_lo:[0,1] neg_hi:[0,1]
	v_pk_add_f32 v[50:51], v[50:51], v[34:35] neg_lo:[0,1] neg_hi:[0,1]
	v_pk_fma_f32 v[82:83], v[206:207], v[214:215], v[82:83]
	v_add_f32_e32 v66, 1.0, v66
	v_cmp_gt_f32_e32 vcc, s90, v66
	v_pk_fma_f32 v[50:51], v[204:205], v[50:51], v[34:35]
	v_pk_add_f32 v[18:19], v[18:19], v[2:3] neg_lo:[0,1] neg_hi:[0,1]
	v_cndmask_b32_e64 v84, 0, 32, vcc
	v_ldexp_f32 v66, v66, v84
	v_log_f32_e32 v66, v66
	v_pk_fma_f32 v[2:3], v[196:197], v[18:19], v[2:3]
	v_mul_f32_e32 v84, 0x3f317217, v66
	v_fma_f32 v84, v66, s91, -v84
	v_fmac_f32_e32 v84, 0x3377d1cf, v66
	v_fmac_f32_e32 v84, 0x3f317217, v66
	v_cmp_lt_f32_e64 s[6:7], |v66|, s97
	v_cvt_pk_f16_f32 v18, v2, v3
	s_nop 0
	v_cndmask_b32_e64 v66, v66, v84, s[6:7]
	v_cndmask_b32_e32 v84, 0, v232, vcc
	v_sub_f32_e32 v66, v66, v84
	v_add_f32_e32 v66, v67, v66
	v_sub_f32_e32 v66, -0.5, v66
	v_mul_f32_e32 v66, 0x3fb8aa3b, v66
	v_exp_f32_e32 v66, v66
	v_max_f32_e64 v67, -v36, 0
	v_mul_f32_e64 v36, |v36|, s89
	v_exp_f32_e32 v36, v36
	v_mul_f32_e32 v66, 0xbfb8aa3b, v66
	v_exp_f32_e32 v66, v66
	v_add_f32_e32 v36, 1.0, v36
	v_cmp_gt_f32_e32 vcc, s90, v36
	v_sub_f32_e32 v84, 1.0, v66
	v_add_f32_e32 v66, v68, v208
	v_cndmask_b32_e64 v68, 0, 32, vcc
	v_ldexp_f32 v36, v36, v68
	v_log_f32_e32 v36, v36
	v_mul_f32_e32 v66, 0xbfb8aa3b, v66
	v_exp_f32_e32 v66, v66
	v_mul_f32_e32 v68, 0x3f317217, v36
	v_fma_f32 v68, v36, s91, -v68
	v_fmac_f32_e32 v68, 0x3377d1cf, v36
	v_fmac_f32_e32 v68, 0x3f317217, v36
	v_cmp_lt_f32_e64 s[6:7], |v36|, s97
	s_nop 1
	v_cndmask_b32_e64 v36, v36, v68, s[6:7]
	v_cndmask_b32_e32 v68, 0, v232, vcc
	v_sub_f32_e32 v36, v36, v68
	v_add_f32_e32 v36, v67, v36
	v_sub_f32_e32 v36, -0.5, v36
	v_mul_f32_e32 v36, 0x3fb8aa3b, v36
	v_exp_f32_e32 v36, v36
	v_exp_f32_e32 v67, v52
	v_mad_i64_i32 v[218:219], s[6:7], v216, s95, v[102:103]
	v_mul_f32_e32 v36, 0xbfb8aa3b, v36
	v_exp_f32_e32 v36, v36
	v_lshlrev_b64 v[214:215], 1, v[218:219]
	v_cvt_pk_f16_f32 v52, v82, v83
	v_lshl_add_u64 v[218:219], s[58:59], 0, v[214:215]
	v_sub_f32_e32 v36, 1.0, v36
	global_store_dword v[218:219], v52, off
	v_cvt_pk_f16_f32 v36, v84, v36
	v_lshl_add_u64 v[218:219], s[66:67], 0, v[214:215]
	v_pk_add_f32 v[34:35], v[66:67], 1.0 op_sel_hi:[1,0]
	global_store_dword v[218:219], v36, off
	v_div_scale_f32 v36, s[6:7], v35, v35, 1.0
	v_rcp_f32_e32 v52, v36
	v_lshl_add_u64 v[2:3], s[70:71], 0, v[214:215]
	global_store_dword v[2:3], v18, off
	v_pk_mul_f32 v[2:3], v[194:195], v[50:51]
	v_fma_f32 v66, -v36, v52, 1.0
	v_fmac_f32_e32 v52, v66, v52
	v_div_scale_f32 v66, vcc, 1.0, v35, 1.0
	v_mul_f32_e32 v67, v66, v52
	v_fma_f32 v68, -v36, v67, v66
	v_fmac_f32_e32 v67, v68, v52
	v_fma_f32 v36, -v36, v67, v66
	v_div_fmas_f32 v36, v36, v52, v67
	v_div_fixup_f32 v67, v36, v35, 1.0
	v_div_scale_f32 v35, s[6:7], v34, v34, 1.0
	v_rcp_f32_e32 v36, v35
	v_pk_mul_f32 v[18:19], v[2:3], v[2:3]
	v_fma_f32 v52, -v35, v36, 1.0
	v_add_f32_e32 v18, v18, v19
	v_fmac_f32_e32 v36, v52, v36
	v_div_scale_f32 v52, vcc, 1.0, v34, 1.0
	v_add_f32_dpp v18, v18, v18 quad_perm:[1,0,3,2] row_mask:0xf bank_mask:0xf bound_ctrl:1
	v_mul_f32_e32 v66, v52, v36
	v_fma_f32 v68, -v35, v66, v52
	v_add_f32_dpp v18, v18, v18 quad_perm:[2,3,0,1] row_mask:0xf bank_mask:0xf bound_ctrl:1
	v_fmac_f32_e32 v66, v68, v36
	v_fma_f32 v35, -v35, v66, v52
	v_add_f32_dpp v18, v18, v18 row_half_mirror row_mask:0xf bank_mask:0xf bound_ctrl:1
	v_div_fmas_f32 v35, v35, v36, v66
	v_div_fixup_f32 v66, v35, v34, 1.0
	v_add_f32_dpp v18, v18, v18 row_mirror row_mask:0xf bank_mask:0xf bound_ctrl:1
	v_mov_b32_e32 v19, v18
	s_nop 1
	v_permlane16_swap_b32_e32 v18, v19
	v_add_f32_e32 v18, v18, v19
	v_add_f32_e32 v18, 0x2b8cbccc, v18
	v_pk_add_f32 v[34:35], v[66:67], -1.0 op_sel_hi:[1,0]
	v_cmp_gt_f32_e32 vcc, s90, v18
	v_mul_f32_e32 v19, 0x4b800000, v18
	v_pk_fma_f32 v[34:35], v[202:203], v[34:35], 1.0 op_sel_hi:[1,1,0]
	v_cndmask_b32_e32 v18, v18, v19, vcc
	v_pk_mul_f32 v[218:219], v[34:35], v[50:51]
	v_rsq_f32_e32 v18, v18
	v_pk_mul_f32 v[34:35], v[82:83], v[218:219]
	v_cvt_pk_f16_f32 v36, v218, v219
	v_fma_f32 v34, v198, v34, 0
	v_fmac_f32_e32 v34, v199, v35
	v_mul_f32_e32 v19, 0x45800000, v18
	v_cndmask_b32_e32 v18, v18, v19, vcc
	v_add_f32_dpp v34, v34, v34 quad_perm:[1,0,3,2] row_mask:0xf bank_mask:0xf bound_ctrl:1
	v_lshl_add_u64 v[82:83], s[68:69], 0, v[214:215]
	v_pk_mul_f32 v[2:3], v[2:3], v[18:19] op_sel_hi:[1,0]
	v_add_f32_dpp v34, v34, v34 quad_perm:[2,3,0,1] row_mask:0xf bank_mask:0xf bound_ctrl:1
	global_store_dword v[82:83], v36, off
	v_cvt_pk_f16_f32 v36, v2, v3
	v_add_f32_dpp v34, v34, v34 row_half_mirror row_mask:0xf bank_mask:0xf bound_ctrl:1
	v_lshl_add_u64 v[18:19], s[72:73], 0, v[214:215]
	v_pk_mul_f32 v[2:3], v[66:67], v[2:3]
	v_add_f32_dpp v34, v34, v34 row_mirror row_mask:0xf bank_mask:0xf bound_ctrl:1
	v_mov_b32_e32 v35, v34
	global_store_dword v[18:19], v36, off
	v_cvt_pk_f16_f32 v18, v2, v3
	v_lshl_add_u64 v[2:3], s[74:75], 0, v[214:215]
	v_permlane16_swap_b32_e32 v34, v35
	global_store_dword v[2:3], v18, off
	v_lshl_add_u64 v[2:3], s[78:79], 0, v[214:215]
	global_store_dword v[2:3], v4, off
	s_and_saveexec_b64 s[6:7], s[4:5]
	s_cbranch_execz .LBB0_1234
	v_add_f32_e32 v4, v34, v35
	v_mad_i64_i32 v[2:3], s[86:87], v216, 48, v[200:201]
	global_store_dword v[2:3], v4, off
; DEVI void rwkv_prep_item(const Params& p, const int l, const int item, char* smem) {
;     ...
;     for (int r = 0; r < 16; ++r) {
;       const int t = t0 + mt * 32 + (r & 3) + 8 * (r >> 2) + 4 * hi; const bool has_prev = (t & (SEQ_ - 1)) != 0;
;       float rv[2], kv[2], vv[2], av[2], kkv[2], kpv[2], omdv[2], gv[2];
;       float ssq = 0.f, bon = 0.f;
;       const u16* pr = PA + (size_t)t * 2560 + h * 64 + 2 * l31;
;       const unsigned cr2 = *(const unsigned*)pr, ck2 = *(const unsigned*)(pr + 768), cv2 = *(const unsigned*)(pr + 1536);
;       unsigned qr2 = 0u, qk2 = 0u, qv2 = 0u;
;       if (has_prev) { qr2 = *(const unsigned*)(pr - 2560); qk2 = *(const unsigned*)(pr + 768 - 2560); qv2 = *(const unsigned*)(pr + 1536 - 2560); }
; #pragma unroll
;       for (int n = 0; n < 2; ++n) {
;         const float cr = __uint_as_float(n ? (cr2 & 0xffff0000u) : (cr2 << 16)), ck = __uint_as_float(n ? (ck2 & 0xffff0000u) : (ck2 << 16)), cv = __uint_as_float(n ? (cv2 & 0xffff0000u) : (cv2 << 16));
;         const float qr = __uint_as_float(n ? (qr2 & 0xffff0000u) : (qr2 << 16)), qk = __uint_as_float(n ? (qk2 & 0xffff0000u) : (qk2 << 16)), qv = __uint_as_float(n ? (qv2 & 0xffff0000u) : (qv2 << 16));
;         rv[n] = cr + (qr - cr) * mur[n]; kv[n] = ck + (qk - ck) * muk[n]; vv[n] = cv + (qv - cv) * muv[n];
;         const float z = -(w0c[n] + aw[n][r]);
;         const float sp = fmaxf(z, 0.f) + __logf(1.f + __expf(-fabsf(z)));
;         const float ew = __expf(-sp - 0.5f);
;         omdv[n] = 1.f - __expf(-ew);
;         av[n] = sigmoidf_(a0c[n] + aa[n][r]);
;         gv[n] = ag[n][r];
;         kkv[n] = kv[n] * kkc[n];
;         kpv[n] = kv[n] * (1.f + (av[n] - 1.f) * kac[n]);
;         ssq += kkv[n] * kkv[n];
;         bon += rv[n] * kpv[n] * rkc[n];
;       }
;       ssq = reduce32(ssq); bon = reduce32(bon);
;       const float rn = rsqrtf(ssq + 1e-12f);
;       {
;         typedef _Float16 h2 __attribute__((ext_vector_type(2)));
;         const size_t o = (size_t)t * 768 + h * 64 + 2 * l31;
;         const float kn0 = kkv[0] * rn, kn1 = kkv[1] * rn;
;         *(h2*)(RW + o) = (h2){(f16)rv[0], (f16)rv[1]};
;         *(h2*)(RW + TS + o) = (h2){(f16)omdv[0], (f16)omdv[1]};
;         *(h2*)(RW + 2 * TS + o) = (h2){(f16)kpv[0], (f16)kpv[1]};
;         *(h2*)(RW + 3 * TS + o) = (h2){(f16)vv[0], (f16)vv[1]};
;         *(h2*)(RW + 4 * TS + o) = (h2){(f16)kn0, (f16)kn1};
.LBB0_1234:
	s_or_b64 exec, exec, s[6:7]
	v_or_b32_e32 v4, 3, v233
	v_mad_i64_i32 v[2:3], s[6:7], v4, s88, v[212:213]
	s_waitcnt vmcnt(7)
	v_mov_b32_e32 v18, v246
	v_mov_b32_e32 v19, v247
	v_mov_b32_e32 v20, v248
	v_mov_b32_e32 v36, v249
	v_mov_b32_e32 v50, v250
	v_add_co_u32_e32 v2, vcc, 0xfffff000, v2
	v_add_f32_e32 v37, v37, v211
	s_nop 0
	v_addc_co_u32_e32 v3, vcc, -1, v3, vcc
	v_mov_b32_e32 v51, v251
	v_or_b32_e32 v253, 8, v233
	v_mad_i64_i32 v[254:255], s[86:87], v253, s88, v[212:213]
	global_load_dword v246, v[254:255], off
	global_load_dword v247, v[254:255], off offset:1536
	global_load_dword v248, v[254:255], off offset:3072
	global_load_dword v249, v[254:255], off offset:-2048
	global_load_dword v250, v[254:255], off offset:-3584
	v_add_co_u32_e32 v254, vcc, 0xfffff000, v254
	s_nop 1
	v_addc_co_u32_e32 v255, vcc, -1, v255, vcc
	global_load_dword v251, v[254:255], off offset:-1024
	v_cvt_pk_f16_f32 v5, v5, v21
	s_nop 0
	v_and_b32_e32 v67, 0xffff0000, v18
	v_lshlrev_b32_e32 v66, 16, v18
	s_nop 0
	v_and_b32_e32 v3, 0xffff0000, v20
	v_lshlrev_b32_e32 v2, 16, v20
	v_add_f32_e32 v20, v85, v210
	v_and_b32_e32 v35, 0xffff0000, v19
	v_lshlrev_b32_e32 v34, 16, v19
	s_nop 0
	v_and_b32_e32 v19, 0xffff0000, v36
	v_lshlrev_b32_e32 v18, 16, v36
	v_max_f32_e64 v36, -v20, 0
	v_mul_f32_e64 v20, |v20|, s89
	v_exp_f32_e32 v20, v20
	s_nop 0
	v_and_b32_e32 v83, 0xffff0000, v51
	v_lshlrev_b32_e32 v82, 16, v51
	v_and_b32_e32 v51, 0xffff0000, v50
	v_add_f32_e32 v20, 1.0, v20
	v_cmp_gt_f32_e32 vcc, s90, v20
	v_lshlrev_b32_e32 v50, 16, v50
	v_pk_add_f32 v[50:51], v[50:51], v[34:35] neg_lo:[0,1] neg_hi:[0,1]
	v_cndmask_b32_e64 v52, 0, 32, vcc
	v_ldexp_f32 v20, v20, v52
	v_log_f32_e32 v20, v20
	v_pk_fma_f32 v[50:51], v[204:205], v[50:51], v[34:35]
	v_pk_add_f32 v[18:19], v[18:19], v[2:3] neg_lo:[0,1] neg_hi:[0,1]
	v_mul_f32_e32 v52, 0x3f317217, v20
	v_fma_f32 v52, v20, s91, -v52
	v_fmac_f32_e32 v52, 0x3377d1cf, v20
	v_fmac_f32_e32 v52, 0x3f317217, v20
	v_cmp_lt_f32_e64 s[6:7], |v20|, s97
	v_pk_fma_f32 v[2:3], v[196:197], v[18:19], v[2:3]
	s_nop 0
	v_cndmask_b32_e64 v20, v20, v52, s[6:7]
	v_cndmask_b32_e32 v52, 0, v232, vcc
	v_sub_f32_e32 v20, v20, v52
	v_max_f32_e64 v52, -v37, 0
	v_mul_f32_e64 v37, |v37|, s89
	v_exp_f32_e32 v37, v37
	v_add_f32_e32 v20, v36, v20
	v_sub_f32_e32 v20, -0.5, v20
	v_mul_f32_e32 v20, 0x3fb8aa3b, v20
	v_add_f32_e32 v37, 1.0, v37
	v_cmp_gt_f32_e32 vcc, s90, v37
	v_exp_f32_e32 v20, v20
	v_add_f32_e32 v36, v69, v208
	v_cndmask_b32_e64 v68, 0, 32, vcc
	v_ldexp_f32 v37, v37, v68
	v_log_f32_e32 v37, v37
	v_mul_f32_e32 v20, 0xbfb8aa3b, v20
	v_exp_f32_e32 v20, v20
	v_mul_f32_e32 v36, 0xbfb8aa3b, v36
	v_mul_f32_e32 v68, 0x3f317217, v37
	v_fma_f32 v68, v37, s91, -v68
	v_fmac_f32_e32 v68, 0x3377d1cf, v37
	v_fmac_f32_e32 v68, 0x3f317217, v37
	v_cmp_lt_f32_e64 s[6:7], |v37|, s97
	v_exp_f32_e32 v36, v36
	v_sub_f32_e32 v20, 1.0, v20
	v_cndmask_b32_e64 v37, v37, v68, s[6:7]
	v_cndmask_b32_e32 v68, 0, v232, vcc
	v_sub_f32_e32 v37, v37, v68
	v_add_f32_e32 v37, v52, v37
	v_sub_f32_e32 v37, -0.5, v37
	v_mul_f32_e32 v37, 0x3fb8aa3b, v37
	v_exp_f32_e32 v37, v37
	v_mad_i64_i32 v[68:69], s[6:7], v4, s95, v[102:103]
	v_cvt_pk_f16_f32 v18, v2, v3
	v_mul_f32_e32 v37, 0xbfb8aa3b, v37
	v_exp_f32_e32 v37, v37
	s_nop 0
	v_sub_f32_e32 v84, 1.0, v37
	v_add_f32_e32 v37, v53, v209
	v_mul_f32_e32 v37, 0xbfb8aa3b, v37
	v_exp_f32_e32 v37, v37
	v_pk_add_f32 v[52:53], v[82:83], v[66:67] neg_lo:[0,1] neg_hi:[0,1]
	v_cvt_pk_f16_f32 v20, v20, v84
	v_pk_fma_f32 v[52:53], v[206:207], v[52:53], v[66:67]
	v_lshlrev_b64 v[66:67], 1, v[68:69]
	v_cvt_pk_f16_f32 v82, v52, v53
	v_lshl_add_u64 v[68:69], s[58:59], 0, v[66:67]
	global_store_dword v[68:69], v82, off
	v_lshl_add_u64 v[68:69], s[66:67], 0, v[66:67]
	v_pk_add_f32 v[34:35], v[36:37], 1.0 op_sel_hi:[1,0]
	global_store_dword v[68:69], v20, off
	v_div_scale_f32 v20, s[6:7], v35, v35, 1.0
	v_rcp_f32_e32 v36, v20
	v_lshl_add_u64 v[2:3], s[70:71], 0, v[66:67]
	global_store_dword v[2:3], v18, off
	v_pk_mul_f32 v[2:3], v[194:195], v[50:51]
	v_fma_f32 v37, -v20, v36, 1.0
	v_fmac_f32_e32 v36, v37, v36
	v_div_scale_f32 v37, vcc, 1.0, v35, 1.0
	v_mul_f32_e32 v68, v37, v36
	v_fma_f32 v69, -v20, v68, v37
	v_fmac_f32_e32 v68, v69, v36
	v_fma_f32 v20, -v20, v68, v37
	v_div_fmas_f32 v20, v20, v36, v68
	v_div_fixup_f32 v37, v20, v35, 1.0
	v_div_scale_f32 v20, s[6:7], v34, v34, 1.0
	v_rcp_f32_e32 v35, v20
	v_pk_mul_f32 v[18:19], v[2:3], v[2:3]
	v_fma_f32 v36, -v20, v35, 1.0
	v_add_f32_e32 v18, v18, v19
	v_fmac_f32_e32 v35, v36, v35
	v_div_scale_f32 v36, vcc, 1.0, v34, 1.0
	v_add_f32_dpp v18, v18, v18 quad_perm:[1,0,3,2] row_mask:0xf bank_mask:0xf bound_ctrl:1
	v_mul_f32_e32 v68, v36, v35
	v_fma_f32 v69, -v20, v68, v36
	v_add_f32_dpp v18, v18, v18 quad_perm:[2,3,0,1] row_mask:0xf bank_mask:0xf bound_ctrl:1
	v_fmac_f32_e32 v68, v69, v35
	v_fma_f32 v20, -v20, v68, v36
	v_add_f32_dpp v18, v18, v18 row_half_mirror row_mask:0xf bank_mask:0xf bound_ctrl:1
	v_div_fmas_f32 v20, v20, v35, v68
	v_div_fixup_f32 v36, v20, v34, 1.0
	v_add_f32_dpp v18, v18, v18 row_mirror row_mask:0xf bank_mask:0xf bound_ctrl:1
	v_mov_b32_e32 v19, v18
	s_nop 1
	v_permlane16_swap_b32_e32 v18, v19
	v_add_f32_e32 v18, v18, v19
	v_add_f32_e32 v18, 0x2b8cbccc, v18
	v_pk_add_f32 v[34:35], v[36:37], -1.0 op_sel_hi:[1,0]
	v_cmp_gt_f32_e32 vcc, s90, v18
	v_mul_f32_e32 v19, 0x4b800000, v18
	v_pk_fma_f32 v[34:35], v[202:203], v[34:35], 1.0 op_sel_hi:[1,1,0]
	v_cndmask_b32_e32 v18, v18, v19, vcc
	v_pk_mul_f32 v[68:69], v[34:35], v[50:51]
	v_rsq_f32_e32 v18, v18
	v_pk_mul_f32 v[34:35], v[52:53], v[68:69]
	v_lshl_add_u64 v[52:53], s[68:69], 0, v[66:67]
	v_fma_f32 v20, v198, v34, 0
	v_fmac_f32_e32 v20, v199, v35
	v_mul_f32_e32 v19, 0x45800000, v18
	v_cndmask_b32_e32 v18, v18, v19, vcc
	v_add_f32_dpp v20, v20, v20 quad_perm:[1,0,3,2] row_mask:0xf bank_mask:0xf bound_ctrl:1
	v_cvt_pk_f16_f32 v35, v68, v69
	v_pk_mul_f32 v[2:3], v[2:3], v[18:19] op_sel_hi:[1,0]
	v_add_f32_dpp v20, v20, v20 quad_perm:[2,3,0,1] row_mask:0xf bank_mask:0xf bound_ctrl:1
	global_store_dword v[52:53], v35, off
	v_cvt_pk_f16_f32 v35, v2, v3
	v_add_f32_dpp v20, v20, v20 row_half_mirror row_mask:0xf bank_mask:0xf bound_ctrl:1
	v_lshl_add_u64 v[18:19], s[72:73], 0, v[66:67]
	v_pk_mul_f32 v[2:3], v[36:37], v[2:3]
	v_add_f32_dpp v20, v20, v20 row_mirror row_mask:0xf bank_mask:0xf bound_ctrl:1
	v_mov_b32_e32 v34, v20
	global_store_dword v[18:19], v35, off
	v_cvt_pk_f16_f32 v18, v2, v3
	v_lshl_add_u64 v[2:3], s[74:75], 0, v[66:67]
	v_permlane16_swap_b32_e32 v20, v34
	global_store_dword v[2:3], v18, off
	v_lshl_add_u64 v[2:3], s[78:79], 0, v[66:67]
	global_store_dword v[2:3], v5, off
	s_and_saveexec_b64 s[6:7], s[4:5]
	s_cbranch_execz .LBB0_1236
	v_add_f32_e32 v5, v20, v34
	v_mad_i64_i32 v[2:3], s[86:87], v4, 48, v[200:201]
	global_store_dword v[2:3], v5, off
; DEVI void rwkv_prep_item(const Params& p, const int l, const int item, char* smem) {
;     ...
;     for (int r = 0; r < 16; ++r) {
;       const int t = t0 + mt * 32 + (r & 3) + 8 * (r >> 2) + 4 * hi; const bool has_prev = (t & (SEQ_ - 1)) != 0;
;       float rv[2], kv[2], vv[2], av[2], kkv[2], kpv[2], omdv[2], gv[2];
;       float ssq = 0.f, bon = 0.f;
;       const u16* pr = PA + (size_t)t * 2560 + h * 64 + 2 * l31;
;       const unsigned cr2 = *(const unsigned*)pr, ck2 = *(const unsigned*)(pr + 768), cv2 = *(const unsigned*)(pr + 1536);
;       unsigned qr2 = 0u, qk2 = 0u, qv2 = 0u;
;       if (has_prev) { qr2 = *(const unsigned*)(pr - 2560); qk2 = *(const unsigned*)(pr + 768 - 2560); qv2 = *(const unsigned*)(pr + 1536 - 2560); }
; #pragma unroll
;       for (int n = 0; n < 2; ++n) {
;         const float cr = __uint_as_float(n ? (cr2 & 0xffff0000u) : (cr2 << 16)), ck = __uint_as_float(n ? (ck2 & 0xffff0000u) : (ck2 << 16)), cv = __uint_as_float(n ? (cv2 & 0xffff0000u) : (cv2 << 16));
;         const float qr = __uint_as_float(n ? (qr2 & 0xffff0000u) : (qr2 << 16)), qk = __uint_as_float(n ? (qk2 & 0xffff0000u) : (qk2 << 16)), qv = __uint_as_float(n ? (qv2 & 0xffff0000u) : (qv2 << 16));
;         rv[n] = cr + (qr - cr) * mur[n]; kv[n] = ck + (qk - ck) * muk[n]; vv[n] = cv + (qv - cv) * muv[n];
;         const float z = -(w0c[n] + aw[n][r]);
;         const float sp = fmaxf(z, 0.f) + __logf(1.f + __expf(-fabsf(z)));
;         const float ew = __expf(-sp - 0.5f);
;         omdv[n] = 1.f - __expf(-ew);
;         av[n] = sigmoidf_(a0c[n] + aa[n][r]);
;         gv[n] = ag[n][r];
;         kkv[n] = kv[n] * kkc[n];
;         kpv[n] = kv[n] * (1.f + (av[n] - 1.f) * kac[n]);
;         ssq += kkv[n] * kkv[n];
;         bon += rv[n] * kpv[n] * rkc[n];
;       }
;       ssq = reduce32(ssq); bon = reduce32(bon);
;       const float rn = rsqrtf(ssq + 1e-12f);
;       {
;         typedef _Float16 h2 __attribute__((ext_vector_type(2)));
;         const size_t o = (size_t)t * 768 + h * 64 + 2 * l31;
;         const float kn0 = kkv[0] * rn, kn1 = kkv[1] * rn;
;         *(h2*)(RW + o) = (h2){(f16)rv[0], (f16)rv[1]};
;         *(h2*)(RW + TS + o) = (h2){(f16)omdv[0], (f16)omdv[1]};
;         *(h2*)(RW + 2 * TS + o) = (h2){(f16)kpv[0], (f16)kpv[1]};
;         *(h2*)(RW + 3 * TS + o) = (h2){(f16)vv[0], (f16)vv[1]};
;         *(h2*)(RW + 4 * TS + o) = (h2){(f16)kn0, (f16)kn1};
.LBB0_1236:
	s_or_b64 exec, exec, s[6:7]
	v_or_b32_e32 v52, 8, v233
	v_mad_i64_i32 v[2:3], s[6:7], v52, s88, v[212:213]
	s_waitcnt vmcnt(7)
	v_mov_b32_e32 v4, v246
	v_mov_b32_e32 v5, v247
	v_mov_b32_e32 v20, v248
	v_mov_b32_e32 v34, v249
	v_mov_b32_e32 v35, v250
	v_add_co_u32_e32 v2, vcc, 0xfffff000, v2
	s_nop 0
	v_and_b32_e32 v37, 0xffff0000, v4
	v_addc_co_u32_e32 v3, vcc, -1, v3, vcc
	v_mov_b32_e32 v21, v251
	v_or_b32_e32 v253, 9, v233
	v_mad_i64_i32 v[254:255], s[86:87], v253, s88, v[212:213]
	global_load_dword v246, v[254:255], off
	global_load_dword v247, v[254:255], off offset:1536
	global_load_dword v248, v[254:255], off offset:3072
	global_load_dword v249, v[254:255], off offset:-2048
	global_load_dword v250, v[254:255], off offset:-3584
	v_add_co_u32_e32 v254, vcc, 0xfffff000, v254
	s_nop 1
	v_addc_co_u32_e32 v255, vcc, -1, v255, vcc
	global_load_dword v251, v[254:255], off offset:-1024
	v_lshlrev_b32_e32 v36, 16, v4
	s_nop 0
	v_and_b32_e32 v19, 0xffff0000, v5
	v_lshlrev_b32_e32 v18, 16, v5
	s_nop 0
	v_and_b32_e32 v5, 0xffff0000, v34
	v_lshlrev_b32_e32 v4, 16, v34
	v_add_f32_e32 v34, v86, v210
	v_and_b32_e32 v3, 0xffff0000, v20
	v_lshlrev_b32_e32 v2, 16, v20
	s_nop 0
	v_lshlrev_b32_e32 v20, 16, v35
	v_pk_add_f32 v[4:5], v[4:5], v[2:3] neg_lo:[0,1] neg_hi:[0,1]
	s_nop 0
	v_and_b32_e32 v51, 0xffff0000, v21
	v_lshlrev_b32_e32 v50, 16, v21
	v_and_b32_e32 v21, 0xffff0000, v35
	v_max_f32_e64 v35, -v34, 0
	v_mul_f32_e64 v34, |v34|, s89
	v_exp_f32_e32 v34, v34
	v_pk_add_f32 v[20:21], v[20:21], v[18:19] neg_lo:[0,1] neg_hi:[0,1]
	v_pk_add_f32 v[50:51], v[50:51], v[36:37] neg_lo:[0,1] neg_hi:[0,1]
	v_pk_fma_f32 v[20:21], v[204:205], v[20:21], v[18:19]
	v_add_f32_e32 v34, 1.0, v34
	v_cmp_gt_f32_e32 vcc, s90, v34
	v_pk_fma_f32 v[36:37], v[206:207], v[50:51], v[36:37]
	v_pk_fma_f32 v[2:3], v[196:197], v[4:5], v[2:3]
	v_cndmask_b32_e64 v53, 0, 32, vcc
	v_ldexp_f32 v34, v34, v53
	v_log_f32_e32 v34, v34
	v_cvt_pk_f16_f32 v4, v2, v3
	v_mul_f32_e32 v53, 0x3f317217, v34
	v_fma_f32 v53, v34, s91, -v53
	v_fmac_f32_e32 v53, 0x3377d1cf, v34
	v_fmac_f32_e32 v53, 0x3f317217, v34
	v_cmp_lt_f32_e64 s[6:7], |v34|, s97
	s_nop 1
	v_cndmask_b32_e64 v34, v34, v53, s[6:7]
	v_cndmask_b32_e32 v53, 0, v232, vcc
	v_sub_f32_e32 v34, v34, v53
	v_add_f32_e32 v34, v35, v34
	v_add_f32_e32 v35, v38, v211
	v_max_f32_e64 v38, -v35, 0
	v_mul_f32_e64 v35, |v35|, s89
	v_exp_f32_e32 v35, v35
	v_sub_f32_e32 v34, -0.5, v34
	v_mul_f32_e32 v34, 0x3fb8aa3b, v34
	v_exp_f32_e32 v34, v34
	v_add_f32_e32 v35, 1.0, v35
	v_cmp_gt_f32_e32 vcc, s90, v35
	v_mul_f32_e32 v34, 0xbfb8aa3b, v34
	s_nop 0
	v_cndmask_b32_e64 v66, 0, 32, vcc
	v_ldexp_f32 v35, v35, v66
	v_log_f32_e32 v35, v35
	v_exp_f32_e32 v34, v34
	v_mul_f32_e32 v66, 0x3f317217, v35
	v_fma_f32 v66, v35, s91, -v66
	v_fmac_f32_e32 v66, 0x3377d1cf, v35
	v_fmac_f32_e32 v66, 0x3f317217, v35
	v_cmp_lt_f32_e64 s[6:7], |v35|, s97
	v_sub_f32_e32 v53, 1.0, v34
	v_add_f32_e32 v34, v70, v208
	v_cndmask_b32_e64 v35, v35, v66, s[6:7]
	v_cndmask_b32_e32 v66, 0, v232, vcc
	v_sub_f32_e32 v35, v35, v66
	v_add_f32_e32 v35, v38, v35
	v_sub_f32_e32 v35, -0.5, v35
	v_mul_f32_e32 v35, 0x3fb8aa3b, v35
	v_exp_f32_e32 v35, v35
	v_mul_f32_e32 v34, 0xbfb8aa3b, v34
	v_exp_f32_e32 v34, v34
	v_mad_i64_i32 v[66:67], s[6:7], v52, s95, v[102:103]
	v_mul_f32_e32 v35, 0xbfb8aa3b, v35
	v_exp_f32_e32 v35, v35
	v_lshlrev_b64 v[50:51], 1, v[66:67]
	v_lshl_add_u64 v[66:67], s[58:59], 0, v[50:51]
	v_lshl_add_u64 v[2:3], s[70:71], 0, v[50:51]
	v_sub_f32_e32 v38, 1.0, v35
	v_add_f32_e32 v35, v54, v209
	v_mul_f32_e32 v35, 0xbfb8aa3b, v35
	v_exp_f32_e32 v35, v35
	v_cvt_pk_f16_f32 v54, v36, v37
	global_store_dword v[66:67], v54, off
	v_cvt_pk_f16_f32 v38, v53, v38
	v_pk_add_f32 v[18:19], v[34:35], 1.0 op_sel_hi:[1,0]
	v_lshl_add_u64 v[66:67], s[66:67], 0, v[50:51]
	v_div_scale_f32 v34, s[6:7], v19, v19, 1.0
	v_rcp_f32_e32 v35, v34
	global_store_dword v[66:67], v38, off
	global_store_dword v[2:3], v4, off
	v_pk_mul_f32 v[2:3], v[194:195], v[20:21]
	v_fma_f32 v38, -v34, v35, 1.0
	v_fmac_f32_e32 v35, v38, v35
	v_div_scale_f32 v38, vcc, 1.0, v19, 1.0
	v_mul_f32_e32 v53, v38, v35
	v_fma_f32 v54, -v34, v53, v38
	v_fmac_f32_e32 v53, v54, v35
	v_fma_f32 v34, -v34, v53, v38
	v_div_fmas_f32 v34, v34, v35, v53
	v_div_fixup_f32 v35, v34, v19, 1.0
	v_div_scale_f32 v19, s[6:7], v18, v18, 1.0
	v_rcp_f32_e32 v34, v19
	v_pk_mul_f32 v[4:5], v[2:3], v[2:3]
	v_fma_f32 v38, -v19, v34, 1.0
	v_add_f32_e32 v4, v4, v5
	v_fmac_f32_e32 v34, v38, v34
	v_div_scale_f32 v38, vcc, 1.0, v18, 1.0
	v_add_f32_dpp v4, v4, v4 quad_perm:[1,0,3,2] row_mask:0xf bank_mask:0xf bound_ctrl:1
	v_mul_f32_e32 v53, v38, v34
	v_fma_f32 v54, -v19, v53, v38
	v_add_f32_dpp v4, v4, v4 quad_perm:[2,3,0,1] row_mask:0xf bank_mask:0xf bound_ctrl:1
	v_fmac_f32_e32 v53, v54, v34
	v_fma_f32 v19, -v19, v53, v38
	v_add_f32_dpp v4, v4, v4 row_half_mirror row_mask:0xf bank_mask:0xf bound_ctrl:1
	v_div_fmas_f32 v19, v19, v34, v53
	v_div_fixup_f32 v34, v19, v18, 1.0
	v_add_f32_dpp v4, v4, v4 row_mirror row_mask:0xf bank_mask:0xf bound_ctrl:1
	v_mov_b32_e32 v5, v4
	s_nop 1
	v_permlane16_swap_b32_e32 v4, v5
	v_add_f32_e32 v4, v4, v5
	v_add_f32_e32 v4, 0x2b8cbccc, v4
	v_pk_add_f32 v[18:19], v[34:35], -1.0 op_sel_hi:[1,0]
	v_cmp_gt_f32_e32 vcc, s90, v4
	v_mul_f32_e32 v5, 0x4b800000, v4
	v_pk_fma_f32 v[18:19], v[202:203], v[18:19], 1.0 op_sel_hi:[1,1,0]
	v_cndmask_b32_e32 v4, v4, v5, vcc
	v_pk_mul_f32 v[66:67], v[18:19], v[20:21]
	v_rsq_f32_e32 v4, v4
	v_pk_mul_f32 v[18:19], v[36:37], v[66:67]
	v_cvt_pk_f16_f32 v38, v66, v67
	v_fma_f32 v18, v198, v18, 0
	v_fmac_f32_e32 v18, v199, v19
	v_mul_f32_e32 v5, 0x45800000, v4
	v_cndmask_b32_e32 v4, v4, v5, vcc
	v_add_f32_dpp v18, v18, v18 quad_perm:[1,0,3,2] row_mask:0xf bank_mask:0xf bound_ctrl:1
	v_pk_mul_f32 v[2:3], v[2:3], v[4:5] op_sel_hi:[1,0]
	v_lshl_add_u64 v[4:5], s[72:73], 0, v[50:51]
	v_add_f32_dpp v18, v18, v18 quad_perm:[2,3,0,1] row_mask:0xf bank_mask:0xf bound_ctrl:1
	v_cvt_pk_f16_f32 v20, v2, v3
	v_pk_mul_f32 v[2:3], v[34:35], v[2:3]
	v_add_f32_dpp v18, v18, v18 row_half_mirror row_mask:0xf bank_mask:0xf bound_ctrl:1
	global_store_dword v[4:5], v20, off
	v_cvt_pk_f16_f32 v4, v2, v3
	v_add_f32_dpp v18, v18, v18 row_mirror row_mask:0xf bank_mask:0xf bound_ctrl:1
	v_mov_b32_e32 v19, v18
	v_lshl_add_u64 v[2:3], s[74:75], 0, v[50:51]
	s_nop 0
	v_permlane16_swap_b32_e32 v18, v19
	v_lshl_add_u64 v[36:37], s[68:69], 0, v[50:51]
	global_store_dword v[2:3], v4, off
	v_cvt_pk_f16_f32 v4, v6, v22
	v_lshl_add_u64 v[2:3], s[78:79], 0, v[50:51]
	global_store_dword v[36:37], v38, off
	global_store_dword v[2:3], v4, off
	s_and_saveexec_b64 s[6:7], s[4:5]
	s_cbranch_execz .LBB0_1238
	v_add_f32_e32 v4, v18, v19
	v_mad_i64_i32 v[2:3], s[86:87], v52, 48, v[200:201]
	global_store_dword v[2:3], v4, off
; DEVI void rwkv_prep_item(const Params& p, const int l, const int item, char* smem) {
;     ...
;     for (int r = 0; r < 16; ++r) {
;       const int t = t0 + mt * 32 + (r & 3) + 8 * (r >> 2) + 4 * hi; const bool has_prev = (t & (SEQ_ - 1)) != 0;
;       float rv[2], kv[2], vv[2], av[2], kkv[2], kpv[2], omdv[2], gv[2];
;       float ssq = 0.f, bon = 0.f;
;       const u16* pr = PA + (size_t)t * 2560 + h * 64 + 2 * l31;
;       const unsigned cr2 = *(const unsigned*)pr, ck2 = *(const unsigned*)(pr + 768), cv2 = *(const unsigned*)(pr + 1536);
;       unsigned qr2 = 0u, qk2 = 0u, qv2 = 0u;
;       if (has_prev) { qr2 = *(const unsigned*)(pr - 2560); qk2 = *(const unsigned*)(pr + 768 - 2560); qv2 = *(const unsigned*)(pr + 1536 - 2560); }
; #pragma unroll
;       for (int n = 0; n < 2; ++n) {
;         const float cr = __uint_as_float(n ? (cr2 & 0xffff0000u) : (cr2 << 16)), ck = __uint_as_float(n ? (ck2 & 0xffff0000u) : (ck2 << 16)), cv = __uint_as_float(n ? (cv2 & 0xffff0000u) : (cv2 << 16));
;         const float qr = __uint_as_float(n ? (qr2 & 0xffff0000u) : (qr2 << 16)), qk = __uint_as_float(n ? (qk2 & 0xffff0000u) : (qk2 << 16)), qv = __uint_as_float(n ? (qv2 & 0xffff0000u) : (qv2 << 16));
;         rv[n] = cr + (qr - cr) * mur[n]; kv[n] = ck + (qk - ck) * muk[n]; vv[n] = cv + (qv - cv) * muv[n];
;         const float z = -(w0c[n] + aw[n][r]);
;         const float sp = fmaxf(z, 0.f) + __logf(1.f + __expf(-fabsf(z)));
;         const float ew = __expf(-sp - 0.5f);
;         omdv[n] = 1.f - __expf(-ew);
;         av[n] = sigmoidf_(a0c[n] + aa[n][r]);
;         gv[n] = ag[n][r];
;         kkv[n] = kv[n] * kkc[n];
;         kpv[n] = kv[n] * (1.f + (av[n] - 1.f) * kac[n]);
;         ssq += kkv[n] * kkv[n];
;         bon += rv[n] * kpv[n] * rkc[n];
;       }
;       ssq = reduce32(ssq); bon = reduce32(bon);
;       const float rn = rsqrtf(ssq + 1e-12f);
;       {
;         typedef _Float16 h2 __attribute__((ext_vector_type(2)));
;         const size_t o = (size_t)t * 768 + h * 64 + 2 * l31;
;         const float kn0 = kkv[0] * rn, kn1 = kkv[1] * rn;
;         *(h2*)(RW + o) = (h2){(f16)rv[0], (f16)rv[1]};
;         *(h2*)(RW + TS + o) = (h2){(f16)omdv[0], (f16)omdv[1]};
;         *(h2*)(RW + 2 * TS + o) = (h2){(f16)kpv[0], (f16)kpv[1]};
;         *(h2*)(RW + 3 * TS + o) = (h2){(f16)vv[0], (f16)vv[1]};
;         *(h2*)(RW + 4 * TS + o) = (h2){(f16)kn0, (f16)kn1};
.LBB0_1238:
	s_or_b64 exec, exec, s[6:7]
	v_or_b32_e32 v6, 9, v233
	v_mad_i64_i32 v[2:3], s[6:7], v6, s88, v[212:213]
	s_waitcnt vmcnt(7)
	v_mov_b32_e32 v4, v246
	v_mov_b32_e32 v5, v247
	v_mov_b32_e32 v20, v248
	v_mov_b32_e32 v22, v249
	v_mov_b32_e32 v34, v250
	v_add_co_u32_e32 v2, vcc, 0xfffff000, v2
	s_nop 0
	v_and_b32_e32 v37, 0xffff0000, v4
	v_addc_co_u32_e32 v3, vcc, -1, v3, vcc
	v_mov_b32_e32 v21, v251
	v_or_b32_e32 v253, 10, v233
	v_mad_i64_i32 v[254:255], s[86:87], v253, s88, v[212:213]
	global_load_dword v246, v[254:255], off
	global_load_dword v247, v[254:255], off offset:1536
	global_load_dword v248, v[254:255], off offset:3072
	global_load_dword v249, v[254:255], off offset:-2048
	global_load_dword v250, v[254:255], off offset:-3584
	v_add_co_u32_e32 v254, vcc, 0xfffff000, v254
	s_nop 1
	v_addc_co_u32_e32 v255, vcc, -1, v255, vcc
	global_load_dword v251, v[254:255], off offset:-1024
	v_lshlrev_b32_e32 v36, 16, v4
	s_nop 0
	v_and_b32_e32 v19, 0xffff0000, v5
	v_lshlrev_b32_e32 v18, 16, v5
	s_nop 0
	v_and_b32_e32 v5, 0xffff0000, v22
	v_lshlrev_b32_e32 v4, 16, v22
	v_add_f32_e32 v22, v87, v210
	v_and_b32_e32 v3, 0xffff0000, v20
	v_lshlrev_b32_e32 v2, 16, v20
	s_nop 0
	v_lshlrev_b32_e32 v20, 16, v34
	v_pk_add_f32 v[4:5], v[4:5], v[2:3] neg_lo:[0,1] neg_hi:[0,1]
	s_nop 0
	v_and_b32_e32 v51, 0xffff0000, v21
	v_lshlrev_b32_e32 v50, 16, v21
	v_and_b32_e32 v21, 0xffff0000, v34
	v_max_f32_e64 v34, -v22, 0
	v_mul_f32_e64 v22, |v22|, s89
	v_exp_f32_e32 v22, v22
	v_pk_add_f32 v[50:51], v[50:51], v[36:37] neg_lo:[0,1] neg_hi:[0,1]
	v_pk_add_f32 v[20:21], v[20:21], v[18:19] neg_lo:[0,1] neg_hi:[0,1]
	v_pk_fma_f32 v[36:37], v[206:207], v[50:51], v[36:37]
	v_add_f32_e32 v22, 1.0, v22
	v_cmp_gt_f32_e32 vcc, s90, v22
	v_cvt_pk_f16_f32 v53, v36, v37
	v_pk_fma_f32 v[20:21], v[204:205], v[20:21], v[18:19]
	v_cndmask_b32_e64 v35, 0, 32, vcc
	v_ldexp_f32 v22, v22, v35
	v_log_f32_e32 v22, v22
	v_pk_fma_f32 v[2:3], v[196:197], v[4:5], v[2:3]
	v_mul_f32_e32 v35, 0x3f317217, v22
	v_fma_f32 v35, v22, s91, -v35
	v_fmac_f32_e32 v35, 0x3377d1cf, v22
	v_fmac_f32_e32 v35, 0x3f317217, v22
	v_cmp_lt_f32_e64 s[6:7], |v22|, s97
	v_cvt_pk_f16_f32 v4, v2, v3
	s_nop 0
	v_cndmask_b32_e64 v22, v22, v35, s[6:7]
	v_cndmask_b32_e32 v35, 0, v232, vcc
	v_sub_f32_e32 v22, v22, v35
	v_add_f32_e32 v35, v39, v211
	v_max_f32_e64 v38, -v35, 0
	v_mul_f32_e64 v35, |v35|, s89
	v_exp_f32_e32 v35, v35
	v_add_f32_e32 v22, v34, v22
	v_sub_f32_e32 v22, -0.5, v22
	v_mul_f32_e32 v22, 0x3fb8aa3b, v22
	v_add_f32_e32 v35, 1.0, v35
	v_cmp_gt_f32_e32 vcc, s90, v35
	v_exp_f32_e32 v22, v22
	v_add_f32_e32 v34, v71, v208
	v_cndmask_b32_e64 v39, 0, 32, vcc
	v_ldexp_f32 v35, v35, v39
	v_log_f32_e32 v35, v35
	v_mul_f32_e32 v22, 0xbfb8aa3b, v22
	v_exp_f32_e32 v22, v22
	v_mul_f32_e32 v34, 0xbfb8aa3b, v34
	v_mul_f32_e32 v39, 0x3f317217, v35
	v_fma_f32 v39, v35, s91, -v39
	v_fmac_f32_e32 v39, 0x3377d1cf, v35
	v_fmac_f32_e32 v39, 0x3f317217, v35
	v_cmp_lt_f32_e64 s[6:7], |v35|, s97
	v_exp_f32_e32 v34, v34
	v_sub_f32_e32 v22, 1.0, v22
	v_cndmask_b32_e64 v35, v35, v39, s[6:7]
	v_cndmask_b32_e32 v39, 0, v232, vcc
	v_sub_f32_e32 v35, v35, v39
	v_add_f32_e32 v35, v38, v35
	v_sub_f32_e32 v35, -0.5, v35
	v_mul_f32_e32 v35, 0x3fb8aa3b, v35
	v_exp_f32_e32 v35, v35
	v_mad_i64_i32 v[38:39], s[6:7], v6, s95, v[102:103]
	v_lshlrev_b64 v[38:39], 1, v[38:39]
	v_mul_f32_e32 v35, 0xbfb8aa3b, v35
	v_exp_f32_e32 v35, v35
	v_lshl_add_u64 v[50:51], s[58:59], 0, v[38:39]
	global_store_dword v[50:51], v53, off
	v_lshl_add_u64 v[50:51], s[66:67], 0, v[38:39]
	v_sub_f32_e32 v52, 1.0, v35
	v_add_f32_e32 v35, v55, v209
	v_mul_f32_e32 v35, 0xbfb8aa3b, v35
	v_exp_f32_e32 v35, v35
	v_cvt_pk_f16_f32 v22, v22, v52
	global_store_dword v[50:51], v22, off
	v_lshl_add_u64 v[2:3], s[70:71], 0, v[38:39]
	v_pk_add_f32 v[18:19], v[34:35], 1.0 op_sel_hi:[1,0]
	global_store_dword v[2:3], v4, off
	v_div_scale_f32 v22, s[6:7], v19, v19, 1.0
	v_rcp_f32_e32 v34, v22
	v_pk_mul_f32 v[2:3], v[194:195], v[20:21]
	v_fma_f32 v35, -v22, v34, 1.0
	v_fmac_f32_e32 v34, v35, v34
	v_div_scale_f32 v35, vcc, 1.0, v19, 1.0
	v_mul_f32_e32 v50, v35, v34
	v_fma_f32 v51, -v22, v50, v35
	v_fmac_f32_e32 v50, v51, v34
	v_fma_f32 v22, -v22, v50, v35
	v_div_fmas_f32 v22, v22, v34, v50
	v_div_fixup_f32 v35, v22, v19, 1.0
	v_div_scale_f32 v19, s[6:7], v18, v18, 1.0
	v_rcp_f32_e32 v22, v19
	v_pk_mul_f32 v[4:5], v[2:3], v[2:3]
	v_fma_f32 v34, -v19, v22, 1.0
	v_add_f32_e32 v4, v4, v5
	v_fmac_f32_e32 v22, v34, v22
	v_div_scale_f32 v34, vcc, 1.0, v18, 1.0
	v_add_f32_dpp v4, v4, v4 quad_perm:[1,0,3,2] row_mask:0xf bank_mask:0xf bound_ctrl:1
	v_mul_f32_e32 v50, v34, v22
	v_fma_f32 v51, -v19, v50, v34
	v_add_f32_dpp v4, v4, v4 quad_perm:[2,3,0,1] row_mask:0xf bank_mask:0xf bound_ctrl:1
	v_fmac_f32_e32 v50, v51, v22
	v_fma_f32 v19, -v19, v50, v34
	v_add_f32_dpp v4, v4, v4 row_half_mirror row_mask:0xf bank_mask:0xf bound_ctrl:1
	v_div_fmas_f32 v19, v19, v22, v50
	v_div_fixup_f32 v34, v19, v18, 1.0
	v_add_f32_dpp v4, v4, v4 row_mirror row_mask:0xf bank_mask:0xf bound_ctrl:1
	v_mov_b32_e32 v5, v4
	s_nop 1
	v_permlane16_swap_b32_e32 v4, v5
	v_add_f32_e32 v4, v4, v5
	v_add_f32_e32 v4, 0x2b8cbccc, v4
	v_pk_add_f32 v[18:19], v[34:35], -1.0 op_sel_hi:[1,0]
	v_cmp_gt_f32_e32 vcc, s90, v4
	v_mul_f32_e32 v5, 0x4b800000, v4
	v_pk_fma_f32 v[18:19], v[202:203], v[18:19], 1.0 op_sel_hi:[1,1,0]
	v_cndmask_b32_e32 v4, v4, v5, vcc
	v_pk_mul_f32 v[50:51], v[18:19], v[20:21]
	v_rsq_f32_e32 v4, v4
	v_pk_mul_f32 v[18:19], v[36:37], v[50:51]
	v_cvt_pk_f16_f32 v22, v50, v51
	v_fma_f32 v18, v198, v18, 0
	v_fmac_f32_e32 v18, v199, v19
	v_mul_f32_e32 v5, 0x45800000, v4
	v_cndmask_b32_e32 v4, v4, v5, vcc
	v_add_f32_dpp v18, v18, v18 quad_perm:[1,0,3,2] row_mask:0xf bank_mask:0xf bound_ctrl:1
	v_pk_mul_f32 v[2:3], v[2:3], v[4:5] op_sel_hi:[1,0]
	v_lshl_add_u64 v[4:5], s[72:73], 0, v[38:39]
	v_add_f32_dpp v18, v18, v18 quad_perm:[2,3,0,1] row_mask:0xf bank_mask:0xf bound_ctrl:1
	v_cvt_pk_f16_f32 v20, v2, v3
	v_pk_mul_f32 v[2:3], v[34:35], v[2:3]
	v_add_f32_dpp v18, v18, v18 row_half_mirror row_mask:0xf bank_mask:0xf bound_ctrl:1
	global_store_dword v[4:5], v20, off
	v_cvt_pk_f16_f32 v4, v2, v3
	v_add_f32_dpp v18, v18, v18 row_mirror row_mask:0xf bank_mask:0xf bound_ctrl:1
	v_mov_b32_e32 v19, v18
	v_lshl_add_u64 v[2:3], s[74:75], 0, v[38:39]
	s_nop 0
	v_permlane16_swap_b32_e32 v18, v19
	v_lshl_add_u64 v[36:37], s[68:69], 0, v[38:39]
	global_store_dword v[2:3], v4, off
	v_cvt_pk_f16_f32 v4, v7, v23
	v_lshl_add_u64 v[2:3], s[78:79], 0, v[38:39]
	global_store_dword v[36:37], v22, off
	global_store_dword v[2:3], v4, off
	s_and_saveexec_b64 s[6:7], s[4:5]
	s_cbranch_execz .LBB0_1240
	v_add_f32_e32 v4, v18, v19
	v_mad_i64_i32 v[2:3], s[86:87], v6, 48, v[200:201]
	global_store_dword v[2:3], v4, off
; DEVI void rwkv_prep_item(const Params& p, const int l, const int item, char* smem) {
;     ...
;     for (int r = 0; r < 16; ++r) {
;       const int t = t0 + mt * 32 + (r & 3) + 8 * (r >> 2) + 4 * hi; const bool has_prev = (t & (SEQ_ - 1)) != 0;
;       float rv[2], kv[2], vv[2], av[2], kkv[2], kpv[2], omdv[2], gv[2];
;       float ssq = 0.f, bon = 0.f;
;       const u16* pr = PA + (size_t)t * 2560 + h * 64 + 2 * l31;
;       const unsigned cr2 = *(const unsigned*)pr, ck2 = *(const unsigned*)(pr + 768), cv2 = *(const unsigned*)(pr + 1536);
;       unsigned qr2 = 0u, qk2 = 0u, qv2 = 0u;
;       if (has_prev) { qr2 = *(const unsigned*)(pr - 2560); qk2 = *(const unsigned*)(pr + 768 - 2560); qv2 = *(const unsigned*)(pr + 1536 - 2560); }
; #pragma unroll
;       for (int n = 0; n < 2; ++n) {
;         const float cr = __uint_as_float(n ? (cr2 & 0xffff0000u) : (cr2 << 16)), ck = __uint_as_float(n ? (ck2 & 0xffff0000u) : (ck2 << 16)), cv = __uint_as_float(n ? (cv2 & 0xffff0000u) : (cv2 << 16));
;         const float qr = __uint_as_float(n ? (qr2 & 0xffff0000u) : (qr2 << 16)), qk = __uint_as_float(n ? (qk2 & 0xffff0000u) : (qk2 << 16)), qv = __uint_as_float(n ? (qv2 & 0xffff0000u) : (qv2 << 16));
;         rv[n] = cr + (qr - cr) * mur[n]; kv[n] = ck + (qk - ck) * muk[n]; vv[n] = cv + (qv - cv) * muv[n];
;         const float z = -(w0c[n] + aw[n][r]);
;         const float sp = fmaxf(z, 0.f) + __logf(1.f + __expf(-fabsf(z)));
;         const float ew = __expf(-sp - 0.5f);
;         omdv[n] = 1.f - __expf(-ew);
;         av[n] = sigmoidf_(a0c[n] + aa[n][r]);
;         gv[n] = ag[n][r];
;         kkv[n] = kv[n] * kkc[n];
;         kpv[n] = kv[n] * (1.f + (av[n] - 1.f) * kac[n]);
;         ssq += kkv[n] * kkv[n];
;         bon += rv[n] * kpv[n] * rkc[n];
;       }
;       ssq = reduce32(ssq); bon = reduce32(bon);
;       const float rn = rsqrtf(ssq + 1e-12f);
;       {
;         typedef _Float16 h2 __attribute__((ext_vector_type(2)));
;         const size_t o = (size_t)t * 768 + h * 64 + 2 * l31;
;         const float kn0 = kkv[0] * rn, kn1 = kkv[1] * rn;
;         *(h2*)(RW + o) = (h2){(f16)rv[0], (f16)rv[1]};
;         *(h2*)(RW + TS + o) = (h2){(f16)omdv[0], (f16)omdv[1]};
;         *(h2*)(RW + 2 * TS + o) = (h2){(f16)kpv[0], (f16)kpv[1]};
;         *(h2*)(RW + 3 * TS + o) = (h2){(f16)vv[0], (f16)vv[1]};
;         *(h2*)(RW + 4 * TS + o) = (h2){(f16)kn0, (f16)kn1};
.LBB0_1240:
	s_or_b64 exec, exec, s[6:7]
	v_or_b32_e32 v36, 10, v233
	v_mad_i64_i32 v[2:3], s[6:7], v36, s88, v[212:213]
	s_waitcnt vmcnt(7)
	v_mov_b32_e32 v4, v246
	v_mov_b32_e32 v5, v247
	v_mov_b32_e32 v18, v248
	v_mov_b32_e32 v20, v249
	v_mov_b32_e32 v21, v250
	v_add_co_u32_e32 v2, vcc, 0xfffff000, v2
	s_nop 0
	v_and_b32_e32 v23, 0xffff0000, v4
	v_addc_co_u32_e32 v3, vcc, -1, v3, vcc
	v_mov_b32_e32 v19, v251
	v_or_b32_e32 v253, 11, v233
	v_mad_i64_i32 v[254:255], s[86:87], v253, s88, v[212:213]
	global_load_dword v246, v[254:255], off
	global_load_dword v247, v[254:255], off offset:1536
	global_load_dword v248, v[254:255], off offset:3072
	global_load_dword v249, v[254:255], off offset:-2048
	global_load_dword v250, v[254:255], off offset:-3584
	v_add_co_u32_e32 v254, vcc, 0xfffff000, v254
	s_nop 1
	v_addc_co_u32_e32 v255, vcc, -1, v255, vcc
	global_load_dword v251, v[254:255], off offset:-1024
	v_lshlrev_b32_e32 v22, 16, v4
	s_nop 0
	v_and_b32_e32 v7, 0xffff0000, v5
	v_lshlrev_b32_e32 v6, 16, v5
	s_nop 0
	v_and_b32_e32 v5, 0xffff0000, v20
	v_lshlrev_b32_e32 v4, 16, v20
	v_add_f32_e32 v20, v88, v210
	v_and_b32_e32 v3, 0xffff0000, v18
	v_lshlrev_b32_e32 v2, 16, v18
	s_nop 0
	v_lshlrev_b32_e32 v18, 16, v21
	v_pk_add_f32 v[4:5], v[4:5], v[2:3] neg_lo:[0,1] neg_hi:[0,1]
	s_nop 0
	v_and_b32_e32 v35, 0xffff0000, v19
	v_lshlrev_b32_e32 v34, 16, v19
	v_and_b32_e32 v19, 0xffff0000, v21
	v_max_f32_e64 v21, -v20, 0
	v_mul_f32_e64 v20, |v20|, s89
	v_exp_f32_e32 v20, v20
	v_pk_add_f32 v[18:19], v[18:19], v[6:7] neg_lo:[0,1] neg_hi:[0,1]
	v_pk_add_f32 v[34:35], v[34:35], v[22:23] neg_lo:[0,1] neg_hi:[0,1]
	v_pk_fma_f32 v[18:19], v[204:205], v[18:19], v[6:7]
	v_add_f32_e32 v20, 1.0, v20
	v_cmp_gt_f32_e32 vcc, s90, v20
	v_pk_fma_f32 v[22:23], v[206:207], v[34:35], v[22:23]
	v_pk_fma_f32 v[2:3], v[196:197], v[4:5], v[2:3]
	v_cndmask_b32_e64 v37, 0, 32, vcc
	v_ldexp_f32 v20, v20, v37
	v_log_f32_e32 v20, v20
	v_cvt_pk_f16_f32 v50, v22, v23
	v_cvt_pk_f16_f32 v4, v2, v3
	v_mul_f32_e32 v37, 0x3f317217, v20
	v_fma_f32 v37, v20, s91, -v37
	v_fmac_f32_e32 v37, 0x3377d1cf, v20
	v_fmac_f32_e32 v37, 0x3f317217, v20
	v_cmp_lt_f32_e64 s[6:7], |v20|, s97
	s_nop 1
	v_cndmask_b32_e64 v20, v20, v37, s[6:7]
	v_cndmask_b32_e32 v37, 0, v232, vcc
	v_sub_f32_e32 v20, v20, v37
	v_add_f32_e32 v20, v21, v20
	v_add_f32_e32 v21, v40, v211
	v_max_f32_e64 v38, -v21, 0
	v_mul_f32_e64 v21, |v21|, s89
	v_exp_f32_e32 v21, v21
	v_sub_f32_e32 v20, -0.5, v20
	v_mul_f32_e32 v20, 0x3fb8aa3b, v20
	v_exp_f32_e32 v20, v20
	v_add_f32_e32 v21, 1.0, v21
	v_cmp_gt_f32_e32 vcc, s90, v21
	v_mul_f32_e32 v20, 0xbfb8aa3b, v20
	s_nop 0
	v_cndmask_b32_e64 v39, 0, 32, vcc
	v_ldexp_f32 v21, v21, v39
	v_log_f32_e32 v21, v21
	v_exp_f32_e32 v20, v20
	v_mul_f32_e32 v39, 0x3f317217, v21
	v_fma_f32 v39, v21, s91, -v39
	v_fmac_f32_e32 v39, 0x3377d1cf, v21
	v_fmac_f32_e32 v39, 0x3f317217, v21
	v_cmp_lt_f32_e64 s[6:7], |v21|, s97
	v_sub_f32_e32 v37, 1.0, v20
	v_add_f32_e32 v20, v72, v208
	v_cndmask_b32_e64 v21, v21, v39, s[6:7]
	v_cndmask_b32_e32 v39, 0, v232, vcc
	v_sub_f32_e32 v21, v21, v39
	v_add_f32_e32 v21, v38, v21
	v_sub_f32_e32 v21, -0.5, v21
	v_mul_f32_e32 v21, 0x3fb8aa3b, v21
	v_exp_f32_e32 v21, v21
	v_mul_f32_e32 v20, 0xbfb8aa3b, v20
	v_exp_f32_e32 v20, v20
	v_mad_i64_i32 v[38:39], s[6:7], v36, s95, v[102:103]
	v_mul_f32_e32 v21, 0xbfb8aa3b, v21
	v_exp_f32_e32 v21, v21
	v_lshlrev_b64 v[34:35], 1, v[38:39]
	v_lshl_add_u64 v[38:39], s[58:59], 0, v[34:35]
	global_store_dword v[38:39], v50, off
	v_sub_f32_e32 v40, 1.0, v21
	v_add_f32_e32 v21, v56, v209
	v_mul_f32_e32 v21, 0xbfb8aa3b, v21
	v_exp_f32_e32 v21, v21
	v_cvt_pk_f16_f32 v37, v37, v40
	v_lshl_add_u64 v[38:39], s[66:67], 0, v[34:35]
	global_store_dword v[38:39], v37, off
	v_pk_add_f32 v[6:7], v[20:21], 1.0 op_sel_hi:[1,0]
	v_lshl_add_u64 v[2:3], s[70:71], 0, v[34:35]
	v_div_scale_f32 v20, s[6:7], v7, v7, 1.0
	v_rcp_f32_e32 v21, v20
	global_store_dword v[2:3], v4, off
	v_pk_mul_f32 v[2:3], v[194:195], v[18:19]
	v_fma_f32 v37, -v20, v21, 1.0
	v_fmac_f32_e32 v21, v37, v21
	v_div_scale_f32 v37, vcc, 1.0, v7, 1.0
	v_mul_f32_e32 v38, v37, v21
	v_fma_f32 v39, -v20, v38, v37
	v_fmac_f32_e32 v38, v39, v21
	v_fma_f32 v20, -v20, v38, v37
	v_div_fmas_f32 v20, v20, v21, v38
	v_div_fixup_f32 v21, v20, v7, 1.0
	v_div_scale_f32 v7, s[6:7], v6, v6, 1.0
	v_rcp_f32_e32 v20, v7
	v_pk_mul_f32 v[4:5], v[2:3], v[2:3]
	v_fma_f32 v37, -v7, v20, 1.0
	v_add_f32_e32 v4, v4, v5
	v_fmac_f32_e32 v20, v37, v20
	v_div_scale_f32 v37, vcc, 1.0, v6, 1.0
	v_add_f32_dpp v4, v4, v4 quad_perm:[1,0,3,2] row_mask:0xf bank_mask:0xf bound_ctrl:1
	v_mul_f32_e32 v38, v37, v20
	v_fma_f32 v39, -v7, v38, v37
	v_add_f32_dpp v4, v4, v4 quad_perm:[2,3,0,1] row_mask:0xf bank_mask:0xf bound_ctrl:1
	v_fmac_f32_e32 v38, v39, v20
	v_fma_f32 v7, -v7, v38, v37
	v_add_f32_dpp v4, v4, v4 row_half_mirror row_mask:0xf bank_mask:0xf bound_ctrl:1
	v_div_fmas_f32 v7, v7, v20, v38
	v_div_fixup_f32 v20, v7, v6, 1.0
	v_add_f32_dpp v4, v4, v4 row_mirror row_mask:0xf bank_mask:0xf bound_ctrl:1
	v_mov_b32_e32 v5, v4
	s_nop 1
	v_permlane16_swap_b32_e32 v4, v5
	v_add_f32_e32 v4, v4, v5
	v_add_f32_e32 v4, 0x2b8cbccc, v4
	v_pk_add_f32 v[6:7], v[20:21], -1.0 op_sel_hi:[1,0]
	v_cmp_gt_f32_e32 vcc, s90, v4
	v_mul_f32_e32 v5, 0x4b800000, v4
	v_pk_fma_f32 v[6:7], v[202:203], v[6:7], 1.0 op_sel_hi:[1,1,0]
	v_cndmask_b32_e32 v4, v4, v5, vcc
	v_pk_mul_f32 v[38:39], v[6:7], v[18:19]
	v_rsq_f32_e32 v4, v4
	v_pk_mul_f32 v[6:7], v[22:23], v[38:39]
	v_cvt_pk_f16_f32 v37, v38, v39
	v_fma_f32 v6, v198, v6, 0
	v_fmac_f32_e32 v6, v199, v7
	v_mul_f32_e32 v5, 0x45800000, v4
	v_cndmask_b32_e32 v4, v4, v5, vcc
	v_add_f32_dpp v6, v6, v6 quad_perm:[1,0,3,2] row_mask:0xf bank_mask:0xf bound_ctrl:1
	v_pk_mul_f32 v[2:3], v[2:3], v[4:5] op_sel_hi:[1,0]
	v_lshl_add_u64 v[4:5], s[72:73], 0, v[34:35]
	v_add_f32_dpp v6, v6, v6 quad_perm:[2,3,0,1] row_mask:0xf bank_mask:0xf bound_ctrl:1
	v_cvt_pk_f16_f32 v18, v2, v3
	v_pk_mul_f32 v[2:3], v[20:21], v[2:3]
	v_add_f32_dpp v6, v6, v6 row_half_mirror row_mask:0xf bank_mask:0xf bound_ctrl:1
	global_store_dword v[4:5], v18, off
	v_cvt_pk_f16_f32 v4, v2, v3
	v_add_f32_dpp v6, v6, v6 row_mirror row_mask:0xf bank_mask:0xf bound_ctrl:1
	v_mov_b32_e32 v7, v6
	v_lshl_add_u64 v[2:3], s[74:75], 0, v[34:35]
	s_nop 0
	v_permlane16_swap_b32_e32 v6, v7
	v_lshl_add_u64 v[22:23], s[68:69], 0, v[34:35]
	global_store_dword v[2:3], v4, off
	v_cvt_pk_f16_f32 v4, v8, v24
	v_lshl_add_u64 v[2:3], s[78:79], 0, v[34:35]
	global_store_dword v[22:23], v37, off
	global_store_dword v[2:3], v4, off
	s_and_saveexec_b64 s[6:7], s[4:5]
	s_cbranch_execz .LBB0_1242
	v_add_f32_e32 v4, v6, v7
	v_mad_i64_i32 v[2:3], s[86:87], v36, 48, v[200:201]
	global_store_dword v[2:3], v4, off
; DEVI void rwkv_prep_item(const Params& p, const int l, const int item, char* smem) {
;     ...
;     for (int r = 0; r < 16; ++r) {
;       const int t = t0 + mt * 32 + (r & 3) + 8 * (r >> 2) + 4 * hi; const bool has_prev = (t & (SEQ_ - 1)) != 0;
;       float rv[2], kv[2], vv[2], av[2], kkv[2], kpv[2], omdv[2], gv[2];
;       float ssq = 0.f, bon = 0.f;
;       const u16* pr = PA + (size_t)t * 2560 + h * 64 + 2 * l31;
;       const unsigned cr2 = *(const unsigned*)pr, ck2 = *(const unsigned*)(pr + 768), cv2 = *(const unsigned*)(pr + 1536);
;       unsigned qr2 = 0u, qk2 = 0u, qv2 = 0u;
;       if (has_prev) { qr2 = *(const unsigned*)(pr - 2560); qk2 = *(const unsigned*)(pr + 768 - 2560); qv2 = *(const unsigned*)(pr + 1536 - 2560); }
; #pragma unroll
;       for (int n = 0; n < 2; ++n) {
;         const float cr = __uint_as_float(n ? (cr2 & 0xffff0000u) : (cr2 << 16)), ck = __uint_as_float(n ? (ck2 & 0xffff0000u) : (ck2 << 16)), cv = __uint_as_float(n ? (cv2 & 0xffff0000u) : (cv2 << 16));
;         const float qr = __uint_as_float(n ? (qr2 & 0xffff0000u) : (qr2 << 16)), qk = __uint_as_float(n ? (qk2 & 0xffff0000u) : (qk2 << 16)), qv = __uint_as_float(n ? (qv2 & 0xffff0000u) : (qv2 << 16));
;         rv[n] = cr + (qr - cr) * mur[n]; kv[n] = ck + (qk - ck) * muk[n]; vv[n] = cv + (qv - cv) * muv[n];
;         const float z = -(w0c[n] + aw[n][r]);
;         const float sp = fmaxf(z, 0.f) + __logf(1.f + __expf(-fabsf(z)));
;         const float ew = __expf(-sp - 0.5f);
;         omdv[n] = 1.f - __expf(-ew);
;         av[n] = sigmoidf_(a0c[n] + aa[n][r]);
;         gv[n] = ag[n][r];
;         kkv[n] = kv[n] * kkc[n];
;         kpv[n] = kv[n] * (1.f + (av[n] - 1.f) * kac[n]);
;         ssq += kkv[n] * kkv[n];
;         bon += rv[n] * kpv[n] * rkc[n];
;       }
;       ssq = reduce32(ssq); bon = reduce32(bon);
;       const float rn = rsqrtf(ssq + 1e-12f);
;       {
;         typedef _Float16 h2 __attribute__((ext_vector_type(2)));
;         const size_t o = (size_t)t * 768 + h * 64 + 2 * l31;
;         const float kn0 = kkv[0] * rn, kn1 = kkv[1] * rn;
;         *(h2*)(RW + o) = (h2){(f16)rv[0], (f16)rv[1]};
;         *(h2*)(RW + TS + o) = (h2){(f16)omdv[0], (f16)omdv[1]};
;         *(h2*)(RW + 2 * TS + o) = (h2){(f16)kpv[0], (f16)kpv[1]};
;         *(h2*)(RW + 3 * TS + o) = (h2){(f16)vv[0], (f16)vv[1]};
;         *(h2*)(RW + 4 * TS + o) = (h2){(f16)kn0, (f16)kn1};
.LBB0_1242:
	s_or_b64 exec, exec, s[6:7]
	v_or_b32_e32 v8, 11, v233
	v_mad_i64_i32 v[2:3], s[6:7], v8, s88, v[212:213]
	s_waitcnt vmcnt(7)
	v_mov_b32_e32 v4, v246
	v_mov_b32_e32 v5, v247
	v_mov_b32_e32 v18, v248
	v_mov_b32_e32 v20, v249
	v_mov_b32_e32 v21, v250
	v_add_co_u32_e32 v2, vcc, 0xfffff000, v2
	s_nop 0
	v_and_b32_e32 v23, 0xffff0000, v4
	v_addc_co_u32_e32 v3, vcc, -1, v3, vcc
	v_mov_b32_e32 v19, v251
	v_or_b32_e32 v253, 16, v233
	v_mad_i64_i32 v[254:255], s[86:87], v253, s88, v[212:213]
	global_load_dword v246, v[254:255], off
	global_load_dword v247, v[254:255], off offset:1536
	global_load_dword v248, v[254:255], off offset:3072
	global_load_dword v249, v[254:255], off offset:-2048
	global_load_dword v250, v[254:255], off offset:-3584
	v_add_co_u32_e32 v254, vcc, 0xfffff000, v254
	s_nop 1
	v_addc_co_u32_e32 v255, vcc, -1, v255, vcc
	global_load_dword v251, v[254:255], off offset:-1024
	v_lshlrev_b32_e32 v22, 16, v4
	s_nop 0
	v_and_b32_e32 v7, 0xffff0000, v5
	v_lshlrev_b32_e32 v6, 16, v5
	s_nop 0
	v_and_b32_e32 v5, 0xffff0000, v20
	v_lshlrev_b32_e32 v4, 16, v20
	v_add_f32_e32 v20, v89, v210
	v_and_b32_e32 v3, 0xffff0000, v18
	v_lshlrev_b32_e32 v2, 16, v18
	s_nop 0
	v_lshlrev_b32_e32 v18, 16, v21
	v_pk_add_f32 v[4:5], v[4:5], v[2:3] neg_lo:[0,1] neg_hi:[0,1]
	s_nop 0
	v_and_b32_e32 v35, 0xffff0000, v19
	v_lshlrev_b32_e32 v34, 16, v19
	v_and_b32_e32 v19, 0xffff0000, v21
	v_max_f32_e64 v21, -v20, 0
	v_mul_f32_e64 v20, |v20|, s89
	v_exp_f32_e32 v20, v20
	v_pk_add_f32 v[18:19], v[18:19], v[6:7] neg_lo:[0,1] neg_hi:[0,1]
	v_pk_add_f32 v[34:35], v[34:35], v[22:23] neg_lo:[0,1] neg_hi:[0,1]
	v_pk_fma_f32 v[18:19], v[204:205], v[18:19], v[6:7]
	v_add_f32_e32 v20, 1.0, v20
	v_cmp_gt_f32_e32 vcc, s90, v20
	v_pk_fma_f32 v[22:23], v[206:207], v[34:35], v[22:23]
	v_pk_fma_f32 v[2:3], v[196:197], v[4:5], v[2:3]
	v_cndmask_b32_e64 v24, 0, 32, vcc
	v_ldexp_f32 v20, v20, v24
	v_log_f32_e32 v20, v20
	v_cvt_pk_f16_f32 v39, v22, v23
	v_cvt_pk_f16_f32 v4, v2, v3
	v_mul_f32_e32 v24, 0x3f317217, v20
	v_fma_f32 v24, v20, s91, -v24
	v_fmac_f32_e32 v24, 0x3377d1cf, v20
	v_fmac_f32_e32 v24, 0x3f317217, v20
	v_cmp_lt_f32_e64 s[6:7], |v20|, s97
	s_nop 1
	v_cndmask_b32_e64 v20, v20, v24, s[6:7]
	v_cndmask_b32_e32 v24, 0, v232, vcc
	v_sub_f32_e32 v20, v20, v24
	v_add_f32_e32 v20, v21, v20
	v_add_f32_e32 v21, v41, v211
	v_max_f32_e64 v36, -v21, 0
	v_mul_f32_e64 v21, |v21|, s89
	v_exp_f32_e32 v21, v21
	v_sub_f32_e32 v20, -0.5, v20
	v_mul_f32_e32 v20, 0x3fb8aa3b, v20
	v_exp_f32_e32 v20, v20
	v_add_f32_e32 v21, 1.0, v21
	v_cmp_gt_f32_e32 vcc, s90, v21
	v_mul_f32_e32 v20, 0xbfb8aa3b, v20
	s_nop 0
	v_cndmask_b32_e64 v37, 0, 32, vcc
	v_ldexp_f32 v21, v21, v37
	v_log_f32_e32 v21, v21
	v_exp_f32_e32 v20, v20
	v_mul_f32_e32 v37, 0x3f317217, v21
	v_fma_f32 v37, v21, s91, -v37
	v_fmac_f32_e32 v37, 0x3377d1cf, v21
	v_fmac_f32_e32 v37, 0x3f317217, v21
	v_cmp_lt_f32_e64 s[6:7], |v21|, s97
	v_sub_f32_e32 v24, 1.0, v20
	v_add_f32_e32 v20, v73, v208
	v_cndmask_b32_e64 v21, v21, v37, s[6:7]
	v_cndmask_b32_e32 v37, 0, v232, vcc
	v_sub_f32_e32 v21, v21, v37
	v_add_f32_e32 v21, v36, v21
	v_sub_f32_e32 v21, -0.5, v21
	v_mul_f32_e32 v21, 0x3fb8aa3b, v21
	v_exp_f32_e32 v21, v21
	v_mul_f32_e32 v20, 0xbfb8aa3b, v20
	v_exp_f32_e32 v20, v20
	v_mad_i64_i32 v[36:37], s[6:7], v8, s95, v[102:103]
	v_mul_f32_e32 v21, 0xbfb8aa3b, v21
	v_exp_f32_e32 v21, v21
	v_lshlrev_b64 v[34:35], 1, v[36:37]
	v_lshl_add_u64 v[36:37], s[58:59], 0, v[34:35]
	global_store_dword v[36:37], v39, off
	v_sub_f32_e32 v38, 1.0, v21
	v_add_f32_e32 v21, v57, v209
	v_mul_f32_e32 v21, 0xbfb8aa3b, v21
	v_exp_f32_e32 v21, v21
	v_cvt_pk_f16_f32 v24, v24, v38
	v_lshl_add_u64 v[36:37], s[66:67], 0, v[34:35]
	global_store_dword v[36:37], v24, off
	v_pk_add_f32 v[6:7], v[20:21], 1.0 op_sel_hi:[1,0]
	v_lshl_add_u64 v[2:3], s[70:71], 0, v[34:35]
	v_div_scale_f32 v20, s[6:7], v7, v7, 1.0
	v_rcp_f32_e32 v21, v20
	global_store_dword v[2:3], v4, off
	v_pk_mul_f32 v[2:3], v[194:195], v[18:19]
	v_fma_f32 v24, -v20, v21, 1.0
	v_fmac_f32_e32 v21, v24, v21
	v_div_scale_f32 v24, vcc, 1.0, v7, 1.0
	v_mul_f32_e32 v36, v24, v21
	v_fma_f32 v37, -v20, v36, v24
	v_fmac_f32_e32 v36, v37, v21
	v_fma_f32 v20, -v20, v36, v24
	v_div_fmas_f32 v20, v20, v21, v36
	v_div_fixup_f32 v21, v20, v7, 1.0
	v_div_scale_f32 v7, s[6:7], v6, v6, 1.0
	v_rcp_f32_e32 v20, v7
	v_pk_mul_f32 v[4:5], v[2:3], v[2:3]
	v_fma_f32 v24, -v7, v20, 1.0
	v_add_f32_e32 v4, v4, v5
	v_fmac_f32_e32 v20, v24, v20
	v_div_scale_f32 v24, vcc, 1.0, v6, 1.0
	v_add_f32_dpp v4, v4, v4 quad_perm:[1,0,3,2] row_mask:0xf bank_mask:0xf bound_ctrl:1
	v_mul_f32_e32 v36, v24, v20
	v_fma_f32 v37, -v7, v36, v24
	v_add_f32_dpp v4, v4, v4 quad_perm:[2,3,0,1] row_mask:0xf bank_mask:0xf bound_ctrl:1
	v_fmac_f32_e32 v36, v37, v20
	v_fma_f32 v7, -v7, v36, v24
	v_add_f32_dpp v4, v4, v4 row_half_mirror row_mask:0xf bank_mask:0xf bound_ctrl:1
	v_div_fmas_f32 v7, v7, v20, v36
	v_div_fixup_f32 v20, v7, v6, 1.0
	v_add_f32_dpp v4, v4, v4 row_mirror row_mask:0xf bank_mask:0xf bound_ctrl:1
	v_mov_b32_e32 v5, v4
	s_nop 1
	v_permlane16_swap_b32_e32 v4, v5
	v_add_f32_e32 v4, v4, v5
	v_add_f32_e32 v4, 0x2b8cbccc, v4
	v_pk_add_f32 v[6:7], v[20:21], -1.0 op_sel_hi:[1,0]
	v_cmp_gt_f32_e32 vcc, s90, v4
	v_mul_f32_e32 v5, 0x4b800000, v4
	v_pk_fma_f32 v[6:7], v[202:203], v[6:7], 1.0 op_sel_hi:[1,1,0]
	v_cndmask_b32_e32 v4, v4, v5, vcc
	v_pk_mul_f32 v[36:37], v[6:7], v[18:19]
	v_rsq_f32_e32 v4, v4
	v_pk_mul_f32 v[6:7], v[22:23], v[36:37]
	v_cvt_pk_f16_f32 v24, v36, v37
	v_fma_f32 v6, v198, v6, 0
	v_fmac_f32_e32 v6, v199, v7
	v_mul_f32_e32 v5, 0x45800000, v4
	v_cndmask_b32_e32 v4, v4, v5, vcc
	v_add_f32_dpp v6, v6, v6 quad_perm:[1,0,3,2] row_mask:0xf bank_mask:0xf bound_ctrl:1
	v_pk_mul_f32 v[2:3], v[2:3], v[4:5] op_sel_hi:[1,0]
	v_lshl_add_u64 v[4:5], s[72:73], 0, v[34:35]
	v_add_f32_dpp v6, v6, v6 quad_perm:[2,3,0,1] row_mask:0xf bank_mask:0xf bound_ctrl:1
	v_cvt_pk_f16_f32 v18, v2, v3
	v_pk_mul_f32 v[2:3], v[20:21], v[2:3]
	v_add_f32_dpp v6, v6, v6 row_half_mirror row_mask:0xf bank_mask:0xf bound_ctrl:1
	global_store_dword v[4:5], v18, off
	v_cvt_pk_f16_f32 v4, v2, v3
	v_add_f32_dpp v6, v6, v6 row_mirror row_mask:0xf bank_mask:0xf bound_ctrl:1
	v_mov_b32_e32 v7, v6
	v_lshl_add_u64 v[2:3], s[74:75], 0, v[34:35]
	s_nop 0
	v_permlane16_swap_b32_e32 v6, v7
	v_lshl_add_u64 v[22:23], s[68:69], 0, v[34:35]
	global_store_dword v[2:3], v4, off
	v_cvt_pk_f16_f32 v4, v9, v25
	v_lshl_add_u64 v[2:3], s[78:79], 0, v[34:35]
	global_store_dword v[22:23], v24, off
	global_store_dword v[2:3], v4, off
	s_and_saveexec_b64 s[6:7], s[4:5]
	s_cbranch_execz .LBB0_1244
	v_add_f32_e32 v4, v6, v7
	v_mad_i64_i32 v[2:3], s[86:87], v8, 48, v[200:201]
	global_store_dword v[2:3], v4, off
; DEVI void rwkv_prep_item(const Params& p, const int l, const int item, char* smem) {
;     ...
;     for (int r = 0; r < 16; ++r) {
;       const int t = t0 + mt * 32 + (r & 3) + 8 * (r >> 2) + 4 * hi; const bool has_prev = (t & (SEQ_ - 1)) != 0;
;       float rv[2], kv[2], vv[2], av[2], kkv[2], kpv[2], omdv[2], gv[2];
;       float ssq = 0.f, bon = 0.f;
;       const u16* pr = PA + (size_t)t * 2560 + h * 64 + 2 * l31;
;       const unsigned cr2 = *(const unsigned*)pr, ck2 = *(const unsigned*)(pr + 768), cv2 = *(const unsigned*)(pr + 1536);
;       unsigned qr2 = 0u, qk2 = 0u, qv2 = 0u;
;       if (has_prev) { qr2 = *(const unsigned*)(pr - 2560); qk2 = *(const unsigned*)(pr + 768 - 2560); qv2 = *(const unsigned*)(pr + 1536 - 2560); }
; #pragma unroll
;       for (int n = 0; n < 2; ++n) {
;         const float cr = __uint_as_float(n ? (cr2 & 0xffff0000u) : (cr2 << 16)), ck = __uint_as_float(n ? (ck2 & 0xffff0000u) : (ck2 << 16)), cv = __uint_as_float(n ? (cv2 & 0xffff0000u) : (cv2 << 16));
;         const float qr = __uint_as_float(n ? (qr2 & 0xffff0000u) : (qr2 << 16)), qk = __uint_as_float(n ? (qk2 & 0xffff0000u) : (qk2 << 16)), qv = __uint_as_float(n ? (qv2 & 0xffff0000u) : (qv2 << 16));
;         rv[n] = cr + (qr - cr) * mur[n]; kv[n] = ck + (qk - ck) * muk[n]; vv[n] = cv + (qv - cv) * muv[n];
;         const float z = -(w0c[n] + aw[n][r]);
;         const float sp = fmaxf(z, 0.f) + __logf(1.f + __expf(-fabsf(z)));
;         const float ew = __expf(-sp - 0.5f);
;         omdv[n] = 1.f - __expf(-ew);
;         av[n] = sigmoidf_(a0c[n] + aa[n][r]);
;         gv[n] = ag[n][r];
;         kkv[n] = kv[n] * kkc[n];
;         kpv[n] = kv[n] * (1.f + (av[n] - 1.f) * kac[n]);
;         ssq += kkv[n] * kkv[n];
;         bon += rv[n] * kpv[n] * rkc[n];
;       }
;       ssq = reduce32(ssq); bon = reduce32(bon);
;       const float rn = rsqrtf(ssq + 1e-12f);
;       {
;         typedef _Float16 h2 __attribute__((ext_vector_type(2)));
;         const size_t o = (size_t)t * 768 + h * 64 + 2 * l31;
;         const float kn0 = kkv[0] * rn, kn1 = kkv[1] * rn;
;         *(h2*)(RW + o) = (h2){(f16)rv[0], (f16)rv[1]};
;         *(h2*)(RW + TS + o) = (h2){(f16)omdv[0], (f16)omdv[1]};
;         *(h2*)(RW + 2 * TS + o) = (h2){(f16)kpv[0], (f16)kpv[1]};
;         *(h2*)(RW + 3 * TS + o) = (h2){(f16)vv[0], (f16)vv[1]};
;         *(h2*)(RW + 4 * TS + o) = (h2){(f16)kn0, (f16)kn1};
.LBB0_1244:
	s_or_b64 exec, exec, s[6:7]
	v_or_b32_e32 v24, 16, v233
	v_mad_i64_i32 v[2:3], s[6:7], v24, s88, v[212:213]
	s_waitcnt vmcnt(7)
	v_mov_b32_e32 v4, v246
	v_mov_b32_e32 v5, v247
	v_mov_b32_e32 v8, v248
	v_mov_b32_e32 v18, v249
	v_mov_b32_e32 v19, v250
	v_add_co_u32_e32 v2, vcc, 0xfffff000, v2
	s_nop 0
	v_and_b32_e32 v21, 0xffff0000, v4
	v_addc_co_u32_e32 v3, vcc, -1, v3, vcc
	v_mov_b32_e32 v9, v251
	v_or_b32_e32 v253, 17, v233
	v_mad_i64_i32 v[254:255], s[86:87], v253, s88, v[212:213]
	global_load_dword v246, v[254:255], off
	global_load_dword v247, v[254:255], off offset:1536
	global_load_dword v248, v[254:255], off offset:3072
	global_load_dword v249, v[254:255], off offset:-2048
	global_load_dword v250, v[254:255], off offset:-3584
	v_add_co_u32_e32 v254, vcc, 0xfffff000, v254
	s_nop 1
	v_addc_co_u32_e32 v255, vcc, -1, v255, vcc
	global_load_dword v251, v[254:255], off offset:-1024
	v_lshlrev_b32_e32 v20, 16, v4
	s_nop 0
	v_and_b32_e32 v7, 0xffff0000, v5
	v_lshlrev_b32_e32 v6, 16, v5
	s_nop 0
	v_and_b32_e32 v5, 0xffff0000, v18
	v_lshlrev_b32_e32 v4, 16, v18
	v_add_f32_e32 v18, v90, v210
	v_and_b32_e32 v3, 0xffff0000, v8
	v_lshlrev_b32_e32 v2, 16, v8
	s_nop 0
	v_lshlrev_b32_e32 v8, 16, v19
	v_pk_add_f32 v[4:5], v[4:5], v[2:3] neg_lo:[0,1] neg_hi:[0,1]
	s_nop 0
	v_and_b32_e32 v23, 0xffff0000, v9
	v_lshlrev_b32_e32 v22, 16, v9
	v_and_b32_e32 v9, 0xffff0000, v19
	v_max_f32_e64 v19, -v18, 0
	v_mul_f32_e64 v18, |v18|, s89
	v_exp_f32_e32 v18, v18
	v_pk_add_f32 v[8:9], v[8:9], v[6:7] neg_lo:[0,1] neg_hi:[0,1]
	v_pk_add_f32 v[22:23], v[22:23], v[20:21] neg_lo:[0,1] neg_hi:[0,1]
	v_pk_fma_f32 v[8:9], v[204:205], v[8:9], v[6:7]
	v_add_f32_e32 v18, 1.0, v18
	v_cmp_gt_f32_e32 vcc, s90, v18
	v_pk_fma_f32 v[20:21], v[206:207], v[22:23], v[20:21]
	v_pk_fma_f32 v[2:3], v[196:197], v[4:5], v[2:3]
	v_cndmask_b32_e64 v25, 0, 32, vcc
	v_ldexp_f32 v18, v18, v25
	v_log_f32_e32 v18, v18
	v_cvt_pk_f16_f32 v37, v20, v21
	v_cvt_pk_f16_f32 v4, v2, v3
	v_mul_f32_e32 v25, 0x3f317217, v18
	v_fma_f32 v25, v18, s91, -v25
	v_fmac_f32_e32 v25, 0x3377d1cf, v18
	v_fmac_f32_e32 v25, 0x3f317217, v18
	v_cmp_lt_f32_e64 s[6:7], |v18|, s97
	s_nop 1
	v_cndmask_b32_e64 v18, v18, v25, s[6:7]
	v_cndmask_b32_e32 v25, 0, v232, vcc
	v_sub_f32_e32 v18, v18, v25
	v_add_f32_e32 v18, v19, v18
	v_add_f32_e32 v19, v42, v211
	v_max_f32_e64 v34, -v19, 0
	v_mul_f32_e64 v19, |v19|, s89
	v_exp_f32_e32 v19, v19
	v_sub_f32_e32 v18, -0.5, v18
	v_mul_f32_e32 v18, 0x3fb8aa3b, v18
	v_exp_f32_e32 v18, v18
	v_add_f32_e32 v19, 1.0, v19
	v_cmp_gt_f32_e32 vcc, s90, v19
	v_mul_f32_e32 v18, 0xbfb8aa3b, v18
	s_nop 0
	v_cndmask_b32_e64 v35, 0, 32, vcc
	v_ldexp_f32 v19, v19, v35
	v_log_f32_e32 v19, v19
	v_exp_f32_e32 v18, v18
	v_mul_f32_e32 v35, 0x3f317217, v19
	v_fma_f32 v35, v19, s91, -v35
	v_fmac_f32_e32 v35, 0x3377d1cf, v19
	v_fmac_f32_e32 v35, 0x3f317217, v19
	v_cmp_lt_f32_e64 s[6:7], |v19|, s97
	v_sub_f32_e32 v25, 1.0, v18
	v_add_f32_e32 v18, v74, v208
	v_cndmask_b32_e64 v19, v19, v35, s[6:7]
	v_cndmask_b32_e32 v35, 0, v232, vcc
	v_sub_f32_e32 v19, v19, v35
	v_add_f32_e32 v19, v34, v19
	v_sub_f32_e32 v19, -0.5, v19
	v_mul_f32_e32 v19, 0x3fb8aa3b, v19
	v_exp_f32_e32 v19, v19
	v_mul_f32_e32 v18, 0xbfb8aa3b, v18
	v_exp_f32_e32 v18, v18
	v_mad_i64_i32 v[34:35], s[6:7], v24, s95, v[102:103]
	v_mul_f32_e32 v19, 0xbfb8aa3b, v19
	v_exp_f32_e32 v19, v19
	v_lshlrev_b64 v[22:23], 1, v[34:35]
	v_lshl_add_u64 v[34:35], s[58:59], 0, v[22:23]
	global_store_dword v[34:35], v37, off
	v_sub_f32_e32 v36, 1.0, v19
	v_add_f32_e32 v19, v58, v209
	v_mul_f32_e32 v19, 0xbfb8aa3b, v19
	v_exp_f32_e32 v19, v19
	v_cvt_pk_f16_f32 v25, v25, v36
	v_lshl_add_u64 v[34:35], s[66:67], 0, v[22:23]
	global_store_dword v[34:35], v25, off
	v_pk_add_f32 v[6:7], v[18:19], 1.0 op_sel_hi:[1,0]
	v_lshl_add_u64 v[2:3], s[70:71], 0, v[22:23]
	v_div_scale_f32 v18, s[6:7], v7, v7, 1.0
	v_rcp_f32_e32 v19, v18
	global_store_dword v[2:3], v4, off
	v_pk_mul_f32 v[2:3], v[194:195], v[8:9]
	v_fma_f32 v25, -v18, v19, 1.0
	v_fmac_f32_e32 v19, v25, v19
	v_div_scale_f32 v25, vcc, 1.0, v7, 1.0
	v_mul_f32_e32 v34, v25, v19
	v_fma_f32 v35, -v18, v34, v25
	v_fmac_f32_e32 v34, v35, v19
	v_fma_f32 v18, -v18, v34, v25
	v_div_fmas_f32 v18, v18, v19, v34
	v_div_fixup_f32 v19, v18, v7, 1.0
	v_div_scale_f32 v7, s[6:7], v6, v6, 1.0
	v_rcp_f32_e32 v18, v7
	v_pk_mul_f32 v[4:5], v[2:3], v[2:3]
	v_fma_f32 v25, -v7, v18, 1.0
	v_add_f32_e32 v4, v4, v5
	v_fmac_f32_e32 v18, v25, v18
	v_div_scale_f32 v25, vcc, 1.0, v6, 1.0
	v_add_f32_dpp v4, v4, v4 quad_perm:[1,0,3,2] row_mask:0xf bank_mask:0xf bound_ctrl:1
	v_mul_f32_e32 v34, v25, v18
	v_fma_f32 v35, -v7, v34, v25
	v_add_f32_dpp v4, v4, v4 quad_perm:[2,3,0,1] row_mask:0xf bank_mask:0xf bound_ctrl:1
	v_fmac_f32_e32 v34, v35, v18
	v_fma_f32 v7, -v7, v34, v25
	v_add_f32_dpp v4, v4, v4 row_half_mirror row_mask:0xf bank_mask:0xf bound_ctrl:1
	v_div_fmas_f32 v7, v7, v18, v34
	v_div_fixup_f32 v18, v7, v6, 1.0
	v_add_f32_dpp v4, v4, v4 row_mirror row_mask:0xf bank_mask:0xf bound_ctrl:1
	v_mov_b32_e32 v5, v4
	s_nop 1
	v_permlane16_swap_b32_e32 v4, v5
	v_add_f32_e32 v4, v4, v5
	v_add_f32_e32 v4, 0x2b8cbccc, v4
	v_pk_add_f32 v[6:7], v[18:19], -1.0 op_sel_hi:[1,0]
	v_cmp_gt_f32_e32 vcc, s90, v4
	v_mul_f32_e32 v5, 0x4b800000, v4
	v_pk_fma_f32 v[6:7], v[202:203], v[6:7], 1.0 op_sel_hi:[1,1,0]
	v_cndmask_b32_e32 v4, v4, v5, vcc
	v_pk_mul_f32 v[34:35], v[6:7], v[8:9]
	v_rsq_f32_e32 v4, v4
	v_pk_mul_f32 v[6:7], v[20:21], v[34:35]
	v_cvt_pk_f16_f32 v25, v34, v35
	v_fma_f32 v6, v198, v6, 0
	v_fmac_f32_e32 v6, v199, v7
	v_mul_f32_e32 v5, 0x45800000, v4
	v_cndmask_b32_e32 v4, v4, v5, vcc
	v_add_f32_dpp v6, v6, v6 quad_perm:[1,0,3,2] row_mask:0xf bank_mask:0xf bound_ctrl:1
	v_pk_mul_f32 v[2:3], v[2:3], v[4:5] op_sel_hi:[1,0]
	v_lshl_add_u64 v[4:5], s[72:73], 0, v[22:23]
	v_add_f32_dpp v6, v6, v6 quad_perm:[2,3,0,1] row_mask:0xf bank_mask:0xf bound_ctrl:1
	v_cvt_pk_f16_f32 v8, v2, v3
	v_pk_mul_f32 v[2:3], v[18:19], v[2:3]
	v_add_f32_dpp v6, v6, v6 row_half_mirror row_mask:0xf bank_mask:0xf bound_ctrl:1
	global_store_dword v[4:5], v8, off
	v_cvt_pk_f16_f32 v4, v2, v3
	v_add_f32_dpp v6, v6, v6 row_mirror row_mask:0xf bank_mask:0xf bound_ctrl:1
	v_mov_b32_e32 v7, v6
	v_lshl_add_u64 v[2:3], s[74:75], 0, v[22:23]
	s_nop 0
	v_permlane16_swap_b32_e32 v6, v7
	v_lshl_add_u64 v[20:21], s[68:69], 0, v[22:23]
	global_store_dword v[2:3], v4, off
	v_cvt_pk_f16_f32 v4, v10, v26
	v_lshl_add_u64 v[2:3], s[78:79], 0, v[22:23]
	global_store_dword v[20:21], v25, off
	global_store_dword v[2:3], v4, off
	s_and_saveexec_b64 s[6:7], s[4:5]
	s_cbranch_execz .LBB0_1246
	v_add_f32_e32 v4, v6, v7
	v_mad_i64_i32 v[2:3], s[86:87], v24, 48, v[200:201]
	global_store_dword v[2:3], v4, off
; DEVI void rwkv_prep_item(const Params& p, const int l, const int item, char* smem) {
;     ...
;     for (int r = 0; r < 16; ++r) {
;       const int t = t0 + mt * 32 + (r & 3) + 8 * (r >> 2) + 4 * hi; const bool has_prev = (t & (SEQ_ - 1)) != 0;
;       float rv[2], kv[2], vv[2], av[2], kkv[2], kpv[2], omdv[2], gv[2];
;       float ssq = 0.f, bon = 0.f;
;       const u16* pr = PA + (size_t)t * 2560 + h * 64 + 2 * l31;
;       const unsigned cr2 = *(const unsigned*)pr, ck2 = *(const unsigned*)(pr + 768), cv2 = *(const unsigned*)(pr + 1536);
;       unsigned qr2 = 0u, qk2 = 0u, qv2 = 0u;
;       if (has_prev) { qr2 = *(const unsigned*)(pr - 2560); qk2 = *(const unsigned*)(pr + 768 - 2560); qv2 = *(const unsigned*)(pr + 1536 - 2560); }
; #pragma unroll
;       for (int n = 0; n < 2; ++n) {
;         const float cr = __uint_as_float(n ? (cr2 & 0xffff0000u) : (cr2 << 16)), ck = __uint_as_float(n ? (ck2 & 0xffff0000u) : (ck2 << 16)), cv = __uint_as_float(n ? (cv2 & 0xffff0000u) : (cv2 << 16));
;         const float qr = __uint_as_float(n ? (qr2 & 0xffff0000u) : (qr2 << 16)), qk = __uint_as_float(n ? (qk2 & 0xffff0000u) : (qk2 << 16)), qv = __uint_as_float(n ? (qv2 & 0xffff0000u) : (qv2 << 16));
;         rv[n] = cr + (qr - cr) * mur[n]; kv[n] = ck + (qk - ck) * muk[n]; vv[n] = cv + (qv - cv) * muv[n];
;         const float z = -(w0c[n] + aw[n][r]);
;         const float sp = fmaxf(z, 0.f) + __logf(1.f + __expf(-fabsf(z)));
;         const float ew = __expf(-sp - 0.5f);
;         omdv[n] = 1.f - __expf(-ew);
;         av[n] = sigmoidf_(a0c[n] + aa[n][r]);
;         gv[n] = ag[n][r];
;         kkv[n] = kv[n] * kkc[n];
;         kpv[n] = kv[n] * (1.f + (av[n] - 1.f) * kac[n]);
;         ssq += kkv[n] * kkv[n];
;         bon += rv[n] * kpv[n] * rkc[n];
;       }
;       ssq = reduce32(ssq); bon = reduce32(bon);
;       const float rn = rsqrtf(ssq + 1e-12f);
;       {
;         typedef _Float16 h2 __attribute__((ext_vector_type(2)));
;         const size_t o = (size_t)t * 768 + h * 64 + 2 * l31;
;         const float kn0 = kkv[0] * rn, kn1 = kkv[1] * rn;
;         *(h2*)(RW + o) = (h2){(f16)rv[0], (f16)rv[1]};
;         *(h2*)(RW + TS + o) = (h2){(f16)omdv[0], (f16)omdv[1]};
;         *(h2*)(RW + 2 * TS + o) = (h2){(f16)kpv[0], (f16)kpv[1]};
;         *(h2*)(RW + 3 * TS + o) = (h2){(f16)vv[0], (f16)vv[1]};
;         *(h2*)(RW + 4 * TS + o) = (h2){(f16)kn0, (f16)kn1};
.LBB0_1246:
	s_or_b64 exec, exec, s[6:7]
	v_or_b32_e32 v10, 17, v233
	v_mad_i64_i32 v[2:3], s[6:7], v10, s88, v[212:213]
	s_waitcnt vmcnt(7)
	v_mov_b32_e32 v4, v246
	v_mov_b32_e32 v5, v247
	v_mov_b32_e32 v8, v248
	v_mov_b32_e32 v18, v249
	v_mov_b32_e32 v19, v250
	v_add_co_u32_e32 v2, vcc, 0xfffff000, v2
	s_nop 0
	v_and_b32_e32 v21, 0xffff0000, v4
	v_addc_co_u32_e32 v3, vcc, -1, v3, vcc
	v_mov_b32_e32 v9, v251
	v_or_b32_e32 v253, 18, v233
	v_mad_i64_i32 v[254:255], s[86:87], v253, s88, v[212:213]
	global_load_dword v246, v[254:255], off
	global_load_dword v247, v[254:255], off offset:1536
	global_load_dword v248, v[254:255], off offset:3072
	global_load_dword v249, v[254:255], off offset:-2048
	global_load_dword v250, v[254:255], off offset:-3584
	v_add_co_u32_e32 v254, vcc, 0xfffff000, v254
	s_nop 1
	v_addc_co_u32_e32 v255, vcc, -1, v255, vcc
	global_load_dword v251, v[254:255], off offset:-1024
	v_lshlrev_b32_e32 v20, 16, v4
	s_nop 0
	v_and_b32_e32 v7, 0xffff0000, v5
	v_lshlrev_b32_e32 v6, 16, v5
	s_nop 0
	v_and_b32_e32 v5, 0xffff0000, v18
	v_lshlrev_b32_e32 v4, 16, v18
	v_add_f32_e32 v18, v91, v210
	v_and_b32_e32 v3, 0xffff0000, v8
	v_lshlrev_b32_e32 v2, 16, v8
	s_nop 0
	v_lshlrev_b32_e32 v8, 16, v19
	v_pk_add_f32 v[4:5], v[4:5], v[2:3] neg_lo:[0,1] neg_hi:[0,1]
	s_nop 0
	v_and_b32_e32 v23, 0xffff0000, v9
	v_lshlrev_b32_e32 v22, 16, v9
	v_and_b32_e32 v9, 0xffff0000, v19
	v_max_f32_e64 v19, -v18, 0
	v_mul_f32_e64 v18, |v18|, s89
	v_exp_f32_e32 v18, v18
	v_pk_add_f32 v[8:9], v[8:9], v[6:7] neg_lo:[0,1] neg_hi:[0,1]
	v_pk_add_f32 v[22:23], v[22:23], v[20:21] neg_lo:[0,1] neg_hi:[0,1]
	v_pk_fma_f32 v[8:9], v[204:205], v[8:9], v[6:7]
	v_add_f32_e32 v18, 1.0, v18
	v_cmp_gt_f32_e32 vcc, s90, v18
	v_pk_fma_f32 v[20:21], v[206:207], v[22:23], v[20:21]
	v_pk_fma_f32 v[2:3], v[196:197], v[4:5], v[2:3]
	v_cndmask_b32_e64 v24, 0, 32, vcc
	v_ldexp_f32 v18, v18, v24
	v_log_f32_e32 v18, v18
	v_cvt_pk_f16_f32 v35, v20, v21
	v_cvt_pk_f16_f32 v4, v2, v3
	v_mul_f32_e32 v24, 0x3f317217, v18
	v_fma_f32 v24, v18, s91, -v24
	v_fmac_f32_e32 v24, 0x3377d1cf, v18
	v_fmac_f32_e32 v24, 0x3f317217, v18
	v_cmp_lt_f32_e64 s[6:7], |v18|, s97
	s_nop 1
	v_cndmask_b32_e64 v18, v18, v24, s[6:7]
	v_cndmask_b32_e32 v24, 0, v232, vcc
	v_sub_f32_e32 v18, v18, v24
	v_add_f32_e32 v18, v19, v18
	v_add_f32_e32 v19, v43, v211
	v_max_f32_e64 v24, -v19, 0
	v_mul_f32_e64 v19, |v19|, s89
	v_exp_f32_e32 v19, v19
	v_sub_f32_e32 v18, -0.5, v18
	v_mul_f32_e32 v18, 0x3fb8aa3b, v18
	v_exp_f32_e32 v18, v18
	v_add_f32_e32 v19, 1.0, v19
	v_cmp_gt_f32_e32 vcc, s90, v19
	v_mul_f32_e32 v18, 0xbfb8aa3b, v18
	s_nop 0
	v_cndmask_b32_e64 v25, 0, 32, vcc
	v_ldexp_f32 v19, v19, v25
	v_log_f32_e32 v19, v19
	v_exp_f32_e32 v18, v18
	v_mul_f32_e32 v25, 0x3f317217, v19
	v_fma_f32 v25, v19, s91, -v25
	v_fmac_f32_e32 v25, 0x3377d1cf, v19
	v_fmac_f32_e32 v25, 0x3f317217, v19
	v_cmp_lt_f32_e64 s[6:7], |v19|, s97
	v_sub_f32_e32 v26, 1.0, v18
	v_add_f32_e32 v18, v75, v208
	v_cndmask_b32_e64 v19, v19, v25, s[6:7]
	v_cndmask_b32_e32 v25, 0, v232, vcc
	v_sub_f32_e32 v19, v19, v25
	v_add_f32_e32 v19, v24, v19
	v_sub_f32_e32 v19, -0.5, v19
	v_mul_f32_e32 v19, 0x3fb8aa3b, v19
	v_exp_f32_e32 v19, v19
	v_mul_f32_e32 v18, 0xbfb8aa3b, v18
	v_exp_f32_e32 v18, v18
	v_mad_i64_i32 v[24:25], s[6:7], v10, s95, v[102:103]
	v_mul_f32_e32 v19, 0xbfb8aa3b, v19
	v_exp_f32_e32 v19, v19
	v_lshlrev_b64 v[22:23], 1, v[24:25]
	v_lshl_add_u64 v[24:25], s[58:59], 0, v[22:23]
	global_store_dword v[24:25], v35, off
	v_sub_f32_e32 v34, 1.0, v19
	v_add_f32_e32 v19, v59, v209
	v_mul_f32_e32 v19, 0xbfb8aa3b, v19
	v_exp_f32_e32 v19, v19
	v_cvt_pk_f16_f32 v26, v26, v34
	v_lshl_add_u64 v[24:25], s[66:67], 0, v[22:23]
	global_store_dword v[24:25], v26, off
	v_pk_add_f32 v[6:7], v[18:19], 1.0 op_sel_hi:[1,0]
	v_lshl_add_u64 v[2:3], s[70:71], 0, v[22:23]
	v_div_scale_f32 v18, s[6:7], v7, v7, 1.0
	v_rcp_f32_e32 v19, v18
	global_store_dword v[2:3], v4, off
	v_pk_mul_f32 v[2:3], v[194:195], v[8:9]
	v_fma_f32 v24, -v18, v19, 1.0
	v_fmac_f32_e32 v19, v24, v19
	v_div_scale_f32 v24, vcc, 1.0, v7, 1.0
	v_mul_f32_e32 v25, v24, v19
	v_fma_f32 v26, -v18, v25, v24
	v_fmac_f32_e32 v25, v26, v19
	v_fma_f32 v18, -v18, v25, v24
	v_div_fmas_f32 v18, v18, v19, v25
	v_div_fixup_f32 v19, v18, v7, 1.0
	v_div_scale_f32 v7, s[6:7], v6, v6, 1.0
	v_rcp_f32_e32 v18, v7
	v_pk_mul_f32 v[4:5], v[2:3], v[2:3]
	v_fma_f32 v24, -v7, v18, 1.0
	v_add_f32_e32 v4, v4, v5
	v_fmac_f32_e32 v18, v24, v18
	v_div_scale_f32 v24, vcc, 1.0, v6, 1.0
	v_add_f32_dpp v4, v4, v4 quad_perm:[1,0,3,2] row_mask:0xf bank_mask:0xf bound_ctrl:1
	v_mul_f32_e32 v25, v24, v18
	v_fma_f32 v26, -v7, v25, v24
	v_add_f32_dpp v4, v4, v4 quad_perm:[2,3,0,1] row_mask:0xf bank_mask:0xf bound_ctrl:1
	v_fmac_f32_e32 v25, v26, v18
	v_fma_f32 v7, -v7, v25, v24
	v_add_f32_dpp v4, v4, v4 row_half_mirror row_mask:0xf bank_mask:0xf bound_ctrl:1
	v_div_fmas_f32 v7, v7, v18, v25
	v_div_fixup_f32 v18, v7, v6, 1.0
	v_add_f32_dpp v4, v4, v4 row_mirror row_mask:0xf bank_mask:0xf bound_ctrl:1
	v_mov_b32_e32 v5, v4
	s_nop 1
	v_permlane16_swap_b32_e32 v4, v5
	v_add_f32_e32 v4, v4, v5
	v_add_f32_e32 v4, 0x2b8cbccc, v4
	v_pk_add_f32 v[6:7], v[18:19], -1.0 op_sel_hi:[1,0]
	v_cmp_gt_f32_e32 vcc, s90, v4
	v_mul_f32_e32 v5, 0x4b800000, v4
	v_pk_fma_f32 v[6:7], v[202:203], v[6:7], 1.0 op_sel_hi:[1,1,0]
	v_cndmask_b32_e32 v4, v4, v5, vcc
	v_pk_mul_f32 v[24:25], v[6:7], v[8:9]
	v_rsq_f32_e32 v4, v4
	v_pk_mul_f32 v[6:7], v[20:21], v[24:25]
	v_cvt_pk_f16_f32 v24, v24, v25
	v_fma_f32 v6, v198, v6, 0
	v_fmac_f32_e32 v6, v199, v7
	v_mul_f32_e32 v5, 0x45800000, v4
	v_cndmask_b32_e32 v4, v4, v5, vcc
	v_add_f32_dpp v6, v6, v6 quad_perm:[1,0,3,2] row_mask:0xf bank_mask:0xf bound_ctrl:1
	v_pk_mul_f32 v[2:3], v[2:3], v[4:5] op_sel_hi:[1,0]
	v_lshl_add_u64 v[4:5], s[72:73], 0, v[22:23]
	v_add_f32_dpp v6, v6, v6 quad_perm:[2,3,0,1] row_mask:0xf bank_mask:0xf bound_ctrl:1
	v_cvt_pk_f16_f32 v8, v2, v3
	v_pk_mul_f32 v[2:3], v[18:19], v[2:3]
	v_add_f32_dpp v6, v6, v6 row_half_mirror row_mask:0xf bank_mask:0xf bound_ctrl:1
	global_store_dword v[4:5], v8, off
	v_cvt_pk_f16_f32 v4, v2, v3
	v_add_f32_dpp v6, v6, v6 row_mirror row_mask:0xf bank_mask:0xf bound_ctrl:1
	v_mov_b32_e32 v7, v6
	v_lshl_add_u64 v[2:3], s[74:75], 0, v[22:23]
	s_nop 0
	v_permlane16_swap_b32_e32 v6, v7
	v_lshl_add_u64 v[20:21], s[68:69], 0, v[22:23]
	global_store_dword v[2:3], v4, off
	v_cvt_pk_f16_f32 v4, v11, v27
	v_lshl_add_u64 v[2:3], s[78:79], 0, v[22:23]
	global_store_dword v[20:21], v24, off
	global_store_dword v[2:3], v4, off
	s_and_saveexec_b64 s[6:7], s[4:5]
	s_cbranch_execz .LBB0_1248
	v_add_f32_e32 v4, v6, v7
	v_mad_i64_i32 v[2:3], s[86:87], v10, 48, v[200:201]
	global_store_dword v[2:3], v4, off
; DEVI void rwkv_prep_item(const Params& p, const int l, const int item, char* smem) {
;     ...
;     for (int r = 0; r < 16; ++r) {
;       const int t = t0 + mt * 32 + (r & 3) + 8 * (r >> 2) + 4 * hi; const bool has_prev = (t & (SEQ_ - 1)) != 0;
;       float rv[2], kv[2], vv[2], av[2], kkv[2], kpv[2], omdv[2], gv[2];
;       float ssq = 0.f, bon = 0.f;
;       const u16* pr = PA + (size_t)t * 2560 + h * 64 + 2 * l31;
;       const unsigned cr2 = *(const unsigned*)pr, ck2 = *(const unsigned*)(pr + 768), cv2 = *(const unsigned*)(pr + 1536);
;       unsigned qr2 = 0u, qk2 = 0u, qv2 = 0u;
;       if (has_prev) { qr2 = *(const unsigned*)(pr - 2560); qk2 = *(const unsigned*)(pr + 768 - 2560); qv2 = *(const unsigned*)(pr + 1536 - 2560); }
; #pragma unroll
;       for (int n = 0; n < 2; ++n) {
;         const float cr = __uint_as_float(n ? (cr2 & 0xffff0000u) : (cr2 << 16)), ck = __uint_as_float(n ? (ck2 & 0xffff0000u) : (ck2 << 16)), cv = __uint_as_float(n ? (cv2 & 0xffff0000u) : (cv2 << 16));
;         const float qr = __uint_as_float(n ? (qr2 & 0xffff0000u) : (qr2 << 16)), qk = __uint_as_float(n ? (qk2 & 0xffff0000u) : (qk2 << 16)), qv = __uint_as_float(n ? (qv2 & 0xffff0000u) : (qv2 << 16));
;         rv[n] = cr + (qr - cr) * mur[n]; kv[n] = ck + (qk - ck) * muk[n]; vv[n] = cv + (qv - cv) * muv[n];
;         const float z = -(w0c[n] + aw[n][r]);
;         const float sp = fmaxf(z, 0.f) + __logf(1.f + __expf(-fabsf(z)));
;         const float ew = __expf(-sp - 0.5f);
;         omdv[n] = 1.f - __expf(-ew);
;         av[n] = sigmoidf_(a0c[n] + aa[n][r]);
;         gv[n] = ag[n][r];
;         kkv[n] = kv[n] * kkc[n];
;         kpv[n] = kv[n] * (1.f + (av[n] - 1.f) * kac[n]);
;         ssq += kkv[n] * kkv[n];
;         bon += rv[n] * kpv[n] * rkc[n];
;       }
;       ssq = reduce32(ssq); bon = reduce32(bon);
;       const float rn = rsqrtf(ssq + 1e-12f);
;       {
;         typedef _Float16 h2 __attribute__((ext_vector_type(2)));
;         const size_t o = (size_t)t * 768 + h * 64 + 2 * l31;
;         const float kn0 = kkv[0] * rn, kn1 = kkv[1] * rn;
;         *(h2*)(RW + o) = (h2){(f16)rv[0], (f16)rv[1]};
;         *(h2*)(RW + TS + o) = (h2){(f16)omdv[0], (f16)omdv[1]};
;         *(h2*)(RW + 2 * TS + o) = (h2){(f16)kpv[0], (f16)kpv[1]};
;         *(h2*)(RW + 3 * TS + o) = (h2){(f16)vv[0], (f16)vv[1]};
;         *(h2*)(RW + 4 * TS + o) = (h2){(f16)kn0, (f16)kn1};
.LBB0_1248:
	s_or_b64 exec, exec, s[6:7]
	v_or_b32_e32 v22, 18, v233
	v_mad_i64_i32 v[2:3], s[6:7], v22, s88, v[212:213]
	s_waitcnt vmcnt(7)
	v_mov_b32_e32 v4, v246
	v_mov_b32_e32 v5, v247
	v_mov_b32_e32 v8, v248
	v_mov_b32_e32 v10, v249
	v_mov_b32_e32 v11, v250
	v_add_co_u32_e32 v2, vcc, 0xfffff000, v2
	s_nop 0
	v_and_b32_e32 v19, 0xffff0000, v4
	v_addc_co_u32_e32 v3, vcc, -1, v3, vcc
	v_mov_b32_e32 v9, v251
	v_or_b32_e32 v253, 19, v233
	v_mad_i64_i32 v[254:255], s[86:87], v253, s88, v[212:213]
	global_load_dword v246, v[254:255], off
	global_load_dword v247, v[254:255], off offset:1536
	global_load_dword v248, v[254:255], off offset:3072
	global_load_dword v249, v[254:255], off offset:-2048
	global_load_dword v250, v[254:255], off offset:-3584
	v_add_co_u32_e32 v254, vcc, 0xfffff000, v254
	s_nop 1
	v_addc_co_u32_e32 v255, vcc, -1, v255, vcc
	global_load_dword v251, v[254:255], off offset:-1024
	v_lshlrev_b32_e32 v18, 16, v4
	s_nop 0
	v_and_b32_e32 v7, 0xffff0000, v5
	v_lshlrev_b32_e32 v6, 16, v5
	s_nop 0
	v_and_b32_e32 v5, 0xffff0000, v10
	v_lshlrev_b32_e32 v4, 16, v10
	v_add_f32_e32 v10, v92, v210
	v_and_b32_e32 v3, 0xffff0000, v8
	v_lshlrev_b32_e32 v2, 16, v8
	s_nop 0
	v_lshlrev_b32_e32 v8, 16, v11
	v_pk_add_f32 v[4:5], v[4:5], v[2:3] neg_lo:[0,1] neg_hi:[0,1]
	s_nop 0
	v_and_b32_e32 v21, 0xffff0000, v9
	v_lshlrev_b32_e32 v20, 16, v9
	v_and_b32_e32 v9, 0xffff0000, v11
	v_max_f32_e64 v11, -v10, 0
	v_mul_f32_e64 v10, |v10|, s89
	v_exp_f32_e32 v10, v10
	v_pk_add_f32 v[8:9], v[8:9], v[6:7] neg_lo:[0,1] neg_hi:[0,1]
	v_pk_add_f32 v[20:21], v[20:21], v[18:19] neg_lo:[0,1] neg_hi:[0,1]
	v_pk_fma_f32 v[8:9], v[204:205], v[8:9], v[6:7]
	v_add_f32_e32 v10, 1.0, v10
	v_cmp_gt_f32_e32 vcc, s90, v10
	v_pk_fma_f32 v[18:19], v[206:207], v[20:21], v[18:19]
	v_pk_fma_f32 v[2:3], v[196:197], v[4:5], v[2:3]
	v_cndmask_b32_e64 v23, 0, 32, vcc
	v_ldexp_f32 v10, v10, v23
	v_log_f32_e32 v10, v10
	v_cvt_pk_f16_f32 v27, v18, v19
	v_cvt_pk_f16_f32 v4, v2, v3
	v_mul_f32_e32 v23, 0x3f317217, v10
	v_fma_f32 v23, v10, s91, -v23
	v_fmac_f32_e32 v23, 0x3377d1cf, v10
	v_fmac_f32_e32 v23, 0x3f317217, v10
	v_cmp_lt_f32_e64 s[6:7], |v10|, s97
	s_nop 1
	v_cndmask_b32_e64 v10, v10, v23, s[6:7]
	v_cndmask_b32_e32 v23, 0, v232, vcc
	v_sub_f32_e32 v10, v10, v23
	v_add_f32_e32 v10, v11, v10
	v_add_f32_e32 v11, v44, v211
	v_max_f32_e64 v24, -v11, 0
	v_mul_f32_e64 v11, |v11|, s89
	v_exp_f32_e32 v11, v11
	v_sub_f32_e32 v10, -0.5, v10
	v_mul_f32_e32 v10, 0x3fb8aa3b, v10
	v_exp_f32_e32 v10, v10
	v_add_f32_e32 v11, 1.0, v11
	v_cmp_gt_f32_e32 vcc, s90, v11
	v_mul_f32_e32 v10, 0xbfb8aa3b, v10
	s_nop 0
	v_cndmask_b32_e64 v25, 0, 32, vcc
	v_ldexp_f32 v11, v11, v25
	v_log_f32_e32 v11, v11
	v_exp_f32_e32 v10, v10
	v_mul_f32_e32 v25, 0x3f317217, v11
	v_fma_f32 v25, v11, s91, -v25
	v_fmac_f32_e32 v25, 0x3377d1cf, v11
	v_fmac_f32_e32 v25, 0x3f317217, v11
	v_cmp_lt_f32_e64 s[6:7], |v11|, s97
	v_sub_f32_e32 v23, 1.0, v10
	v_add_f32_e32 v10, v76, v208
	v_cndmask_b32_e64 v11, v11, v25, s[6:7]
	v_cndmask_b32_e32 v25, 0, v232, vcc
	v_sub_f32_e32 v11, v11, v25
	v_add_f32_e32 v11, v24, v11
	v_sub_f32_e32 v11, -0.5, v11
	v_mul_f32_e32 v11, 0x3fb8aa3b, v11
	v_exp_f32_e32 v11, v11
	v_mul_f32_e32 v10, 0xbfb8aa3b, v10
	v_exp_f32_e32 v10, v10
	v_mad_i64_i32 v[24:25], s[6:7], v22, s95, v[102:103]
	v_mul_f32_e32 v11, 0xbfb8aa3b, v11
	v_exp_f32_e32 v11, v11
	v_lshlrev_b64 v[20:21], 1, v[24:25]
	v_lshl_add_u64 v[24:25], s[58:59], 0, v[20:21]
	global_store_dword v[24:25], v27, off
	v_sub_f32_e32 v26, 1.0, v11
	v_add_f32_e32 v11, v60, v209
	v_mul_f32_e32 v11, 0xbfb8aa3b, v11
	v_exp_f32_e32 v11, v11
	v_cvt_pk_f16_f32 v23, v23, v26
	v_lshl_add_u64 v[24:25], s[66:67], 0, v[20:21]
	global_store_dword v[24:25], v23, off
	v_pk_add_f32 v[6:7], v[10:11], 1.0 op_sel_hi:[1,0]
	v_lshl_add_u64 v[2:3], s[70:71], 0, v[20:21]
	v_div_scale_f32 v10, s[6:7], v7, v7, 1.0
	v_rcp_f32_e32 v11, v10
	global_store_dword v[2:3], v4, off
	v_pk_mul_f32 v[2:3], v[194:195], v[8:9]
	v_fma_f32 v23, -v10, v11, 1.0
	v_fmac_f32_e32 v11, v23, v11
	v_div_scale_f32 v23, vcc, 1.0, v7, 1.0
	v_mul_f32_e32 v24, v23, v11
	v_fma_f32 v25, -v10, v24, v23
	v_fmac_f32_e32 v24, v25, v11
	v_fma_f32 v10, -v10, v24, v23
	v_div_fmas_f32 v10, v10, v11, v24
	v_div_fixup_f32 v11, v10, v7, 1.0
	v_div_scale_f32 v7, s[6:7], v6, v6, 1.0
	v_rcp_f32_e32 v10, v7
	v_pk_mul_f32 v[4:5], v[2:3], v[2:3]
	v_fma_f32 v23, -v7, v10, 1.0
	v_add_f32_e32 v4, v4, v5
	v_fmac_f32_e32 v10, v23, v10
	v_div_scale_f32 v23, vcc, 1.0, v6, 1.0
	v_add_f32_dpp v4, v4, v4 quad_perm:[1,0,3,2] row_mask:0xf bank_mask:0xf bound_ctrl:1
	v_mul_f32_e32 v24, v23, v10
	v_fma_f32 v25, -v7, v24, v23
	v_add_f32_dpp v4, v4, v4 quad_perm:[2,3,0,1] row_mask:0xf bank_mask:0xf bound_ctrl:1
	v_fmac_f32_e32 v24, v25, v10
	v_fma_f32 v7, -v7, v24, v23
	v_add_f32_dpp v4, v4, v4 row_half_mirror row_mask:0xf bank_mask:0xf bound_ctrl:1
	v_div_fmas_f32 v7, v7, v10, v24
	v_div_fixup_f32 v10, v7, v6, 1.0
	v_add_f32_dpp v4, v4, v4 row_mirror row_mask:0xf bank_mask:0xf bound_ctrl:1
	v_mov_b32_e32 v5, v4
	s_nop 1
	v_permlane16_swap_b32_e32 v4, v5
	v_add_f32_e32 v4, v4, v5
	v_add_f32_e32 v4, 0x2b8cbccc, v4
	v_pk_add_f32 v[6:7], v[10:11], -1.0 op_sel_hi:[1,0]
	v_cmp_gt_f32_e32 vcc, s90, v4
	v_mul_f32_e32 v5, 0x4b800000, v4
	v_pk_fma_f32 v[6:7], v[202:203], v[6:7], 1.0 op_sel_hi:[1,1,0]
	v_cndmask_b32_e32 v4, v4, v5, vcc
	v_pk_mul_f32 v[24:25], v[6:7], v[8:9]
	v_rsq_f32_e32 v4, v4
	v_pk_mul_f32 v[6:7], v[18:19], v[24:25]
	v_cvt_pk_f16_f32 v23, v24, v25
	v_fma_f32 v6, v198, v6, 0
	v_fmac_f32_e32 v6, v199, v7
	v_mul_f32_e32 v5, 0x45800000, v4
	v_cndmask_b32_e32 v4, v4, v5, vcc
	v_add_f32_dpp v6, v6, v6 quad_perm:[1,0,3,2] row_mask:0xf bank_mask:0xf bound_ctrl:1
	v_pk_mul_f32 v[2:3], v[2:3], v[4:5] op_sel_hi:[1,0]
	v_lshl_add_u64 v[4:5], s[72:73], 0, v[20:21]
	v_add_f32_dpp v6, v6, v6 quad_perm:[2,3,0,1] row_mask:0xf bank_mask:0xf bound_ctrl:1
	v_cvt_pk_f16_f32 v8, v2, v3
	v_pk_mul_f32 v[2:3], v[10:11], v[2:3]
	v_add_f32_dpp v6, v6, v6 row_half_mirror row_mask:0xf bank_mask:0xf bound_ctrl:1
	global_store_dword v[4:5], v8, off
	v_cvt_pk_f16_f32 v4, v2, v3
	v_add_f32_dpp v6, v6, v6 row_mirror row_mask:0xf bank_mask:0xf bound_ctrl:1
	v_mov_b32_e32 v7, v6
	v_lshl_add_u64 v[2:3], s[74:75], 0, v[20:21]
	s_nop 0
	v_permlane16_swap_b32_e32 v6, v7
	v_lshl_add_u64 v[18:19], s[68:69], 0, v[20:21]
	global_store_dword v[2:3], v4, off
	v_cvt_pk_f16_f32 v4, v12, v28
	v_lshl_add_u64 v[2:3], s[78:79], 0, v[20:21]
	global_store_dword v[18:19], v23, off
	global_store_dword v[2:3], v4, off
	s_and_saveexec_b64 s[6:7], s[4:5]
	s_cbranch_execz .LBB0_1250
	v_add_f32_e32 v4, v6, v7
	v_mad_i64_i32 v[2:3], s[86:87], v22, 48, v[200:201]
	global_store_dword v[2:3], v4, off
; DEVI void rwkv_prep_item(const Params& p, const int l, const int item, char* smem) {
;     ...
;     for (int r = 0; r < 16; ++r) {
;       const int t = t0 + mt * 32 + (r & 3) + 8 * (r >> 2) + 4 * hi; const bool has_prev = (t & (SEQ_ - 1)) != 0;
;       float rv[2], kv[2], vv[2], av[2], kkv[2], kpv[2], omdv[2], gv[2];
;       float ssq = 0.f, bon = 0.f;
;       const u16* pr = PA + (size_t)t * 2560 + h * 64 + 2 * l31;
;       const unsigned cr2 = *(const unsigned*)pr, ck2 = *(const unsigned*)(pr + 768), cv2 = *(const unsigned*)(pr + 1536);
;       unsigned qr2 = 0u, qk2 = 0u, qv2 = 0u;
;       if (has_prev) { qr2 = *(const unsigned*)(pr - 2560); qk2 = *(const unsigned*)(pr + 768 - 2560); qv2 = *(const unsigned*)(pr + 1536 - 2560); }
; #pragma unroll
;       for (int n = 0; n < 2; ++n) {
;         const float cr = __uint_as_float(n ? (cr2 & 0xffff0000u) : (cr2 << 16)), ck = __uint_as_float(n ? (ck2 & 0xffff0000u) : (ck2 << 16)), cv = __uint_as_float(n ? (cv2 & 0xffff0000u) : (cv2 << 16));
;         const float qr = __uint_as_float(n ? (qr2 & 0xffff0000u) : (qr2 << 16)), qk = __uint_as_float(n ? (qk2 & 0xffff0000u) : (qk2 << 16)), qv = __uint_as_float(n ? (qv2 & 0xffff0000u) : (qv2 << 16));
;         rv[n] = cr + (qr - cr) * mur[n]; kv[n] = ck + (qk - ck) * muk[n]; vv[n] = cv + (qv - cv) * muv[n];
;         const float z = -(w0c[n] + aw[n][r]);
;         const float sp = fmaxf(z, 0.f) + __logf(1.f + __expf(-fabsf(z)));
;         const float ew = __expf(-sp - 0.5f);
;         omdv[n] = 1.f - __expf(-ew);
;         av[n] = sigmoidf_(a0c[n] + aa[n][r]);
;         gv[n] = ag[n][r];
;         kkv[n] = kv[n] * kkc[n];
;         kpv[n] = kv[n] * (1.f + (av[n] - 1.f) * kac[n]);
;         ssq += kkv[n] * kkv[n];
;         bon += rv[n] * kpv[n] * rkc[n];
;       }
;       ssq = reduce32(ssq); bon = reduce32(bon);
;       const float rn = rsqrtf(ssq + 1e-12f);
;       {
;         typedef _Float16 h2 __attribute__((ext_vector_type(2)));
;         const size_t o = (size_t)t * 768 + h * 64 + 2 * l31;
;         const float kn0 = kkv[0] * rn, kn1 = kkv[1] * rn;
;         *(h2*)(RW + o) = (h2){(f16)rv[0], (f16)rv[1]};
;         *(h2*)(RW + TS + o) = (h2){(f16)omdv[0], (f16)omdv[1]};
;         *(h2*)(RW + 2 * TS + o) = (h2){(f16)kpv[0], (f16)kpv[1]};
;         *(h2*)(RW + 3 * TS + o) = (h2){(f16)vv[0], (f16)vv[1]};
;         *(h2*)(RW + 4 * TS + o) = (h2){(f16)kn0, (f16)kn1};
.LBB0_1250:
	s_or_b64 exec, exec, s[6:7]
	v_or_b32_e32 v12, 19, v233
	v_mad_i64_i32 v[2:3], s[6:7], v12, s88, v[212:213]
	s_waitcnt vmcnt(7)
	v_mov_b32_e32 v4, v246
	v_mov_b32_e32 v5, v247
	v_mov_b32_e32 v8, v248
	v_mov_b32_e32 v10, v249
	v_mov_b32_e32 v11, v250
	v_add_co_u32_e32 v2, vcc, 0xfffff000, v2
	s_nop 0
	v_and_b32_e32 v19, 0xffff0000, v4
	v_addc_co_u32_e32 v3, vcc, -1, v3, vcc
	v_mov_b32_e32 v9, v251
	v_or_b32_e32 v253, 24, v233
	v_mad_i64_i32 v[254:255], s[86:87], v253, s88, v[212:213]
	global_load_dword v246, v[254:255], off
	global_load_dword v247, v[254:255], off offset:1536
	global_load_dword v248, v[254:255], off offset:3072
	global_load_dword v249, v[254:255], off offset:-2048
	global_load_dword v250, v[254:255], off offset:-3584
	v_add_co_u32_e32 v254, vcc, 0xfffff000, v254
	s_nop 1
	v_addc_co_u32_e32 v255, vcc, -1, v255, vcc
	global_load_dword v251, v[254:255], off offset:-1024
	v_lshlrev_b32_e32 v18, 16, v4
	s_nop 0
	v_and_b32_e32 v7, 0xffff0000, v5
	v_lshlrev_b32_e32 v6, 16, v5
	s_nop 0
	v_and_b32_e32 v5, 0xffff0000, v10
	v_lshlrev_b32_e32 v4, 16, v10
	v_add_f32_e32 v10, v93, v210
	v_and_b32_e32 v3, 0xffff0000, v8
	v_lshlrev_b32_e32 v2, 16, v8
	s_nop 0
	v_lshlrev_b32_e32 v8, 16, v11
	v_pk_add_f32 v[4:5], v[4:5], v[2:3] neg_lo:[0,1] neg_hi:[0,1]
	s_nop 0
	v_and_b32_e32 v21, 0xffff0000, v9
	v_lshlrev_b32_e32 v20, 16, v9
	v_and_b32_e32 v9, 0xffff0000, v11
	v_max_f32_e64 v11, -v10, 0
	v_mul_f32_e64 v10, |v10|, s89
	v_exp_f32_e32 v10, v10
	v_pk_add_f32 v[8:9], v[8:9], v[6:7] neg_lo:[0,1] neg_hi:[0,1]
	v_pk_add_f32 v[20:21], v[20:21], v[18:19] neg_lo:[0,1] neg_hi:[0,1]
	v_pk_fma_f32 v[8:9], v[204:205], v[8:9], v[6:7]
	v_add_f32_e32 v10, 1.0, v10
	v_cmp_gt_f32_e32 vcc, s90, v10
	v_pk_fma_f32 v[18:19], v[206:207], v[20:21], v[18:19]
	v_pk_fma_f32 v[2:3], v[196:197], v[4:5], v[2:3]
	v_cndmask_b32_e64 v22, 0, 32, vcc
	v_ldexp_f32 v10, v10, v22
	v_log_f32_e32 v10, v10
	v_cvt_pk_f16_f32 v26, v18, v19
	v_cvt_pk_f16_f32 v4, v2, v3
	v_mul_f32_e32 v22, 0x3f317217, v10
	v_fma_f32 v22, v10, s91, -v22
	v_fmac_f32_e32 v22, 0x3377d1cf, v10
	v_fmac_f32_e32 v22, 0x3f317217, v10
	v_cmp_lt_f32_e64 s[6:7], |v10|, s97
	s_nop 1
	v_cndmask_b32_e64 v10, v10, v22, s[6:7]
	v_cndmask_b32_e32 v22, 0, v232, vcc
	v_sub_f32_e32 v10, v10, v22
	v_add_f32_e32 v10, v11, v10
	v_add_f32_e32 v11, v45, v211
	v_max_f32_e64 v22, -v11, 0
	v_mul_f32_e64 v11, |v11|, s89
	v_exp_f32_e32 v11, v11
	v_sub_f32_e32 v10, -0.5, v10
	v_mul_f32_e32 v10, 0x3fb8aa3b, v10
	v_exp_f32_e32 v10, v10
	v_add_f32_e32 v11, 1.0, v11
	v_cmp_gt_f32_e32 vcc, s90, v11
	v_mul_f32_e32 v10, 0xbfb8aa3b, v10
	s_nop 0
	v_cndmask_b32_e64 v23, 0, 32, vcc
	v_ldexp_f32 v11, v11, v23
	v_log_f32_e32 v11, v11
	v_exp_f32_e32 v10, v10
	v_mul_f32_e32 v23, 0x3f317217, v11
	v_fma_f32 v23, v11, s91, -v23
	v_fmac_f32_e32 v23, 0x3377d1cf, v11
	v_fmac_f32_e32 v23, 0x3f317217, v11
	v_cmp_lt_f32_e64 s[6:7], |v11|, s97
	v_sub_f32_e32 v24, 1.0, v10
	v_add_f32_e32 v10, v77, v208
	v_cndmask_b32_e64 v11, v11, v23, s[6:7]
	v_cndmask_b32_e32 v23, 0, v232, vcc
	v_sub_f32_e32 v11, v11, v23
	v_add_f32_e32 v11, v22, v11
	v_sub_f32_e32 v11, -0.5, v11
	v_mul_f32_e32 v11, 0x3fb8aa3b, v11
	v_exp_f32_e32 v11, v11
	v_mul_f32_e32 v10, 0xbfb8aa3b, v10
	v_exp_f32_e32 v10, v10
	v_mad_i64_i32 v[22:23], s[6:7], v12, s95, v[102:103]
	v_mul_f32_e32 v11, 0xbfb8aa3b, v11
	v_exp_f32_e32 v11, v11
	v_lshlrev_b64 v[20:21], 1, v[22:23]
	v_lshl_add_u64 v[22:23], s[58:59], 0, v[20:21]
	global_store_dword v[22:23], v26, off
	v_sub_f32_e32 v25, 1.0, v11
	v_add_f32_e32 v11, v61, v209
	v_mul_f32_e32 v11, 0xbfb8aa3b, v11
	v_exp_f32_e32 v11, v11
	v_cvt_pk_f16_f32 v24, v24, v25
	v_lshl_add_u64 v[22:23], s[66:67], 0, v[20:21]
	global_store_dword v[22:23], v24, off
	v_pk_add_f32 v[6:7], v[10:11], 1.0 op_sel_hi:[1,0]
	v_lshl_add_u64 v[2:3], s[70:71], 0, v[20:21]
	v_div_scale_f32 v10, s[6:7], v7, v7, 1.0
	v_rcp_f32_e32 v11, v10
	global_store_dword v[2:3], v4, off
	v_pk_mul_f32 v[2:3], v[194:195], v[8:9]
	v_fma_f32 v22, -v10, v11, 1.0
	v_fmac_f32_e32 v11, v22, v11
	v_div_scale_f32 v22, vcc, 1.0, v7, 1.0
	v_mul_f32_e32 v23, v22, v11
	v_fma_f32 v24, -v10, v23, v22
	v_fmac_f32_e32 v23, v24, v11
	v_fma_f32 v10, -v10, v23, v22
	v_div_fmas_f32 v10, v10, v11, v23
	v_div_fixup_f32 v11, v10, v7, 1.0
	v_div_scale_f32 v7, s[6:7], v6, v6, 1.0
	v_rcp_f32_e32 v10, v7
	v_pk_mul_f32 v[4:5], v[2:3], v[2:3]
	v_fma_f32 v22, -v7, v10, 1.0
	v_add_f32_e32 v4, v4, v5
	v_fmac_f32_e32 v10, v22, v10
	v_div_scale_f32 v22, vcc, 1.0, v6, 1.0
	v_add_f32_dpp v4, v4, v4 quad_perm:[1,0,3,2] row_mask:0xf bank_mask:0xf bound_ctrl:1
	v_mul_f32_e32 v23, v22, v10
	v_fma_f32 v24, -v7, v23, v22
	v_add_f32_dpp v4, v4, v4 quad_perm:[2,3,0,1] row_mask:0xf bank_mask:0xf bound_ctrl:1
	v_fmac_f32_e32 v23, v24, v10
	v_fma_f32 v7, -v7, v23, v22
	v_add_f32_dpp v4, v4, v4 row_half_mirror row_mask:0xf bank_mask:0xf bound_ctrl:1
	v_div_fmas_f32 v7, v7, v10, v23
	v_div_fixup_f32 v10, v7, v6, 1.0
	v_add_f32_dpp v4, v4, v4 row_mirror row_mask:0xf bank_mask:0xf bound_ctrl:1
	v_mov_b32_e32 v5, v4
	s_nop 1
	v_permlane16_swap_b32_e32 v4, v5
	v_add_f32_e32 v4, v4, v5
	v_add_f32_e32 v4, 0x2b8cbccc, v4
	v_pk_add_f32 v[6:7], v[10:11], -1.0 op_sel_hi:[1,0]
	v_cmp_gt_f32_e32 vcc, s90, v4
	v_mul_f32_e32 v5, 0x4b800000, v4
	v_pk_fma_f32 v[6:7], v[202:203], v[6:7], 1.0 op_sel_hi:[1,1,0]
	v_cndmask_b32_e32 v4, v4, v5, vcc
	v_pk_mul_f32 v[22:23], v[6:7], v[8:9]
	v_rsq_f32_e32 v4, v4
	v_pk_mul_f32 v[6:7], v[18:19], v[22:23]
	v_cvt_pk_f16_f32 v22, v22, v23
	v_fma_f32 v6, v198, v6, 0
	v_fmac_f32_e32 v6, v199, v7
	v_mul_f32_e32 v5, 0x45800000, v4
	v_cndmask_b32_e32 v4, v4, v5, vcc
	v_add_f32_dpp v6, v6, v6 quad_perm:[1,0,3,2] row_mask:0xf bank_mask:0xf bound_ctrl:1
	v_pk_mul_f32 v[2:3], v[2:3], v[4:5] op_sel_hi:[1,0]
	v_lshl_add_u64 v[4:5], s[72:73], 0, v[20:21]
	v_add_f32_dpp v6, v6, v6 quad_perm:[2,3,0,1] row_mask:0xf bank_mask:0xf bound_ctrl:1
	v_cvt_pk_f16_f32 v8, v2, v3
	v_pk_mul_f32 v[2:3], v[10:11], v[2:3]
	v_add_f32_dpp v6, v6, v6 row_half_mirror row_mask:0xf bank_mask:0xf bound_ctrl:1
	global_store_dword v[4:5], v8, off
	v_cvt_pk_f16_f32 v4, v2, v3
	v_add_f32_dpp v6, v6, v6 row_mirror row_mask:0xf bank_mask:0xf bound_ctrl:1
	v_mov_b32_e32 v7, v6
	v_lshl_add_u64 v[2:3], s[74:75], 0, v[20:21]
	s_nop 0
	v_permlane16_swap_b32_e32 v6, v7
	v_lshl_add_u64 v[18:19], s[68:69], 0, v[20:21]
	global_store_dword v[2:3], v4, off
	v_cvt_pk_f16_f32 v4, v13, v29
	v_lshl_add_u64 v[2:3], s[78:79], 0, v[20:21]
	global_store_dword v[18:19], v22, off
	global_store_dword v[2:3], v4, off
	s_and_saveexec_b64 s[6:7], s[4:5]
	s_cbranch_execz .LBB0_1252
	v_add_f32_e32 v4, v6, v7
	v_mad_i64_i32 v[2:3], s[86:87], v12, 48, v[200:201]
	global_store_dword v[2:3], v4, off
; DEVI void rwkv_prep_item(const Params& p, const int l, const int item, char* smem) {
;     ...
;     for (int r = 0; r < 16; ++r) {
;       const int t = t0 + mt * 32 + (r & 3) + 8 * (r >> 2) + 4 * hi; const bool has_prev = (t & (SEQ_ - 1)) != 0;
;       float rv[2], kv[2], vv[2], av[2], kkv[2], kpv[2], omdv[2], gv[2];
;       float ssq = 0.f, bon = 0.f;
;       const u16* pr = PA + (size_t)t * 2560 + h * 64 + 2 * l31;
;       const unsigned cr2 = *(const unsigned*)pr, ck2 = *(const unsigned*)(pr + 768), cv2 = *(const unsigned*)(pr + 1536);
;       unsigned qr2 = 0u, qk2 = 0u, qv2 = 0u;
;       if (has_prev) { qr2 = *(const unsigned*)(pr - 2560); qk2 = *(const unsigned*)(pr + 768 - 2560); qv2 = *(const unsigned*)(pr + 1536 - 2560); }
; #pragma unroll
;       for (int n = 0; n < 2; ++n) {
;         const float cr = __uint_as_float(n ? (cr2 & 0xffff0000u) : (cr2 << 16)), ck = __uint_as_float(n ? (ck2 & 0xffff0000u) : (ck2 << 16)), cv = __uint_as_float(n ? (cv2 & 0xffff0000u) : (cv2 << 16));
;         const float qr = __uint_as_float(n ? (qr2 & 0xffff0000u) : (qr2 << 16)), qk = __uint_as_float(n ? (qk2 & 0xffff0000u) : (qk2 << 16)), qv = __uint_as_float(n ? (qv2 & 0xffff0000u) : (qv2 << 16));
;         rv[n] = cr + (qr - cr) * mur[n]; kv[n] = ck + (qk - ck) * muk[n]; vv[n] = cv + (qv - cv) * muv[n];
;         const float z = -(w0c[n] + aw[n][r]);
;         const float sp = fmaxf(z, 0.f) + __logf(1.f + __expf(-fabsf(z)));
;         const float ew = __expf(-sp - 0.5f);
;         omdv[n] = 1.f - __expf(-ew);
;         av[n] = sigmoidf_(a0c[n] + aa[n][r]);
;         gv[n] = ag[n][r];
;         kkv[n] = kv[n] * kkc[n];
;         kpv[n] = kv[n] * (1.f + (av[n] - 1.f) * kac[n]);
;         ssq += kkv[n] * kkv[n];
;         bon += rv[n] * kpv[n] * rkc[n];
;       }
;       ssq = reduce32(ssq); bon = reduce32(bon);
;       const float rn = rsqrtf(ssq + 1e-12f);
;       {
;         typedef _Float16 h2 __attribute__((ext_vector_type(2)));
;         const size_t o = (size_t)t * 768 + h * 64 + 2 * l31;
;         const float kn0 = kkv[0] * rn, kn1 = kkv[1] * rn;
;         *(h2*)(RW + o) = (h2){(f16)rv[0], (f16)rv[1]};
;         *(h2*)(RW + TS + o) = (h2){(f16)omdv[0], (f16)omdv[1]};
;         *(h2*)(RW + 2 * TS + o) = (h2){(f16)kpv[0], (f16)kpv[1]};
;         *(h2*)(RW + 3 * TS + o) = (h2){(f16)vv[0], (f16)vv[1]};
;         *(h2*)(RW + 4 * TS + o) = (h2){(f16)kn0, (f16)kn1};
.LBB0_1252:
	s_or_b64 exec, exec, s[6:7]
	v_or_b32_e32 v20, 24, v233
	v_mad_i64_i32 v[2:3], s[6:7], v20, s88, v[212:213]
	s_waitcnt vmcnt(7)
	v_mov_b32_e32 v4, v246
	v_mov_b32_e32 v5, v247
	v_mov_b32_e32 v8, v248
	v_mov_b32_e32 v10, v249
	v_mov_b32_e32 v11, v250
	v_add_co_u32_e32 v2, vcc, 0xfffff000, v2
	s_nop 0
	v_and_b32_e32 v13, 0xffff0000, v4
	v_addc_co_u32_e32 v3, vcc, -1, v3, vcc
	v_mov_b32_e32 v9, v251
	v_or_b32_e32 v253, 25, v233
	v_mad_i64_i32 v[254:255], s[86:87], v253, s88, v[212:213]
	global_load_dword v246, v[254:255], off
	global_load_dword v247, v[254:255], off offset:1536
	global_load_dword v248, v[254:255], off offset:3072
	global_load_dword v249, v[254:255], off offset:-2048
	global_load_dword v250, v[254:255], off offset:-3584
	v_add_co_u32_e32 v254, vcc, 0xfffff000, v254
	s_nop 1
	v_addc_co_u32_e32 v255, vcc, -1, v255, vcc
	global_load_dword v251, v[254:255], off offset:-1024
	v_lshlrev_b32_e32 v12, 16, v4
	s_nop 0
	v_and_b32_e32 v7, 0xffff0000, v5
	v_lshlrev_b32_e32 v6, 16, v5
	s_nop 0
	v_and_b32_e32 v5, 0xffff0000, v10
	v_lshlrev_b32_e32 v4, 16, v10
	v_add_f32_e32 v10, v94, v210
	v_and_b32_e32 v3, 0xffff0000, v8
	v_lshlrev_b32_e32 v2, 16, v8
	s_nop 0
	v_lshlrev_b32_e32 v8, 16, v11
	v_pk_add_f32 v[4:5], v[4:5], v[2:3] neg_lo:[0,1] neg_hi:[0,1]
	s_nop 0
	v_and_b32_e32 v19, 0xffff0000, v9
	v_lshlrev_b32_e32 v18, 16, v9
	v_and_b32_e32 v9, 0xffff0000, v11
	v_max_f32_e64 v11, -v10, 0
	v_mul_f32_e64 v10, |v10|, s89
	v_exp_f32_e32 v10, v10
	v_pk_add_f32 v[8:9], v[8:9], v[6:7] neg_lo:[0,1] neg_hi:[0,1]
	v_pk_add_f32 v[18:19], v[18:19], v[12:13] neg_lo:[0,1] neg_hi:[0,1]
	v_pk_fma_f32 v[8:9], v[204:205], v[8:9], v[6:7]
	v_add_f32_e32 v10, 1.0, v10
	v_cmp_gt_f32_e32 vcc, s90, v10
	v_pk_fma_f32 v[12:13], v[206:207], v[18:19], v[12:13]
	v_pk_fma_f32 v[2:3], v[196:197], v[4:5], v[2:3]
	v_cndmask_b32_e64 v21, 0, 32, vcc
	v_ldexp_f32 v10, v10, v21
	v_log_f32_e32 v10, v10
	v_cvt_pk_f16_f32 v25, v12, v13
	v_cvt_pk_f16_f32 v4, v2, v3
	v_mul_f32_e32 v21, 0x3f317217, v10
	v_fma_f32 v21, v10, s91, -v21
	v_fmac_f32_e32 v21, 0x3377d1cf, v10
	v_fmac_f32_e32 v21, 0x3f317217, v10
	v_cmp_lt_f32_e64 s[6:7], |v10|, s97
	s_nop 1
	v_cndmask_b32_e64 v10, v10, v21, s[6:7]
	v_cndmask_b32_e32 v21, 0, v232, vcc
	v_sub_f32_e32 v10, v10, v21
	v_add_f32_e32 v10, v11, v10
	v_add_f32_e32 v11, v46, v211
	v_max_f32_e64 v22, -v11, 0
	v_mul_f32_e64 v11, |v11|, s89
	v_exp_f32_e32 v11, v11
	v_sub_f32_e32 v10, -0.5, v10
	v_mul_f32_e32 v10, 0x3fb8aa3b, v10
	v_exp_f32_e32 v10, v10
	v_add_f32_e32 v11, 1.0, v11
	v_cmp_gt_f32_e32 vcc, s90, v11
	v_mul_f32_e32 v10, 0xbfb8aa3b, v10
	s_nop 0
	v_cndmask_b32_e64 v23, 0, 32, vcc
	v_ldexp_f32 v11, v11, v23
	v_log_f32_e32 v11, v11
	v_exp_f32_e32 v10, v10
	v_mul_f32_e32 v23, 0x3f317217, v11
	v_fma_f32 v23, v11, s91, -v23
	v_fmac_f32_e32 v23, 0x3377d1cf, v11
	v_fmac_f32_e32 v23, 0x3f317217, v11
	v_cmp_lt_f32_e64 s[6:7], |v11|, s97
	v_sub_f32_e32 v21, 1.0, v10
	v_add_f32_e32 v10, v78, v208
	v_cndmask_b32_e64 v11, v11, v23, s[6:7]
	v_cndmask_b32_e32 v23, 0, v232, vcc
	v_sub_f32_e32 v11, v11, v23
	v_add_f32_e32 v11, v22, v11
	v_sub_f32_e32 v11, -0.5, v11
	v_mul_f32_e32 v11, 0x3fb8aa3b, v11
	v_exp_f32_e32 v11, v11
	v_mul_f32_e32 v10, 0xbfb8aa3b, v10
	v_exp_f32_e32 v10, v10
	v_mad_i64_i32 v[22:23], s[6:7], v20, s95, v[102:103]
	v_mul_f32_e32 v11, 0xbfb8aa3b, v11
	v_exp_f32_e32 v11, v11
	v_lshlrev_b64 v[18:19], 1, v[22:23]
	v_lshl_add_u64 v[22:23], s[58:59], 0, v[18:19]
	global_store_dword v[22:23], v25, off
	v_sub_f32_e32 v24, 1.0, v11
	v_add_f32_e32 v11, v62, v209
	v_mul_f32_e32 v11, 0xbfb8aa3b, v11
	v_exp_f32_e32 v11, v11
	v_cvt_pk_f16_f32 v21, v21, v24
	v_lshl_add_u64 v[22:23], s[66:67], 0, v[18:19]
	global_store_dword v[22:23], v21, off
	v_pk_add_f32 v[6:7], v[10:11], 1.0 op_sel_hi:[1,0]
	v_lshl_add_u64 v[2:3], s[70:71], 0, v[18:19]
	v_div_scale_f32 v10, s[6:7], v7, v7, 1.0
	v_rcp_f32_e32 v11, v10
	global_store_dword v[2:3], v4, off
	v_pk_mul_f32 v[2:3], v[194:195], v[8:9]
	v_fma_f32 v21, -v10, v11, 1.0
	v_fmac_f32_e32 v11, v21, v11
	v_div_scale_f32 v21, vcc, 1.0, v7, 1.0
	v_mul_f32_e32 v22, v21, v11
	v_fma_f32 v23, -v10, v22, v21
	v_fmac_f32_e32 v22, v23, v11
	v_fma_f32 v10, -v10, v22, v21
	v_div_fmas_f32 v10, v10, v11, v22
	v_div_fixup_f32 v11, v10, v7, 1.0
	v_div_scale_f32 v7, s[6:7], v6, v6, 1.0
	v_rcp_f32_e32 v10, v7
	v_pk_mul_f32 v[4:5], v[2:3], v[2:3]
	v_fma_f32 v21, -v7, v10, 1.0
	v_add_f32_e32 v4, v4, v5
	v_fmac_f32_e32 v10, v21, v10
	v_div_scale_f32 v21, vcc, 1.0, v6, 1.0
	v_add_f32_dpp v4, v4, v4 quad_perm:[1,0,3,2] row_mask:0xf bank_mask:0xf bound_ctrl:1
	v_mul_f32_e32 v22, v21, v10
	v_fma_f32 v23, -v7, v22, v21
	v_add_f32_dpp v4, v4, v4 quad_perm:[2,3,0,1] row_mask:0xf bank_mask:0xf bound_ctrl:1
	v_fmac_f32_e32 v22, v23, v10
	v_fma_f32 v7, -v7, v22, v21
	v_add_f32_dpp v4, v4, v4 row_half_mirror row_mask:0xf bank_mask:0xf bound_ctrl:1
	v_div_fmas_f32 v7, v7, v10, v22
	v_div_fixup_f32 v10, v7, v6, 1.0
	v_add_f32_dpp v4, v4, v4 row_mirror row_mask:0xf bank_mask:0xf bound_ctrl:1
	v_mov_b32_e32 v5, v4
	s_nop 1
	v_permlane16_swap_b32_e32 v4, v5
	v_add_f32_e32 v4, v4, v5
	v_add_f32_e32 v4, 0x2b8cbccc, v4
	v_pk_add_f32 v[6:7], v[10:11], -1.0 op_sel_hi:[1,0]
	v_cmp_gt_f32_e32 vcc, s90, v4
	v_mul_f32_e32 v5, 0x4b800000, v4
	v_pk_fma_f32 v[6:7], v[202:203], v[6:7], 1.0 op_sel_hi:[1,1,0]
	v_cndmask_b32_e32 v4, v4, v5, vcc
	v_pk_mul_f32 v[22:23], v[6:7], v[8:9]
	v_rsq_f32_e32 v4, v4
	v_pk_mul_f32 v[6:7], v[12:13], v[22:23]
	v_cvt_pk_f16_f32 v21, v22, v23
	v_fma_f32 v6, v198, v6, 0
	v_fmac_f32_e32 v6, v199, v7
	v_mul_f32_e32 v5, 0x45800000, v4
	v_cndmask_b32_e32 v4, v4, v5, vcc
	v_add_f32_dpp v6, v6, v6 quad_perm:[1,0,3,2] row_mask:0xf bank_mask:0xf bound_ctrl:1
	v_pk_mul_f32 v[2:3], v[2:3], v[4:5] op_sel_hi:[1,0]
	v_lshl_add_u64 v[4:5], s[72:73], 0, v[18:19]
	v_add_f32_dpp v6, v6, v6 quad_perm:[2,3,0,1] row_mask:0xf bank_mask:0xf bound_ctrl:1
	v_cvt_pk_f16_f32 v8, v2, v3
	v_pk_mul_f32 v[2:3], v[10:11], v[2:3]
	v_add_f32_dpp v6, v6, v6 row_half_mirror row_mask:0xf bank_mask:0xf bound_ctrl:1
	global_store_dword v[4:5], v8, off
	v_cvt_pk_f16_f32 v4, v2, v3
	v_add_f32_dpp v6, v6, v6 row_mirror row_mask:0xf bank_mask:0xf bound_ctrl:1
	v_mov_b32_e32 v7, v6
	v_lshl_add_u64 v[2:3], s[74:75], 0, v[18:19]
	s_nop 0
	v_permlane16_swap_b32_e32 v6, v7
	v_lshl_add_u64 v[12:13], s[68:69], 0, v[18:19]
	global_store_dword v[2:3], v4, off
	v_cvt_pk_f16_f32 v4, v14, v30
	v_lshl_add_u64 v[2:3], s[78:79], 0, v[18:19]
	global_store_dword v[12:13], v21, off
	global_store_dword v[2:3], v4, off
	s_and_saveexec_b64 s[6:7], s[4:5]
	s_cbranch_execz .LBB0_1254
	v_add_f32_e32 v4, v6, v7
	v_mad_i64_i32 v[2:3], s[86:87], v20, 48, v[200:201]
	global_store_dword v[2:3], v4, off
; DEVI void rwkv_prep_item(const Params& p, const int l, const int item, char* smem) {
;     ...
;     for (int r = 0; r < 16; ++r) {
;       const int t = t0 + mt * 32 + (r & 3) + 8 * (r >> 2) + 4 * hi; const bool has_prev = (t & (SEQ_ - 1)) != 0;
;       float rv[2], kv[2], vv[2], av[2], kkv[2], kpv[2], omdv[2], gv[2];
;       float ssq = 0.f, bon = 0.f;
;       const u16* pr = PA + (size_t)t * 2560 + h * 64 + 2 * l31;
;       const unsigned cr2 = *(const unsigned*)pr, ck2 = *(const unsigned*)(pr + 768), cv2 = *(const unsigned*)(pr + 1536);
;       unsigned qr2 = 0u, qk2 = 0u, qv2 = 0u;
;       if (has_prev) { qr2 = *(const unsigned*)(pr - 2560); qk2 = *(const unsigned*)(pr + 768 - 2560); qv2 = *(const unsigned*)(pr + 1536 - 2560); }
; #pragma unroll
;       for (int n = 0; n < 2; ++n) {
;         const float cr = __uint_as_float(n ? (cr2 & 0xffff0000u) : (cr2 << 16)), ck = __uint_as_float(n ? (ck2 & 0xffff0000u) : (ck2 << 16)), cv = __uint_as_float(n ? (cv2 & 0xffff0000u) : (cv2 << 16));
;         const float qr = __uint_as_float(n ? (qr2 & 0xffff0000u) : (qr2 << 16)), qk = __uint_as_float(n ? (qk2 & 0xffff0000u) : (qk2 << 16)), qv = __uint_as_float(n ? (qv2 & 0xffff0000u) : (qv2 << 16));
;         rv[n] = cr + (qr - cr) * mur[n]; kv[n] = ck + (qk - ck) * muk[n]; vv[n] = cv + (qv - cv) * muv[n];
;         const float z = -(w0c[n] + aw[n][r]);
;         const float sp = fmaxf(z, 0.f) + __logf(1.f + __expf(-fabsf(z)));
;         const float ew = __expf(-sp - 0.5f);
;         omdv[n] = 1.f - __expf(-ew);
;         av[n] = sigmoidf_(a0c[n] + aa[n][r]);
;         gv[n] = ag[n][r];
;         kkv[n] = kv[n] * kkc[n];
;         kpv[n] = kv[n] * (1.f + (av[n] - 1.f) * kac[n]);
;         ssq += kkv[n] * kkv[n];
;         bon += rv[n] * kpv[n] * rkc[n];
;       }
;       ssq = reduce32(ssq); bon = reduce32(bon);
;       const float rn = rsqrtf(ssq + 1e-12f);
;       {
;         typedef _Float16 h2 __attribute__((ext_vector_type(2)));
;         const size_t o = (size_t)t * 768 + h * 64 + 2 * l31;
;         const float kn0 = kkv[0] * rn, kn1 = kkv[1] * rn;
;         *(h2*)(RW + o) = (h2){(f16)rv[0], (f16)rv[1]};
;         *(h2*)(RW + TS + o) = (h2){(f16)omdv[0], (f16)omdv[1]};
;         *(h2*)(RW + 2 * TS + o) = (h2){(f16)kpv[0], (f16)kpv[1]};
;         *(h2*)(RW + 3 * TS + o) = (h2){(f16)vv[0], (f16)vv[1]};
;         *(h2*)(RW + 4 * TS + o) = (h2){(f16)kn0, (f16)kn1};
.LBB0_1254:
	s_or_b64 exec, exec, s[6:7]
	v_or_b32_e32 v14, 25, v233
	v_mad_i64_i32 v[2:3], s[6:7], v14, s88, v[212:213]
	s_waitcnt vmcnt(7)
	v_mov_b32_e32 v4, v246
	v_mov_b32_e32 v5, v247
	v_mov_b32_e32 v8, v248
	v_mov_b32_e32 v10, v249
	v_mov_b32_e32 v11, v250
	v_add_co_u32_e32 v2, vcc, 0xfffff000, v2
	s_nop 0
	v_and_b32_e32 v13, 0xffff0000, v4
	v_addc_co_u32_e32 v3, vcc, -1, v3, vcc
	v_mov_b32_e32 v9, v251
	v_or_b32_e32 v253, 26, v233
	v_mad_i64_i32 v[254:255], s[86:87], v253, s88, v[212:213]
	global_load_dword v246, v[254:255], off
	global_load_dword v247, v[254:255], off offset:1536
	global_load_dword v248, v[254:255], off offset:3072
	global_load_dword v249, v[254:255], off offset:-2048
	global_load_dword v250, v[254:255], off offset:-3584
	v_add_co_u32_e32 v254, vcc, 0xfffff000, v254
	s_nop 1
	v_addc_co_u32_e32 v255, vcc, -1, v255, vcc
	global_load_dword v251, v[254:255], off offset:-1024
	v_lshlrev_b32_e32 v12, 16, v4
	s_nop 0
	v_and_b32_e32 v7, 0xffff0000, v5
	v_lshlrev_b32_e32 v6, 16, v5
	s_nop 0
	v_and_b32_e32 v5, 0xffff0000, v10
	v_lshlrev_b32_e32 v4, 16, v10
	v_add_f32_e32 v10, v95, v210
	v_and_b32_e32 v3, 0xffff0000, v8
	v_lshlrev_b32_e32 v2, 16, v8
	s_nop 0
	v_lshlrev_b32_e32 v8, 16, v11
	v_pk_add_f32 v[4:5], v[4:5], v[2:3] neg_lo:[0,1] neg_hi:[0,1]
	s_nop 0
	v_and_b32_e32 v19, 0xffff0000, v9
	v_lshlrev_b32_e32 v18, 16, v9
	v_and_b32_e32 v9, 0xffff0000, v11
	v_max_f32_e64 v11, -v10, 0
	v_mul_f32_e64 v10, |v10|, s89
	v_exp_f32_e32 v10, v10
	v_pk_add_f32 v[8:9], v[8:9], v[6:7] neg_lo:[0,1] neg_hi:[0,1]
	v_pk_add_f32 v[18:19], v[18:19], v[12:13] neg_lo:[0,1] neg_hi:[0,1]
	v_pk_fma_f32 v[8:9], v[204:205], v[8:9], v[6:7]
	v_add_f32_e32 v10, 1.0, v10
	v_cmp_gt_f32_e32 vcc, s90, v10
	v_pk_fma_f32 v[12:13], v[206:207], v[18:19], v[12:13]
	v_pk_fma_f32 v[2:3], v[196:197], v[4:5], v[2:3]
	v_cndmask_b32_e64 v20, 0, 32, vcc
	v_ldexp_f32 v10, v10, v20
	v_log_f32_e32 v10, v10
	v_cvt_pk_f16_f32 v24, v12, v13
	v_cvt_pk_f16_f32 v4, v2, v3
	v_mul_f32_e32 v20, 0x3f317217, v10
	v_fma_f32 v20, v10, s91, -v20
	v_fmac_f32_e32 v20, 0x3377d1cf, v10
	v_fmac_f32_e32 v20, 0x3f317217, v10
	v_cmp_lt_f32_e64 s[6:7], |v10|, s97
	s_nop 1
	v_cndmask_b32_e64 v10, v10, v20, s[6:7]
	v_cndmask_b32_e32 v20, 0, v232, vcc
	v_sub_f32_e32 v10, v10, v20
	v_add_f32_e32 v10, v11, v10
	v_add_f32_e32 v11, v47, v211
	v_max_f32_e64 v20, -v11, 0
	v_mul_f32_e64 v11, |v11|, s89
	v_exp_f32_e32 v11, v11
	v_sub_f32_e32 v10, -0.5, v10
	v_mul_f32_e32 v10, 0x3fb8aa3b, v10
	v_exp_f32_e32 v10, v10
	v_add_f32_e32 v11, 1.0, v11
	v_cmp_gt_f32_e32 vcc, s90, v11
	v_mul_f32_e32 v10, 0xbfb8aa3b, v10
	s_nop 0
	v_cndmask_b32_e64 v21, 0, 32, vcc
	v_ldexp_f32 v11, v11, v21
	v_log_f32_e32 v11, v11
	v_exp_f32_e32 v10, v10
	v_mul_f32_e32 v21, 0x3f317217, v11
	v_fma_f32 v21, v11, s91, -v21
	v_fmac_f32_e32 v21, 0x3377d1cf, v11
	v_fmac_f32_e32 v21, 0x3f317217, v11
	v_cmp_lt_f32_e64 s[6:7], |v11|, s97
	v_sub_f32_e32 v22, 1.0, v10
	v_add_f32_e32 v10, v79, v208
	v_cndmask_b32_e64 v11, v11, v21, s[6:7]
	v_cndmask_b32_e32 v21, 0, v232, vcc
	v_sub_f32_e32 v11, v11, v21
	v_add_f32_e32 v11, v20, v11
	v_sub_f32_e32 v11, -0.5, v11
	v_mul_f32_e32 v11, 0x3fb8aa3b, v11
	v_exp_f32_e32 v11, v11
	v_mul_f32_e32 v10, 0xbfb8aa3b, v10
	v_exp_f32_e32 v10, v10
	v_mad_i64_i32 v[20:21], s[6:7], v14, s95, v[102:103]
	v_mul_f32_e32 v11, 0xbfb8aa3b, v11
	v_exp_f32_e32 v11, v11
	v_lshlrev_b64 v[18:19], 1, v[20:21]
	v_lshl_add_u64 v[20:21], s[58:59], 0, v[18:19]
	global_store_dword v[20:21], v24, off
	v_sub_f32_e32 v23, 1.0, v11
	v_add_f32_e32 v11, v63, v209
	v_mul_f32_e32 v11, 0xbfb8aa3b, v11
	v_exp_f32_e32 v11, v11
	v_cvt_pk_f16_f32 v22, v22, v23
	v_lshl_add_u64 v[20:21], s[66:67], 0, v[18:19]
	global_store_dword v[20:21], v22, off
	v_pk_add_f32 v[6:7], v[10:11], 1.0 op_sel_hi:[1,0]
	v_lshl_add_u64 v[2:3], s[70:71], 0, v[18:19]
	v_div_scale_f32 v10, s[6:7], v7, v7, 1.0
	v_rcp_f32_e32 v11, v10
	global_store_dword v[2:3], v4, off
	v_pk_mul_f32 v[2:3], v[194:195], v[8:9]
	v_fma_f32 v20, -v10, v11, 1.0
	v_fmac_f32_e32 v11, v20, v11
	v_div_scale_f32 v20, vcc, 1.0, v7, 1.0
	v_mul_f32_e32 v21, v20, v11
	v_fma_f32 v22, -v10, v21, v20
	v_fmac_f32_e32 v21, v22, v11
	v_fma_f32 v10, -v10, v21, v20
	v_div_fmas_f32 v10, v10, v11, v21
	v_div_fixup_f32 v11, v10, v7, 1.0
	v_div_scale_f32 v7, s[6:7], v6, v6, 1.0
	v_rcp_f32_e32 v10, v7
	v_pk_mul_f32 v[4:5], v[2:3], v[2:3]
	v_fma_f32 v20, -v7, v10, 1.0
	v_add_f32_e32 v4, v4, v5
	v_fmac_f32_e32 v10, v20, v10
	v_div_scale_f32 v20, vcc, 1.0, v6, 1.0
	v_add_f32_dpp v4, v4, v4 quad_perm:[1,0,3,2] row_mask:0xf bank_mask:0xf bound_ctrl:1
	v_mul_f32_e32 v21, v20, v10
	v_fma_f32 v22, -v7, v21, v20
	v_add_f32_dpp v4, v4, v4 quad_perm:[2,3,0,1] row_mask:0xf bank_mask:0xf bound_ctrl:1
	v_fmac_f32_e32 v21, v22, v10
	v_fma_f32 v7, -v7, v21, v20
	v_add_f32_dpp v4, v4, v4 row_half_mirror row_mask:0xf bank_mask:0xf bound_ctrl:1
	v_div_fmas_f32 v7, v7, v10, v21
	v_div_fixup_f32 v10, v7, v6, 1.0
	v_add_f32_dpp v4, v4, v4 row_mirror row_mask:0xf bank_mask:0xf bound_ctrl:1
	v_mov_b32_e32 v5, v4
	s_nop 1
	v_permlane16_swap_b32_e32 v4, v5
	v_add_f32_e32 v4, v4, v5
	v_add_f32_e32 v4, 0x2b8cbccc, v4
	v_pk_add_f32 v[6:7], v[10:11], -1.0 op_sel_hi:[1,0]
	v_cmp_gt_f32_e32 vcc, s90, v4
	v_mul_f32_e32 v5, 0x4b800000, v4
	v_pk_fma_f32 v[6:7], v[202:203], v[6:7], 1.0 op_sel_hi:[1,1,0]
	v_cndmask_b32_e32 v4, v4, v5, vcc
	v_pk_mul_f32 v[20:21], v[6:7], v[8:9]
	v_rsq_f32_e32 v4, v4
	v_pk_mul_f32 v[6:7], v[12:13], v[20:21]
	v_cvt_pk_f16_f32 v20, v20, v21
	v_fma_f32 v6, v198, v6, 0
	v_fmac_f32_e32 v6, v199, v7
	v_mul_f32_e32 v5, 0x45800000, v4
	v_cndmask_b32_e32 v4, v4, v5, vcc
	v_add_f32_dpp v6, v6, v6 quad_perm:[1,0,3,2] row_mask:0xf bank_mask:0xf bound_ctrl:1
	v_pk_mul_f32 v[2:3], v[2:3], v[4:5] op_sel_hi:[1,0]
	v_lshl_add_u64 v[4:5], s[72:73], 0, v[18:19]
	v_add_f32_dpp v6, v6, v6 quad_perm:[2,3,0,1] row_mask:0xf bank_mask:0xf bound_ctrl:1
	v_cvt_pk_f16_f32 v8, v2, v3
	v_pk_mul_f32 v[2:3], v[10:11], v[2:3]
	v_add_f32_dpp v6, v6, v6 row_half_mirror row_mask:0xf bank_mask:0xf bound_ctrl:1
	global_store_dword v[4:5], v8, off
	v_cvt_pk_f16_f32 v4, v2, v3
	v_add_f32_dpp v6, v6, v6 row_mirror row_mask:0xf bank_mask:0xf bound_ctrl:1
	v_mov_b32_e32 v7, v6
	v_lshl_add_u64 v[2:3], s[74:75], 0, v[18:19]
	s_nop 0
	v_permlane16_swap_b32_e32 v6, v7
	v_lshl_add_u64 v[12:13], s[68:69], 0, v[18:19]
	global_store_dword v[2:3], v4, off
	v_cvt_pk_f16_f32 v4, v15, v31
	v_lshl_add_u64 v[2:3], s[78:79], 0, v[18:19]
	global_store_dword v[12:13], v20, off
	global_store_dword v[2:3], v4, off
	s_and_saveexec_b64 s[6:7], s[4:5]
	s_cbranch_execz .LBB0_1256
	v_add_f32_e32 v4, v6, v7
	v_mad_i64_i32 v[2:3], s[86:87], v14, 48, v[200:201]
	global_store_dword v[2:3], v4, off
; DEVI void rwkv_prep_item(const Params& p, const int l, const int item, char* smem) {
;     ...
;     for (int r = 0; r < 16; ++r) {
;       const int t = t0 + mt * 32 + (r & 3) + 8 * (r >> 2) + 4 * hi; const bool has_prev = (t & (SEQ_ - 1)) != 0;
;       float rv[2], kv[2], vv[2], av[2], kkv[2], kpv[2], omdv[2], gv[2];
;       float ssq = 0.f, bon = 0.f;
;       const u16* pr = PA + (size_t)t * 2560 + h * 64 + 2 * l31;
;       const unsigned cr2 = *(const unsigned*)pr, ck2 = *(const unsigned*)(pr + 768), cv2 = *(const unsigned*)(pr + 1536);
;       unsigned qr2 = 0u, qk2 = 0u, qv2 = 0u;
;       if (has_prev) { qr2 = *(const unsigned*)(pr - 2560); qk2 = *(const unsigned*)(pr + 768 - 2560); qv2 = *(const unsigned*)(pr + 1536 - 2560); }
; #pragma unroll
;       for (int n = 0; n < 2; ++n) {
;         const float cr = __uint_as_float(n ? (cr2 & 0xffff0000u) : (cr2 << 16)), ck = __uint_as_float(n ? (ck2 & 0xffff0000u) : (ck2 << 16)), cv = __uint_as_float(n ? (cv2 & 0xffff0000u) : (cv2 << 16));
;         const float qr = __uint_as_float(n ? (qr2 & 0xffff0000u) : (qr2 << 16)), qk = __uint_as_float(n ? (qk2 & 0xffff0000u) : (qk2 << 16)), qv = __uint_as_float(n ? (qv2 & 0xffff0000u) : (qv2 << 16));
;         rv[n] = cr + (qr - cr) * mur[n]; kv[n] = ck + (qk - ck) * muk[n]; vv[n] = cv + (qv - cv) * muv[n];
;         const float z = -(w0c[n] + aw[n][r]);
;         const float sp = fmaxf(z, 0.f) + __logf(1.f + __expf(-fabsf(z)));
;         const float ew = __expf(-sp - 0.5f);
;         omdv[n] = 1.f - __expf(-ew);
;         av[n] = sigmoidf_(a0c[n] + aa[n][r]);
;         gv[n] = ag[n][r];
;         kkv[n] = kv[n] * kkc[n];
;         kpv[n] = kv[n] * (1.f + (av[n] - 1.f) * kac[n]);
;         ssq += kkv[n] * kkv[n];
;         bon += rv[n] * kpv[n] * rkc[n];
;       }
;       ssq = reduce32(ssq); bon = reduce32(bon);
;       const float rn = rsqrtf(ssq + 1e-12f);
;       {
;         typedef _Float16 h2 __attribute__((ext_vector_type(2)));
;         const size_t o = (size_t)t * 768 + h * 64 + 2 * l31;
;         const float kn0 = kkv[0] * rn, kn1 = kkv[1] * rn;
;         *(h2*)(RW + o) = (h2){(f16)rv[0], (f16)rv[1]};
;         *(h2*)(RW + TS + o) = (h2){(f16)omdv[0], (f16)omdv[1]};
;         *(h2*)(RW + 2 * TS + o) = (h2){(f16)kpv[0], (f16)kpv[1]};
;         *(h2*)(RW + 3 * TS + o) = (h2){(f16)vv[0], (f16)vv[1]};
;         *(h2*)(RW + 4 * TS + o) = (h2){(f16)kn0, (f16)kn1};
.LBB0_1256:
	s_or_b64 exec, exec, s[6:7]
	v_or_b32_e32 v18, 26, v233
	v_mad_i64_i32 v[2:3], s[6:7], v18, s88, v[212:213]
	s_waitcnt vmcnt(7)
	v_mov_b32_e32 v4, v246
	v_mov_b32_e32 v5, v247
	v_mov_b32_e32 v8, v248
	v_mov_b32_e32 v10, v249
	v_mov_b32_e32 v11, v250
	v_add_co_u32_e32 v2, vcc, 0xfffff000, v2
	s_nop 0
	v_and_b32_e32 v13, 0xffff0000, v4
	v_addc_co_u32_e32 v3, vcc, -1, v3, vcc
	v_mov_b32_e32 v9, v251
	v_or_b32_e32 v253, 27, v233
	v_mad_i64_i32 v[254:255], s[86:87], v253, s88, v[212:213]
	global_load_dword v246, v[254:255], off
	global_load_dword v247, v[254:255], off offset:1536
	global_load_dword v248, v[254:255], off offset:3072
	global_load_dword v249, v[254:255], off offset:-2048
	global_load_dword v250, v[254:255], off offset:-3584
	v_add_co_u32_e32 v254, vcc, 0xfffff000, v254
	s_nop 1
	v_addc_co_u32_e32 v255, vcc, -1, v255, vcc
	global_load_dword v251, v[254:255], off offset:-1024
	v_lshlrev_b32_e32 v12, 16, v4
	s_nop 0
	v_and_b32_e32 v7, 0xffff0000, v5
	v_lshlrev_b32_e32 v6, 16, v5
	s_nop 0
	v_and_b32_e32 v5, 0xffff0000, v10
	v_lshlrev_b32_e32 v4, 16, v10
	v_add_f32_e32 v10, v96, v210
	v_and_b32_e32 v3, 0xffff0000, v8
	v_lshlrev_b32_e32 v2, 16, v8
	s_nop 0
	v_lshlrev_b32_e32 v8, 16, v11
	v_pk_add_f32 v[4:5], v[4:5], v[2:3] neg_lo:[0,1] neg_hi:[0,1]
	s_nop 0
	v_and_b32_e32 v15, 0xffff0000, v9
	v_lshlrev_b32_e32 v14, 16, v9
	v_and_b32_e32 v9, 0xffff0000, v11
	v_max_f32_e64 v11, -v10, 0
	v_mul_f32_e64 v10, |v10|, s89
	v_exp_f32_e32 v10, v10
	v_pk_add_f32 v[8:9], v[8:9], v[6:7] neg_lo:[0,1] neg_hi:[0,1]
	v_pk_add_f32 v[14:15], v[14:15], v[12:13] neg_lo:[0,1] neg_hi:[0,1]
	v_pk_fma_f32 v[8:9], v[204:205], v[8:9], v[6:7]
	v_add_f32_e32 v10, 1.0, v10
	v_cmp_gt_f32_e32 vcc, s90, v10
	v_pk_fma_f32 v[12:13], v[206:207], v[14:15], v[12:13]
	v_pk_fma_f32 v[2:3], v[196:197], v[4:5], v[2:3]
	v_cndmask_b32_e64 v19, 0, 32, vcc
	v_ldexp_f32 v10, v10, v19
	v_log_f32_e32 v10, v10
	v_cvt_pk_f16_f32 v23, v12, v13
	v_cvt_pk_f16_f32 v4, v2, v3
	v_mul_f32_e32 v19, 0x3f317217, v10
	v_fma_f32 v19, v10, s91, -v19
	v_fmac_f32_e32 v19, 0x3377d1cf, v10
	v_fmac_f32_e32 v19, 0x3f317217, v10
	v_cmp_lt_f32_e64 s[6:7], |v10|, s97
	s_nop 1
	v_cndmask_b32_e64 v10, v10, v19, s[6:7]
	v_cndmask_b32_e32 v19, 0, v232, vcc
	v_sub_f32_e32 v10, v10, v19
	v_add_f32_e32 v10, v11, v10
	v_add_f32_e32 v11, v48, v211
	v_max_f32_e64 v20, -v11, 0
	v_mul_f32_e64 v11, |v11|, s89
	v_exp_f32_e32 v11, v11
	v_sub_f32_e32 v10, -0.5, v10
	v_mul_f32_e32 v10, 0x3fb8aa3b, v10
	v_exp_f32_e32 v10, v10
	v_add_f32_e32 v11, 1.0, v11
	v_cmp_gt_f32_e32 vcc, s90, v11
	v_mul_f32_e32 v10, 0xbfb8aa3b, v10
	s_nop 0
	v_cndmask_b32_e64 v21, 0, 32, vcc
	v_ldexp_f32 v11, v11, v21
	v_log_f32_e32 v11, v11
	v_exp_f32_e32 v10, v10
	v_mul_f32_e32 v21, 0x3f317217, v11
	v_fma_f32 v21, v11, s91, -v21
	v_fmac_f32_e32 v21, 0x3377d1cf, v11
	v_fmac_f32_e32 v21, 0x3f317217, v11
	v_cmp_lt_f32_e64 s[6:7], |v11|, s97
	v_sub_f32_e32 v19, 1.0, v10
	v_add_f32_e32 v10, v80, v208
	v_cndmask_b32_e64 v11, v11, v21, s[6:7]
	v_cndmask_b32_e32 v21, 0, v232, vcc
	v_sub_f32_e32 v11, v11, v21
	v_add_f32_e32 v11, v20, v11
	v_sub_f32_e32 v11, -0.5, v11
	v_mul_f32_e32 v11, 0x3fb8aa3b, v11
	v_exp_f32_e32 v11, v11
	v_mul_f32_e32 v10, 0xbfb8aa3b, v10
	v_exp_f32_e32 v10, v10
	v_mad_i64_i32 v[20:21], s[6:7], v18, s95, v[102:103]
	v_mul_f32_e32 v11, 0xbfb8aa3b, v11
	v_exp_f32_e32 v11, v11
	v_lshlrev_b64 v[14:15], 1, v[20:21]
	v_lshl_add_u64 v[20:21], s[58:59], 0, v[14:15]
	global_store_dword v[20:21], v23, off
	v_sub_f32_e32 v22, 1.0, v11
	v_add_f32_e32 v11, v64, v209
	v_mul_f32_e32 v11, 0xbfb8aa3b, v11
	v_exp_f32_e32 v11, v11
	v_cvt_pk_f16_f32 v19, v19, v22
	v_lshl_add_u64 v[20:21], s[66:67], 0, v[14:15]
	global_store_dword v[20:21], v19, off
	v_pk_add_f32 v[6:7], v[10:11], 1.0 op_sel_hi:[1,0]
	v_lshl_add_u64 v[2:3], s[70:71], 0, v[14:15]
	v_div_scale_f32 v10, s[6:7], v7, v7, 1.0
	v_rcp_f32_e32 v11, v10
	global_store_dword v[2:3], v4, off
	v_pk_mul_f32 v[2:3], v[194:195], v[8:9]
	v_fma_f32 v19, -v10, v11, 1.0
	v_fmac_f32_e32 v11, v19, v11
	v_div_scale_f32 v19, vcc, 1.0, v7, 1.0
	v_mul_f32_e32 v20, v19, v11
	v_fma_f32 v21, -v10, v20, v19
	v_fmac_f32_e32 v20, v21, v11
	v_fma_f32 v10, -v10, v20, v19
	v_div_fmas_f32 v10, v10, v11, v20
	v_div_fixup_f32 v11, v10, v7, 1.0
	v_div_scale_f32 v7, s[6:7], v6, v6, 1.0
	v_rcp_f32_e32 v10, v7
	v_pk_mul_f32 v[4:5], v[2:3], v[2:3]
	v_fma_f32 v19, -v7, v10, 1.0
	v_add_f32_e32 v4, v4, v5
	v_fmac_f32_e32 v10, v19, v10
	v_div_scale_f32 v19, vcc, 1.0, v6, 1.0
	v_add_f32_dpp v4, v4, v4 quad_perm:[1,0,3,2] row_mask:0xf bank_mask:0xf bound_ctrl:1
	v_mul_f32_e32 v20, v19, v10
	v_fma_f32 v21, -v7, v20, v19
	v_add_f32_dpp v4, v4, v4 quad_perm:[2,3,0,1] row_mask:0xf bank_mask:0xf bound_ctrl:1
	v_fmac_f32_e32 v20, v21, v10
	v_fma_f32 v7, -v7, v20, v19
	v_add_f32_dpp v4, v4, v4 row_half_mirror row_mask:0xf bank_mask:0xf bound_ctrl:1
	v_div_fmas_f32 v7, v7, v10, v20
	v_div_fixup_f32 v10, v7, v6, 1.0
	v_add_f32_dpp v4, v4, v4 row_mirror row_mask:0xf bank_mask:0xf bound_ctrl:1
	v_mov_b32_e32 v5, v4
	s_nop 1
	v_permlane16_swap_b32_e32 v4, v5
	v_add_f32_e32 v4, v4, v5
	v_add_f32_e32 v4, 0x2b8cbccc, v4
	v_pk_add_f32 v[6:7], v[10:11], -1.0 op_sel_hi:[1,0]
	v_cmp_gt_f32_e32 vcc, s90, v4
	v_mul_f32_e32 v5, 0x4b800000, v4
	v_pk_fma_f32 v[6:7], v[202:203], v[6:7], 1.0 op_sel_hi:[1,1,0]
	v_cndmask_b32_e32 v4, v4, v5, vcc
	v_pk_mul_f32 v[20:21], v[6:7], v[8:9]
	v_rsq_f32_e32 v4, v4
	v_pk_mul_f32 v[6:7], v[12:13], v[20:21]
	v_cvt_pk_f16_f32 v19, v20, v21
	v_fma_f32 v6, v198, v6, 0
	v_fmac_f32_e32 v6, v199, v7
	v_mul_f32_e32 v5, 0x45800000, v4
	v_cndmask_b32_e32 v4, v4, v5, vcc
	v_add_f32_dpp v6, v6, v6 quad_perm:[1,0,3,2] row_mask:0xf bank_mask:0xf bound_ctrl:1
	v_pk_mul_f32 v[2:3], v[2:3], v[4:5] op_sel_hi:[1,0]
	v_lshl_add_u64 v[4:5], s[72:73], 0, v[14:15]
	v_add_f32_dpp v6, v6, v6 quad_perm:[2,3,0,1] row_mask:0xf bank_mask:0xf bound_ctrl:1
	v_cvt_pk_f16_f32 v8, v2, v3
	v_pk_mul_f32 v[2:3], v[10:11], v[2:3]
	v_add_f32_dpp v6, v6, v6 row_half_mirror row_mask:0xf bank_mask:0xf bound_ctrl:1
	global_store_dword v[4:5], v8, off
	v_cvt_pk_f16_f32 v4, v2, v3
	v_add_f32_dpp v6, v6, v6 row_mirror row_mask:0xf bank_mask:0xf bound_ctrl:1
	v_mov_b32_e32 v7, v6
	v_lshl_add_u64 v[2:3], s[74:75], 0, v[14:15]
	s_nop 0
	v_permlane16_swap_b32_e32 v6, v7
	v_lshl_add_u64 v[12:13], s[68:69], 0, v[14:15]
	global_store_dword v[2:3], v4, off
	v_cvt_pk_f16_f32 v4, v16, v32
	v_lshl_add_u64 v[2:3], s[78:79], 0, v[14:15]
	global_store_dword v[12:13], v19, off
	global_store_dword v[2:3], v4, off
	s_and_saveexec_b64 s[6:7], s[4:5]
	s_cbranch_execz .LBB0_1258
	v_add_f32_e32 v4, v6, v7
	v_mad_i64_i32 v[2:3], s[86:87], v18, 48, v[200:201]
	global_store_dword v[2:3], v4, off
; DEVI void rwkv_prep_item(const Params& p, const int l, const int item, char* smem) {
;     ...
;     for (int r = 0; r < 16; ++r) {
;       const int t = t0 + mt * 32 + (r & 3) + 8 * (r >> 2) + 4 * hi; const bool has_prev = (t & (SEQ_ - 1)) != 0;
;       float rv[2], kv[2], vv[2], av[2], kkv[2], kpv[2], omdv[2], gv[2];
;       float ssq = 0.f, bon = 0.f;
;       const u16* pr = PA + (size_t)t * 2560 + h * 64 + 2 * l31;
;       const unsigned cr2 = *(const unsigned*)pr, ck2 = *(const unsigned*)(pr + 768), cv2 = *(const unsigned*)(pr + 1536);
;       unsigned qr2 = 0u, qk2 = 0u, qv2 = 0u;
;       if (has_prev) { qr2 = *(const unsigned*)(pr - 2560); qk2 = *(const unsigned*)(pr + 768 - 2560); qv2 = *(const unsigned*)(pr + 1536 - 2560); }
; #pragma unroll
;       for (int n = 0; n < 2; ++n) {
;         const float cr = __uint_as_float(n ? (cr2 & 0xffff0000u) : (cr2 << 16)), ck = __uint_as_float(n ? (ck2 & 0xffff0000u) : (ck2 << 16)), cv = __uint_as_float(n ? (cv2 & 0xffff0000u) : (cv2 << 16));
;         const float qr = __uint_as_float(n ? (qr2 & 0xffff0000u) : (qr2 << 16)), qk = __uint_as_float(n ? (qk2 & 0xffff0000u) : (qk2 << 16)), qv = __uint_as_float(n ? (qv2 & 0xffff0000u) : (qv2 << 16));
;         rv[n] = cr + (qr - cr) * mur[n]; kv[n] = ck + (qk - ck) * muk[n]; vv[n] = cv + (qv - cv) * muv[n];
;         const float z = -(w0c[n] + aw[n][r]);
;         const float sp = fmaxf(z, 0.f) + __logf(1.f + __expf(-fabsf(z)));
;         const float ew = __expf(-sp - 0.5f);
;         omdv[n] = 1.f - __expf(-ew);
;         av[n] = sigmoidf_(a0c[n] + aa[n][r]);
;         gv[n] = ag[n][r];
;         kkv[n] = kv[n] * kkc[n];
;         kpv[n] = kv[n] * (1.f + (av[n] - 1.f) * kac[n]);
;         ssq += kkv[n] * kkv[n];
;         bon += rv[n] * kpv[n] * rkc[n];
;       }
;       ssq = reduce32(ssq); bon = reduce32(bon);
;       const float rn = rsqrtf(ssq + 1e-12f);
;       {
;         typedef _Float16 h2 __attribute__((ext_vector_type(2)));
;         const size_t o = (size_t)t * 768 + h * 64 + 2 * l31;
;         const float kn0 = kkv[0] * rn, kn1 = kkv[1] * rn;
;         *(h2*)(RW + o) = (h2){(f16)rv[0], (f16)rv[1]};
;         *(h2*)(RW + TS + o) = (h2){(f16)omdv[0], (f16)omdv[1]};
;         *(h2*)(RW + 2 * TS + o) = (h2){(f16)kpv[0], (f16)kpv[1]};
;         *(h2*)(RW + 3 * TS + o) = (h2){(f16)vv[0], (f16)vv[1]};
;         *(h2*)(RW + 4 * TS + o) = (h2){(f16)kn0, (f16)kn1};
.LBB0_1258:
	s_or_b64 exec, exec, s[6:7]
	v_or_b32_e32 v2, 27, v233
	v_mad_i64_i32 v[4:5], s[6:7], v2, s88, v[212:213]
	v_add_co_u32_e32 v6, vcc, 0xfffff000, v4
	s_waitcnt vmcnt(7)
	v_mov_b32_e32 v3, v246
	s_nop 0
	v_addc_co_u32_e32 v7, vcc, -1, v5, vcc
	v_mov_b32_e32 v12, v247
	v_mov_b32_e32 v14, v248
	v_mov_b32_e32 v16, v250
	v_mov_b32_e32 v20, v251
	v_mov_b32_e32 v22, v249
	v_add_f32_e32 v4, v97, v210
	v_add_f32_e32 v5, v81, v208
	v_add_f32_e32 v6, v49, v211
	v_max_f32_e64 v8, -v4, 0
	v_mul_f32_e64 v4, |v4|, s89
	v_mul_f32_e32 v9, 0xbfb8aa3b, v5
	v_max_f32_e64 v10, -v6, 0
	v_mul_f32_e64 v5, |v6|, s89
	v_exp_f32_e32 v6, v4
	v_exp_f32_e32 v11, v5
	v_mad_i64_i32 v[4:5], s[6:7], v2, s95, v[102:103]
	v_add_f32_e32 v6, 1.0, v6
	v_add_f32_e32 v11, 1.0, v11
	v_cmp_gt_f32_e32 vcc, s90, v6
	v_cmp_gt_f32_e64 s[6:7], s90, v11
	v_add_f32_e32 v7, v65, v209
	v_cndmask_b32_e64 v13, 0, 32, vcc
	v_cndmask_b32_e64 v15, 0, 32, s[6:7]
	v_ldexp_f32 v6, v6, v13
	v_ldexp_f32 v11, v11, v15
	v_log_f32_e32 v6, v6
	v_log_f32_e32 v11, v11
	v_cndmask_b32_e32 v13, 0, v232, vcc
	v_cndmask_b32_e64 v15, 0, v232, s[6:7]
	v_mul_f32_e32 v18, 0x3f317217, v6
	v_mul_f32_e32 v19, 0x3f317217, v11
	v_fma_f32 v18, v6, s91, -v18
	v_fma_f32 v19, v11, s91, -v19
	v_fmac_f32_e32 v18, 0x3377d1cf, v6
	v_fmac_f32_e32 v19, 0x3377d1cf, v11
	v_fmac_f32_e32 v18, 0x3f317217, v6
	v_cmp_lt_f32_e64 vcc, |v6|, s97
	v_fmac_f32_e32 v19, 0x3f317217, v11
	v_mul_f32_e32 v7, 0xbfb8aa3b, v7
	v_cndmask_b32_e32 v6, v6, v18, vcc
	v_cmp_lt_f32_e64 vcc, |v11|, s97
	v_sub_f32_e32 v6, v6, v13
	v_add_f32_e32 v6, v8, v6
	v_cndmask_b32_e32 v11, v11, v19, vcc
	v_sub_f32_e32 v11, v11, v15
	v_add_f32_e32 v8, v10, v11
	v_sub_f32_e32 v6, -0.5, v6
	v_sub_f32_e32 v8, -0.5, v8
	v_mul_f32_e32 v6, 0x3fb8aa3b, v6
	v_mul_f32_e32 v8, 0x3fb8aa3b, v8
	v_exp_f32_e32 v10, v6
	v_exp_f32_e32 v8, v8
	v_exp_f32_e32 v6, v9
	v_exp_f32_e32 v7, v7
	v_mul_f32_e32 v9, 0xbfb8aa3b, v10
	v_mul_f32_e32 v8, 0xbfb8aa3b, v8
	v_exp_f32_e32 v10, v9
	v_exp_f32_e32 v11, v8
	v_lshlrev_b64 v[8:9], 1, v[4:5]
	v_lshl_add_u64 v[4:5], s[58:59], 0, v[8:9]
	v_sub_f32_e32 v10, 1.0, v10
	v_sub_f32_e32 v11, 1.0, v11
	v_cvt_pk_f16_f32 v24, v10, v11
	v_pk_add_f32 v[6:7], v[6:7], 1.0 op_sel_hi:[1,0]
	s_nop 0
	v_and_b32_e32 v11, 0xffff0000, v3
	v_lshlrev_b32_e32 v10, 16, v3
	s_nop 0
	v_and_b32_e32 v13, 0xffff0000, v12
	s_nop 0
	v_and_b32_e32 v21, 0xffff0000, v20
	v_lshlrev_b32_e32 v20, 16, v20
	v_pk_add_f32 v[20:21], v[20:21], v[10:11] neg_lo:[0,1] neg_hi:[0,1]
	v_and_b32_e32 v19, 0xffff0000, v16
	v_pk_fma_f32 v[10:11], v[206:207], v[20:21], v[10:11]
	v_lshlrev_b32_e32 v18, 16, v16
	v_cvt_pk_f16_f32 v3, v10, v11
	global_store_dword v[4:5], v3, off
	v_div_scale_f32 v3, s[6:7], v7, v7, 1.0
	v_rcp_f32_e32 v16, v3
	v_lshlrev_b32_e32 v12, 16, v12
	v_lshl_add_u64 v[4:5], s[66:67], 0, v[8:9]
	global_store_dword v[4:5], v24, off
	v_pk_add_f32 v[4:5], v[18:19], v[12:13] neg_lo:[0,1] neg_hi:[0,1]
	v_and_b32_e32 v15, 0xffff0000, v14
	v_pk_fma_f32 v[12:13], v[204:205], v[4:5], v[12:13]
	v_fma_f32 v4, -v3, v16, 1.0
	v_fmac_f32_e32 v16, v4, v16
	v_div_scale_f32 v4, vcc, 1.0, v7, 1.0
	v_mul_f32_e32 v5, v4, v16
	v_fma_f32 v18, -v3, v5, v4
	v_fmac_f32_e32 v5, v18, v16
	v_fma_f32 v3, -v3, v5, v4
	v_div_scale_f32 v4, s[6:7], v6, v6, 1.0
	v_rcp_f32_e32 v18, v4
	v_div_fmas_f32 v3, v3, v16, v5
	v_div_fixup_f32 v7, v3, v7, 1.0
	v_lshlrev_b32_e32 v14, 16, v14
	v_fma_f32 v3, -v4, v18, 1.0
	v_fmac_f32_e32 v18, v3, v18
	v_div_scale_f32 v3, vcc, 1.0, v6, 1.0
	v_mul_f32_e32 v5, v3, v18
	v_fma_f32 v16, -v4, v5, v3
	v_fmac_f32_e32 v5, v16, v18
	v_fma_f32 v3, -v4, v5, v3
	v_div_fmas_f32 v3, v3, v18, v5
	v_div_fixup_f32 v6, v3, v6, 1.0
	v_pk_add_f32 v[4:5], v[6:7], -1.0 op_sel_hi:[1,0]
	s_nop 0
	v_and_b32_e32 v23, 0xffff0000, v22
	v_pk_fma_f32 v[4:5], v[202:203], v[4:5], 1.0 op_sel_hi:[1,1,0]
	v_lshlrev_b32_e32 v22, 16, v22
	v_pk_mul_f32 v[18:19], v[4:5], v[12:13]
	v_pk_mul_f32 v[12:13], v[194:195], v[12:13]
	v_pk_mul_f32 v[4:5], v[10:11], v[18:19]
	v_lshl_add_u64 v[10:11], s[68:69], 0, v[8:9]
	v_fma_f32 v3, v198, v4, 0
	v_fmac_f32_e32 v3, v199, v5
	v_cvt_pk_f16_f32 v5, v18, v19
	global_store_dword v[10:11], v5, off
	v_pk_add_f32 v[10:11], v[22:23], v[14:15] neg_lo:[0,1] neg_hi:[0,1]
	v_add_f32_dpp v3, v3, v3 quad_perm:[1,0,3,2] row_mask:0xf bank_mask:0xf bound_ctrl:1
	v_pk_fma_f32 v[10:11], v[196:197], v[10:11], v[14:15]
	v_pk_mul_f32 v[14:15], v[12:13], v[12:13]
	v_add_f32_dpp v3, v3, v3 quad_perm:[2,3,0,1] row_mask:0xf bank_mask:0xf bound_ctrl:1
	v_add_f32_e32 v5, v14, v15
	s_nop 0
	v_add_f32_dpp v3, v3, v3 row_half_mirror row_mask:0xf bank_mask:0xf bound_ctrl:1
	v_add_f32_dpp v5, v5, v5 quad_perm:[1,0,3,2] row_mask:0xf bank_mask:0xf bound_ctrl:1
	s_nop 0
	v_add_f32_dpp v3, v3, v3 row_mirror row_mask:0xf bank_mask:0xf bound_ctrl:1
	v_add_f32_dpp v5, v5, v5 quad_perm:[2,3,0,1] row_mask:0xf bank_mask:0xf bound_ctrl:1
	v_mov_b32_e32 v4, v3
	s_nop 1
	v_permlane16_swap_b32_e32 v3, v4
	v_add_f32_dpp v5, v5, v5 row_half_mirror row_mask:0xf bank_mask:0xf bound_ctrl:1
	s_nop 1
	v_add_f32_dpp v5, v5, v5 row_mirror row_mask:0xf bank_mask:0xf bound_ctrl:1
	v_mov_b32_e32 v14, v5
	s_nop 1
	v_permlane16_swap_b32_e32 v5, v14
	v_add_f32_e32 v5, v5, v14
	v_add_f32_e32 v5, 0x2b8cbccc, v5
	v_mul_f32_e32 v14, 0x4b800000, v5
	v_cmp_gt_f32_e32 vcc, s90, v5
	s_nop 1
	v_cndmask_b32_e32 v5, v5, v14, vcc
	v_rsq_f32_e32 v5, v5
	v_cvt_pk_f16_f32 v14, v10, v11
	v_lshl_add_u64 v[10:11], s[70:71], 0, v[8:9]
	global_store_dword v[10:11], v14, off
	v_mul_f32_e32 v10, 0x45800000, v5
	v_cndmask_b32_e32 v10, v5, v10, vcc
	v_pk_mul_f32 v[10:11], v[12:13], v[10:11] op_sel_hi:[1,0]
	v_lshl_add_u64 v[12:13], s[72:73], 0, v[8:9]
	v_cvt_pk_f16_f32 v5, v10, v11
	v_pk_mul_f32 v[6:7], v[6:7], v[10:11]
	global_store_dword v[12:13], v5, off
	v_cvt_pk_f16_f32 v5, v6, v7
	v_lshl_add_u64 v[6:7], s[74:75], 0, v[8:9]
	global_store_dword v[6:7], v5, off
	v_cvt_pk_f16_f32 v5, v17, v33
	v_lshl_add_u64 v[6:7], s[78:79], 0, v[8:9]
	global_store_dword v[6:7], v5, off
	s_and_saveexec_b64 s[6:7], s[4:5]
	s_cbranch_execz .LBB0_1225
	v_add_f32_e32 v4, v3, v4
	v_mad_i64_i32 v[2:3], s[86:87], v2, 48, v[200:201]
	global_store_dword v[2:3], v4, off
	s_branch .LBB0_1225

; DEVI void rwkv_scan_item(const Params& p, const int item, char* smem) {
;     ...
;   const int rsub = lane >> 4, kp = lane & 15;
;   const int row16 = (wid & 3) * 4 + rsub;
;   f32x2 Sa = {0.f, 0.f}, Sb = {0.f, 0.f};
;     ...
;   for (int c = 0; c < NC; ++c) {
;     if (wid >= 4) {
;       if (c + 1 < NC) load_chunk(c + 1, (c + 1) & 1);
;       if (c >= 1) store_y(c - 1);
;     } else {
;       const float* sb = buf + (c & 1) * 12288 + kp * 4;
;       float* yb = ybuf + (c & 1) * 2048 + row16 * 4 + (kp >> 2);
;       const int vofs = 320 + rq * 16 + row16 - kp * 4;
.LBB0_1288:
	s_or_b64 exec, exec, s[58:59]
	s_lshl_b32 s52, s36, 2
	s_lshl_b32 s58, s64, 4
	s_and_b32 s52, s52, 0xc0
	s_and_b32 s60, s58, 48
	s_lshl_b64 s[58:59], s[56:57], 1
	s_lshl_b64 s[56:57], s[56:57], 2
	s_add_u32 s56, s34, s56
	v_lshl_add_u64 v[68:69], v[50:51], 0, s[58:59]
	v_lshl_add_u64 v[70:71], v[52:53], 0, s[58:59]
	v_lshl_add_u64 v[72:73], v[54:55], 0, s[58:59]
	v_lshl_add_u64 v[74:75], v[56:57], 0, s[58:59]
	v_lshl_add_u64 v[76:77], v[58:59], 0, s[58:59]
	v_lshl_add_u64 v[78:79], v[60:61], 0, s[58:59]
	s_addc_u32 s57, s35, s57
	s_lshl_b32 s58, s60, 2
	s_add_u32 s56, s56, s58
	s_addc_u32 s57, s57, 0
	v_mov_b32_e32 v26, v47
	v_mov_b32_e32 v27, v47
	v_lshl_add_u64 v[66:67], s[56:57], 0, v[46:47]
	v_add_u32_e32 v63, s60, v93
	v_add_u32_e32 v97, s52, v95
	s_mov_b32 s65, 0
	s_mov_b64 s[56:57], 0
	v_mov_b64_e32 v[28:29], v[26:27]
	v_mov_b32_e32 v100, v47
	v_mov_b32_e32 v101, v47
	v_mov_b32_e32 v102, v47
	v_mov_b32_e32 v103, v47
	s_waitcnt lgkmcnt(0)
	s_barrier
	s_branch .LBB0_1290

; DEVI void rwkv_scan_item(const Params& p, const int item, char* smem) {
;     ...
;   for (int c = 0; c < NC; ++c) {
;     if (wid >= 4) {
;       if (c + 1 < NC) load_chunk(c + 1, (c + 1) & 1);
;       if (c >= 1) store_y(c - 1);
;     } else {
;       const float* sb = buf + (c & 1) * 12288 + kp * 4;
;       float* yb = ybuf + (c & 1) * 2048 + row16 * 4 + (kp >> 2);
;       const int vofs = 320 + rq * 16 + row16 - kp * 4;
;       f32x4 kkA, wA, kaA, kA, rA, kkB, wB, kaB, kB, rB; float vA, vB;
;       RW_LD(0, A)
; #pragma unroll 2
;       for (int s = 0; s < 32; s += 2) {
;         RW_LD(s + 1, B)
;         __builtin_amdgcn_sched_barrier(0);
;         RW_STEP(s, A)
;         __builtin_amdgcn_sched_barrier(0);
;         if (s + 2 < 32) RW_LD(s + 2, A)
;         __builtin_amdgcn_sched_barrier(0);
;         RW_STEP(s + 1, B)
;         __builtin_amdgcn_sched_barrier(0);
;       }
.LBB0_1290:
	s_and_saveexec_b64 s[58:59], s[2:3]
	s_xor_b64 s[58:59], exec, s[58:59]
	s_cbranch_execz .LBB0_1295
	s_and_b32 s52, s65, 1
	s_mul_i32 s52, s52, 0xc000
	v_add_u32_e32 v98, s52, v83
	ds_read_b128 v[2:5], v98
	v_lshl_add_u32 v99, v63, 2, v98
	ds_read_b32 v22, v99 offset:1280
	ds_read_b128 v[14:17], v98 offset:768
	ds_read_b128 v[6:9], v98 offset:256
	ds_read_b128 v[10:13], v98 offset:512
	ds_read_b128 v[18:21], v98 offset:1024
	s_and_b32 s52, s65, 1
	s_lshl_b32 s52, s52, 13
	s_add_i32 s52, s52, 0x18010
	v_add_u32_e32 v97, s52, v94
	s_waitcnt lgkmcnt(0)
	v_pk_mul_f32 v[104:105], v[100:101], v[2:3]
	s_nop 0
	v_pk_fma_f32 v[104:105], v[102:103], v[4:5], v[104:105]
	s_nop 0
	v_add_f32_e32 v104, v104, v105
	ds_read_b32 v40, v99 offset:2816
	ds_read_b128 v[36:39], v98 offset:2304
	v_add_f32_dpp v104, v104, v104 quad_perm:[1,0,3,2] row_mask:0xf bank_mask:0xf bound_ctrl:1
	ds_read_b128 v[24:27], v98 offset:1536
	ds_read_b128 v[28:31], v98 offset:1792
	v_add_f32_dpp v104, v104, v104 quad_perm:[2,3,0,1] row_mask:0xf bank_mask:0xf bound_ctrl:1
	v_pk_mul_f32 v[14:15], v[14:15], v[22:23] op_sel_hi:[1,0]
	v_pk_mul_f32 v[16:17], v[16:17], v[22:23] op_sel_hi:[1,0]
	v_add_f32_dpp v104, v104, v104 row_half_mirror row_mask:0xf bank_mask:0xf bound_ctrl:1
	s_waitcnt lgkmcnt(5)
	v_pk_fma_f32 v[14:15], v[100:101], v[6:7], v[14:15]
	v_pk_fma_f32 v[16:17], v[102:103], v[8:9], v[16:17]
	v_add_f32_dpp v104, v104, v104 row_mirror row_mask:0xf bank_mask:0xf bound_ctrl:1
	v_pk_fma_f32 v[100:101], v[10:11], v[104:105], v[14:15] op_sel_hi:[1,0,1] neg_lo:[0,1,0] neg_hi:[0,1,0]
	v_pk_fma_f32 v[102:103], v[12:13], v[104:105], v[16:17] op_sel_hi:[1,0,1] neg_lo:[0,1,0] neg_hi:[0,1,0]
	v_pk_mul_f32 v[106:107], v[100:101], v[18:19]
	ds_read_b128 v[32:35], v98 offset:2048
	v_pk_fma_f32 v[106:107], v[102:103], v[20:21], v[106:107]
	s_waitcnt lgkmcnt(2)
	v_pk_mul_f32 v[104:105], v[100:101], v[24:25]
	v_add_f32_e32 v106, v106, v107
	ds_read_b128 v[84:87], v98 offset:2560
	v_pk_fma_f32 v[104:105], v[102:103], v[26:27], v[104:105]
	v_add_f32_dpp v106, v106, v106 quad_perm:[1,0,3,2] row_mask:0xf bank_mask:0xf bound_ctrl:1
	v_add_f32_e32 v104, v104, v105
	s_nop 0
	v_add_f32_dpp v106, v106, v106 quad_perm:[2,3,0,1] row_mask:0xf bank_mask:0xf bound_ctrl:1
	ds_write_b32 v97, v106 offset:0
	ds_read_b32 v22, v99 offset:4352
	ds_read_b128 v[14:17], v98 offset:3840
	v_add_f32_dpp v104, v104, v104 quad_perm:[1,0,3,2] row_mask:0xf bank_mask:0xf bound_ctrl:1
	ds_read_b128 v[2:5], v98 offset:3072
	ds_read_b128 v[6:9], v98 offset:3328
	v_add_f32_dpp v104, v104, v104 quad_perm:[2,3,0,1] row_mask:0xf bank_mask:0xf bound_ctrl:1
	v_pk_mul_f32 v[36:37], v[36:37], v[40:41] op_sel_hi:[1,0]
	v_pk_mul_f32 v[38:39], v[38:39], v[40:41] op_sel_hi:[1,0]
	v_add_f32_dpp v104, v104, v104 row_half_mirror row_mask:0xf bank_mask:0xf bound_ctrl:1
	s_waitcnt lgkmcnt(5)
	v_pk_fma_f32 v[36:37], v[100:101], v[28:29], v[36:37]
	v_pk_fma_f32 v[38:39], v[102:103], v[30:31], v[38:39]
	v_add_f32_dpp v104, v104, v104 row_mirror row_mask:0xf bank_mask:0xf bound_ctrl:1
	v_pk_fma_f32 v[100:101], v[32:33], v[104:105], v[36:37] op_sel_hi:[1,0,1] neg_lo:[0,1,0] neg_hi:[0,1,0]
	v_pk_fma_f32 v[102:103], v[34:35], v[104:105], v[38:39] op_sel_hi:[1,0,1] neg_lo:[0,1,0] neg_hi:[0,1,0]
	v_pk_mul_f32 v[106:107], v[100:101], v[84:85]
	ds_read_b128 v[10:13], v98 offset:3584
	v_pk_fma_f32 v[106:107], v[102:103], v[86:87], v[106:107]
	s_waitcnt lgkmcnt(2)
	v_pk_mul_f32 v[104:105], v[100:101], v[2:3]
	v_add_f32_e32 v106, v106, v107
	ds_read_b128 v[18:21], v98 offset:4096
	v_pk_fma_f32 v[104:105], v[102:103], v[4:5], v[104:105]
	v_add_f32_dpp v106, v106, v106 quad_perm:[1,0,3,2] row_mask:0xf bank_mask:0xf bound_ctrl:1
	v_add_f32_e32 v104, v104, v105
	s_nop 0
	v_add_f32_dpp v106, v106, v106 quad_perm:[2,3,0,1] row_mask:0xf bank_mask:0xf bound_ctrl:1
	ds_write_b32 v97, v106 offset:256
	ds_read_b32 v40, v99 offset:5888
	ds_read_b128 v[36:39], v98 offset:5376
	v_add_f32_dpp v104, v104, v104 quad_perm:[1,0,3,2] row_mask:0xf bank_mask:0xf bound_ctrl:1
	ds_read_b128 v[24:27], v98 offset:4608
	ds_read_b128 v[28:31], v98 offset:4864
	v_add_f32_dpp v104, v104, v104 quad_perm:[2,3,0,1] row_mask:0xf bank_mask:0xf bound_ctrl:1
	v_pk_mul_f32 v[14:15], v[14:15], v[22:23] op_sel_hi:[1,0]
	v_pk_mul_f32 v[16:17], v[16:17], v[22:23] op_sel_hi:[1,0]
	v_add_f32_dpp v104, v104, v104 row_half_mirror row_mask:0xf bank_mask:0xf bound_ctrl:1
	s_waitcnt lgkmcnt(5)
	v_pk_fma_f32 v[14:15], v[100:101], v[6:7], v[14:15]
	v_pk_fma_f32 v[16:17], v[102:103], v[8:9], v[16:17]
	v_add_f32_dpp v104, v104, v104 row_mirror row_mask:0xf bank_mask:0xf bound_ctrl:1
	v_pk_fma_f32 v[100:101], v[10:11], v[104:105], v[14:15] op_sel_hi:[1,0,1] neg_lo:[0,1,0] neg_hi:[0,1,0]
	v_pk_fma_f32 v[102:103], v[12:13], v[104:105], v[16:17] op_sel_hi:[1,0,1] neg_lo:[0,1,0] neg_hi:[0,1,0]
	v_pk_mul_f32 v[106:107], v[100:101], v[18:19]
	ds_read_b128 v[32:35], v98 offset:5120
	v_pk_fma_f32 v[106:107], v[102:103], v[20:21], v[106:107]
	s_waitcnt lgkmcnt(2)
	v_pk_mul_f32 v[104:105], v[100:101], v[24:25]
	v_add_f32_e32 v106, v106, v107
	ds_read_b128 v[84:87], v98 offset:5632
	v_pk_fma_f32 v[104:105], v[102:103], v[26:27], v[104:105]
	v_add_f32_dpp v106, v106, v106 quad_perm:[1,0,3,2] row_mask:0xf bank_mask:0xf bound_ctrl:1
	v_add_f32_e32 v104, v104, v105
	s_nop 0
	v_add_f32_dpp v106, v106, v106 quad_perm:[2,3,0,1] row_mask:0xf bank_mask:0xf bound_ctrl:1
	ds_write_b32 v97, v106 offset:512
	ds_read_b32 v22, v99 offset:7424
	ds_read_b128 v[14:17], v98 offset:6912
	v_add_f32_dpp v104, v104, v104 quad_perm:[1,0,3,2] row_mask:0xf bank_mask:0xf bound_ctrl:1
	ds_read_b128 v[2:5], v98 offset:6144
	ds_read_b128 v[6:9], v98 offset:6400
	v_add_f32_dpp v104, v104, v104 quad_perm:[2,3,0,1] row_mask:0xf bank_mask:0xf bound_ctrl:1
	v_pk_mul_f32 v[36:37], v[36:37], v[40:41] op_sel_hi:[1,0]
	v_pk_mul_f32 v[38:39], v[38:39], v[40:41] op_sel_hi:[1,0]
	v_add_f32_dpp v104, v104, v104 row_half_mirror row_mask:0xf bank_mask:0xf bound_ctrl:1
	s_waitcnt lgkmcnt(5)
; DEVI void rwkv_scan_item(const Params& p, const int item, char* smem) {
;     ...
;   for (int c = 0; c < NC; ++c) {
;     if (wid >= 4) {
;       if (c + 1 < NC) load_chunk(c + 1, (c + 1) & 1);
;       if (c >= 1) store_y(c - 1);
;     } else {
;       const float* sb = buf + (c & 1) * 12288 + kp * 4;
;       float* yb = ybuf + (c & 1) * 2048 + row16 * 4 + (kp >> 2);
;       const int vofs = 320 + rq * 16 + row16 - kp * 4;
;       f32x4 kkA, wA, kaA, kA, rA, kkB, wB, kaB, kB, rB; float vA, vB;
;       RW_LD(0, A)
; #pragma unroll 2
;       for (int s = 0; s < 32; s += 2) {
;         RW_LD(s + 1, B)
;         __builtin_amdgcn_sched_barrier(0);
;         RW_STEP(s, A)
;         __builtin_amdgcn_sched_barrier(0);
;         if (s + 2 < 32) RW_LD(s + 2, A)
;         __builtin_amdgcn_sched_barrier(0);
;         RW_STEP(s + 1, B)
;         __builtin_amdgcn_sched_barrier(0);
;       }
	v_pk_fma_f32 v[36:37], v[100:101], v[28:29], v[36:37]
	v_pk_fma_f32 v[38:39], v[102:103], v[30:31], v[38:39]
	v_add_f32_dpp v104, v104, v104 row_mirror row_mask:0xf bank_mask:0xf bound_ctrl:1
	v_pk_fma_f32 v[100:101], v[32:33], v[104:105], v[36:37] op_sel_hi:[1,0,1] neg_lo:[0,1,0] neg_hi:[0,1,0]
	v_pk_fma_f32 v[102:103], v[34:35], v[104:105], v[38:39] op_sel_hi:[1,0,1] neg_lo:[0,1,0] neg_hi:[0,1,0]
	v_pk_mul_f32 v[106:107], v[100:101], v[84:85]
	ds_read_b128 v[10:13], v98 offset:6656
	v_pk_fma_f32 v[106:107], v[102:103], v[86:87], v[106:107]
	s_waitcnt lgkmcnt(2)
	v_pk_mul_f32 v[104:105], v[100:101], v[2:3]
	v_add_f32_e32 v106, v106, v107
	ds_read_b128 v[18:21], v98 offset:7168
	v_pk_fma_f32 v[104:105], v[102:103], v[4:5], v[104:105]
	v_add_f32_dpp v106, v106, v106 quad_perm:[1,0,3,2] row_mask:0xf bank_mask:0xf bound_ctrl:1
	v_add_f32_e32 v104, v104, v105
	s_nop 0
	v_add_f32_dpp v106, v106, v106 quad_perm:[2,3,0,1] row_mask:0xf bank_mask:0xf bound_ctrl:1
	ds_write_b32 v97, v106 offset:768
	ds_read_b32 v40, v99 offset:8960
	ds_read_b128 v[36:39], v98 offset:8448
	v_add_f32_dpp v104, v104, v104 quad_perm:[1,0,3,2] row_mask:0xf bank_mask:0xf bound_ctrl:1
	ds_read_b128 v[24:27], v98 offset:7680
	ds_read_b128 v[28:31], v98 offset:7936
	v_add_f32_dpp v104, v104, v104 quad_perm:[2,3,0,1] row_mask:0xf bank_mask:0xf bound_ctrl:1
	v_pk_mul_f32 v[14:15], v[14:15], v[22:23] op_sel_hi:[1,0]
	v_pk_mul_f32 v[16:17], v[16:17], v[22:23] op_sel_hi:[1,0]
	v_add_f32_dpp v104, v104, v104 row_half_mirror row_mask:0xf bank_mask:0xf bound_ctrl:1
	s_waitcnt lgkmcnt(5)
	v_pk_fma_f32 v[14:15], v[100:101], v[6:7], v[14:15]
	v_pk_fma_f32 v[16:17], v[102:103], v[8:9], v[16:17]
	v_add_f32_dpp v104, v104, v104 row_mirror row_mask:0xf bank_mask:0xf bound_ctrl:1
	v_pk_fma_f32 v[100:101], v[10:11], v[104:105], v[14:15] op_sel_hi:[1,0,1] neg_lo:[0,1,0] neg_hi:[0,1,0]
	v_pk_fma_f32 v[102:103], v[12:13], v[104:105], v[16:17] op_sel_hi:[1,0,1] neg_lo:[0,1,0] neg_hi:[0,1,0]
	v_pk_mul_f32 v[106:107], v[100:101], v[18:19]
	ds_read_b128 v[32:35], v98 offset:8192
	v_pk_fma_f32 v[106:107], v[102:103], v[20:21], v[106:107]
	s_waitcnt lgkmcnt(2)
	v_pk_mul_f32 v[104:105], v[100:101], v[24:25]
	v_add_f32_e32 v106, v106, v107
	ds_read_b128 v[84:87], v98 offset:8704
	v_pk_fma_f32 v[104:105], v[102:103], v[26:27], v[104:105]
	v_add_f32_dpp v106, v106, v106 quad_perm:[1,0,3,2] row_mask:0xf bank_mask:0xf bound_ctrl:1
	v_add_f32_e32 v104, v104, v105
	s_nop 0
	v_add_f32_dpp v106, v106, v106 quad_perm:[2,3,0,1] row_mask:0xf bank_mask:0xf bound_ctrl:1
	ds_write_b32 v97, v106 offset:1024
	ds_read_b32 v22, v99 offset:10496
	ds_read_b128 v[14:17], v98 offset:9984
	v_add_f32_dpp v104, v104, v104 quad_perm:[1,0,3,2] row_mask:0xf bank_mask:0xf bound_ctrl:1
	ds_read_b128 v[2:5], v98 offset:9216
	ds_read_b128 v[6:9], v98 offset:9472
	v_add_f32_dpp v104, v104, v104 quad_perm:[2,3,0,1] row_mask:0xf bank_mask:0xf bound_ctrl:1
	v_pk_mul_f32 v[36:37], v[36:37], v[40:41] op_sel_hi:[1,0]
	v_pk_mul_f32 v[38:39], v[38:39], v[40:41] op_sel_hi:[1,0]
	v_add_f32_dpp v104, v104, v104 row_half_mirror row_mask:0xf bank_mask:0xf bound_ctrl:1
	s_waitcnt lgkmcnt(5)
	v_pk_fma_f32 v[36:37], v[100:101], v[28:29], v[36:37]
	v_pk_fma_f32 v[38:39], v[102:103], v[30:31], v[38:39]
	v_add_f32_dpp v104, v104, v104 row_mirror row_mask:0xf bank_mask:0xf bound_ctrl:1
	v_pk_fma_f32 v[100:101], v[32:33], v[104:105], v[36:37] op_sel_hi:[1,0,1] neg_lo:[0,1,0] neg_hi:[0,1,0]
	v_pk_fma_f32 v[102:103], v[34:35], v[104:105], v[38:39] op_sel_hi:[1,0,1] neg_lo:[0,1,0] neg_hi:[0,1,0]
	v_pk_mul_f32 v[106:107], v[100:101], v[84:85]
	ds_read_b128 v[10:13], v98 offset:9728
	v_pk_fma_f32 v[106:107], v[102:103], v[86:87], v[106:107]
	s_waitcnt lgkmcnt(2)
	v_pk_mul_f32 v[104:105], v[100:101], v[2:3]
	v_add_f32_e32 v106, v106, v107
	ds_read_b128 v[18:21], v98 offset:10240
	v_pk_fma_f32 v[104:105], v[102:103], v[4:5], v[104:105]
	v_add_f32_dpp v106, v106, v106 quad_perm:[1,0,3,2] row_mask:0xf bank_mask:0xf bound_ctrl:1
	v_add_f32_e32 v104, v104, v105
	s_nop 0
	v_add_f32_dpp v106, v106, v106 quad_perm:[2,3,0,1] row_mask:0xf bank_mask:0xf bound_ctrl:1
	ds_write_b32 v97, v106 offset:1280
	ds_read_b32 v40, v99 offset:12032
	ds_read_b128 v[36:39], v98 offset:11520
	v_add_f32_dpp v104, v104, v104 quad_perm:[1,0,3,2] row_mask:0xf bank_mask:0xf bound_ctrl:1
	ds_read_b128 v[24:27], v98 offset:10752
	ds_read_b128 v[28:31], v98 offset:11008
	v_add_f32_dpp v104, v104, v104 quad_perm:[2,3,0,1] row_mask:0xf bank_mask:0xf bound_ctrl:1
	v_pk_mul_f32 v[14:15], v[14:15], v[22:23] op_sel_hi:[1,0]
	v_pk_mul_f32 v[16:17], v[16:17], v[22:23] op_sel_hi:[1,0]
	v_add_f32_dpp v104, v104, v104 row_half_mirror row_mask:0xf bank_mask:0xf bound_ctrl:1
	s_waitcnt lgkmcnt(5)
	v_pk_fma_f32 v[14:15], v[100:101], v[6:7], v[14:15]
	v_pk_fma_f32 v[16:17], v[102:103], v[8:9], v[16:17]
	v_add_f32_dpp v104, v104, v104 row_mirror row_mask:0xf bank_mask:0xf bound_ctrl:1
	v_pk_fma_f32 v[100:101], v[10:11], v[104:105], v[14:15] op_sel_hi:[1,0,1] neg_lo:[0,1,0] neg_hi:[0,1,0]
	v_pk_fma_f32 v[102:103], v[12:13], v[104:105], v[16:17] op_sel_hi:[1,0,1] neg_lo:[0,1,0] neg_hi:[0,1,0]
	v_pk_mul_f32 v[106:107], v[100:101], v[18:19]
	ds_read_b128 v[32:35], v98 offset:11264
	v_pk_fma_f32 v[106:107], v[102:103], v[20:21], v[106:107]
	s_waitcnt lgkmcnt(2)
; DEVI void rwkv_scan_item(const Params& p, const int item, char* smem) {
;     ...
;   for (int c = 0; c < NC; ++c) {
;     if (wid >= 4) {
;       if (c + 1 < NC) load_chunk(c + 1, (c + 1) & 1);
;       if (c >= 1) store_y(c - 1);
;     } else {
;       const float* sb = buf + (c & 1) * 12288 + kp * 4;
;       float* yb = ybuf + (c & 1) * 2048 + row16 * 4 + (kp >> 2);
;       const int vofs = 320 + rq * 16 + row16 - kp * 4;
;       f32x4 kkA, wA, kaA, kA, rA, kkB, wB, kaB, kB, rB; float vA, vB;
;       RW_LD(0, A)
; #pragma unroll 2
;       for (int s = 0; s < 32; s += 2) {
;         RW_LD(s + 1, B)
;         __builtin_amdgcn_sched_barrier(0);
;         RW_STEP(s, A)
;         __builtin_amdgcn_sched_barrier(0);
;         if (s + 2 < 32) RW_LD(s + 2, A)
;         __builtin_amdgcn_sched_barrier(0);
;         RW_STEP(s + 1, B)
;         __builtin_amdgcn_sched_barrier(0);
;       }
	v_pk_mul_f32 v[104:105], v[100:101], v[24:25]
	v_add_f32_e32 v106, v106, v107
	ds_read_b128 v[84:87], v98 offset:11776
	v_pk_fma_f32 v[104:105], v[102:103], v[26:27], v[104:105]
	v_add_f32_dpp v106, v106, v106 quad_perm:[1,0,3,2] row_mask:0xf bank_mask:0xf bound_ctrl:1
	v_add_f32_e32 v104, v104, v105
	s_nop 0
	v_add_f32_dpp v106, v106, v106 quad_perm:[2,3,0,1] row_mask:0xf bank_mask:0xf bound_ctrl:1
	ds_write_b32 v97, v106 offset:1536
	ds_read_b32 v22, v99 offset:13568
	ds_read_b128 v[14:17], v98 offset:13056
	v_add_f32_dpp v104, v104, v104 quad_perm:[1,0,3,2] row_mask:0xf bank_mask:0xf bound_ctrl:1
	ds_read_b128 v[2:5], v98 offset:12288
	ds_read_b128 v[6:9], v98 offset:12544
	v_add_f32_dpp v104, v104, v104 quad_perm:[2,3,0,1] row_mask:0xf bank_mask:0xf bound_ctrl:1
	v_pk_mul_f32 v[36:37], v[36:37], v[40:41] op_sel_hi:[1,0]
	v_pk_mul_f32 v[38:39], v[38:39], v[40:41] op_sel_hi:[1,0]
	v_add_f32_dpp v104, v104, v104 row_half_mirror row_mask:0xf bank_mask:0xf bound_ctrl:1
	s_waitcnt lgkmcnt(5)
	v_pk_fma_f32 v[36:37], v[100:101], v[28:29], v[36:37]
	v_pk_fma_f32 v[38:39], v[102:103], v[30:31], v[38:39]
	v_add_f32_dpp v104, v104, v104 row_mirror row_mask:0xf bank_mask:0xf bound_ctrl:1
	v_pk_fma_f32 v[100:101], v[32:33], v[104:105], v[36:37] op_sel_hi:[1,0,1] neg_lo:[0,1,0] neg_hi:[0,1,0]
	v_pk_fma_f32 v[102:103], v[34:35], v[104:105], v[38:39] op_sel_hi:[1,0,1] neg_lo:[0,1,0] neg_hi:[0,1,0]
	v_pk_mul_f32 v[106:107], v[100:101], v[84:85]
	ds_read_b128 v[10:13], v98 offset:12800
	v_pk_fma_f32 v[106:107], v[102:103], v[86:87], v[106:107]
	s_waitcnt lgkmcnt(2)
	v_pk_mul_f32 v[104:105], v[100:101], v[2:3]
	v_add_f32_e32 v106, v106, v107
	ds_read_b128 v[18:21], v98 offset:13312
	v_pk_fma_f32 v[104:105], v[102:103], v[4:5], v[104:105]
	v_add_f32_dpp v106, v106, v106 quad_perm:[1,0,3,2] row_mask:0xf bank_mask:0xf bound_ctrl:1
	v_add_f32_e32 v104, v104, v105
	s_nop 0
	v_add_f32_dpp v106, v106, v106 quad_perm:[2,3,0,1] row_mask:0xf bank_mask:0xf bound_ctrl:1
	ds_write_b32 v97, v106 offset:1792
	ds_read_b32 v40, v99 offset:15104
	ds_read_b128 v[36:39], v98 offset:14592
	v_add_f32_dpp v104, v104, v104 quad_perm:[1,0,3,2] row_mask:0xf bank_mask:0xf bound_ctrl:1
	ds_read_b128 v[24:27], v98 offset:13824
	ds_read_b128 v[28:31], v98 offset:14080
	v_add_f32_dpp v104, v104, v104 quad_perm:[2,3,0,1] row_mask:0xf bank_mask:0xf bound_ctrl:1
	v_pk_mul_f32 v[14:15], v[14:15], v[22:23] op_sel_hi:[1,0]
	v_pk_mul_f32 v[16:17], v[16:17], v[22:23] op_sel_hi:[1,0]
	v_add_f32_dpp v104, v104, v104 row_half_mirror row_mask:0xf bank_mask:0xf bound_ctrl:1
	s_waitcnt lgkmcnt(5)
	v_pk_fma_f32 v[14:15], v[100:101], v[6:7], v[14:15]
	v_pk_fma_f32 v[16:17], v[102:103], v[8:9], v[16:17]
	v_add_f32_dpp v104, v104, v104 row_mirror row_mask:0xf bank_mask:0xf bound_ctrl:1
	v_pk_fma_f32 v[100:101], v[10:11], v[104:105], v[14:15] op_sel_hi:[1,0,1] neg_lo:[0,1,0] neg_hi:[0,1,0]
	v_pk_fma_f32 v[102:103], v[12:13], v[104:105], v[16:17] op_sel_hi:[1,0,1] neg_lo:[0,1,0] neg_hi:[0,1,0]
	v_pk_mul_f32 v[106:107], v[100:101], v[18:19]
	ds_read_b128 v[32:35], v98 offset:14336
	v_pk_fma_f32 v[106:107], v[102:103], v[20:21], v[106:107]
	s_waitcnt lgkmcnt(2)
	v_pk_mul_f32 v[104:105], v[100:101], v[24:25]
	v_add_f32_e32 v106, v106, v107
	ds_read_b128 v[84:87], v98 offset:14848
	v_pk_fma_f32 v[104:105], v[102:103], v[26:27], v[104:105]
	v_add_f32_dpp v106, v106, v106 quad_perm:[1,0,3,2] row_mask:0xf bank_mask:0xf bound_ctrl:1
	v_add_f32_e32 v104, v104, v105
	s_nop 0
	v_add_f32_dpp v106, v106, v106 quad_perm:[2,3,0,1] row_mask:0xf bank_mask:0xf bound_ctrl:1
	ds_write_b32 v97, v106 offset:2048
	ds_read_b32 v22, v99 offset:16640
	ds_read_b128 v[14:17], v98 offset:16128
	v_add_f32_dpp v104, v104, v104 quad_perm:[1,0,3,2] row_mask:0xf bank_mask:0xf bound_ctrl:1
	ds_read_b128 v[2:5], v98 offset:15360
	ds_read_b128 v[6:9], v98 offset:15616
	v_add_f32_dpp v104, v104, v104 quad_perm:[2,3,0,1] row_mask:0xf bank_mask:0xf bound_ctrl:1
	v_pk_mul_f32 v[36:37], v[36:37], v[40:41] op_sel_hi:[1,0]
	v_pk_mul_f32 v[38:39], v[38:39], v[40:41] op_sel_hi:[1,0]
	v_add_f32_dpp v104, v104, v104 row_half_mirror row_mask:0xf bank_mask:0xf bound_ctrl:1
	s_waitcnt lgkmcnt(5)
	v_pk_fma_f32 v[36:37], v[100:101], v[28:29], v[36:37]
	v_pk_fma_f32 v[38:39], v[102:103], v[30:31], v[38:39]
	v_add_f32_dpp v104, v104, v104 row_mirror row_mask:0xf bank_mask:0xf bound_ctrl:1
	v_pk_fma_f32 v[100:101], v[32:33], v[104:105], v[36:37] op_sel_hi:[1,0,1] neg_lo:[0,1,0] neg_hi:[0,1,0]
	v_pk_fma_f32 v[102:103], v[34:35], v[104:105], v[38:39] op_sel_hi:[1,0,1] neg_lo:[0,1,0] neg_hi:[0,1,0]
	v_pk_mul_f32 v[106:107], v[100:101], v[84:85]
	ds_read_b128 v[10:13], v98 offset:15872
	v_pk_fma_f32 v[106:107], v[102:103], v[86:87], v[106:107]
	s_waitcnt lgkmcnt(2)
	v_pk_mul_f32 v[104:105], v[100:101], v[2:3]
	v_add_f32_e32 v106, v106, v107
	ds_read_b128 v[18:21], v98 offset:16384
	v_pk_fma_f32 v[104:105], v[102:103], v[4:5], v[104:105]
	v_add_f32_dpp v106, v106, v106 quad_perm:[1,0,3,2] row_mask:0xf bank_mask:0xf bound_ctrl:1
	v_add_f32_e32 v104, v104, v105
	s_nop 0
	v_add_f32_dpp v106, v106, v106 quad_perm:[2,3,0,1] row_mask:0xf bank_mask:0xf bound_ctrl:1
	ds_write_b32 v97, v106 offset:2304
	ds_read_b32 v40, v99 offset:18176
	ds_read_b128 v[36:39], v98 offset:17664
	v_add_f32_dpp v104, v104, v104 quad_perm:[1,0,3,2] row_mask:0xf bank_mask:0xf bound_ctrl:1
	ds_read_b128 v[24:27], v98 offset:16896
	ds_read_b128 v[28:31], v98 offset:17152
	v_add_f32_dpp v104, v104, v104 quad_perm:[2,3,0,1] row_mask:0xf bank_mask:0xf bound_ctrl:1
	v_pk_mul_f32 v[14:15], v[14:15], v[22:23] op_sel_hi:[1,0]
	v_pk_mul_f32 v[16:17], v[16:17], v[22:23] op_sel_hi:[1,0]
	v_add_f32_dpp v104, v104, v104 row_half_mirror row_mask:0xf bank_mask:0xf bound_ctrl:1
	s_waitcnt lgkmcnt(5)
; DEVI void rwkv_scan_item(const Params& p, const int item, char* smem) {
;     ...
;   for (int c = 0; c < NC; ++c) {
;     if (wid >= 4) {
;       if (c + 1 < NC) load_chunk(c + 1, (c + 1) & 1);
;       if (c >= 1) store_y(c - 1);
;     } else {
;       const float* sb = buf + (c & 1) * 12288 + kp * 4;
;       float* yb = ybuf + (c & 1) * 2048 + row16 * 4 + (kp >> 2);
;       const int vofs = 320 + rq * 16 + row16 - kp * 4;
;       f32x4 kkA, wA, kaA, kA, rA, kkB, wB, kaB, kB, rB; float vA, vB;
;       RW_LD(0, A)
; #pragma unroll 2
;       for (int s = 0; s < 32; s += 2) {
;         RW_LD(s + 1, B)
;         __builtin_amdgcn_sched_barrier(0);
;         RW_STEP(s, A)
;         __builtin_amdgcn_sched_barrier(0);
;         if (s + 2 < 32) RW_LD(s + 2, A)
;         __builtin_amdgcn_sched_barrier(0);
;         RW_STEP(s + 1, B)
;         __builtin_amdgcn_sched_barrier(0);
;       }
	v_pk_fma_f32 v[14:15], v[100:101], v[6:7], v[14:15]
	v_pk_fma_f32 v[16:17], v[102:103], v[8:9], v[16:17]
	v_add_f32_dpp v104, v104, v104 row_mirror row_mask:0xf bank_mask:0xf bound_ctrl:1
	v_pk_fma_f32 v[100:101], v[10:11], v[104:105], v[14:15] op_sel_hi:[1,0,1] neg_lo:[0,1,0] neg_hi:[0,1,0]
	v_pk_fma_f32 v[102:103], v[12:13], v[104:105], v[16:17] op_sel_hi:[1,0,1] neg_lo:[0,1,0] neg_hi:[0,1,0]
	v_pk_mul_f32 v[106:107], v[100:101], v[18:19]
	ds_read_b128 v[32:35], v98 offset:17408
	v_pk_fma_f32 v[106:107], v[102:103], v[20:21], v[106:107]
	s_waitcnt lgkmcnt(2)
	v_pk_mul_f32 v[104:105], v[100:101], v[24:25]
	v_add_f32_e32 v106, v106, v107
	ds_read_b128 v[84:87], v98 offset:17920
	v_pk_fma_f32 v[104:105], v[102:103], v[26:27], v[104:105]
	v_add_f32_dpp v106, v106, v106 quad_perm:[1,0,3,2] row_mask:0xf bank_mask:0xf bound_ctrl:1
	v_add_f32_e32 v104, v104, v105
	s_nop 0
	v_add_f32_dpp v106, v106, v106 quad_perm:[2,3,0,1] row_mask:0xf bank_mask:0xf bound_ctrl:1
	ds_write_b32 v97, v106 offset:2560
	ds_read_b32 v22, v99 offset:19712
	ds_read_b128 v[14:17], v98 offset:19200
	v_add_f32_dpp v104, v104, v104 quad_perm:[1,0,3,2] row_mask:0xf bank_mask:0xf bound_ctrl:1
	ds_read_b128 v[2:5], v98 offset:18432
	ds_read_b128 v[6:9], v98 offset:18688
	v_add_f32_dpp v104, v104, v104 quad_perm:[2,3,0,1] row_mask:0xf bank_mask:0xf bound_ctrl:1
	v_pk_mul_f32 v[36:37], v[36:37], v[40:41] op_sel_hi:[1,0]
	v_pk_mul_f32 v[38:39], v[38:39], v[40:41] op_sel_hi:[1,0]
	v_add_f32_dpp v104, v104, v104 row_half_mirror row_mask:0xf bank_mask:0xf bound_ctrl:1
	s_waitcnt lgkmcnt(5)
	v_pk_fma_f32 v[36:37], v[100:101], v[28:29], v[36:37]
	v_pk_fma_f32 v[38:39], v[102:103], v[30:31], v[38:39]
	v_add_f32_dpp v104, v104, v104 row_mirror row_mask:0xf bank_mask:0xf bound_ctrl:1
	v_pk_fma_f32 v[100:101], v[32:33], v[104:105], v[36:37] op_sel_hi:[1,0,1] neg_lo:[0,1,0] neg_hi:[0,1,0]
	v_pk_fma_f32 v[102:103], v[34:35], v[104:105], v[38:39] op_sel_hi:[1,0,1] neg_lo:[0,1,0] neg_hi:[0,1,0]
	v_pk_mul_f32 v[106:107], v[100:101], v[84:85]
	ds_read_b128 v[10:13], v98 offset:18944
	v_pk_fma_f32 v[106:107], v[102:103], v[86:87], v[106:107]
	s_waitcnt lgkmcnt(2)
	v_pk_mul_f32 v[104:105], v[100:101], v[2:3]
	v_add_f32_e32 v106, v106, v107
	ds_read_b128 v[18:21], v98 offset:19456
	v_pk_fma_f32 v[104:105], v[102:103], v[4:5], v[104:105]
	v_add_f32_dpp v106, v106, v106 quad_perm:[1,0,3,2] row_mask:0xf bank_mask:0xf bound_ctrl:1
	v_add_f32_e32 v104, v104, v105
	s_nop 0
	v_add_f32_dpp v106, v106, v106 quad_perm:[2,3,0,1] row_mask:0xf bank_mask:0xf bound_ctrl:1
	ds_write_b32 v97, v106 offset:2816
	ds_read_b32 v40, v99 offset:21248
	ds_read_b128 v[36:39], v98 offset:20736
	v_add_f32_dpp v104, v104, v104 quad_perm:[1,0,3,2] row_mask:0xf bank_mask:0xf bound_ctrl:1
	ds_read_b128 v[24:27], v98 offset:19968
	ds_read_b128 v[28:31], v98 offset:20224
	v_add_f32_dpp v104, v104, v104 quad_perm:[2,3,0,1] row_mask:0xf bank_mask:0xf bound_ctrl:1
	v_pk_mul_f32 v[14:15], v[14:15], v[22:23] op_sel_hi:[1,0]
	v_pk_mul_f32 v[16:17], v[16:17], v[22:23] op_sel_hi:[1,0]
	v_add_f32_dpp v104, v104, v104 row_half_mirror row_mask:0xf bank_mask:0xf bound_ctrl:1
	s_waitcnt lgkmcnt(5)
	v_pk_fma_f32 v[14:15], v[100:101], v[6:7], v[14:15]
	v_pk_fma_f32 v[16:17], v[102:103], v[8:9], v[16:17]
	v_add_f32_dpp v104, v104, v104 row_mirror row_mask:0xf bank_mask:0xf bound_ctrl:1
	v_pk_fma_f32 v[100:101], v[10:11], v[104:105], v[14:15] op_sel_hi:[1,0,1] neg_lo:[0,1,0] neg_hi:[0,1,0]
	v_pk_fma_f32 v[102:103], v[12:13], v[104:105], v[16:17] op_sel_hi:[1,0,1] neg_lo:[0,1,0] neg_hi:[0,1,0]
	v_pk_mul_f32 v[106:107], v[100:101], v[18:19]
	ds_read_b128 v[32:35], v98 offset:20480
	v_pk_fma_f32 v[106:107], v[102:103], v[20:21], v[106:107]
	s_waitcnt lgkmcnt(2)
	v_pk_mul_f32 v[104:105], v[100:101], v[24:25]
	v_add_f32_e32 v106, v106, v107
	ds_read_b128 v[84:87], v98 offset:20992
	v_pk_fma_f32 v[104:105], v[102:103], v[26:27], v[104:105]
	v_add_f32_dpp v106, v106, v106 quad_perm:[1,0,3,2] row_mask:0xf bank_mask:0xf bound_ctrl:1
	v_add_f32_e32 v104, v104, v105
	s_nop 0
	v_add_f32_dpp v106, v106, v106 quad_perm:[2,3,0,1] row_mask:0xf bank_mask:0xf bound_ctrl:1
	ds_write_b32 v97, v106 offset:3072
	ds_read_b32 v22, v99 offset:22784
	ds_read_b128 v[14:17], v98 offset:22272
	v_add_f32_dpp v104, v104, v104 quad_perm:[1,0,3,2] row_mask:0xf bank_mask:0xf bound_ctrl:1
	ds_read_b128 v[2:5], v98 offset:21504
	ds_read_b128 v[6:9], v98 offset:21760
	v_add_f32_dpp v104, v104, v104 quad_perm:[2,3,0,1] row_mask:0xf bank_mask:0xf bound_ctrl:1
	v_pk_mul_f32 v[36:37], v[36:37], v[40:41] op_sel_hi:[1,0]
	v_pk_mul_f32 v[38:39], v[38:39], v[40:41] op_sel_hi:[1,0]
	v_add_f32_dpp v104, v104, v104 row_half_mirror row_mask:0xf bank_mask:0xf bound_ctrl:1
	s_waitcnt lgkmcnt(5)
	v_pk_fma_f32 v[36:37], v[100:101], v[28:29], v[36:37]
	v_pk_fma_f32 v[38:39], v[102:103], v[30:31], v[38:39]
	v_add_f32_dpp v104, v104, v104 row_mirror row_mask:0xf bank_mask:0xf bound_ctrl:1
	v_pk_fma_f32 v[100:101], v[32:33], v[104:105], v[36:37] op_sel_hi:[1,0,1] neg_lo:[0,1,0] neg_hi:[0,1,0]
	v_pk_fma_f32 v[102:103], v[34:35], v[104:105], v[38:39] op_sel_hi:[1,0,1] neg_lo:[0,1,0] neg_hi:[0,1,0]
	v_pk_mul_f32 v[106:107], v[100:101], v[84:85]
	ds_read_b128 v[10:13], v98 offset:22016
	v_pk_fma_f32 v[106:107], v[102:103], v[86:87], v[106:107]
	s_waitcnt lgkmcnt(2)
; DEVI void rwkv_scan_item(const Params& p, const int item, char* smem) {
;     ...
;   for (int c = 0; c < NC; ++c) {
;     if (wid >= 4) {
;       if (c + 1 < NC) load_chunk(c + 1, (c + 1) & 1);
;       if (c >= 1) store_y(c - 1);
;     } else {
;       const float* sb = buf + (c & 1) * 12288 + kp * 4;
;       float* yb = ybuf + (c & 1) * 2048 + row16 * 4 + (kp >> 2);
;       const int vofs = 320 + rq * 16 + row16 - kp * 4;
;       f32x4 kkA, wA, kaA, kA, rA, kkB, wB, kaB, kB, rB; float vA, vB;
;       RW_LD(0, A)
; #pragma unroll 2
;       for (int s = 0; s < 32; s += 2) {
;         RW_LD(s + 1, B)
;         __builtin_amdgcn_sched_barrier(0);
;         RW_STEP(s, A)
;         __builtin_amdgcn_sched_barrier(0);
;         if (s + 2 < 32) RW_LD(s + 2, A)
;         __builtin_amdgcn_sched_barrier(0);
;         RW_STEP(s + 1, B)
;         __builtin_amdgcn_sched_barrier(0);
;       }
	v_pk_mul_f32 v[104:105], v[100:101], v[2:3]
	v_add_f32_e32 v106, v106, v107
	ds_read_b128 v[18:21], v98 offset:22528
	v_pk_fma_f32 v[104:105], v[102:103], v[4:5], v[104:105]
	v_add_f32_dpp v106, v106, v106 quad_perm:[1,0,3,2] row_mask:0xf bank_mask:0xf bound_ctrl:1
	v_add_f32_e32 v104, v104, v105
	s_nop 0
	v_add_f32_dpp v106, v106, v106 quad_perm:[2,3,0,1] row_mask:0xf bank_mask:0xf bound_ctrl:1
	ds_write_b32 v97, v106 offset:3328
	ds_read_b32 v40, v99 offset:24320
	ds_read_b128 v[36:39], v98 offset:23808
	v_add_f32_dpp v104, v104, v104 quad_perm:[1,0,3,2] row_mask:0xf bank_mask:0xf bound_ctrl:1
	ds_read_b128 v[24:27], v98 offset:23040
	ds_read_b128 v[28:31], v98 offset:23296
	v_add_f32_dpp v104, v104, v104 quad_perm:[2,3,0,1] row_mask:0xf bank_mask:0xf bound_ctrl:1
	v_pk_mul_f32 v[14:15], v[14:15], v[22:23] op_sel_hi:[1,0]
	v_pk_mul_f32 v[16:17], v[16:17], v[22:23] op_sel_hi:[1,0]
	v_add_f32_dpp v104, v104, v104 row_half_mirror row_mask:0xf bank_mask:0xf bound_ctrl:1
	s_waitcnt lgkmcnt(5)
	v_pk_fma_f32 v[14:15], v[100:101], v[6:7], v[14:15]
	v_pk_fma_f32 v[16:17], v[102:103], v[8:9], v[16:17]
	v_add_f32_dpp v104, v104, v104 row_mirror row_mask:0xf bank_mask:0xf bound_ctrl:1
	v_pk_fma_f32 v[100:101], v[10:11], v[104:105], v[14:15] op_sel_hi:[1,0,1] neg_lo:[0,1,0] neg_hi:[0,1,0]
	v_pk_fma_f32 v[102:103], v[12:13], v[104:105], v[16:17] op_sel_hi:[1,0,1] neg_lo:[0,1,0] neg_hi:[0,1,0]
	v_pk_mul_f32 v[106:107], v[100:101], v[18:19]
	ds_read_b128 v[32:35], v98 offset:23552
	v_pk_fma_f32 v[106:107], v[102:103], v[20:21], v[106:107]
	s_waitcnt lgkmcnt(2)
	v_pk_mul_f32 v[104:105], v[100:101], v[24:25]
	v_add_f32_e32 v106, v106, v107
	ds_read_b128 v[84:87], v98 offset:24064
	v_pk_fma_f32 v[104:105], v[102:103], v[26:27], v[104:105]
	v_add_f32_dpp v106, v106, v106 quad_perm:[1,0,3,2] row_mask:0xf bank_mask:0xf bound_ctrl:1
	v_add_f32_e32 v104, v104, v105
	s_nop 0
	v_add_f32_dpp v106, v106, v106 quad_perm:[2,3,0,1] row_mask:0xf bank_mask:0xf bound_ctrl:1
	ds_write_b32 v97, v106 offset:3584
	ds_read_b32 v22, v99 offset:25856
	ds_read_b128 v[14:17], v98 offset:25344
	v_add_f32_dpp v104, v104, v104 quad_perm:[1,0,3,2] row_mask:0xf bank_mask:0xf bound_ctrl:1
	ds_read_b128 v[2:5], v98 offset:24576
	ds_read_b128 v[6:9], v98 offset:24832
	v_add_f32_dpp v104, v104, v104 quad_perm:[2,3,0,1] row_mask:0xf bank_mask:0xf bound_ctrl:1
	v_pk_mul_f32 v[36:37], v[36:37], v[40:41] op_sel_hi:[1,0]
	v_pk_mul_f32 v[38:39], v[38:39], v[40:41] op_sel_hi:[1,0]
	v_add_f32_dpp v104, v104, v104 row_half_mirror row_mask:0xf bank_mask:0xf bound_ctrl:1
	s_waitcnt lgkmcnt(5)
	v_pk_fma_f32 v[36:37], v[100:101], v[28:29], v[36:37]
	v_pk_fma_f32 v[38:39], v[102:103], v[30:31], v[38:39]
	v_add_f32_dpp v104, v104, v104 row_mirror row_mask:0xf bank_mask:0xf bound_ctrl:1
	v_pk_fma_f32 v[100:101], v[32:33], v[104:105], v[36:37] op_sel_hi:[1,0,1] neg_lo:[0,1,0] neg_hi:[0,1,0]
	v_pk_fma_f32 v[102:103], v[34:35], v[104:105], v[38:39] op_sel_hi:[1,0,1] neg_lo:[0,1,0] neg_hi:[0,1,0]
	v_pk_mul_f32 v[106:107], v[100:101], v[84:85]
	ds_read_b128 v[10:13], v98 offset:25088
	v_pk_fma_f32 v[106:107], v[102:103], v[86:87], v[106:107]
	s_waitcnt lgkmcnt(2)
	v_pk_mul_f32 v[104:105], v[100:101], v[2:3]
	v_add_f32_e32 v106, v106, v107
	ds_read_b128 v[18:21], v98 offset:25600
	v_pk_fma_f32 v[104:105], v[102:103], v[4:5], v[104:105]
	v_add_f32_dpp v106, v106, v106 quad_perm:[1,0,3,2] row_mask:0xf bank_mask:0xf bound_ctrl:1
	v_add_f32_e32 v104, v104, v105
	s_nop 0
	v_add_f32_dpp v106, v106, v106 quad_perm:[2,3,0,1] row_mask:0xf bank_mask:0xf bound_ctrl:1
	ds_write_b32 v97, v106 offset:3840
	ds_read_b32 v40, v99 offset:27392
	ds_read_b128 v[36:39], v98 offset:26880
	v_add_f32_dpp v104, v104, v104 quad_perm:[1,0,3,2] row_mask:0xf bank_mask:0xf bound_ctrl:1
	ds_read_b128 v[24:27], v98 offset:26112
	ds_read_b128 v[28:31], v98 offset:26368
	v_add_f32_dpp v104, v104, v104 quad_perm:[2,3,0,1] row_mask:0xf bank_mask:0xf bound_ctrl:1
	v_pk_mul_f32 v[14:15], v[14:15], v[22:23] op_sel_hi:[1,0]
	v_pk_mul_f32 v[16:17], v[16:17], v[22:23] op_sel_hi:[1,0]
	v_add_f32_dpp v104, v104, v104 row_half_mirror row_mask:0xf bank_mask:0xf bound_ctrl:1
	s_waitcnt lgkmcnt(5)
	v_pk_fma_f32 v[14:15], v[100:101], v[6:7], v[14:15]
	v_pk_fma_f32 v[16:17], v[102:103], v[8:9], v[16:17]
	v_add_f32_dpp v104, v104, v104 row_mirror row_mask:0xf bank_mask:0xf bound_ctrl:1
	v_pk_fma_f32 v[100:101], v[10:11], v[104:105], v[14:15] op_sel_hi:[1,0,1] neg_lo:[0,1,0] neg_hi:[0,1,0]
	v_pk_fma_f32 v[102:103], v[12:13], v[104:105], v[16:17] op_sel_hi:[1,0,1] neg_lo:[0,1,0] neg_hi:[0,1,0]
	v_pk_mul_f32 v[106:107], v[100:101], v[18:19]
	ds_read_b128 v[32:35], v98 offset:26624
	v_pk_fma_f32 v[106:107], v[102:103], v[20:21], v[106:107]
	s_waitcnt lgkmcnt(2)
	v_pk_mul_f32 v[104:105], v[100:101], v[24:25]
	v_add_f32_e32 v106, v106, v107
	ds_read_b128 v[84:87], v98 offset:27136
	v_pk_fma_f32 v[104:105], v[102:103], v[26:27], v[104:105]
	v_add_f32_dpp v106, v106, v106 quad_perm:[1,0,3,2] row_mask:0xf bank_mask:0xf bound_ctrl:1
	v_add_f32_e32 v104, v104, v105
	s_nop 0
	v_add_f32_dpp v106, v106, v106 quad_perm:[2,3,0,1] row_mask:0xf bank_mask:0xf bound_ctrl:1
	ds_write_b32 v97, v106 offset:4096
	ds_read_b32 v22, v99 offset:28928
	ds_read_b128 v[14:17], v98 offset:28416
	v_add_f32_dpp v104, v104, v104 quad_perm:[1,0,3,2] row_mask:0xf bank_mask:0xf bound_ctrl:1
	ds_read_b128 v[2:5], v98 offset:27648
	ds_read_b128 v[6:9], v98 offset:27904
	v_add_f32_dpp v104, v104, v104 quad_perm:[2,3,0,1] row_mask:0xf bank_mask:0xf bound_ctrl:1
	v_pk_mul_f32 v[36:37], v[36:37], v[40:41] op_sel_hi:[1,0]
	v_pk_mul_f32 v[38:39], v[38:39], v[40:41] op_sel_hi:[1,0]
	v_add_f32_dpp v104, v104, v104 row_half_mirror row_mask:0xf bank_mask:0xf bound_ctrl:1
	s_waitcnt lgkmcnt(5)
; DEVI void rwkv_scan_item(const Params& p, const int item, char* smem) {
;     ...
;   for (int c = 0; c < NC; ++c) {
;     if (wid >= 4) {
;       if (c + 1 < NC) load_chunk(c + 1, (c + 1) & 1);
;       if (c >= 1) store_y(c - 1);
;     } else {
;       const float* sb = buf + (c & 1) * 12288 + kp * 4;
;       float* yb = ybuf + (c & 1) * 2048 + row16 * 4 + (kp >> 2);
;       const int vofs = 320 + rq * 16 + row16 - kp * 4;
;       f32x4 kkA, wA, kaA, kA, rA, kkB, wB, kaB, kB, rB; float vA, vB;
;       RW_LD(0, A)
; #pragma unroll 2
;       for (int s = 0; s < 32; s += 2) {
;         RW_LD(s + 1, B)
;         __builtin_amdgcn_sched_barrier(0);
;         RW_STEP(s, A)
;         __builtin_amdgcn_sched_barrier(0);
;         if (s + 2 < 32) RW_LD(s + 2, A)
;         __builtin_amdgcn_sched_barrier(0);
;         RW_STEP(s + 1, B)
;         __builtin_amdgcn_sched_barrier(0);
;       }
	v_pk_fma_f32 v[36:37], v[100:101], v[28:29], v[36:37]
	v_pk_fma_f32 v[38:39], v[102:103], v[30:31], v[38:39]
	v_add_f32_dpp v104, v104, v104 row_mirror row_mask:0xf bank_mask:0xf bound_ctrl:1
	v_pk_fma_f32 v[100:101], v[32:33], v[104:105], v[36:37] op_sel_hi:[1,0,1] neg_lo:[0,1,0] neg_hi:[0,1,0]
	v_pk_fma_f32 v[102:103], v[34:35], v[104:105], v[38:39] op_sel_hi:[1,0,1] neg_lo:[0,1,0] neg_hi:[0,1,0]
	v_pk_mul_f32 v[106:107], v[100:101], v[84:85]
	ds_read_b128 v[10:13], v98 offset:28160
	v_pk_fma_f32 v[106:107], v[102:103], v[86:87], v[106:107]
	s_waitcnt lgkmcnt(2)
	v_pk_mul_f32 v[104:105], v[100:101], v[2:3]
	v_add_f32_e32 v106, v106, v107
	ds_read_b128 v[18:21], v98 offset:28672
	v_pk_fma_f32 v[104:105], v[102:103], v[4:5], v[104:105]
	v_add_f32_dpp v106, v106, v106 quad_perm:[1,0,3,2] row_mask:0xf bank_mask:0xf bound_ctrl:1
	v_add_f32_e32 v104, v104, v105
	s_nop 0
	v_add_f32_dpp v106, v106, v106 quad_perm:[2,3,0,1] row_mask:0xf bank_mask:0xf bound_ctrl:1
	ds_write_b32 v97, v106 offset:4352
	ds_read_b32 v40, v99 offset:30464
	ds_read_b128 v[36:39], v98 offset:29952
	v_add_f32_dpp v104, v104, v104 quad_perm:[1,0,3,2] row_mask:0xf bank_mask:0xf bound_ctrl:1
	ds_read_b128 v[24:27], v98 offset:29184
	ds_read_b128 v[28:31], v98 offset:29440
	v_add_f32_dpp v104, v104, v104 quad_perm:[2,3,0,1] row_mask:0xf bank_mask:0xf bound_ctrl:1
	v_pk_mul_f32 v[14:15], v[14:15], v[22:23] op_sel_hi:[1,0]
	v_pk_mul_f32 v[16:17], v[16:17], v[22:23] op_sel_hi:[1,0]
	v_add_f32_dpp v104, v104, v104 row_half_mirror row_mask:0xf bank_mask:0xf bound_ctrl:1
	s_waitcnt lgkmcnt(5)
	v_pk_fma_f32 v[14:15], v[100:101], v[6:7], v[14:15]
	v_pk_fma_f32 v[16:17], v[102:103], v[8:9], v[16:17]
	v_add_f32_dpp v104, v104, v104 row_mirror row_mask:0xf bank_mask:0xf bound_ctrl:1
	v_pk_fma_f32 v[100:101], v[10:11], v[104:105], v[14:15] op_sel_hi:[1,0,1] neg_lo:[0,1,0] neg_hi:[0,1,0]
	v_pk_fma_f32 v[102:103], v[12:13], v[104:105], v[16:17] op_sel_hi:[1,0,1] neg_lo:[0,1,0] neg_hi:[0,1,0]
	v_pk_mul_f32 v[106:107], v[100:101], v[18:19]
	ds_read_b128 v[32:35], v98 offset:29696
	v_pk_fma_f32 v[106:107], v[102:103], v[20:21], v[106:107]
	s_waitcnt lgkmcnt(2)
	v_pk_mul_f32 v[104:105], v[100:101], v[24:25]
	v_add_f32_e32 v106, v106, v107
	ds_read_b128 v[84:87], v98 offset:30208
	v_pk_fma_f32 v[104:105], v[102:103], v[26:27], v[104:105]
	v_add_f32_dpp v106, v106, v106 quad_perm:[1,0,3,2] row_mask:0xf bank_mask:0xf bound_ctrl:1
	v_add_f32_e32 v104, v104, v105
	s_nop 0
	v_add_f32_dpp v106, v106, v106 quad_perm:[2,3,0,1] row_mask:0xf bank_mask:0xf bound_ctrl:1
	ds_write_b32 v97, v106 offset:4608
	ds_read_b32 v22, v99 offset:32000
	ds_read_b128 v[14:17], v98 offset:31488
	v_add_f32_dpp v104, v104, v104 quad_perm:[1,0,3,2] row_mask:0xf bank_mask:0xf bound_ctrl:1
	ds_read_b128 v[2:5], v98 offset:30720
	ds_read_b128 v[6:9], v98 offset:30976
	v_add_f32_dpp v104, v104, v104 quad_perm:[2,3,0,1] row_mask:0xf bank_mask:0xf bound_ctrl:1
	v_pk_mul_f32 v[36:37], v[36:37], v[40:41] op_sel_hi:[1,0]
	v_pk_mul_f32 v[38:39], v[38:39], v[40:41] op_sel_hi:[1,0]
	v_add_f32_dpp v104, v104, v104 row_half_mirror row_mask:0xf bank_mask:0xf bound_ctrl:1
	s_waitcnt lgkmcnt(5)
	v_pk_fma_f32 v[36:37], v[100:101], v[28:29], v[36:37]
	v_pk_fma_f32 v[38:39], v[102:103], v[30:31], v[38:39]
	v_add_f32_dpp v104, v104, v104 row_mirror row_mask:0xf bank_mask:0xf bound_ctrl:1
	v_pk_fma_f32 v[100:101], v[32:33], v[104:105], v[36:37] op_sel_hi:[1,0,1] neg_lo:[0,1,0] neg_hi:[0,1,0]
	v_pk_fma_f32 v[102:103], v[34:35], v[104:105], v[38:39] op_sel_hi:[1,0,1] neg_lo:[0,1,0] neg_hi:[0,1,0]
	v_pk_mul_f32 v[106:107], v[100:101], v[84:85]
	ds_read_b128 v[10:13], v98 offset:31232
	v_pk_fma_f32 v[106:107], v[102:103], v[86:87], v[106:107]
	s_waitcnt lgkmcnt(2)
	v_pk_mul_f32 v[104:105], v[100:101], v[2:3]
	v_add_f32_e32 v106, v106, v107
	ds_read_b128 v[18:21], v98 offset:31744
	v_pk_fma_f32 v[104:105], v[102:103], v[4:5], v[104:105]
	v_add_f32_dpp v106, v106, v106 quad_perm:[1,0,3,2] row_mask:0xf bank_mask:0xf bound_ctrl:1
	v_add_f32_e32 v104, v104, v105
	s_nop 0
	v_add_f32_dpp v106, v106, v106 quad_perm:[2,3,0,1] row_mask:0xf bank_mask:0xf bound_ctrl:1
	ds_write_b32 v97, v106 offset:4864
	ds_read_b32 v40, v99 offset:33536
	ds_read_b128 v[36:39], v98 offset:33024
	v_add_f32_dpp v104, v104, v104 quad_perm:[1,0,3,2] row_mask:0xf bank_mask:0xf bound_ctrl:1
	ds_read_b128 v[24:27], v98 offset:32256
	ds_read_b128 v[28:31], v98 offset:32512
	v_add_f32_dpp v104, v104, v104 quad_perm:[2,3,0,1] row_mask:0xf bank_mask:0xf bound_ctrl:1
	v_pk_mul_f32 v[14:15], v[14:15], v[22:23] op_sel_hi:[1,0]
	v_pk_mul_f32 v[16:17], v[16:17], v[22:23] op_sel_hi:[1,0]
	v_add_f32_dpp v104, v104, v104 row_half_mirror row_mask:0xf bank_mask:0xf bound_ctrl:1
	s_waitcnt lgkmcnt(5)
	v_pk_fma_f32 v[14:15], v[100:101], v[6:7], v[14:15]
	v_pk_fma_f32 v[16:17], v[102:103], v[8:9], v[16:17]
	v_add_f32_dpp v104, v104, v104 row_mirror row_mask:0xf bank_mask:0xf bound_ctrl:1
	v_pk_fma_f32 v[100:101], v[10:11], v[104:105], v[14:15] op_sel_hi:[1,0,1] neg_lo:[0,1,0] neg_hi:[0,1,0]
	v_pk_fma_f32 v[102:103], v[12:13], v[104:105], v[16:17] op_sel_hi:[1,0,1] neg_lo:[0,1,0] neg_hi:[0,1,0]
	v_pk_mul_f32 v[106:107], v[100:101], v[18:19]
	ds_read_b128 v[32:35], v98 offset:32768
	v_pk_fma_f32 v[106:107], v[102:103], v[20:21], v[106:107]
	s_waitcnt lgkmcnt(2)
; DEVI void rwkv_scan_item(const Params& p, const int item, char* smem) {
;     ...
;   for (int c = 0; c < NC; ++c) {
;     if (wid >= 4) {
;       if (c + 1 < NC) load_chunk(c + 1, (c + 1) & 1);
;       if (c >= 1) store_y(c - 1);
;     } else {
;       const float* sb = buf + (c & 1) * 12288 + kp * 4;
;       float* yb = ybuf + (c & 1) * 2048 + row16 * 4 + (kp >> 2);
;       const int vofs = 320 + rq * 16 + row16 - kp * 4;
;       f32x4 kkA, wA, kaA, kA, rA, kkB, wB, kaB, kB, rB; float vA, vB;
;       RW_LD(0, A)
; #pragma unroll 2
;       for (int s = 0; s < 32; s += 2) {
;         RW_LD(s + 1, B)
;         __builtin_amdgcn_sched_barrier(0);
;         RW_STEP(s, A)
;         __builtin_amdgcn_sched_barrier(0);
;         if (s + 2 < 32) RW_LD(s + 2, A)
;         __builtin_amdgcn_sched_barrier(0);
;         RW_STEP(s + 1, B)
;         __builtin_amdgcn_sched_barrier(0);
;       }
	v_pk_mul_f32 v[104:105], v[100:101], v[24:25]
	v_add_f32_e32 v106, v106, v107
	ds_read_b128 v[84:87], v98 offset:33280
	v_pk_fma_f32 v[104:105], v[102:103], v[26:27], v[104:105]
	v_add_f32_dpp v106, v106, v106 quad_perm:[1,0,3,2] row_mask:0xf bank_mask:0xf bound_ctrl:1
	v_add_f32_e32 v104, v104, v105
	s_nop 0
	v_add_f32_dpp v106, v106, v106 quad_perm:[2,3,0,1] row_mask:0xf bank_mask:0xf bound_ctrl:1
	ds_write_b32 v97, v106 offset:5120
	ds_read_b32 v22, v99 offset:35072
	ds_read_b128 v[14:17], v98 offset:34560
	v_add_f32_dpp v104, v104, v104 quad_perm:[1,0,3,2] row_mask:0xf bank_mask:0xf bound_ctrl:1
	ds_read_b128 v[2:5], v98 offset:33792
	ds_read_b128 v[6:9], v98 offset:34048
	v_add_f32_dpp v104, v104, v104 quad_perm:[2,3,0,1] row_mask:0xf bank_mask:0xf bound_ctrl:1
	v_pk_mul_f32 v[36:37], v[36:37], v[40:41] op_sel_hi:[1,0]
	v_pk_mul_f32 v[38:39], v[38:39], v[40:41] op_sel_hi:[1,0]
	v_add_f32_dpp v104, v104, v104 row_half_mirror row_mask:0xf bank_mask:0xf bound_ctrl:1
	s_waitcnt lgkmcnt(5)
	v_pk_fma_f32 v[36:37], v[100:101], v[28:29], v[36:37]
	v_pk_fma_f32 v[38:39], v[102:103], v[30:31], v[38:39]
	v_add_f32_dpp v104, v104, v104 row_mirror row_mask:0xf bank_mask:0xf bound_ctrl:1
	v_pk_fma_f32 v[100:101], v[32:33], v[104:105], v[36:37] op_sel_hi:[1,0,1] neg_lo:[0,1,0] neg_hi:[0,1,0]
	v_pk_fma_f32 v[102:103], v[34:35], v[104:105], v[38:39] op_sel_hi:[1,0,1] neg_lo:[0,1,0] neg_hi:[0,1,0]
	v_pk_mul_f32 v[106:107], v[100:101], v[84:85]
	ds_read_b128 v[10:13], v98 offset:34304
	v_pk_fma_f32 v[106:107], v[102:103], v[86:87], v[106:107]
	s_waitcnt lgkmcnt(2)
	v_pk_mul_f32 v[104:105], v[100:101], v[2:3]
	v_add_f32_e32 v106, v106, v107
	ds_read_b128 v[18:21], v98 offset:34816
	v_pk_fma_f32 v[104:105], v[102:103], v[4:5], v[104:105]
	v_add_f32_dpp v106, v106, v106 quad_perm:[1,0,3,2] row_mask:0xf bank_mask:0xf bound_ctrl:1
	v_add_f32_e32 v104, v104, v105
	s_nop 0
	v_add_f32_dpp v106, v106, v106 quad_perm:[2,3,0,1] row_mask:0xf bank_mask:0xf bound_ctrl:1
	ds_write_b32 v97, v106 offset:5376
	ds_read_b32 v40, v99 offset:36608
	ds_read_b128 v[36:39], v98 offset:36096
	v_add_f32_dpp v104, v104, v104 quad_perm:[1,0,3,2] row_mask:0xf bank_mask:0xf bound_ctrl:1
	ds_read_b128 v[24:27], v98 offset:35328
	ds_read_b128 v[28:31], v98 offset:35584
	v_add_f32_dpp v104, v104, v104 quad_perm:[2,3,0,1] row_mask:0xf bank_mask:0xf bound_ctrl:1
	v_pk_mul_f32 v[14:15], v[14:15], v[22:23] op_sel_hi:[1,0]
	v_pk_mul_f32 v[16:17], v[16:17], v[22:23] op_sel_hi:[1,0]
	v_add_f32_dpp v104, v104, v104 row_half_mirror row_mask:0xf bank_mask:0xf bound_ctrl:1
	s_waitcnt lgkmcnt(5)
	v_pk_fma_f32 v[14:15], v[100:101], v[6:7], v[14:15]
	v_pk_fma_f32 v[16:17], v[102:103], v[8:9], v[16:17]
	v_add_f32_dpp v104, v104, v104 row_mirror row_mask:0xf bank_mask:0xf bound_ctrl:1
	v_pk_fma_f32 v[100:101], v[10:11], v[104:105], v[14:15] op_sel_hi:[1,0,1] neg_lo:[0,1,0] neg_hi:[0,1,0]
	v_pk_fma_f32 v[102:103], v[12:13], v[104:105], v[16:17] op_sel_hi:[1,0,1] neg_lo:[0,1,0] neg_hi:[0,1,0]
	v_pk_mul_f32 v[106:107], v[100:101], v[18:19]
	ds_read_b128 v[32:35], v98 offset:35840
	v_pk_fma_f32 v[106:107], v[102:103], v[20:21], v[106:107]
	s_waitcnt lgkmcnt(2)
	v_pk_mul_f32 v[104:105], v[100:101], v[24:25]
	v_add_f32_e32 v106, v106, v107
	ds_read_b128 v[84:87], v98 offset:36352
	v_pk_fma_f32 v[104:105], v[102:103], v[26:27], v[104:105]
	v_add_f32_dpp v106, v106, v106 quad_perm:[1,0,3,2] row_mask:0xf bank_mask:0xf bound_ctrl:1
	v_add_f32_e32 v104, v104, v105
	s_nop 0
	v_add_f32_dpp v106, v106, v106 quad_perm:[2,3,0,1] row_mask:0xf bank_mask:0xf bound_ctrl:1
	ds_write_b32 v97, v106 offset:5632
	ds_read_b32 v22, v99 offset:38144
	ds_read_b128 v[14:17], v98 offset:37632
	v_add_f32_dpp v104, v104, v104 quad_perm:[1,0,3,2] row_mask:0xf bank_mask:0xf bound_ctrl:1
	ds_read_b128 v[2:5], v98 offset:36864
	ds_read_b128 v[6:9], v98 offset:37120
	v_add_f32_dpp v104, v104, v104 quad_perm:[2,3,0,1] row_mask:0xf bank_mask:0xf bound_ctrl:1
	v_pk_mul_f32 v[36:37], v[36:37], v[40:41] op_sel_hi:[1,0]
	v_pk_mul_f32 v[38:39], v[38:39], v[40:41] op_sel_hi:[1,0]
	v_add_f32_dpp v104, v104, v104 row_half_mirror row_mask:0xf bank_mask:0xf bound_ctrl:1
	s_waitcnt lgkmcnt(5)
	v_pk_fma_f32 v[36:37], v[100:101], v[28:29], v[36:37]
	v_pk_fma_f32 v[38:39], v[102:103], v[30:31], v[38:39]
	v_add_f32_dpp v104, v104, v104 row_mirror row_mask:0xf bank_mask:0xf bound_ctrl:1
	v_pk_fma_f32 v[100:101], v[32:33], v[104:105], v[36:37] op_sel_hi:[1,0,1] neg_lo:[0,1,0] neg_hi:[0,1,0]
	v_pk_fma_f32 v[102:103], v[34:35], v[104:105], v[38:39] op_sel_hi:[1,0,1] neg_lo:[0,1,0] neg_hi:[0,1,0]
	v_pk_mul_f32 v[106:107], v[100:101], v[84:85]
	ds_read_b128 v[10:13], v98 offset:37376
	v_pk_fma_f32 v[106:107], v[102:103], v[86:87], v[106:107]
	s_waitcnt lgkmcnt(2)
	v_pk_mul_f32 v[104:105], v[100:101], v[2:3]
	v_add_f32_e32 v106, v106, v107
	ds_read_b128 v[18:21], v98 offset:37888
	v_pk_fma_f32 v[104:105], v[102:103], v[4:5], v[104:105]
	v_add_f32_dpp v106, v106, v106 quad_perm:[1,0,3,2] row_mask:0xf bank_mask:0xf bound_ctrl:1
	v_add_f32_e32 v104, v104, v105
	s_nop 0
	v_add_f32_dpp v106, v106, v106 quad_perm:[2,3,0,1] row_mask:0xf bank_mask:0xf bound_ctrl:1
	ds_write_b32 v97, v106 offset:5888
	ds_read_b32 v40, v99 offset:39680
	ds_read_b128 v[36:39], v98 offset:39168
	v_add_f32_dpp v104, v104, v104 quad_perm:[1,0,3,2] row_mask:0xf bank_mask:0xf bound_ctrl:1
	ds_read_b128 v[24:27], v98 offset:38400
	ds_read_b128 v[28:31], v98 offset:38656
	v_add_f32_dpp v104, v104, v104 quad_perm:[2,3,0,1] row_mask:0xf bank_mask:0xf bound_ctrl:1
	v_pk_mul_f32 v[14:15], v[14:15], v[22:23] op_sel_hi:[1,0]
	v_pk_mul_f32 v[16:17], v[16:17], v[22:23] op_sel_hi:[1,0]
	v_add_f32_dpp v104, v104, v104 row_half_mirror row_mask:0xf bank_mask:0xf bound_ctrl:1
	s_waitcnt lgkmcnt(5)
; DEVI void rwkv_scan_item(const Params& p, const int item, char* smem) {
;     ...
;   for (int c = 0; c < NC; ++c) {
;     if (wid >= 4) {
;       if (c + 1 < NC) load_chunk(c + 1, (c + 1) & 1);
;       if (c >= 1) store_y(c - 1);
;     } else {
;       const float* sb = buf + (c & 1) * 12288 + kp * 4;
;       float* yb = ybuf + (c & 1) * 2048 + row16 * 4 + (kp >> 2);
;       const int vofs = 320 + rq * 16 + row16 - kp * 4;
;       f32x4 kkA, wA, kaA, kA, rA, kkB, wB, kaB, kB, rB; float vA, vB;
;       RW_LD(0, A)
; #pragma unroll 2
;       for (int s = 0; s < 32; s += 2) {
;         RW_LD(s + 1, B)
;         __builtin_amdgcn_sched_barrier(0);
;         RW_STEP(s, A)
;         __builtin_amdgcn_sched_barrier(0);
;         if (s + 2 < 32) RW_LD(s + 2, A)
;         __builtin_amdgcn_sched_barrier(0);
;         RW_STEP(s + 1, B)
;         __builtin_amdgcn_sched_barrier(0);
;       }
	v_pk_fma_f32 v[14:15], v[100:101], v[6:7], v[14:15]
	v_pk_fma_f32 v[16:17], v[102:103], v[8:9], v[16:17]
	v_add_f32_dpp v104, v104, v104 row_mirror row_mask:0xf bank_mask:0xf bound_ctrl:1
	v_pk_fma_f32 v[100:101], v[10:11], v[104:105], v[14:15] op_sel_hi:[1,0,1] neg_lo:[0,1,0] neg_hi:[0,1,0]
	v_pk_fma_f32 v[102:103], v[12:13], v[104:105], v[16:17] op_sel_hi:[1,0,1] neg_lo:[0,1,0] neg_hi:[0,1,0]
	v_pk_mul_f32 v[106:107], v[100:101], v[18:19]
	ds_read_b128 v[32:35], v98 offset:38912
	v_pk_fma_f32 v[106:107], v[102:103], v[20:21], v[106:107]
	s_waitcnt lgkmcnt(2)
	v_pk_mul_f32 v[104:105], v[100:101], v[24:25]
	v_add_f32_e32 v106, v106, v107
	ds_read_b128 v[84:87], v98 offset:39424
	v_pk_fma_f32 v[104:105], v[102:103], v[26:27], v[104:105]
	v_add_f32_dpp v106, v106, v106 quad_perm:[1,0,3,2] row_mask:0xf bank_mask:0xf bound_ctrl:1
	v_add_f32_e32 v104, v104, v105
	s_nop 0
	v_add_f32_dpp v106, v106, v106 quad_perm:[2,3,0,1] row_mask:0xf bank_mask:0xf bound_ctrl:1
	ds_write_b32 v97, v106 offset:6144
	ds_read_b32 v22, v99 offset:41216
	ds_read_b128 v[14:17], v98 offset:40704
	v_add_f32_dpp v104, v104, v104 quad_perm:[1,0,3,2] row_mask:0xf bank_mask:0xf bound_ctrl:1
	ds_read_b128 v[2:5], v98 offset:39936
	ds_read_b128 v[6:9], v98 offset:40192
	v_add_f32_dpp v104, v104, v104 quad_perm:[2,3,0,1] row_mask:0xf bank_mask:0xf bound_ctrl:1
	v_pk_mul_f32 v[36:37], v[36:37], v[40:41] op_sel_hi:[1,0]
	v_pk_mul_f32 v[38:39], v[38:39], v[40:41] op_sel_hi:[1,0]
	v_add_f32_dpp v104, v104, v104 row_half_mirror row_mask:0xf bank_mask:0xf bound_ctrl:1
	s_waitcnt lgkmcnt(5)
	v_pk_fma_f32 v[36:37], v[100:101], v[28:29], v[36:37]
	v_pk_fma_f32 v[38:39], v[102:103], v[30:31], v[38:39]
	v_add_f32_dpp v104, v104, v104 row_mirror row_mask:0xf bank_mask:0xf bound_ctrl:1
	v_pk_fma_f32 v[100:101], v[32:33], v[104:105], v[36:37] op_sel_hi:[1,0,1] neg_lo:[0,1,0] neg_hi:[0,1,0]
	v_pk_fma_f32 v[102:103], v[34:35], v[104:105], v[38:39] op_sel_hi:[1,0,1] neg_lo:[0,1,0] neg_hi:[0,1,0]
	v_pk_mul_f32 v[106:107], v[100:101], v[84:85]
	ds_read_b128 v[10:13], v98 offset:40448
	v_pk_fma_f32 v[106:107], v[102:103], v[86:87], v[106:107]
	s_waitcnt lgkmcnt(2)
	v_pk_mul_f32 v[104:105], v[100:101], v[2:3]
	v_add_f32_e32 v106, v106, v107
	ds_read_b128 v[18:21], v98 offset:40960
	v_pk_fma_f32 v[104:105], v[102:103], v[4:5], v[104:105]
	v_add_f32_dpp v106, v106, v106 quad_perm:[1,0,3,2] row_mask:0xf bank_mask:0xf bound_ctrl:1
	v_add_f32_e32 v104, v104, v105
	s_nop 0
	v_add_f32_dpp v106, v106, v106 quad_perm:[2,3,0,1] row_mask:0xf bank_mask:0xf bound_ctrl:1
	ds_write_b32 v97, v106 offset:6400
	ds_read_b32 v40, v99 offset:42752
	ds_read_b128 v[36:39], v98 offset:42240
	v_add_f32_dpp v104, v104, v104 quad_perm:[1,0,3,2] row_mask:0xf bank_mask:0xf bound_ctrl:1
	ds_read_b128 v[24:27], v98 offset:41472
	ds_read_b128 v[28:31], v98 offset:41728
	v_add_f32_dpp v104, v104, v104 quad_perm:[2,3,0,1] row_mask:0xf bank_mask:0xf bound_ctrl:1
	v_pk_mul_f32 v[14:15], v[14:15], v[22:23] op_sel_hi:[1,0]
	v_pk_mul_f32 v[16:17], v[16:17], v[22:23] op_sel_hi:[1,0]
	v_add_f32_dpp v104, v104, v104 row_half_mirror row_mask:0xf bank_mask:0xf bound_ctrl:1
	s_waitcnt lgkmcnt(5)
	v_pk_fma_f32 v[14:15], v[100:101], v[6:7], v[14:15]
	v_pk_fma_f32 v[16:17], v[102:103], v[8:9], v[16:17]
	v_add_f32_dpp v104, v104, v104 row_mirror row_mask:0xf bank_mask:0xf bound_ctrl:1
	v_pk_fma_f32 v[100:101], v[10:11], v[104:105], v[14:15] op_sel_hi:[1,0,1] neg_lo:[0,1,0] neg_hi:[0,1,0]
	v_pk_fma_f32 v[102:103], v[12:13], v[104:105], v[16:17] op_sel_hi:[1,0,1] neg_lo:[0,1,0] neg_hi:[0,1,0]
	v_pk_mul_f32 v[106:107], v[100:101], v[18:19]
	ds_read_b128 v[32:35], v98 offset:41984
	v_pk_fma_f32 v[106:107], v[102:103], v[20:21], v[106:107]
	s_waitcnt lgkmcnt(2)
	v_pk_mul_f32 v[104:105], v[100:101], v[24:25]
	v_add_f32_e32 v106, v106, v107
	ds_read_b128 v[84:87], v98 offset:42496
	v_pk_fma_f32 v[104:105], v[102:103], v[26:27], v[104:105]
	v_add_f32_dpp v106, v106, v106 quad_perm:[1,0,3,2] row_mask:0xf bank_mask:0xf bound_ctrl:1
	v_add_f32_e32 v104, v104, v105
	s_nop 0
	v_add_f32_dpp v106, v106, v106 quad_perm:[2,3,0,1] row_mask:0xf bank_mask:0xf bound_ctrl:1
	ds_write_b32 v97, v106 offset:6656
	ds_read_b32 v22, v99 offset:44288
	ds_read_b128 v[14:17], v98 offset:43776
	v_add_f32_dpp v104, v104, v104 quad_perm:[1,0,3,2] row_mask:0xf bank_mask:0xf bound_ctrl:1
	ds_read_b128 v[2:5], v98 offset:43008
	ds_read_b128 v[6:9], v98 offset:43264
	v_add_f32_dpp v104, v104, v104 quad_perm:[2,3,0,1] row_mask:0xf bank_mask:0xf bound_ctrl:1
	v_pk_mul_f32 v[36:37], v[36:37], v[40:41] op_sel_hi:[1,0]
	v_pk_mul_f32 v[38:39], v[38:39], v[40:41] op_sel_hi:[1,0]
	v_add_f32_dpp v104, v104, v104 row_half_mirror row_mask:0xf bank_mask:0xf bound_ctrl:1
	s_waitcnt lgkmcnt(5)
	v_pk_fma_f32 v[36:37], v[100:101], v[28:29], v[36:37]
	v_pk_fma_f32 v[38:39], v[102:103], v[30:31], v[38:39]
	v_add_f32_dpp v104, v104, v104 row_mirror row_mask:0xf bank_mask:0xf bound_ctrl:1
	v_pk_fma_f32 v[100:101], v[32:33], v[104:105], v[36:37] op_sel_hi:[1,0,1] neg_lo:[0,1,0] neg_hi:[0,1,0]
	v_pk_fma_f32 v[102:103], v[34:35], v[104:105], v[38:39] op_sel_hi:[1,0,1] neg_lo:[0,1,0] neg_hi:[0,1,0]
	v_pk_mul_f32 v[106:107], v[100:101], v[84:85]
	ds_read_b128 v[10:13], v98 offset:43520
	v_pk_fma_f32 v[106:107], v[102:103], v[86:87], v[106:107]
	s_waitcnt lgkmcnt(2)
; DEVI void rwkv_scan_item(const Params& p, const int item, char* smem) {
;     ...
;   for (int c = 0; c < NC; ++c) {
;     if (wid >= 4) {
;       if (c + 1 < NC) load_chunk(c + 1, (c + 1) & 1);
;       if (c >= 1) store_y(c - 1);
;     } else {
;       const float* sb = buf + (c & 1) * 12288 + kp * 4;
;       float* yb = ybuf + (c & 1) * 2048 + row16 * 4 + (kp >> 2);
;       const int vofs = 320 + rq * 16 + row16 - kp * 4;
;       f32x4 kkA, wA, kaA, kA, rA, kkB, wB, kaB, kB, rB; float vA, vB;
;       RW_LD(0, A)
; #pragma unroll 2
;       for (int s = 0; s < 32; s += 2) {
;         RW_LD(s + 1, B)
;         __builtin_amdgcn_sched_barrier(0);
;         RW_STEP(s, A)
;         __builtin_amdgcn_sched_barrier(0);
;         if (s + 2 < 32) RW_LD(s + 2, A)
;         __builtin_amdgcn_sched_barrier(0);
;         RW_STEP(s + 1, B)
;         __builtin_amdgcn_sched_barrier(0);
;       }
	v_pk_mul_f32 v[104:105], v[100:101], v[2:3]
	v_add_f32_e32 v106, v106, v107
	ds_read_b128 v[18:21], v98 offset:44032
	v_pk_fma_f32 v[104:105], v[102:103], v[4:5], v[104:105]
	v_add_f32_dpp v106, v106, v106 quad_perm:[1,0,3,2] row_mask:0xf bank_mask:0xf bound_ctrl:1
	v_add_f32_e32 v104, v104, v105
	s_nop 0
	v_add_f32_dpp v106, v106, v106 quad_perm:[2,3,0,1] row_mask:0xf bank_mask:0xf bound_ctrl:1
	ds_write_b32 v97, v106 offset:6912
	ds_read_b32 v40, v99 offset:45824
	ds_read_b128 v[36:39], v98 offset:45312
	v_add_f32_dpp v104, v104, v104 quad_perm:[1,0,3,2] row_mask:0xf bank_mask:0xf bound_ctrl:1
	ds_read_b128 v[24:27], v98 offset:44544
	ds_read_b128 v[28:31], v98 offset:44800
	v_add_f32_dpp v104, v104, v104 quad_perm:[2,3,0,1] row_mask:0xf bank_mask:0xf bound_ctrl:1
	v_pk_mul_f32 v[14:15], v[14:15], v[22:23] op_sel_hi:[1,0]
	v_pk_mul_f32 v[16:17], v[16:17], v[22:23] op_sel_hi:[1,0]
	v_add_f32_dpp v104, v104, v104 row_half_mirror row_mask:0xf bank_mask:0xf bound_ctrl:1
	s_waitcnt lgkmcnt(5)
	v_pk_fma_f32 v[14:15], v[100:101], v[6:7], v[14:15]
	v_pk_fma_f32 v[16:17], v[102:103], v[8:9], v[16:17]
	v_add_f32_dpp v104, v104, v104 row_mirror row_mask:0xf bank_mask:0xf bound_ctrl:1
	v_pk_fma_f32 v[100:101], v[10:11], v[104:105], v[14:15] op_sel_hi:[1,0,1] neg_lo:[0,1,0] neg_hi:[0,1,0]
	v_pk_fma_f32 v[102:103], v[12:13], v[104:105], v[16:17] op_sel_hi:[1,0,1] neg_lo:[0,1,0] neg_hi:[0,1,0]
	v_pk_mul_f32 v[106:107], v[100:101], v[18:19]
	ds_read_b128 v[32:35], v98 offset:45056
	v_pk_fma_f32 v[106:107], v[102:103], v[20:21], v[106:107]
	s_waitcnt lgkmcnt(2)
	v_pk_mul_f32 v[104:105], v[100:101], v[24:25]
	v_add_f32_e32 v106, v106, v107
	ds_read_b128 v[84:87], v98 offset:45568
	v_pk_fma_f32 v[104:105], v[102:103], v[26:27], v[104:105]
	v_add_f32_dpp v106, v106, v106 quad_perm:[1,0,3,2] row_mask:0xf bank_mask:0xf bound_ctrl:1
	v_add_f32_e32 v104, v104, v105
	s_nop 0
	v_add_f32_dpp v106, v106, v106 quad_perm:[2,3,0,1] row_mask:0xf bank_mask:0xf bound_ctrl:1
	ds_write_b32 v97, v106 offset:7168
	ds_read_b32 v22, v99 offset:47360
	ds_read_b128 v[14:17], v98 offset:46848
	v_add_f32_dpp v104, v104, v104 quad_perm:[1,0,3,2] row_mask:0xf bank_mask:0xf bound_ctrl:1
	ds_read_b128 v[2:5], v98 offset:46080
	ds_read_b128 v[6:9], v98 offset:46336
	v_add_f32_dpp v104, v104, v104 quad_perm:[2,3,0,1] row_mask:0xf bank_mask:0xf bound_ctrl:1
	v_pk_mul_f32 v[36:37], v[36:37], v[40:41] op_sel_hi:[1,0]
	v_pk_mul_f32 v[38:39], v[38:39], v[40:41] op_sel_hi:[1,0]
	v_add_f32_dpp v104, v104, v104 row_half_mirror row_mask:0xf bank_mask:0xf bound_ctrl:1
	s_waitcnt lgkmcnt(5)
	v_pk_fma_f32 v[36:37], v[100:101], v[28:29], v[36:37]
	v_pk_fma_f32 v[38:39], v[102:103], v[30:31], v[38:39]
	v_add_f32_dpp v104, v104, v104 row_mirror row_mask:0xf bank_mask:0xf bound_ctrl:1
	v_pk_fma_f32 v[100:101], v[32:33], v[104:105], v[36:37] op_sel_hi:[1,0,1] neg_lo:[0,1,0] neg_hi:[0,1,0]
	v_pk_fma_f32 v[102:103], v[34:35], v[104:105], v[38:39] op_sel_hi:[1,0,1] neg_lo:[0,1,0] neg_hi:[0,1,0]
	v_pk_mul_f32 v[106:107], v[100:101], v[84:85]
	ds_read_b128 v[10:13], v98 offset:46592
	v_pk_fma_f32 v[106:107], v[102:103], v[86:87], v[106:107]
	s_waitcnt lgkmcnt(2)
	v_pk_mul_f32 v[104:105], v[100:101], v[2:3]
	v_add_f32_e32 v106, v106, v107
	ds_read_b128 v[18:21], v98 offset:47104
	v_pk_fma_f32 v[104:105], v[102:103], v[4:5], v[104:105]
	v_add_f32_dpp v106, v106, v106 quad_perm:[1,0,3,2] row_mask:0xf bank_mask:0xf bound_ctrl:1
	v_add_f32_e32 v104, v104, v105
	s_nop 0
	v_add_f32_dpp v106, v106, v106 quad_perm:[2,3,0,1] row_mask:0xf bank_mask:0xf bound_ctrl:1
	ds_write_b32 v97, v106 offset:7424
	ds_read_b32 v40, v99 offset:48896
	ds_read_b128 v[36:39], v98 offset:48384
	v_add_f32_dpp v104, v104, v104 quad_perm:[1,0,3,2] row_mask:0xf bank_mask:0xf bound_ctrl:1
	ds_read_b128 v[24:27], v98 offset:47616
	ds_read_b128 v[28:31], v98 offset:47872
	v_add_f32_dpp v104, v104, v104 quad_perm:[2,3,0,1] row_mask:0xf bank_mask:0xf bound_ctrl:1
	v_pk_mul_f32 v[14:15], v[14:15], v[22:23] op_sel_hi:[1,0]
	v_pk_mul_f32 v[16:17], v[16:17], v[22:23] op_sel_hi:[1,0]
	v_add_f32_dpp v104, v104, v104 row_half_mirror row_mask:0xf bank_mask:0xf bound_ctrl:1
	s_waitcnt lgkmcnt(5)
	v_pk_fma_f32 v[14:15], v[100:101], v[6:7], v[14:15]
	v_pk_fma_f32 v[16:17], v[102:103], v[8:9], v[16:17]
	v_add_f32_dpp v104, v104, v104 row_mirror row_mask:0xf bank_mask:0xf bound_ctrl:1
	v_pk_fma_f32 v[100:101], v[10:11], v[104:105], v[14:15] op_sel_hi:[1,0,1] neg_lo:[0,1,0] neg_hi:[0,1,0]
	v_pk_fma_f32 v[102:103], v[12:13], v[104:105], v[16:17] op_sel_hi:[1,0,1] neg_lo:[0,1,0] neg_hi:[0,1,0]
	v_pk_mul_f32 v[106:107], v[100:101], v[18:19]
	ds_read_b128 v[32:35], v98 offset:48128
	v_pk_fma_f32 v[106:107], v[102:103], v[20:21], v[106:107]
	s_waitcnt lgkmcnt(2)
	v_pk_mul_f32 v[104:105], v[100:101], v[24:25]
	v_add_f32_e32 v106, v106, v107
	ds_read_b128 v[84:87], v98 offset:48640
	v_pk_fma_f32 v[104:105], v[102:103], v[26:27], v[104:105]
	v_add_f32_dpp v106, v106, v106 quad_perm:[1,0,3,2] row_mask:0xf bank_mask:0xf bound_ctrl:1
	v_add_f32_e32 v104, v104, v105
	s_nop 0
	v_add_f32_dpp v106, v106, v106 quad_perm:[2,3,0,1] row_mask:0xf bank_mask:0xf bound_ctrl:1
	ds_write_b32 v97, v106 offset:7680
	v_add_f32_dpp v104, v104, v104 quad_perm:[1,0,3,2] row_mask:0xf bank_mask:0xf bound_ctrl:1
	v_pk_mul_f32 v[36:37], v[36:37], v[40:41] op_sel_hi:[1,0]
	v_pk_mul_f32 v[38:39], v[38:39], v[40:41] op_sel_hi:[1,0]
	v_add_f32_dpp v104, v104, v104 quad_perm:[2,3,0,1] row_mask:0xf bank_mask:0xf bound_ctrl:1
	s_waitcnt lgkmcnt(1)
	v_pk_fma_f32 v[36:37], v[100:101], v[28:29], v[36:37]
	v_pk_fma_f32 v[38:39], v[102:103], v[30:31], v[38:39]
	v_add_f32_dpp v104, v104, v104 row_half_mirror row_mask:0xf bank_mask:0xf bound_ctrl:1
	s_nop 1
	v_add_f32_dpp v104, v104, v104 row_mirror row_mask:0xf bank_mask:0xf bound_ctrl:1
	v_pk_fma_f32 v[100:101], v[32:33], v[104:105], v[36:37] op_sel_hi:[1,0,1] neg_lo:[0,1,0] neg_hi:[0,1,0]
	v_pk_fma_f32 v[102:103], v[34:35], v[104:105], v[38:39] op_sel_hi:[1,0,1] neg_lo:[0,1,0] neg_hi:[0,1,0]
	v_pk_mul_f32 v[106:107], v[100:101], v[84:85]
	s_nop 0
	v_pk_fma_f32 v[106:107], v[102:103], v[86:87], v[106:107]
	s_nop 0
	v_add_f32_e32 v106, v106, v107
	s_nop 1
	v_add_f32_dpp v106, v106, v106 quad_perm:[1,0,3,2] row_mask:0xf bank_mask:0xf bound_ctrl:1
	s_nop 1
	v_add_f32_dpp v106, v106, v106 quad_perm:[2,3,0,1] row_mask:0xf bank_mask:0xf bound_ctrl:1
	ds_write_b32 v97, v106 offset:7936

; #define WAITL() asm volatile("s_waitcnt lgkmcnt(0)" ::: "memory")
; template <int EPI> ...
;     ...
;         WAITL();
; #pragma unroll
;         for (int m = 0; m < 4; ++m)
; #pragma unroll
;           for (int n = 0; n < 2; ++n)
; #pragma unroll
;             for (int j = 0; j < 4; ++j) ep[(m * 16 + fq * 4 + j) * 32 + n * 16 + fr] = acc[ai][bj][m][n][j];
;         WAITL();
;         const int grow0 = brow + ai * 128 + wr * 64, gcol0 = bcol + bj * 128 + wc * 32;
;         if (EPI == 1) {
;           const size_t idx0 = (size_t)(grow0 + (lane >> 3)) * 2048 + gcol0 + (lane & 7) * 4;
;           const float* xp = xin + idx0; float* op = xout + idx0; const float* lp = ep + (lane >> 3) * 32 + (lane & 7) * 4;
; #pragma unroll
;           for (int i = 0; i < 8; ++i) {
;             const float4 v = *(const float4*)(lp + i * 256);
;             float4 x = *(const float4*)xp;
;             x.x += v.x; x.y += v.y; x.z += v.z; x.w += v.w;
;             *(float4*)op = x;
;             xp += 16384; op += 16384;
;             asm volatile("" : "+v"(xp), "+v"(op));
;           }
.LBB0_1425:
	s_waitcnt lgkmcnt(0)
	ds_write2_b32 v160, v114, v126 offset1:16
	ds_write2_b32 v160, v115, v127 offset0:32 offset1:48
	ds_write2_b32 v160, v116, v128 offset0:64 offset1:80
	ds_write2_b32 v160, v117, v129 offset0:96 offset1:112
	v_add_u32_e32 v114, 0x800, v160
	s_and_b32 s36, s36, 0x7fffff8
	v_or_b32_e32 v144, s87, v158
	ds_write2_b32 v114, v106, v122 offset1:16
	ds_write2_b32 v114, v107, v123 offset0:32 offset1:48
	ds_write2_b32 v114, v108, v124 offset0:64 offset1:80
	ds_write2_b32 v114, v109, v125 offset0:96 offset1:112
	v_add_u32_e32 v106, 0x1000, v160
	v_or_b32_e32 v134, s36, v131
	v_ashrrev_i32_e32 v145, 31, v144
	ds_write2_b32 v106, v102, v118 offset1:16
	ds_write2_b32 v106, v103, v119 offset0:32 offset1:48
	ds_write2_b32 v106, v104, v120 offset0:64 offset1:80
	ds_write2_b32 v106, v105, v121 offset0:96 offset1:112
	v_add_u32_e32 v102, 0x1800, v160
	v_lshlrev_b32_e32 v142, 5, v134
	ds_write2_b32 v102, v98, v110 offset1:16
	ds_write2_b32 v102, v99, v111 offset0:32 offset1:48
	ds_write2_b32 v102, v100, v112 offset0:64 offset1:80
	ds_write2_b32 v102, v101, v113 offset0:96 offset1:112
	v_lshlrev_b64 v[98:99], 13, v[144:145]
	v_ashrrev_i32_e32 v143, 31, v142
	v_lshl_add_u64 v[98:99], v[140:141], 0, v[98:99]
	s_waitcnt lgkmcnt(0)
	v_lshl_add_u64 v[98:99], v[142:143], 2, v[98:99]
	global_load_dwordx4 v[176:179], v[98:99], off
	v_lshl_add_u64 v[208:209], v[98:99], 0, s[72:73]
	global_load_dwordx4 v[180:183], v[208:209], off
	v_lshl_add_u64 v[208:209], v[208:209], 0, s[72:73]
	global_load_dwordx4 v[184:187], v[208:209], off
	v_lshl_add_u64 v[208:209], v[208:209], 0, s[72:73]
	global_load_dwordx4 v[188:191], v[208:209], off
	v_lshl_add_u64 v[208:209], v[208:209], 0, s[72:73]
	global_load_dwordx4 v[192:195], v[208:209], off
	v_lshl_add_u64 v[208:209], v[208:209], 0, s[72:73]
	global_load_dwordx4 v[196:199], v[208:209], off
	v_lshl_add_u64 v[208:209], v[208:209], 0, s[72:73]
	global_load_dwordx4 v[200:203], v[208:209], off
	v_lshl_add_u64 v[208:209], v[208:209], 0, s[72:73]
	global_load_dwordx4 v[204:207], v[208:209], off
	ds_read_b128 v[116:119], v159
	v_lshl_add_u64 v[100:101], v[98:99], 0, s[72:73]
	v_mov_b64_e32 v[104:105], v[100:101]
	s_mov_b32 s36, s35
	s_waitcnt vmcnt(7) lgkmcnt(0)
	v_pk_add_f32 v[176:177], v[116:117], v[176:177]
	v_pk_add_f32 v[178:179], v[118:119], v[178:179]
	global_store_dwordx4 v[98:99], v[176:179], off
	ds_read_b128 v[116:119], v159 offset:1024
	v_lshl_add_u64 v[104:105], v[104:105], 0, s[72:73]
	v_lshl_add_u64 v[112:113], v[100:101], 0, s[72:73]
	s_waitcnt vmcnt(7) lgkmcnt(0)
	v_pk_add_f32 v[180:181], v[116:117], v[180:181]
	v_pk_add_f32 v[182:183], v[118:119], v[182:183]
	global_store_dwordx4 v[100:101], v[180:183], off
	ds_read_b128 v[116:119], v159 offset:2048
	v_lshl_add_u64 v[100:101], v[104:105], 0, s[72:73]
	v_lshl_add_u64 v[104:105], v[112:113], 0, s[72:73]
	s_waitcnt vmcnt(7) lgkmcnt(0)
	v_pk_add_f32 v[184:185], v[116:117], v[184:185]
	v_pk_add_f32 v[186:187], v[118:119], v[186:187]
	global_store_dwordx4 v[112:113], v[184:187], off
	ds_read_b128 v[116:119], v159 offset:3072
	v_lshl_add_u64 v[100:101], v[100:101], 0, s[72:73]
	v_lshl_add_u64 v[112:113], v[104:105], 0, s[72:73]
	s_waitcnt vmcnt(7) lgkmcnt(0)
	v_pk_add_f32 v[188:189], v[116:117], v[188:189]
	v_pk_add_f32 v[190:191], v[118:119], v[190:191]
	global_store_dwordx4 v[104:105], v[188:191], off
	ds_read_b128 v[116:119], v159 offset:4096
	v_lshl_add_u64 v[100:101], v[100:101], 0, s[72:73]
	v_lshl_add_u64 v[104:105], v[112:113], 0, s[72:73]
	s_waitcnt vmcnt(7) lgkmcnt(0)
	v_pk_add_f32 v[192:193], v[116:117], v[192:193]
	v_pk_add_f32 v[194:195], v[118:119], v[194:195]
	global_store_dwordx4 v[112:113], v[192:195], off
	ds_read_b128 v[116:119], v159 offset:5120
	v_lshl_add_u64 v[100:101], v[100:101], 0, s[72:73]
	v_lshl_add_u64 v[112:113], v[104:105], 0, s[72:73]
	s_waitcnt vmcnt(7) lgkmcnt(0)
	v_pk_add_f32 v[196:197], v[116:117], v[196:197]
	v_pk_add_f32 v[198:199], v[118:119], v[198:199]
	global_store_dwordx4 v[104:105], v[196:199], off
	ds_read_b128 v[116:119], v159 offset:6144
	v_lshl_add_u64 v[100:101], v[100:101], 0, s[72:73]
	v_lshl_add_u64 v[104:105], v[112:113], 0, s[72:73]
	s_waitcnt vmcnt(7) lgkmcnt(0)
	v_pk_add_f32 v[200:201], v[116:117], v[200:201]
	v_pk_add_f32 v[202:203], v[118:119], v[202:203]
	global_store_dwordx4 v[112:113], v[200:203], off
	ds_read_b128 v[116:119], v159 offset:7168
	v_lshl_add_u64 v[100:101], v[100:101], 0, s[72:73]
	v_lshl_add_u64 v[112:113], v[104:105], 0, s[72:73]
	s_waitcnt vmcnt(7) lgkmcnt(0)
	v_pk_add_f32 v[204:205], v[116:117], v[204:205]
	v_pk_add_f32 v[206:207], v[118:119], v[206:207]
	global_store_dwordx4 v[104:105], v[204:207], off
	s_waitcnt lgkmcnt(0)
	ds_write2_b32 v160, v66, v82 offset1:16
	ds_write2_b32 v160, v67, v83 offset0:32 offset1:48
	ds_write2_b32 v160, v68, v84 offset0:64 offset1:80
	ds_write2_b32 v160, v69, v85 offset0:96 offset1:112
	ds_write2_b32 v114, v70, v86 offset1:16
	ds_write2_b32 v114, v71, v87 offset0:32 offset1:48
	ds_write2_b32 v114, v72, v88 offset0:64 offset1:80
	ds_write2_b32 v114, v73, v89 offset0:96 offset1:112
	ds_write2_b32 v106, v74, v90 offset1:16
	ds_write2_b32 v106, v75, v91 offset0:32 offset1:48
	ds_write2_b32 v106, v76, v92 offset0:64 offset1:80
	ds_write2_b32 v106, v77, v93 offset0:96 offset1:112
	ds_write2_b32 v102, v78, v94 offset1:16
	ds_write2_b32 v102, v79, v95 offset0:32 offset1:48
	ds_write2_b32 v102, v80, v96 offset0:64 offset1:80
	ds_write2_b32 v102, v81, v97 offset0:96 offset1:112
	s_waitcnt lgkmcnt(0)
; #define WAITL() asm volatile("s_waitcnt lgkmcnt(0)" ::: "memory")
; template <int EPI> ...
;     ...
;         WAITL();
; #pragma unroll
;         for (int m = 0; m < 4; ++m)
; #pragma unroll
;           for (int n = 0; n < 2; ++n)
; #pragma unroll
;             for (int j = 0; j < 4; ++j) ep[(m * 16 + fq * 4 + j) * 32 + n * 16 + fr] = acc[ai][bj][m][n][j];
;         WAITL();
;         const int grow0 = brow + ai * 128 + wr * 64, gcol0 = bcol + bj * 128 + wc * 32;
;         if (EPI == 1) {
;           const size_t idx0 = (size_t)(grow0 + (lane >> 3)) * 2048 + gcol0 + (lane & 7) * 4;
;           const float* xp = xin + idx0; float* op = xout + idx0; const float* lp = ep + (lane >> 3) * 32 + (lane & 7) * 4;
; #pragma unroll
;           for (int i = 0; i < 8; ++i) {
;             const float4 v = *(const float4*)(lp + i * 256);
;             float4 x = *(const float4*)xp;
;             x.x += v.x; x.y += v.y; x.z += v.z; x.w += v.w;
;             *(float4*)op = x;
;             xp += 16384; op += 16384;
;             asm volatile("" : "+v"(xp), "+v"(op));
;           }
	global_load_dwordx4 v[176:179], v[98:99], off offset:512
	v_lshl_add_u64 v[208:209], v[98:99], 0, s[74:75]
	global_load_dwordx4 v[180:183], v[208:209], off
	v_lshl_add_u64 v[208:209], v[208:209], 0, s[72:73]
	global_load_dwordx4 v[184:187], v[208:209], off
	v_lshl_add_u64 v[208:209], v[208:209], 0, s[72:73]
	global_load_dwordx4 v[188:191], v[208:209], off
	v_lshl_add_u64 v[208:209], v[208:209], 0, s[72:73]
	global_load_dwordx4 v[192:195], v[208:209], off
	v_lshl_add_u64 v[208:209], v[208:209], 0, s[72:73]
	global_load_dwordx4 v[196:199], v[208:209], off
	v_lshl_add_u64 v[208:209], v[208:209], 0, s[72:73]
	global_load_dwordx4 v[200:203], v[208:209], off
	v_lshl_add_u64 v[208:209], v[208:209], 0, s[72:73]
	global_load_dwordx4 v[204:207], v[208:209], off
	ds_read_b128 v[70:73], v159
	v_lshl_add_u64 v[74:75], v[98:99], 0, s[74:75]
	v_mov_b64_e32 v[76:77], v[74:75]
	s_waitcnt vmcnt(7) lgkmcnt(0)
	v_pk_add_f32 v[176:177], v[70:71], v[176:177]
	v_pk_add_f32 v[178:179], v[72:73], v[178:179]
	global_store_dwordx4 v[98:99], v[176:179], off offset:512
	ds_read_b128 v[70:73], v159 offset:1024
	v_lshl_add_u64 v[76:77], v[76:77], 0, s[72:73]
	v_lshl_add_u64 v[78:79], v[74:75], 0, s[72:73]
	s_waitcnt vmcnt(7) lgkmcnt(0)
	v_pk_add_f32 v[180:181], v[70:71], v[180:181]
	v_pk_add_f32 v[182:183], v[72:73], v[182:183]
	global_store_dwordx4 v[74:75], v[180:183], off
	ds_read_b128 v[70:73], v159 offset:2048
	v_lshl_add_u64 v[74:75], v[76:77], 0, s[72:73]
	v_lshl_add_u64 v[76:77], v[78:79], 0, s[72:73]
	s_waitcnt vmcnt(7) lgkmcnt(0)
	v_pk_add_f32 v[184:185], v[70:71], v[184:185]
	v_pk_add_f32 v[186:187], v[72:73], v[186:187]
	global_store_dwordx4 v[78:79], v[184:187], off
	ds_read_b128 v[70:73], v159 offset:3072
	v_lshl_add_u64 v[74:75], v[74:75], 0, s[72:73]
	v_lshl_add_u64 v[78:79], v[76:77], 0, s[72:73]
	s_waitcnt vmcnt(7) lgkmcnt(0)
	v_pk_add_f32 v[188:189], v[70:71], v[188:189]
	v_pk_add_f32 v[190:191], v[72:73], v[190:191]
	global_store_dwordx4 v[76:77], v[188:191], off
	ds_read_b128 v[70:73], v159 offset:4096
	v_lshl_add_u64 v[74:75], v[74:75], 0, s[72:73]
	v_lshl_add_u64 v[76:77], v[78:79], 0, s[72:73]
	s_waitcnt vmcnt(7) lgkmcnt(0)
	v_pk_add_f32 v[192:193], v[70:71], v[192:193]
	v_pk_add_f32 v[194:195], v[72:73], v[194:195]
	global_store_dwordx4 v[78:79], v[192:195], off
	ds_read_b128 v[70:73], v159 offset:5120
	v_lshl_add_u64 v[74:75], v[74:75], 0, s[72:73]
	v_lshl_add_u64 v[78:79], v[76:77], 0, s[72:73]
	s_waitcnt vmcnt(7) lgkmcnt(0)
	v_pk_add_f32 v[196:197], v[70:71], v[196:197]
	v_pk_add_f32 v[198:199], v[72:73], v[198:199]
	global_store_dwordx4 v[76:77], v[196:199], off
	ds_read_b128 v[70:73], v159 offset:6144
	v_lshl_add_u64 v[74:75], v[74:75], 0, s[72:73]
	v_lshl_add_u64 v[76:77], v[78:79], 0, s[72:73]
	s_waitcnt vmcnt(7) lgkmcnt(0)
	v_pk_add_f32 v[200:201], v[70:71], v[200:201]
	v_pk_add_f32 v[202:203], v[72:73], v[202:203]
	global_store_dwordx4 v[78:79], v[200:203], off
	ds_read_b128 v[70:73], v159 offset:7168
	v_lshl_add_u64 v[74:75], v[74:75], 0, s[72:73]
	v_lshl_add_u64 v[80:81], v[76:77], 0, s[72:73]
	v_add_co_u32_e32 v78, vcc, s34, v98
	s_waitcnt vmcnt(7) lgkmcnt(0)
	v_pk_add_f32 v[204:205], v[70:71], v[204:205]
	v_pk_add_f32 v[206:207], v[72:73], v[206:207]
	global_store_dwordx4 v[76:77], v[204:207], off
	s_waitcnt lgkmcnt(0)
	ds_write2_b32 v160, v34, v50 offset1:16
	ds_write2_b32 v160, v35, v51 offset0:32 offset1:48
	ds_write2_b32 v160, v36, v52 offset0:64 offset1:80
	ds_write2_b32 v160, v37, v53 offset0:96 offset1:112
	ds_write2_b32 v114, v38, v54 offset1:16
	ds_write2_b32 v114, v39, v55 offset0:32 offset1:48
	ds_write2_b32 v114, v40, v56 offset0:64 offset1:80
	ds_write2_b32 v114, v41, v57 offset0:96 offset1:112
	ds_write2_b32 v106, v42, v58 offset1:16
	ds_write2_b32 v106, v43, v59 offset0:32 offset1:48
	ds_write2_b32 v106, v44, v60 offset0:64 offset1:80
	ds_write2_b32 v106, v45, v61 offset0:96 offset1:112
	ds_write2_b32 v102, v46, v62 offset1:16
	ds_write2_b32 v102, v47, v63 offset0:32 offset1:48
	ds_write2_b32 v102, v48, v64 offset0:64 offset1:80
	ds_write2_b32 v102, v49, v65 offset0:96 offset1:112
	v_addc_co_u32_e32 v79, vcc, 0, v99, vcc
	s_waitcnt lgkmcnt(0)
	global_load_dwordx4 v[176:179], v[78:79], off
	v_lshl_add_u64 v[208:209], v[98:99], 0, s[78:79]
	global_load_dwordx4 v[180:183], v[208:209], off
	v_lshl_add_u64 v[208:209], v[208:209], 0, s[72:73]
	global_load_dwordx4 v[184:187], v[208:209], off
	v_lshl_add_u64 v[208:209], v[208:209], 0, s[72:73]
	global_load_dwordx4 v[188:191], v[208:209], off
	v_lshl_add_u64 v[208:209], v[208:209], 0, s[72:73]
	global_load_dwordx4 v[192:195], v[208:209], off
	v_lshl_add_u64 v[208:209], v[208:209], 0, s[72:73]
	global_load_dwordx4 v[196:199], v[208:209], off
	v_lshl_add_u64 v[208:209], v[208:209], 0, s[72:73]
	global_load_dwordx4 v[200:203], v[208:209], off
	v_lshl_add_u64 v[208:209], v[208:209], 0, s[72:73]
	global_load_dwordx4 v[204:207], v[208:209], off
	ds_read_b128 v[38:41], v159
	v_lshl_add_u64 v[42:43], v[98:99], 0, s[78:79]
	v_mov_b64_e32 v[44:45], v[42:43]
	s_andn2_b64 vcc, exec, s[82:83]
	s_waitcnt vmcnt(7) lgkmcnt(0)
	v_pk_add_f32 v[176:177], v[38:39], v[176:177]
	v_pk_add_f32 v[178:179], v[40:41], v[178:179]
	global_store_dwordx4 v[78:79], v[176:179], off
	ds_read_b128 v[38:41], v159 offset:1024
	v_lshl_add_u64 v[44:45], v[44:45], 0, s[72:73]
	v_lshl_add_u64 v[46:47], v[42:43], 0, s[72:73]
	s_waitcnt vmcnt(7) lgkmcnt(0)
	v_pk_add_f32 v[180:181], v[38:39], v[180:181]
	v_pk_add_f32 v[182:183], v[40:41], v[182:183]
	global_store_dwordx4 v[42:43], v[180:183], off
	ds_read_b128 v[38:41], v159 offset:2048
	v_lshl_add_u64 v[42:43], v[44:45], 0, s[72:73]
	v_lshl_add_u64 v[44:45], v[46:47], 0, s[72:73]
	s_waitcnt vmcnt(7) lgkmcnt(0)
; template <int EPI> ...
;     ...
;         const int grow0 = brow + ai * 128 + wr * 64, gcol0 = bcol + bj * 128 + wc * 32;
;         if (EPI == 1) {
;           const size_t idx0 = (size_t)(grow0 + (lane >> 3)) * 2048 + gcol0 + (lane & 7) * 4;
;           const float* xp = xin + idx0; float* op = xout + idx0; const float* lp = ep + (lane >> 3) * 32 + (lane & 7) * 4;
; #pragma unroll
;           for (int i = 0; i < 8; ++i) {
;             const float4 v = *(const float4*)(lp + i * 256);
;             float4 x = *(const float4*)xp;
;             x.x += v.x; x.y += v.y; x.z += v.z; x.w += v.w;
;             *(float4*)op = x;
;             xp += 16384; op += 16384;
;             asm volatile("" : "+v"(xp), "+v"(op));
;           }
	v_pk_add_f32 v[184:185], v[38:39], v[184:185]
	v_pk_add_f32 v[186:187], v[40:41], v[186:187]
	global_store_dwordx4 v[46:47], v[184:187], off
	ds_read_b128 v[38:41], v159 offset:3072
	v_lshl_add_u64 v[42:43], v[42:43], 0, s[72:73]
	v_lshl_add_u64 v[46:47], v[44:45], 0, s[72:73]
	s_waitcnt vmcnt(7) lgkmcnt(0)
	v_pk_add_f32 v[188:189], v[38:39], v[188:189]
	v_pk_add_f32 v[190:191], v[40:41], v[190:191]
	global_store_dwordx4 v[44:45], v[188:191], off
	ds_read_b128 v[38:41], v159 offset:4096
	v_lshl_add_u64 v[42:43], v[42:43], 0, s[72:73]
	v_lshl_add_u64 v[44:45], v[46:47], 0, s[72:73]
	s_waitcnt vmcnt(7) lgkmcnt(0)
	v_pk_add_f32 v[192:193], v[38:39], v[192:193]
	v_pk_add_f32 v[194:195], v[40:41], v[194:195]
	global_store_dwordx4 v[46:47], v[192:195], off
	ds_read_b128 v[38:41], v159 offset:5120
	v_lshl_add_u64 v[42:43], v[42:43], 0, s[72:73]
	v_lshl_add_u64 v[46:47], v[44:45], 0, s[72:73]
	s_waitcnt vmcnt(7) lgkmcnt(0)
	v_pk_add_f32 v[196:197], v[38:39], v[196:197]
	v_pk_add_f32 v[198:199], v[40:41], v[198:199]
	global_store_dwordx4 v[44:45], v[196:199], off
	ds_read_b128 v[38:41], v159 offset:6144
	v_lshl_add_u64 v[42:43], v[42:43], 0, s[72:73]
	v_lshl_add_u64 v[44:45], v[46:47], 0, s[72:73]
	s_waitcnt vmcnt(7) lgkmcnt(0)
	v_pk_add_f32 v[200:201], v[38:39], v[200:201]
	v_pk_add_f32 v[202:203], v[40:41], v[202:203]
	global_store_dwordx4 v[46:47], v[200:203], off
	ds_read_b128 v[38:41], v159 offset:7168
	v_lshl_add_u64 v[42:43], v[42:43], 0, s[72:73]
	v_lshl_add_u64 v[48:49], v[44:45], 0, s[72:73]
	v_lshl_add_u64 v[46:47], v[98:99], 0, s[76:77]
	s_waitcnt vmcnt(7) lgkmcnt(0)
	v_pk_add_f32 v[204:205], v[38:39], v[204:205]
	v_pk_add_f32 v[206:207], v[40:41], v[206:207]
	global_store_dwordx4 v[44:45], v[204:207], off
	s_waitcnt lgkmcnt(0)
	ds_write2_b32 v160, v2, v18 offset1:16
	ds_write2_b32 v160, v3, v19 offset0:32 offset1:48
	ds_write2_b32 v160, v4, v20 offset0:64 offset1:80
	ds_write2_b32 v160, v5, v21 offset0:96 offset1:112
	ds_write2_b32 v114, v6, v22 offset1:16
	ds_write2_b32 v114, v7, v23 offset0:32 offset1:48
	ds_write2_b32 v114, v8, v24 offset0:64 offset1:80
	ds_write2_b32 v114, v9, v25 offset0:96 offset1:112
	ds_write2_b32 v106, v10, v26 offset1:16
	ds_write2_b32 v106, v11, v27 offset0:32 offset1:48
	ds_write2_b32 v106, v12, v28 offset0:64 offset1:80
	ds_write2_b32 v106, v13, v29 offset0:96 offset1:112
	ds_write2_b32 v102, v14, v30 offset1:16
	ds_write2_b32 v102, v15, v31 offset0:32 offset1:48
	ds_write2_b32 v102, v16, v32 offset0:64 offset1:80
	ds_write2_b32 v102, v17, v33 offset0:96 offset1:112
	s_waitcnt lgkmcnt(0)
	global_load_dwordx4 v[176:179], v[46:47], off offset:512
	v_lshl_add_u64 v[208:209], v[98:99], 0, s[80:81]
	global_load_dwordx4 v[180:183], v[208:209], off
	v_lshl_add_u64 v[208:209], v[208:209], 0, s[72:73]
	global_load_dwordx4 v[184:187], v[208:209], off
	v_lshl_add_u64 v[208:209], v[208:209], 0, s[72:73]
	global_load_dwordx4 v[188:191], v[208:209], off
	v_lshl_add_u64 v[208:209], v[208:209], 0, s[72:73]
	global_load_dwordx4 v[192:195], v[208:209], off
	v_lshl_add_u64 v[208:209], v[208:209], 0, s[72:73]
	global_load_dwordx4 v[196:199], v[208:209], off
	v_lshl_add_u64 v[208:209], v[208:209], 0, s[72:73]
	global_load_dwordx4 v[200:203], v[208:209], off
	v_lshl_add_u64 v[208:209], v[208:209], 0, s[72:73]
	global_load_dwordx4 v[204:207], v[208:209], off
	ds_read_b128 v[6:9], v159
	v_lshl_add_u64 v[10:11], v[98:99], 0, s[80:81]
	v_mov_b64_e32 v[12:13], v[10:11]
	s_waitcnt vmcnt(7) lgkmcnt(0)
	v_pk_add_f32 v[176:177], v[6:7], v[176:177]
	v_pk_add_f32 v[178:179], v[8:9], v[178:179]
	global_store_dwordx4 v[46:47], v[176:179], off offset:512
	ds_read_b128 v[6:9], v159 offset:1024
	v_lshl_add_u64 v[12:13], v[12:13], 0, s[72:73]
	v_lshl_add_u64 v[14:15], v[10:11], 0, s[72:73]
	s_waitcnt vmcnt(7) lgkmcnt(0)
	v_pk_add_f32 v[180:181], v[6:7], v[180:181]
	v_pk_add_f32 v[182:183], v[8:9], v[182:183]
	global_store_dwordx4 v[10:11], v[180:183], off
	ds_read_b128 v[6:9], v159 offset:2048
	v_lshl_add_u64 v[10:11], v[12:13], 0, s[72:73]
	v_lshl_add_u64 v[12:13], v[14:15], 0, s[72:73]
	s_waitcnt vmcnt(7) lgkmcnt(0)
	v_pk_add_f32 v[184:185], v[6:7], v[184:185]
	v_pk_add_f32 v[186:187], v[8:9], v[186:187]
	global_store_dwordx4 v[14:15], v[184:187], off
	ds_read_b128 v[6:9], v159 offset:3072
	v_lshl_add_u64 v[10:11], v[10:11], 0, s[72:73]
	v_lshl_add_u64 v[14:15], v[12:13], 0, s[72:73]
	s_waitcnt vmcnt(7) lgkmcnt(0)
	v_pk_add_f32 v[188:189], v[6:7], v[188:189]
	v_pk_add_f32 v[190:191], v[8:9], v[190:191]
	global_store_dwordx4 v[12:13], v[188:191], off
	ds_read_b128 v[6:9], v159 offset:4096
	v_lshl_add_u64 v[10:11], v[10:11], 0, s[72:73]
	v_lshl_add_u64 v[12:13], v[14:15], 0, s[72:73]
	s_waitcnt vmcnt(7) lgkmcnt(0)
	v_pk_add_f32 v[192:193], v[6:7], v[192:193]
	v_pk_add_f32 v[194:195], v[8:9], v[194:195]
	global_store_dwordx4 v[14:15], v[192:195], off
	ds_read_b128 v[6:9], v159 offset:5120
	v_lshl_add_u64 v[10:11], v[10:11], 0, s[72:73]
	v_lshl_add_u64 v[14:15], v[12:13], 0, s[72:73]
	s_waitcnt vmcnt(7) lgkmcnt(0)
	v_pk_add_f32 v[196:197], v[6:7], v[196:197]
	v_pk_add_f32 v[198:199], v[8:9], v[198:199]
	global_store_dwordx4 v[12:13], v[196:199], off
	ds_read_b128 v[6:9], v159 offset:6144
	v_lshl_add_u64 v[10:11], v[10:11], 0, s[72:73]
	v_lshl_add_u64 v[12:13], v[14:15], 0, s[72:73]
	s_waitcnt vmcnt(7) lgkmcnt(0)
	v_pk_add_f32 v[200:201], v[6:7], v[200:201]
	v_pk_add_f32 v[202:203], v[8:9], v[202:203]
	global_store_dwordx4 v[14:15], v[200:203], off
	ds_read_b128 v[6:9], v159 offset:7168
	v_lshl_add_u64 v[10:11], v[10:11], 0, s[72:73]
	v_lshl_add_u64 v[14:15], v[12:13], 0, s[72:73]
	s_waitcnt vmcnt(7) lgkmcnt(0)
	v_pk_add_f32 v[204:205], v[6:7], v[204:205]
	v_pk_add_f32 v[206:207], v[8:9], v[206:207]
	global_store_dwordx4 v[12:13], v[204:207], off
	s_waitcnt lgkmcnt(0)
	s_barrier
	s_cbranch_vccz .LBB0_1442

; #define WAITL() asm volatile("s_waitcnt lgkmcnt(0)" ::: "memory")
; template <int EPI> ...
;     ...
;         WAITL();
; #pragma unroll
;         for (int m = 0; m < 4; ++m)
; #pragma unroll
;           for (int n = 0; n < 2; ++n)
; #pragma unroll
;             for (int j = 0; j < 4; ++j) ep[(m * 16 + fq * 4 + j) * 32 + n * 16 + fr] = acc[ai][bj][m][n][j];
;         WAITL();
;         const int grow0 = brow + ai * 128 + wr * 64, gcol0 = bcol + bj * 128 + wc * 32;
;         if (EPI == 1) {
;           const size_t idx0 = (size_t)(grow0 + (lane >> 3)) * 2048 + gcol0 + (lane & 7) * 4;
;           const float* xp = xin + idx0; float* op = xout + idx0; const float* lp = ep + (lane >> 3) * 32 + (lane & 7) * 4;
; #pragma unroll
;           for (int i = 0; i < 8; ++i) {
;             const float4 v = *(const float4*)(lp + i * 256);
;             float4 x = *(const float4*)xp;
;             x.x += v.x; x.y += v.y; x.z += v.z; x.w += v.w;
;             *(float4*)op = x;
;             xp += 16384; op += 16384;
;             asm volatile("" : "+v"(xp), "+v"(op));
;           }
.LBB0_1548:
	s_waitcnt lgkmcnt(0)
	ds_write2_b32 v159, v114, v126 offset1:16
	ds_write2_b32 v159, v115, v127 offset0:32 offset1:48
	ds_write2_b32 v159, v116, v128 offset0:64 offset1:80
	ds_write2_b32 v159, v117, v129 offset0:96 offset1:112
	v_add_u32_e32 v114, 0x800, v159
	s_and_b32 s35, s35, 0x7fffff8
	v_or_b32_e32 v144, s82, v1
	ds_write2_b32 v114, v106, v122 offset1:16
	ds_write2_b32 v114, v107, v123 offset0:32 offset1:48
	ds_write2_b32 v114, v108, v124 offset0:64 offset1:80
	ds_write2_b32 v114, v109, v125 offset0:96 offset1:112
	v_add_u32_e32 v106, 0x1000, v159
	v_or_b32_e32 v134, s35, v131
	v_ashrrev_i32_e32 v145, 31, v144
	ds_write2_b32 v106, v102, v118 offset1:16
	ds_write2_b32 v106, v103, v119 offset0:32 offset1:48
	ds_write2_b32 v106, v104, v120 offset0:64 offset1:80
	ds_write2_b32 v106, v105, v121 offset0:96 offset1:112
	v_add_u32_e32 v102, 0x1800, v159
	v_lshlrev_b32_e32 v142, 5, v134
	ds_write2_b32 v102, v98, v110 offset1:16
	ds_write2_b32 v102, v99, v111 offset0:32 offset1:48
	ds_write2_b32 v102, v100, v112 offset0:64 offset1:80
	ds_write2_b32 v102, v101, v113 offset0:96 offset1:112
	v_lshlrev_b64 v[98:99], 13, v[144:145]
	v_ashrrev_i32_e32 v143, 31, v142
	v_lshl_add_u64 v[98:99], v[140:141], 0, v[98:99]
	s_waitcnt lgkmcnt(0)
	v_lshl_add_u64 v[98:99], v[142:143], 2, v[98:99]
	global_load_dwordx4 v[176:179], v[98:99], off
	v_lshl_add_u64 v[208:209], v[98:99], 0, s[68:69]
	global_load_dwordx4 v[180:183], v[208:209], off
	v_lshl_add_u64 v[208:209], v[208:209], 0, s[68:69]
	global_load_dwordx4 v[184:187], v[208:209], off
	v_lshl_add_u64 v[208:209], v[208:209], 0, s[68:69]
	global_load_dwordx4 v[188:191], v[208:209], off
	v_lshl_add_u64 v[208:209], v[208:209], 0, s[68:69]
	global_load_dwordx4 v[192:195], v[208:209], off
	v_lshl_add_u64 v[208:209], v[208:209], 0, s[68:69]
	global_load_dwordx4 v[196:199], v[208:209], off
	v_lshl_add_u64 v[208:209], v[208:209], 0, s[68:69]
	global_load_dwordx4 v[200:203], v[208:209], off
	v_lshl_add_u64 v[208:209], v[208:209], 0, s[68:69]
	global_load_dwordx4 v[204:207], v[208:209], off
	ds_read_b128 v[116:119], v158
	v_lshl_add_u64 v[100:101], v[98:99], 0, s[68:69]
	v_mov_b64_e32 v[104:105], v[100:101]
	s_mov_b32 s35, s34
	s_waitcnt vmcnt(7) lgkmcnt(0)
	v_pk_add_f32 v[176:177], v[116:117], v[176:177]
	v_pk_add_f32 v[178:179], v[118:119], v[178:179]
	global_store_dwordx4 v[98:99], v[176:179], off
	ds_read_b128 v[116:119], v158 offset:1024
	v_lshl_add_u64 v[100:101], v[100:101], 0, s[68:69]
	v_lshl_add_u64 v[112:113], v[104:105], 0, s[68:69]
	s_waitcnt vmcnt(7) lgkmcnt(0)
	v_pk_add_f32 v[180:181], v[116:117], v[180:181]
	v_pk_add_f32 v[182:183], v[118:119], v[182:183]
	global_store_dwordx4 v[104:105], v[180:183], off
	ds_read_b128 v[116:119], v158 offset:2048
	v_lshl_add_u64 v[100:101], v[100:101], 0, s[68:69]
	v_lshl_add_u64 v[104:105], v[112:113], 0, s[68:69]
	s_waitcnt vmcnt(7) lgkmcnt(0)
	v_pk_add_f32 v[184:185], v[116:117], v[184:185]
	v_pk_add_f32 v[186:187], v[118:119], v[186:187]
	global_store_dwordx4 v[112:113], v[184:187], off
	ds_read_b128 v[116:119], v158 offset:3072
	v_lshl_add_u64 v[100:101], v[100:101], 0, s[68:69]
	v_lshl_add_u64 v[112:113], v[104:105], 0, s[68:69]
	s_waitcnt vmcnt(7) lgkmcnt(0)
	v_pk_add_f32 v[188:189], v[116:117], v[188:189]
	v_pk_add_f32 v[190:191], v[118:119], v[190:191]
	global_store_dwordx4 v[104:105], v[188:191], off
	ds_read_b128 v[116:119], v158 offset:4096
	v_lshl_add_u64 v[100:101], v[100:101], 0, s[68:69]
	v_lshl_add_u64 v[104:105], v[112:113], 0, s[68:69]
	s_waitcnt vmcnt(7) lgkmcnt(0)
	v_pk_add_f32 v[192:193], v[116:117], v[192:193]
	v_pk_add_f32 v[194:195], v[118:119], v[194:195]
	global_store_dwordx4 v[112:113], v[192:195], off
	ds_read_b128 v[116:119], v158 offset:5120
	v_lshl_add_u64 v[100:101], v[100:101], 0, s[68:69]
	v_lshl_add_u64 v[112:113], v[104:105], 0, s[68:69]
	s_waitcnt vmcnt(7) lgkmcnt(0)
	v_pk_add_f32 v[196:197], v[116:117], v[196:197]
	v_pk_add_f32 v[198:199], v[118:119], v[198:199]
	global_store_dwordx4 v[104:105], v[196:199], off
	ds_read_b128 v[116:119], v158 offset:6144
	v_lshl_add_u64 v[100:101], v[100:101], 0, s[68:69]
	v_lshl_add_u64 v[104:105], v[112:113], 0, s[68:69]
	s_waitcnt vmcnt(7) lgkmcnt(0)
	v_pk_add_f32 v[200:201], v[116:117], v[200:201]
	v_pk_add_f32 v[202:203], v[118:119], v[202:203]
	global_store_dwordx4 v[112:113], v[200:203], off
	ds_read_b128 v[116:119], v158 offset:7168
	v_lshl_add_u64 v[100:101], v[100:101], 0, s[68:69]
	v_lshl_add_u64 v[112:113], v[104:105], 0, s[68:69]
	s_waitcnt vmcnt(7) lgkmcnt(0)
	v_pk_add_f32 v[204:205], v[116:117], v[204:205]
	v_pk_add_f32 v[206:207], v[118:119], v[206:207]
	global_store_dwordx4 v[104:105], v[204:207], off
	s_waitcnt lgkmcnt(0)
	ds_write2_b32 v159, v66, v82 offset1:16
	ds_write2_b32 v159, v67, v83 offset0:32 offset1:48
	ds_write2_b32 v159, v68, v84 offset0:64 offset1:80
	ds_write2_b32 v159, v69, v85 offset0:96 offset1:112
	ds_write2_b32 v114, v70, v86 offset1:16
	ds_write2_b32 v114, v71, v87 offset0:32 offset1:48
	ds_write2_b32 v114, v72, v88 offset0:64 offset1:80
	ds_write2_b32 v114, v73, v89 offset0:96 offset1:112
	ds_write2_b32 v106, v74, v90 offset1:16
	ds_write2_b32 v106, v75, v91 offset0:32 offset1:48
	ds_write2_b32 v106, v76, v92 offset0:64 offset1:80
	ds_write2_b32 v106, v77, v93 offset0:96 offset1:112
	ds_write2_b32 v102, v78, v94 offset1:16
	ds_write2_b32 v102, v79, v95 offset0:32 offset1:48
	ds_write2_b32 v102, v80, v96 offset0:64 offset1:80
	ds_write2_b32 v102, v81, v97 offset0:96 offset1:112
	s_waitcnt lgkmcnt(0)
; #define WAITL() asm volatile("s_waitcnt lgkmcnt(0)" ::: "memory")
; template <int EPI> ...
;     ...
;         WAITL();
; #pragma unroll
;         for (int m = 0; m < 4; ++m)
; #pragma unroll
;           for (int n = 0; n < 2; ++n)
; #pragma unroll
;             for (int j = 0; j < 4; ++j) ep[(m * 16 + fq * 4 + j) * 32 + n * 16 + fr] = acc[ai][bj][m][n][j];
;         WAITL();
;         const int grow0 = brow + ai * 128 + wr * 64, gcol0 = bcol + bj * 128 + wc * 32;
;         if (EPI == 1) {
;           const size_t idx0 = (size_t)(grow0 + (lane >> 3)) * 2048 + gcol0 + (lane & 7) * 4;
;           const float* xp = xin + idx0; float* op = xout + idx0; const float* lp = ep + (lane >> 3) * 32 + (lane & 7) * 4;
; #pragma unroll
;           for (int i = 0; i < 8; ++i) {
;             const float4 v = *(const float4*)(lp + i * 256);
;             float4 x = *(const float4*)xp;
;             x.x += v.x; x.y += v.y; x.z += v.z; x.w += v.w;
;             *(float4*)op = x;
;             xp += 16384; op += 16384;
;             asm volatile("" : "+v"(xp), "+v"(op));
;           }
	global_load_dwordx4 v[176:179], v[98:99], off offset:512
	v_lshl_add_u64 v[208:209], v[98:99], 0, s[70:71]
	global_load_dwordx4 v[180:183], v[208:209], off
	v_lshl_add_u64 v[208:209], v[208:209], 0, s[68:69]
	global_load_dwordx4 v[184:187], v[208:209], off
	v_lshl_add_u64 v[208:209], v[208:209], 0, s[68:69]
	global_load_dwordx4 v[188:191], v[208:209], off
	v_lshl_add_u64 v[208:209], v[208:209], 0, s[68:69]
	global_load_dwordx4 v[192:195], v[208:209], off
	v_lshl_add_u64 v[208:209], v[208:209], 0, s[68:69]
	global_load_dwordx4 v[196:199], v[208:209], off
	v_lshl_add_u64 v[208:209], v[208:209], 0, s[68:69]
	global_load_dwordx4 v[200:203], v[208:209], off
	v_lshl_add_u64 v[208:209], v[208:209], 0, s[68:69]
	global_load_dwordx4 v[204:207], v[208:209], off
	ds_read_b128 v[70:73], v158
	v_lshl_add_u64 v[74:75], v[98:99], 0, s[70:71]
	v_mov_b64_e32 v[76:77], v[74:75]
	s_waitcnt vmcnt(7) lgkmcnt(0)
	v_pk_add_f32 v[176:177], v[70:71], v[176:177]
	v_pk_add_f32 v[178:179], v[72:73], v[178:179]
	global_store_dwordx4 v[98:99], v[176:179], off offset:512
	ds_read_b128 v[70:73], v158 offset:1024
	v_lshl_add_u64 v[74:75], v[74:75], 0, s[68:69]
	v_lshl_add_u64 v[78:79], v[76:77], 0, s[68:69]
	s_waitcnt vmcnt(7) lgkmcnt(0)
	v_pk_add_f32 v[180:181], v[70:71], v[180:181]
	v_pk_add_f32 v[182:183], v[72:73], v[182:183]
	global_store_dwordx4 v[76:77], v[180:183], off
	ds_read_b128 v[70:73], v158 offset:2048
	v_lshl_add_u64 v[74:75], v[74:75], 0, s[68:69]
	v_lshl_add_u64 v[76:77], v[78:79], 0, s[68:69]
	s_waitcnt vmcnt(7) lgkmcnt(0)
	v_pk_add_f32 v[184:185], v[70:71], v[184:185]
	v_pk_add_f32 v[186:187], v[72:73], v[186:187]
	global_store_dwordx4 v[78:79], v[184:187], off
	ds_read_b128 v[70:73], v158 offset:3072
	v_lshl_add_u64 v[74:75], v[74:75], 0, s[68:69]
	v_lshl_add_u64 v[78:79], v[76:77], 0, s[68:69]
	s_waitcnt vmcnt(7) lgkmcnt(0)
	v_pk_add_f32 v[188:189], v[70:71], v[188:189]
	v_pk_add_f32 v[190:191], v[72:73], v[190:191]
	global_store_dwordx4 v[76:77], v[188:191], off
	ds_read_b128 v[70:73], v158 offset:4096
	v_lshl_add_u64 v[74:75], v[74:75], 0, s[68:69]
	v_lshl_add_u64 v[76:77], v[78:79], 0, s[68:69]
	s_waitcnt vmcnt(7) lgkmcnt(0)
	v_pk_add_f32 v[192:193], v[70:71], v[192:193]
	v_pk_add_f32 v[194:195], v[72:73], v[194:195]
	global_store_dwordx4 v[78:79], v[192:195], off
	ds_read_b128 v[70:73], v158 offset:5120
	v_lshl_add_u64 v[74:75], v[74:75], 0, s[68:69]
	v_lshl_add_u64 v[78:79], v[76:77], 0, s[68:69]
	s_waitcnt vmcnt(7) lgkmcnt(0)
	v_pk_add_f32 v[196:197], v[70:71], v[196:197]
	v_pk_add_f32 v[198:199], v[72:73], v[198:199]
	global_store_dwordx4 v[76:77], v[196:199], off
	ds_read_b128 v[70:73], v158 offset:6144
	v_lshl_add_u64 v[74:75], v[74:75], 0, s[68:69]
	v_lshl_add_u64 v[76:77], v[78:79], 0, s[68:69]
	s_waitcnt vmcnt(7) lgkmcnt(0)
	v_pk_add_f32 v[200:201], v[70:71], v[200:201]
	v_pk_add_f32 v[202:203], v[72:73], v[202:203]
	global_store_dwordx4 v[78:79], v[200:203], off
	ds_read_b128 v[70:73], v158 offset:7168
	v_lshl_add_u64 v[74:75], v[74:75], 0, s[68:69]
	v_lshl_add_u64 v[80:81], v[76:77], 0, s[68:69]
	v_add_co_u32_e32 v78, vcc, s10, v98
	s_waitcnt vmcnt(7) lgkmcnt(0)
	v_pk_add_f32 v[204:205], v[70:71], v[204:205]
	v_pk_add_f32 v[206:207], v[72:73], v[206:207]
	global_store_dwordx4 v[76:77], v[204:207], off
	s_waitcnt lgkmcnt(0)
	ds_write2_b32 v159, v34, v50 offset1:16
	ds_write2_b32 v159, v35, v51 offset0:32 offset1:48
	ds_write2_b32 v159, v36, v52 offset0:64 offset1:80
	ds_write2_b32 v159, v37, v53 offset0:96 offset1:112
	ds_write2_b32 v114, v38, v54 offset1:16
	ds_write2_b32 v114, v39, v55 offset0:32 offset1:48
	ds_write2_b32 v114, v40, v56 offset0:64 offset1:80
	ds_write2_b32 v114, v41, v57 offset0:96 offset1:112
	ds_write2_b32 v106, v42, v58 offset1:16
	ds_write2_b32 v106, v43, v59 offset0:32 offset1:48
	ds_write2_b32 v106, v44, v60 offset0:64 offset1:80
	ds_write2_b32 v106, v45, v61 offset0:96 offset1:112
	ds_write2_b32 v102, v46, v62 offset1:16
	ds_write2_b32 v102, v47, v63 offset0:32 offset1:48
	ds_write2_b32 v102, v48, v64 offset0:64 offset1:80
	ds_write2_b32 v102, v49, v65 offset0:96 offset1:112
	v_addc_co_u32_e32 v79, vcc, 0, v99, vcc
	s_waitcnt lgkmcnt(0)
	global_load_dwordx4 v[176:179], v[78:79], off
	v_lshl_add_u64 v[208:209], v[98:99], 0, s[72:73]
	global_load_dwordx4 v[180:183], v[208:209], off
	v_lshl_add_u64 v[208:209], v[208:209], 0, s[68:69]
	global_load_dwordx4 v[184:187], v[208:209], off
	v_lshl_add_u64 v[208:209], v[208:209], 0, s[68:69]
	global_load_dwordx4 v[188:191], v[208:209], off
	v_lshl_add_u64 v[208:209], v[208:209], 0, s[68:69]
	global_load_dwordx4 v[192:195], v[208:209], off
	v_lshl_add_u64 v[208:209], v[208:209], 0, s[68:69]
	global_load_dwordx4 v[196:199], v[208:209], off
	v_lshl_add_u64 v[208:209], v[208:209], 0, s[68:69]
	global_load_dwordx4 v[200:203], v[208:209], off
	v_lshl_add_u64 v[208:209], v[208:209], 0, s[68:69]
	global_load_dwordx4 v[204:207], v[208:209], off
	ds_read_b128 v[38:41], v158
	v_lshl_add_u64 v[42:43], v[98:99], 0, s[72:73]
	v_mov_b64_e32 v[44:45], v[42:43]
	s_andn2_b64 vcc, exec, s[76:77]
	s_waitcnt vmcnt(7) lgkmcnt(0)
	v_pk_add_f32 v[176:177], v[38:39], v[176:177]
	v_pk_add_f32 v[178:179], v[40:41], v[178:179]
	global_store_dwordx4 v[78:79], v[176:179], off
	ds_read_b128 v[38:41], v158 offset:1024
	v_lshl_add_u64 v[42:43], v[42:43], 0, s[68:69]
	v_lshl_add_u64 v[46:47], v[44:45], 0, s[68:69]
	s_waitcnt vmcnt(7) lgkmcnt(0)
	v_pk_add_f32 v[180:181], v[38:39], v[180:181]
	v_pk_add_f32 v[182:183], v[40:41], v[182:183]
	global_store_dwordx4 v[44:45], v[180:183], off
	ds_read_b128 v[38:41], v158 offset:2048
	v_lshl_add_u64 v[42:43], v[42:43], 0, s[68:69]
	v_lshl_add_u64 v[44:45], v[46:47], 0, s[68:69]
	s_waitcnt vmcnt(7) lgkmcnt(0)
; template <int EPI> ...
;     ...
;         const int grow0 = brow + ai * 128 + wr * 64, gcol0 = bcol + bj * 128 + wc * 32;
;         if (EPI == 1) {
;           const size_t idx0 = (size_t)(grow0 + (lane >> 3)) * 2048 + gcol0 + (lane & 7) * 4;
;           const float* xp = xin + idx0; float* op = xout + idx0; const float* lp = ep + (lane >> 3) * 32 + (lane & 7) * 4;
; #pragma unroll
;           for (int i = 0; i < 8; ++i) {
;             const float4 v = *(const float4*)(lp + i * 256);
;             float4 x = *(const float4*)xp;
;             x.x += v.x; x.y += v.y; x.z += v.z; x.w += v.w;
;             *(float4*)op = x;
;             xp += 16384; op += 16384;
;             asm volatile("" : "+v"(xp), "+v"(op));
;           }
	v_pk_add_f32 v[184:185], v[38:39], v[184:185]
	v_pk_add_f32 v[186:187], v[40:41], v[186:187]
	global_store_dwordx4 v[46:47], v[184:187], off
	ds_read_b128 v[38:41], v158 offset:3072
	v_lshl_add_u64 v[42:43], v[42:43], 0, s[68:69]
	v_lshl_add_u64 v[46:47], v[44:45], 0, s[68:69]
	s_waitcnt vmcnt(7) lgkmcnt(0)
	v_pk_add_f32 v[188:189], v[38:39], v[188:189]
	v_pk_add_f32 v[190:191], v[40:41], v[190:191]
	global_store_dwordx4 v[44:45], v[188:191], off
	ds_read_b128 v[38:41], v158 offset:4096
	v_lshl_add_u64 v[42:43], v[42:43], 0, s[68:69]
	v_lshl_add_u64 v[44:45], v[46:47], 0, s[68:69]
	s_waitcnt vmcnt(7) lgkmcnt(0)
	v_pk_add_f32 v[192:193], v[38:39], v[192:193]
	v_pk_add_f32 v[194:195], v[40:41], v[194:195]
	global_store_dwordx4 v[46:47], v[192:195], off
	ds_read_b128 v[38:41], v158 offset:5120
	v_lshl_add_u64 v[42:43], v[42:43], 0, s[68:69]
	v_lshl_add_u64 v[46:47], v[44:45], 0, s[68:69]
	s_waitcnt vmcnt(7) lgkmcnt(0)
	v_pk_add_f32 v[196:197], v[38:39], v[196:197]
	v_pk_add_f32 v[198:199], v[40:41], v[198:199]
	global_store_dwordx4 v[44:45], v[196:199], off
	ds_read_b128 v[38:41], v158 offset:6144
	v_lshl_add_u64 v[42:43], v[42:43], 0, s[68:69]
	v_lshl_add_u64 v[44:45], v[46:47], 0, s[68:69]
	s_waitcnt vmcnt(7) lgkmcnt(0)
	v_pk_add_f32 v[200:201], v[38:39], v[200:201]
	v_pk_add_f32 v[202:203], v[40:41], v[202:203]
	global_store_dwordx4 v[46:47], v[200:203], off
	ds_read_b128 v[38:41], v158 offset:7168
	v_lshl_add_u64 v[42:43], v[42:43], 0, s[68:69]
	v_lshl_add_u64 v[48:49], v[44:45], 0, s[68:69]
	v_lshl_add_u64 v[46:47], v[98:99], 0, s[4:5]
	s_waitcnt vmcnt(7) lgkmcnt(0)
	v_pk_add_f32 v[204:205], v[38:39], v[204:205]
	v_pk_add_f32 v[206:207], v[40:41], v[206:207]
	global_store_dwordx4 v[44:45], v[204:207], off
	s_waitcnt lgkmcnt(0)
	ds_write2_b32 v159, v2, v18 offset1:16
	ds_write2_b32 v159, v3, v19 offset0:32 offset1:48
	ds_write2_b32 v159, v4, v20 offset0:64 offset1:80
	ds_write2_b32 v159, v5, v21 offset0:96 offset1:112
	ds_write2_b32 v114, v6, v22 offset1:16
	ds_write2_b32 v114, v7, v23 offset0:32 offset1:48
	ds_write2_b32 v114, v8, v24 offset0:64 offset1:80
	ds_write2_b32 v114, v9, v25 offset0:96 offset1:112
	ds_write2_b32 v106, v10, v26 offset1:16
	ds_write2_b32 v106, v11, v27 offset0:32 offset1:48
	ds_write2_b32 v106, v12, v28 offset0:64 offset1:80
	ds_write2_b32 v106, v13, v29 offset0:96 offset1:112
	ds_write2_b32 v102, v14, v30 offset1:16
	ds_write2_b32 v102, v15, v31 offset0:32 offset1:48
	ds_write2_b32 v102, v16, v32 offset0:64 offset1:80
	ds_write2_b32 v102, v17, v33 offset0:96 offset1:112
	s_waitcnt lgkmcnt(0)
	global_load_dwordx4 v[176:179], v[46:47], off offset:512
	v_lshl_add_u64 v[208:209], v[98:99], 0, s[74:75]
	global_load_dwordx4 v[180:183], v[208:209], off
	v_lshl_add_u64 v[208:209], v[208:209], 0, s[68:69]
	global_load_dwordx4 v[184:187], v[208:209], off
	v_lshl_add_u64 v[208:209], v[208:209], 0, s[68:69]
	global_load_dwordx4 v[188:191], v[208:209], off
	v_lshl_add_u64 v[208:209], v[208:209], 0, s[68:69]
	global_load_dwordx4 v[192:195], v[208:209], off
	v_lshl_add_u64 v[208:209], v[208:209], 0, s[68:69]
	global_load_dwordx4 v[196:199], v[208:209], off
	v_lshl_add_u64 v[208:209], v[208:209], 0, s[68:69]
	global_load_dwordx4 v[200:203], v[208:209], off
	v_lshl_add_u64 v[208:209], v[208:209], 0, s[68:69]
	global_load_dwordx4 v[204:207], v[208:209], off
	ds_read_b128 v[6:9], v158
	v_lshl_add_u64 v[10:11], v[98:99], 0, s[74:75]
	v_mov_b64_e32 v[12:13], v[10:11]
	s_waitcnt vmcnt(7) lgkmcnt(0)
	v_pk_add_f32 v[176:177], v[6:7], v[176:177]
	v_pk_add_f32 v[178:179], v[8:9], v[178:179]
	global_store_dwordx4 v[46:47], v[176:179], off offset:512
	ds_read_b128 v[6:9], v158 offset:1024
	v_lshl_add_u64 v[10:11], v[10:11], 0, s[68:69]
	v_lshl_add_u64 v[14:15], v[12:13], 0, s[68:69]
	s_waitcnt vmcnt(7) lgkmcnt(0)
	v_pk_add_f32 v[180:181], v[6:7], v[180:181]
	v_pk_add_f32 v[182:183], v[8:9], v[182:183]
	global_store_dwordx4 v[12:13], v[180:183], off
	ds_read_b128 v[6:9], v158 offset:2048
	v_lshl_add_u64 v[10:11], v[10:11], 0, s[68:69]
	v_lshl_add_u64 v[12:13], v[14:15], 0, s[68:69]
	s_waitcnt vmcnt(7) lgkmcnt(0)
	v_pk_add_f32 v[184:185], v[6:7], v[184:185]
	v_pk_add_f32 v[186:187], v[8:9], v[186:187]
	global_store_dwordx4 v[14:15], v[184:187], off
	ds_read_b128 v[6:9], v158 offset:3072
	v_lshl_add_u64 v[10:11], v[10:11], 0, s[68:69]
	v_lshl_add_u64 v[14:15], v[12:13], 0, s[68:69]
	s_waitcnt vmcnt(7) lgkmcnt(0)
	v_pk_add_f32 v[188:189], v[6:7], v[188:189]
	v_pk_add_f32 v[190:191], v[8:9], v[190:191]
	global_store_dwordx4 v[12:13], v[188:191], off
	ds_read_b128 v[6:9], v158 offset:4096
	v_lshl_add_u64 v[10:11], v[10:11], 0, s[68:69]
	v_lshl_add_u64 v[12:13], v[14:15], 0, s[68:69]
	s_waitcnt vmcnt(7) lgkmcnt(0)
	v_pk_add_f32 v[192:193], v[6:7], v[192:193]
	v_pk_add_f32 v[194:195], v[8:9], v[194:195]
	global_store_dwordx4 v[14:15], v[192:195], off
	ds_read_b128 v[6:9], v158 offset:5120
	v_lshl_add_u64 v[10:11], v[10:11], 0, s[68:69]
	v_lshl_add_u64 v[14:15], v[12:13], 0, s[68:69]
	s_waitcnt vmcnt(7) lgkmcnt(0)
	v_pk_add_f32 v[196:197], v[6:7], v[196:197]
	v_pk_add_f32 v[198:199], v[8:9], v[198:199]
	global_store_dwordx4 v[12:13], v[196:199], off
	ds_read_b128 v[6:9], v158 offset:6144
	v_lshl_add_u64 v[10:11], v[10:11], 0, s[68:69]
	v_lshl_add_u64 v[12:13], v[14:15], 0, s[68:69]
	s_waitcnt vmcnt(7) lgkmcnt(0)
	v_pk_add_f32 v[200:201], v[6:7], v[200:201]
	v_pk_add_f32 v[202:203], v[8:9], v[202:203]
	global_store_dwordx4 v[14:15], v[200:203], off
	ds_read_b128 v[6:9], v158 offset:7168
	v_lshl_add_u64 v[10:11], v[10:11], 0, s[68:69]
	v_lshl_add_u64 v[14:15], v[12:13], 0, s[68:69]
	s_waitcnt vmcnt(7) lgkmcnt(0)
	v_pk_add_f32 v[204:205], v[6:7], v[204:205]
	v_pk_add_f32 v[206:207], v[8:9], v[206:207]
	global_store_dwordx4 v[12:13], v[204:207], off
	s_waitcnt lgkmcnt(0)
	s_barrier
	s_cbranch_vccz .LBB0_1565

; #define PH(n, ...) if (ph_begin <= (n) && (n) < ph_end) { __VA_ARGS__; if ((n) + 1 < ph_end) gsync(grid, bar_ctr, nbar); }
; __global__ void __launch_bounds__(NTHR) fwd_kernel(Params p, int ph_begin, int ph_end) {
;   extern __shared__ __attribute__((aligned(16))) char smem[];
;   cg::grid_group grid = cg::this_grid();
;   unsigned* bar_ctr = (unsigned*)(p.ws + OFF_CNT) + 200;
;   int nbar = 0;
;   PH(0, convert_phase(p, smem); norm_phase(p.in[0], p.in[1], (u16*)(p.ws + OFF_HM), nullptr))
;   layer_phases<0>(p, ph_begin, ph_end, grid, bar_ctr, nbar, smem);
;   layer_phases<1>(p, ph_begin, ph_end, grid, bar_ctr, nbar, smem);
;   PH(19, norm_phase(p.out, p.in[34], nullptr, p.out))
;     ...
; }
	.amdhsa_kernel _Z10fwd_kernel6Paramsii
		.amdhsa_group_segment_fixed_size 16
		.amdhsa_private_segment_fixed_size 0
		.amdhsa_kernarg_size 560
		.amdhsa_user_sgpr_count 2
		.amdhsa_user_sgpr_dispatch_ptr 0
		.amdhsa_user_sgpr_queue_ptr 0
		.amdhsa_user_sgpr_kernarg_segment_ptr 1
		.amdhsa_user_sgpr_dispatch_id 0
		.amdhsa_user_sgpr_kernarg_preload_length 0
		.amdhsa_user_sgpr_kernarg_preload_offset 0
		.amdhsa_user_sgpr_private_segment_size 0
		.amdhsa_uses_dynamic_stack 0
		.amdhsa_enable_private_segment 0
		.amdhsa_system_sgpr_workgroup_id_x 1
		.amdhsa_system_sgpr_workgroup_id_y 0
		.amdhsa_system_sgpr_workgroup_id_z 0
		.amdhsa_system_sgpr_workgroup_info 0
		.amdhsa_system_vgpr_workitem_id 2
		.amdhsa_next_free_vgpr 256
		.amdhsa_next_free_sgpr 100
		.amdhsa_accum_offset 256
		.amdhsa_reserve_vcc 1
		.amdhsa_float_round_mode_32 0
		.amdhsa_float_round_mode_16_64 0
		.amdhsa_float_denorm_mode_32 3
		.amdhsa_float_denorm_mode_16_64 3
		.amdhsa_dx10_clamp 1
		.amdhsa_ieee_mode 1
		.amdhsa_fp16_overflow 0
		.amdhsa_tg_split 0
		.amdhsa_exception_fp_ieee_invalid_op 0
		.amdhsa_exception_fp_denorm_src 0
		.amdhsa_exception_fp_ieee_div_zero 0
		.amdhsa_exception_fp_ieee_overflow 0
		.amdhsa_exception_fp_ieee_underflow 0
		.amdhsa_exception_fp_ieee_inexact 0
		.amdhsa_exception_int_div_zero 0
	.end_amdhsa_kernel

; #define PH(n, ...) if (ph_begin <= (n) && (n) < ph_end) { __VA_ARGS__; if ((n) + 1 < ph_end) gsync(grid, bar_ctr, nbar); }
; __global__ void __launch_bounds__(NTHR) fwd_kernel(Params p, int ph_begin, int ph_end) {
;   extern __shared__ __attribute__((aligned(16))) char smem[];
;   cg::grid_group grid = cg::this_grid();
;   unsigned* bar_ctr = (unsigned*)(p.ws + OFF_CNT) + 200;
;   int nbar = 0;
;   PH(0, convert_phase(p, smem); norm_phase(p.in[0], p.in[1], (u16*)(p.ws + OFF_HM), nullptr))
;   layer_phases<0>(p, ph_begin, ph_end, grid, bar_ctr, nbar, smem);
;   layer_phases<1>(p, ph_begin, ph_end, grid, bar_ctr, nbar, smem);
;   PH(19, norm_phase(p.out, p.in[34], nullptr, p.out))
;     ...
; }
amdhsa.kernels:
  - .agpr_count:     0
    .args:
      - .offset:         0
        .size:           296
        .value_kind:     by_value
      - .offset:         296
        .size:           4
        .value_kind:     by_value
      - .offset:         300
        .size:           4
        .value_kind:     by_value
      - .offset:         304
        .size:           4
        .value_kind:     hidden_block_count_x
      - .offset:         308
        .size:           4
        .value_kind:     hidden_block_count_y
      - .offset:         312
        .size:           4
        .value_kind:     hidden_block_count_z
      - .offset:         316
        .size:           2
        .value_kind:     hidden_group_size_x
      - .offset:         318
        .size:           2
        .value_kind:     hidden_group_size_y
      - .offset:         320
        .size:           2
        .value_kind:     hidden_group_size_z
      - .offset:         322
        .size:           2
        .value_kind:     hidden_remainder_x
      - .offset:         324
        .size:           2
        .value_kind:     hidden_remainder_y
      - .offset:         326
        .size:           2
        .value_kind:     hidden_remainder_z
      - .offset:         344
        .size:           8
        .value_kind:     hidden_global_offset_x
      - .offset:         352
        .size:           8
        .value_kind:     hidden_global_offset_y
      - .offset:         360
        .size:           8
        .value_kind:     hidden_global_offset_z
      - .offset:         368
        .size:           2
        .value_kind:     hidden_grid_dims
      - .offset:         392
        .size:           8
        .value_kind:     hidden_multigrid_sync_arg
      - .offset:         424
        .size:           4
        .value_kind:     hidden_dynamic_lds_size
    .group_segment_fixed_size: 16
    .kernarg_segment_align: 8
    .kernarg_segment_size: 560
    .language:       OpenCL C
    .language_version:
      - 2
      - 0
    .max_flat_workgroup_size: 512
    .name:           _Z10fwd_kernel6Paramsii
    .private_segment_fixed_size: 0
    .sgpr_count:     106
    .sgpr_spill_count: 53
    .symbol:         _Z10fwd_kernel6Paramsii.kd
    .uniform_work_group_size: 1
    .uses_dynamic_stack: false
    .vgpr_count:     256
    .vgpr_spill_count: 0
    .wavefront_size: 64
